# one kernel-wide static s_setprio 1 for workgroups 256..511, all per-segment priority flips removed
# baseline (speedup 1.0000x reference)
_Z6k_mega6Params:
	s_cmpk_gt_u32 s2, 0xff
	s_cbranch_scc0 .Lkprio0
	s_setprio 1
.Lkprio0:
	s_load_dwordx8 s[68:75], s[0:1], 0xa0
	s_load_dwordx8 s[80:87], s[0:1], 0x80
	s_add_u32 s22, s0, 0xb8
	s_addc_u32 s23, s1, 0
	v_and_b32_e32 v220, 0x3ff, v0
	v_cmp_eq_u32_e64 s[6:7], 0, v220
	s_mov_b64 s[4:5], exec
	s_nop 0
	v_writelane_b32 v254, s6, 0
	s_nop 1
	v_writelane_b32 v254, s7, 1
	s_and_b64 s[6:7], s[4:5], s[6:7]
	s_mov_b64 exec, s[6:7]
	s_cbranch_execz .LBB0_2
	v_mov_b32_e32 v2, 0
	v_mov_b32_e32 v3, v2
	v_mov_b32_e32 v4, v2
	v_mov_b32_e32 v5, v2
	v_mov_b32_e32 v1, 0x10600
	ds_write_b128 v1, v[2:5]

.LBB0_208:
	s_add_i32 s27, s5, 64
	s_min_u32 s30, s27, 0x3e0
	s_lshl_b32 s30, s30, 1
	v_lshl_add_u64 v[180:181], v[154:155], 0, s[30:31]
	v_lshl_add_u64 v[184:185], v[158:159], 0, s[30:31]
	v_lshl_add_u64 v[188:189], v[160:161], 0, s[30:31]
	v_lshl_add_u64 v[192:193], v[162:163], 0, s[30:31]
	v_lshl_add_u64 v[196:197], v[156:157], 0, s[30:31]
	v_lshl_add_u64 v[200:201], v[164:165], 0, s[30:31]
	global_load_dwordx4 v[180:183], v[180:181], off
	ds_read_b128 v[204:207], v178 offset:32768
	global_load_dwordx4 v[184:187], v[184:185], off
	ds_read_b128 v[208:211], v178 offset:33792
	global_load_dwordx4 v[188:191], v[188:189], off
	ds_read_b128 v[212:215], v178 offset:34816
	global_load_dwordx4 v[192:195], v[192:193], off
	ds_read_b128 v[216:219], v178 offset:35840
	global_load_dwordx4 v[196:199], v[196:197], off
	ds_read_b128 v[222:225], v176
	global_load_dwordx4 v[200:203], v[200:201], off
	ds_read_b128 v[226:229], v176 offset:1024
	ds_read_b128 v[230:233], v176 offset:2048
	ds_read_b128 v[234:237], v176 offset:3072
	ds_read_b128 v[238:241], v176 offset:4096
	ds_read_b128 v[242:245], v176 offset:5120
	ds_read_b128 v[246:249], v176 offset:6144
	ds_read_b128 v[250:253], v176 offset:7168
	s_waitcnt lgkmcnt(7)
	v_mfma_f32_16x16x32_bf16 v[124:127], v[222:225], v[204:207], v[124:127]
	v_mfma_f32_16x16x32_bf16 v[120:123], v[222:225], v[208:211], v[120:123]
	v_mfma_f32_16x16x32_bf16 v[60:63], v[222:225], v[212:215], v[60:63]
	v_mfma_f32_16x16x32_bf16 v[56:59], v[222:225], v[216:219], v[56:59]
	s_waitcnt vmcnt(11)
	ds_write_b128 v152, v[128:131] offset:16384
	s_waitcnt lgkmcnt(7)
	v_mfma_f32_16x16x32_bf16 v[116:119], v[226:229], v[204:207], v[116:119]
	v_mfma_f32_16x16x32_bf16 v[112:115], v[226:229], v[208:211], v[112:115]
	v_mfma_f32_16x16x32_bf16 v[52:55], v[226:229], v[212:215], v[52:55]
	v_mfma_f32_16x16x32_bf16 v[48:51], v[226:229], v[216:219], v[48:51]
	s_waitcnt vmcnt(9)
	ds_write_b128 v152, v[136:139] offset:20480
	s_waitcnt lgkmcnt(7)
	v_mfma_f32_16x16x32_bf16 v[108:111], v[230:233], v[204:207], v[108:111]
	v_mfma_f32_16x16x32_bf16 v[104:107], v[230:233], v[208:211], v[104:107]
	v_mfma_f32_16x16x32_bf16 v[44:47], v[230:233], v[212:215], v[44:47]
	v_mfma_f32_16x16x32_bf16 v[40:43], v[230:233], v[216:219], v[40:43]
	s_waitcnt vmcnt(8)
	ds_write_b128 v152, v[140:143] offset:24576
	s_waitcnt lgkmcnt(7)
	v_mfma_f32_16x16x32_bf16 v[100:103], v[234:237], v[204:207], v[100:103]
	v_mfma_f32_16x16x32_bf16 v[96:99], v[234:237], v[208:211], v[96:99]
	v_mfma_f32_16x16x32_bf16 v[36:39], v[234:237], v[212:215], v[36:39]
	v_mfma_f32_16x16x32_bf16 v[32:35], v[234:237], v[216:219], v[32:35]
	s_waitcnt vmcnt(7)
	ds_write_b128 v152, v[144:147] offset:28672
	s_waitcnt lgkmcnt(7)
	v_mfma_f32_16x16x32_bf16 v[92:95], v[238:241], v[204:207], v[92:95]
	v_mfma_f32_16x16x32_bf16 v[88:91], v[238:241], v[208:211], v[88:91]
	v_mfma_f32_16x16x32_bf16 v[28:31], v[238:241], v[212:215], v[28:31]
	v_mfma_f32_16x16x32_bf16 v[24:27], v[238:241], v[216:219], v[24:27]
	s_waitcnt vmcnt(7)
	ds_write_b128 v152, v[132:135] offset:40960
	s_waitcnt lgkmcnt(7)
	v_mfma_f32_16x16x32_bf16 v[84:87], v[242:245], v[204:207], v[84:87]
	v_mfma_f32_16x16x32_bf16 v[80:83], v[242:245], v[208:211], v[80:83]
	v_mfma_f32_16x16x32_bf16 v[20:23], v[242:245], v[212:215], v[20:23]
	v_mfma_f32_16x16x32_bf16 v[16:19], v[242:245], v[216:219], v[16:19]
	s_waitcnt vmcnt(6)
	ds_write_b128 v152, v[148:151] offset:45056
	s_waitcnt lgkmcnt(7)
	v_mfma_f32_16x16x32_bf16 v[76:79], v[246:249], v[204:207], v[76:79]
	v_mfma_f32_16x16x32_bf16 v[72:75], v[246:249], v[208:211], v[72:75]
	v_mfma_f32_16x16x32_bf16 v[12:15], v[246:249], v[212:215], v[12:15]
	v_mfma_f32_16x16x32_bf16 v[8:11], v[246:249], v[216:219], v[8:11]
	s_waitcnt lgkmcnt(6)
	v_mfma_f32_16x16x32_bf16 v[68:71], v[250:253], v[204:207], v[68:71]
	v_mfma_f32_16x16x32_bf16 v[64:67], v[250:253], v[208:211], v[64:67]
	v_mfma_f32_16x16x32_bf16 v[4:7], v[250:253], v[212:215], v[4:7]
	v_mfma_f32_16x16x32_bf16 v[0:3], v[250:253], v[216:219], v[0:3]
	s_min_u32 s5, s5, 0x380
	s_lshl_b32 s30, s5, 1
	s_mov_b32 s53, s31
	s_add_i32 s52, s30, 0xc0
	v_lshl_add_u64 v[128:129], v[154:155], 0, s[30:31]
	v_lshl_add_u64 v[132:133], v[156:157], 0, s[30:31]
	v_lshl_add_u64 v[136:137], v[158:159], 0, s[52:53]
	v_lshl_add_u64 v[140:141], v[160:161], 0, s[52:53]
	v_lshl_add_u64 v[144:145], v[162:163], 0, s[52:53]
	v_lshl_add_u64 v[148:149], v[164:165], 0, s[52:53]
	s_waitcnt lgkmcnt(0)
	s_barrier
	global_load_dwordx4 v[128:131], v[128:129], off offset:192
	ds_read_b128 v[204:207], v175 offset:40960
	global_load_dwordx4 v[132:135], v[132:133], off offset:192
	ds_read_b128 v[208:211], v175 offset:41984
	global_load_dwordx4 v[136:139], v[136:137], off
	ds_read_b128 v[212:215], v175 offset:43008
	global_load_dwordx4 v[140:143], v[140:141], off
	ds_read_b128 v[216:219], v175 offset:44032
	global_load_dwordx4 v[144:147], v[144:145], off
	ds_read_b128 v[222:225], v177
	global_load_dwordx4 v[148:151], v[148:149], off
	ds_read_b128 v[226:229], v177 offset:1024
	ds_read_b128 v[230:233], v177 offset:2048
	ds_read_b128 v[234:237], v177 offset:3072
	ds_read_b128 v[238:241], v177 offset:4096
	ds_read_b128 v[242:245], v177 offset:5120
	ds_read_b128 v[246:249], v177 offset:6144
	ds_read_b128 v[250:253], v177 offset:7168
	s_waitcnt lgkmcnt(7)
	v_mfma_f32_16x16x32_bf16 v[124:127], v[222:225], v[204:207], v[124:127]
	v_mfma_f32_16x16x32_bf16 v[120:123], v[222:225], v[208:211], v[120:123]
	v_mfma_f32_16x16x32_bf16 v[60:63], v[222:225], v[212:215], v[60:63]
	v_mfma_f32_16x16x32_bf16 v[56:59], v[222:225], v[216:219], v[56:59]
	s_waitcnt vmcnt(11)
	ds_write_b128 v152, v[180:183]
	s_waitcnt lgkmcnt(7)
	v_mfma_f32_16x16x32_bf16 v[116:119], v[226:229], v[204:207], v[116:119]
	v_mfma_f32_16x16x32_bf16 v[112:115], v[226:229], v[208:211], v[112:115]
	v_mfma_f32_16x16x32_bf16 v[52:55], v[226:229], v[212:215], v[52:55]
	v_mfma_f32_16x16x32_bf16 v[48:51], v[226:229], v[216:219], v[48:51]
	s_waitcnt vmcnt(10)
	ds_write_b128 v152, v[184:187] offset:4096
	s_waitcnt lgkmcnt(7)
	v_mfma_f32_16x16x32_bf16 v[108:111], v[230:233], v[204:207], v[108:111]
	v_mfma_f32_16x16x32_bf16 v[104:107], v[230:233], v[208:211], v[104:107]
	v_mfma_f32_16x16x32_bf16 v[44:47], v[230:233], v[212:215], v[44:47]
	v_mfma_f32_16x16x32_bf16 v[40:43], v[230:233], v[216:219], v[40:43]
	s_waitcnt vmcnt(9)
	ds_write_b128 v152, v[188:191] offset:8192
	s_waitcnt lgkmcnt(7)
	v_mfma_f32_16x16x32_bf16 v[100:103], v[234:237], v[204:207], v[100:103]
	v_mfma_f32_16x16x32_bf16 v[96:99], v[234:237], v[208:211], v[96:99]
	v_mfma_f32_16x16x32_bf16 v[36:39], v[234:237], v[212:215], v[36:39]
	v_mfma_f32_16x16x32_bf16 v[32:35], v[234:237], v[216:219], v[32:35]
	s_waitcnt vmcnt(8)
	ds_write_b128 v152, v[192:195] offset:12288
	s_waitcnt lgkmcnt(7)
	v_mfma_f32_16x16x32_bf16 v[92:95], v[238:241], v[204:207], v[92:95]
	v_mfma_f32_16x16x32_bf16 v[88:91], v[238:241], v[208:211], v[88:91]
	v_mfma_f32_16x16x32_bf16 v[28:31], v[238:241], v[212:215], v[28:31]
	v_mfma_f32_16x16x32_bf16 v[24:27], v[238:241], v[216:219], v[24:27]
	s_waitcnt vmcnt(7)
	ds_write_b128 v152, v[196:199] offset:32768
	s_waitcnt lgkmcnt(7)
	v_mfma_f32_16x16x32_bf16 v[84:87], v[242:245], v[204:207], v[84:87]
	v_mfma_f32_16x16x32_bf16 v[80:83], v[242:245], v[208:211], v[80:83]
	v_mfma_f32_16x16x32_bf16 v[20:23], v[242:245], v[212:215], v[20:23]
	v_mfma_f32_16x16x32_bf16 v[16:19], v[242:245], v[216:219], v[16:19]
	s_waitcnt vmcnt(6)
	ds_write_b128 v152, v[200:203] offset:36864
	s_waitcnt lgkmcnt(7)
	v_mfma_f32_16x16x32_bf16 v[76:79], v[246:249], v[204:207], v[76:79]
	v_mfma_f32_16x16x32_bf16 v[72:75], v[246:249], v[208:211], v[72:75]
	v_mfma_f32_16x16x32_bf16 v[12:15], v[246:249], v[212:215], v[12:15]
	v_mfma_f32_16x16x32_bf16 v[8:11], v[246:249], v[216:219], v[8:11]
	s_waitcnt lgkmcnt(6)
	v_mfma_f32_16x16x32_bf16 v[68:71], v[250:253], v[204:207], v[68:71]
	v_mfma_f32_16x16x32_bf16 v[64:67], v[250:253], v[208:211], v[64:67]
	v_mfma_f32_16x16x32_bf16 v[4:7], v[250:253], v[212:215], v[4:7]
	v_mfma_f32_16x16x32_bf16 v[0:3], v[250:253], v[216:219], v[0:3]
	s_add_i32 s1, s1, 2
	s_cmp_lt_u32 s1, 30
	s_mov_b32 s5, s27
	s_waitcnt lgkmcnt(0)
	s_barrier
	s_cbranch_scc1 .LBB0_208
	s_waitcnt vmcnt(5)
	v_mov_b32_e32 v128, v220
	s_cmp_gt_i32 s26, 15
	v_and_b32_e32 v158, 15, v128
	v_and_b32_e32 v160, 64, v128
	v_and_b32_e32 v129, 0xffffff80, v128
	v_lshrrev_b32_e32 v128, 2, v128
	v_add_u32_e32 v130, s4, v129
	v_and_b32_e32 v159, 12, v128
	s_waitcnt vmcnt(3)
	v_or_b32_e32 v136, v130, v159
	v_ashrrev_i32_e32 v128, 14, v130
	s_waitcnt vmcnt(0)
	v_or_b32_e32 v150, 16, v136
	v_or_b32_e32 v148, 32, v136
	v_or_b32_e32 v146, 48, v136
	v_or_b32_e32 v142, 64, v136
	v_or_b32_e32 v140, 0x50, v136
	v_or_b32_e32 v138, 0x60, v136
	v_or_b32_e32 v134, 0x70, v136
	s_mov_b64 s[4:5], -1
	v_ashrrev_i32_e32 v137, 31, v136
	v_lshlrev_b32_e32 v132, 1, v159
	v_mov_b32_e32 v250, s0
	v_and_b32_e32 v250, 0x80, v250
	v_add_u32_e32 v250, v250, v160
	v_mul_u32_u24_e32 v250, 30, v250
	v_lshrrev_b32_e32 v251, 3, v158
	v_mul_u32_u24_e32 v251, 0xf0, v251
	v_add_u32_e32 v250, v250, v251
	v_lshrrev_b32_e32 v251, 2, v159
	v_mul_u32_u24_e32 v251, 0x7c0, v251
	v_sub_u32_e32 v250, v250, v251
	v_ashrrev_i32_e32 v251, 31, v250
	v_and_b32_e32 v252, 8, v159
	v_lshlrev_b32_e32 v252, 5, v252
	v_and_b32_e32 v253, 4, v159
	v_lshl_or_b32 v252, v253, 1, v252
	v_lshl_or_b32 v252, v158, 4, v252
	v_mov_b32_e32 v253, 0
	v_ashrrev_i32_e32 v129, 31, v128
	v_ashrrev_i32_e32 v151, 31, v150
	v_ashrrev_i32_e32 v149, 31, v148
	v_ashrrev_i32_e32 v147, 31, v146
	v_ashrrev_i32_e32 v143, 31, v142
	v_ashrrev_i32_e32 v141, 31, v140
	v_ashrrev_i32_e32 v139, 31, v138
	v_ashrrev_i32_e32 v135, 31, v134
	s_cbranch_scc0 .LBB0_211
	v_lshl_add_u64 v[144:145], v[136:137], 2, s[8:9]
	global_load_dwordx4 v[162:165], v[144:145], off
	s_add_i32 s1, s0, 0xfffff800
	s_and_b32 s5, s0, 0x180
	s_ashr_i32 s4, s1, 9
	v_or_b32_e32 v154, s5, v160
	s_ashr_i32 s5, s4, 31
	v_lshlrev_b64 v[144:145], 9, v[128:129]
	s_lshl_b64 s[4:5], s[4:5], 7
	v_lshrrev_b32_e32 v152, 7, v130
	v_lshl_add_u64 v[130:131], v[144:145], 0, s[4:5]
	v_and_or_b32 v130, v152, s38, v130
	v_lshlrev_b64 v[130:131], 16, v[130:131]
	v_mov_b32_e32 v133, v153
	v_lshl_or_b32 v130, v154, 7, v130
	v_lshl_add_u64 v[178:179], s[12:13], 0, v[252:253]
	v_mov_b32_e32 v145, v131
	v_mov_b32_e32 v181, v131
	v_lshlrev_b64 v[156:157], 1, v[130:131]
	v_or_b32_e32 v144, 0x800, v130
	v_or_b32_e32 v180, 0x1000, v130
	v_or_b32_e32 v130, 0x1800, v130
	v_lshl_add_u64 v[182:183], v[178:179], 0, v[156:157]
	v_lshlrev_b64 v[154:155], 1, v[144:145]
	v_lshlrev_b64 v[144:145], 1, v[180:181]
	v_lshlrev_b64 v[130:131], 1, v[130:131]
	v_lshl_add_u64 v[176:177], v[150:151], 2, s[8:9]
	v_lshl_add_u64 v[180:181], v[178:179], 0, v[154:155]
	v_lshl_add_u64 v[184:185], v[178:179], 0, v[144:145]
	v_lshl_add_u64 v[178:179], v[178:179], 0, v[130:131]
	s_waitcnt vmcnt(0)
	v_mul_f32_e32 v133, v124, v162
	v_mul_f32_e32 v152, v125, v163
	v_mul_f32_e32 v161, v126, v164
	v_mul_f32_e32 v175, v127, v165
	v_mul_f32_e32 v186, v120, v162
	v_mul_f32_e32 v187, v121, v163
	v_mul_f32_e32 v188, v122, v164
	v_mul_f32_e32 v189, v123, v165
	v_mul_f32_e32 v190, v60, v162
	v_mul_f32_e32 v191, v61, v163
	v_mul_f32_e32 v194, v56, v162
	v_mul_f32_e32 v195, v57, v163
	v_cvt_pk_bf16_f32 v162, v133, v152
	v_cvt_pk_bf16_f32 v163, v161, v175
	v_mul_f32_e32 v192, v62, v164
	v_mul_f32_e32 v193, v63, v165
	v_mul_f32_e32 v196, v58, v164
	v_mul_f32_e32 v197, v59, v165
	v_cvt_pk_bf16_f32 v164, v186, v187
	v_cvt_pk_bf16_f32 v165, v188, v189
	v_cvt_pk_bf16_f32 v186, v190, v191
	v_cvt_pk_bf16_f32 v187, v192, v193
	v_cvt_pk_bf16_f32 v188, v194, v195
	v_cvt_pk_bf16_f32 v189, v196, v197
	global_store_dwordx2 v[182:183], v[162:163], off
	global_store_dwordx2 v[180:181], v[164:165], off
	global_store_dwordx2 v[184:185], v[186:187], off
	global_store_dwordx2 v[178:179], v[188:189], off
	global_load_dwordx4 v[162:165], v[176:177], off
	v_bitop3_b32 v133, v136, 28, 16 bitop3:0xc8
	v_lshlrev_b32_e32 v152, 1, v133
	v_lshl_add_u64 v[178:179], s[12:13], 0, v[252:253]
	v_lshl_add_u64 v[180:181], v[178:179], 0, v[156:157]
	v_lshl_add_u64 v[176:177], v[148:149], 2, s[8:9]
	v_lshl_add_u64 v[182:183], v[178:179], 0, v[154:155]
	v_lshl_add_u64 v[184:185], v[178:179], 0, v[144:145]
	v_lshl_add_u64 v[178:179], v[178:179], 0, v[130:131]
	s_waitcnt vmcnt(0)
	v_mul_f32_e32 v133, v116, v162
	v_mul_f32_e32 v152, v117, v163
	v_mul_f32_e32 v161, v118, v164
	v_mul_f32_e32 v175, v119, v165
	v_mul_f32_e32 v186, v112, v162
	v_mul_f32_e32 v187, v113, v163
	v_mul_f32_e32 v188, v114, v164
	v_mul_f32_e32 v189, v115, v165
	v_mul_f32_e32 v190, v52, v162
	v_mul_f32_e32 v191, v53, v163
	v_mul_f32_e32 v194, v48, v162
	v_mul_f32_e32 v195, v49, v163
	v_cvt_pk_bf16_f32 v162, v133, v152
	v_cvt_pk_bf16_f32 v163, v161, v175
	v_mul_f32_e32 v192, v54, v164
	v_mul_f32_e32 v193, v55, v165
	v_mul_f32_e32 v196, v50, v164
	v_mul_f32_e32 v197, v51, v165
	v_cvt_pk_bf16_f32 v164, v186, v187
	v_cvt_pk_bf16_f32 v165, v188, v189
	v_cvt_pk_bf16_f32 v186, v190, v191
	v_cvt_pk_bf16_f32 v187, v192, v193
	v_cvt_pk_bf16_f32 v188, v194, v195
	v_cvt_pk_bf16_f32 v189, v196, v197
	global_store_dwordx2 v[180:181], v[162:163], off offset:512
	global_store_dwordx2 v[182:183], v[164:165], off offset:512
	global_store_dwordx2 v[184:185], v[186:187], off offset:512
	global_store_dwordx2 v[178:179], v[188:189], off offset:512
	global_load_dwordx4 v[162:165], v[176:177], off
	v_bitop3_b32 v133, v136, 44, 32 bitop3:0xc8
	v_lshlrev_b32_e32 v152, 1, v133
	v_lshl_add_u64 v[178:179], s[12:13], 0, v[252:253]
	v_lshl_add_u64 v[180:181], v[178:179], 0, v[156:157]
	v_lshl_add_u64 v[176:177], v[146:147], 2, s[8:9]
	v_lshl_add_u64 v[182:183], v[178:179], 0, v[154:155]
	v_lshl_add_u64 v[184:185], v[178:179], 0, v[144:145]
	v_lshl_add_u64 v[178:179], v[178:179], 0, v[130:131]
	s_waitcnt vmcnt(0)
	v_mul_f32_e32 v133, v108, v162
	v_mul_f32_e32 v152, v109, v163
	v_mul_f32_e32 v161, v110, v164
	v_mul_f32_e32 v175, v111, v165
	v_mul_f32_e32 v186, v104, v162
	v_mul_f32_e32 v187, v105, v163
	v_mul_f32_e32 v188, v106, v164
	v_mul_f32_e32 v189, v107, v165
	v_mul_f32_e32 v190, v44, v162
	v_mul_f32_e32 v191, v45, v163
	v_mul_f32_e32 v194, v40, v162
	v_mul_f32_e32 v195, v41, v163
	v_cvt_pk_bf16_f32 v162, v133, v152
	v_cvt_pk_bf16_f32 v163, v161, v175
	v_mul_f32_e32 v192, v46, v164
	v_mul_f32_e32 v193, v47, v165
	v_mul_f32_e32 v196, v42, v164
	v_mul_f32_e32 v197, v43, v165
	v_cvt_pk_bf16_f32 v164, v186, v187
	v_cvt_pk_bf16_f32 v165, v188, v189
	v_cvt_pk_bf16_f32 v186, v190, v191
	v_cvt_pk_bf16_f32 v187, v192, v193
	v_cvt_pk_bf16_f32 v188, v194, v195
	v_cvt_pk_bf16_f32 v189, v196, v197
	global_store_dwordx2 v[180:181], v[162:163], off offset:1024
	global_store_dwordx2 v[182:183], v[164:165], off offset:1024
	global_store_dwordx2 v[184:185], v[186:187], off offset:1024
	global_store_dwordx2 v[178:179], v[188:189], off offset:1024
	global_load_dwordx4 v[162:165], v[176:177], off
	v_bitop3_b32 v133, v136, 60, 48 bitop3:0xc8
	v_lshlrev_b32_e32 v152, 1, v133
	v_lshl_add_u64 v[178:179], s[12:13], 0, v[252:253]
	v_lshl_add_u64 v[180:181], v[178:179], 0, v[156:157]
	v_lshl_add_u64 v[176:177], v[142:143], 2, s[8:9]
	v_lshl_add_u64 v[182:183], v[178:179], 0, v[154:155]
	v_lshl_add_u64 v[184:185], v[178:179], 0, v[144:145]
	v_lshl_add_u64 v[178:179], v[178:179], 0, v[130:131]
	s_waitcnt vmcnt(0)
	v_mul_f32_e32 v133, v100, v162
	v_mul_f32_e32 v152, v101, v163
	v_mul_f32_e32 v161, v102, v164
	v_mul_f32_e32 v175, v103, v165
	v_mul_f32_e32 v186, v96, v162
	v_mul_f32_e32 v187, v97, v163
	v_mul_f32_e32 v188, v98, v164
	v_mul_f32_e32 v189, v99, v165
	v_mul_f32_e32 v190, v36, v162
	v_mul_f32_e32 v191, v37, v163
	v_mul_f32_e32 v194, v32, v162
	v_mul_f32_e32 v195, v33, v163
	v_cvt_pk_bf16_f32 v162, v133, v152
	v_cvt_pk_bf16_f32 v163, v161, v175
	v_mul_f32_e32 v192, v38, v164
	v_mul_f32_e32 v193, v39, v165
	v_mul_f32_e32 v196, v34, v164
	v_mul_f32_e32 v197, v35, v165
	v_cvt_pk_bf16_f32 v164, v186, v187
	v_cvt_pk_bf16_f32 v165, v188, v189
	v_cvt_pk_bf16_f32 v186, v190, v191
	v_cvt_pk_bf16_f32 v187, v192, v193
	v_cvt_pk_bf16_f32 v188, v194, v195
	v_cvt_pk_bf16_f32 v189, v196, v197
	global_store_dwordx2 v[180:181], v[162:163], off offset:1536
	global_store_dwordx2 v[182:183], v[164:165], off offset:1536
	global_store_dwordx2 v[184:185], v[186:187], off offset:1536
	global_store_dwordx2 v[178:179], v[188:189], off offset:1536
	global_load_dwordx4 v[162:165], v[176:177], off
	v_bitop3_b32 v133, v136, s39, 64 bitop3:0xc8
	v_lshlrev_b32_e32 v152, 1, v133
	v_lshl_add_u64 v[178:179], s[12:13], 0, v[252:253]
	v_lshl_add_u64 v[180:181], v[178:179], 0, v[156:157]
	v_lshl_add_u64 v[176:177], v[140:141], 2, s[8:9]
	v_lshl_add_u64 v[182:183], v[178:179], 0, v[154:155]
	v_lshl_add_u64 v[184:185], v[178:179], 0, v[144:145]
	v_lshl_add_u64 v[178:179], v[178:179], 0, v[130:131]
	s_waitcnt vmcnt(0)
	v_mul_f32_e32 v133, v92, v162
	v_mul_f32_e32 v152, v93, v163
	v_mul_f32_e32 v161, v94, v164
	v_mul_f32_e32 v175, v95, v165
	v_mul_f32_e32 v186, v88, v162
	v_mul_f32_e32 v187, v89, v163
	v_mul_f32_e32 v188, v90, v164
	v_mul_f32_e32 v189, v91, v165
	v_mul_f32_e32 v190, v28, v162
	v_mul_f32_e32 v191, v29, v163
	v_mul_f32_e32 v194, v24, v162
	v_mul_f32_e32 v195, v25, v163
	v_cvt_pk_bf16_f32 v162, v133, v152
	v_cvt_pk_bf16_f32 v163, v161, v175
	v_mul_f32_e32 v192, v30, v164
	v_mul_f32_e32 v193, v31, v165
	v_mul_f32_e32 v196, v26, v164
	v_mul_f32_e32 v197, v27, v165
	v_cvt_pk_bf16_f32 v164, v186, v187
	v_cvt_pk_bf16_f32 v165, v188, v189
	v_cvt_pk_bf16_f32 v186, v190, v191
	v_cvt_pk_bf16_f32 v187, v192, v193
	v_cvt_pk_bf16_f32 v188, v194, v195
	v_cvt_pk_bf16_f32 v189, v196, v197
	global_store_dwordx2 v[180:181], v[162:163], off offset:2048
	global_store_dwordx2 v[182:183], v[164:165], off offset:2048
	global_store_dwordx2 v[184:185], v[186:187], off offset:2048
	global_store_dwordx2 v[178:179], v[188:189], off offset:2048
	global_load_dwordx4 v[162:165], v[176:177], off
	v_bitop3_b32 v133, v136, s40, v166 bitop3:0xc8
	v_lshlrev_b32_e32 v152, 1, v133
	v_lshl_add_u64 v[178:179], s[12:13], 0, v[252:253]
	v_lshl_add_u64 v[180:181], v[178:179], 0, v[156:157]
	v_lshl_add_u64 v[176:177], v[138:139], 2, s[8:9]
	v_lshl_add_u64 v[182:183], v[178:179], 0, v[154:155]
	v_lshl_add_u64 v[184:185], v[178:179], 0, v[144:145]
	v_lshl_add_u64 v[178:179], v[178:179], 0, v[130:131]
	s_waitcnt vmcnt(0)
	v_mul_f32_e32 v133, v84, v162
	v_mul_f32_e32 v152, v85, v163
	v_mul_f32_e32 v161, v86, v164
	v_mul_f32_e32 v175, v87, v165
	v_mul_f32_e32 v186, v80, v162
	v_mul_f32_e32 v187, v81, v163
	v_mul_f32_e32 v188, v82, v164
	v_mul_f32_e32 v189, v83, v165
	v_mul_f32_e32 v190, v20, v162
	v_mul_f32_e32 v191, v21, v163
	v_mul_f32_e32 v194, v16, v162
	v_mul_f32_e32 v195, v17, v163
	v_cvt_pk_bf16_f32 v162, v133, v152
	v_cvt_pk_bf16_f32 v163, v161, v175
	v_mul_f32_e32 v192, v22, v164
	v_mul_f32_e32 v193, v23, v165
	v_mul_f32_e32 v196, v18, v164
	v_mul_f32_e32 v197, v19, v165
	v_cvt_pk_bf16_f32 v164, v186, v187
	v_cvt_pk_bf16_f32 v165, v188, v189
	v_cvt_pk_bf16_f32 v186, v190, v191
	v_cvt_pk_bf16_f32 v187, v192, v193
	v_cvt_pk_bf16_f32 v188, v194, v195
	v_cvt_pk_bf16_f32 v189, v196, v197
	global_store_dwordx2 v[180:181], v[162:163], off offset:2560
	global_store_dwordx2 v[182:183], v[164:165], off offset:2560
	global_store_dwordx2 v[184:185], v[186:187], off offset:2560
	global_store_dwordx2 v[178:179], v[188:189], off offset:2560
	global_load_dwordx4 v[162:165], v[176:177], off
	v_bitop3_b32 v133, v136, s41, v167 bitop3:0xc8
	v_lshlrev_b32_e32 v152, 1, v133
	v_lshl_add_u64 v[178:179], s[12:13], 0, v[252:253]
	v_lshl_add_u64 v[180:181], v[178:179], 0, v[156:157]
	v_lshl_add_u64 v[176:177], v[134:135], 2, s[8:9]
	v_lshl_add_u64 v[182:183], v[178:179], 0, v[154:155]
	v_lshl_add_u64 v[184:185], v[178:179], 0, v[144:145]
	v_lshl_add_u64 v[178:179], v[178:179], 0, v[130:131]
	s_waitcnt vmcnt(0)
	v_mul_f32_e32 v133, v76, v162
	v_mul_f32_e32 v152, v77, v163
	v_mul_f32_e32 v161, v78, v164
	v_mul_f32_e32 v175, v79, v165
	v_mul_f32_e32 v186, v72, v162
	v_mul_f32_e32 v187, v73, v163
	v_mul_f32_e32 v188, v74, v164
	v_mul_f32_e32 v189, v75, v165
	v_mul_f32_e32 v190, v12, v162
	v_mul_f32_e32 v191, v13, v163
	v_mul_f32_e32 v194, v8, v162
	v_mul_f32_e32 v195, v9, v163
	v_cvt_pk_bf16_f32 v162, v133, v152
	v_cvt_pk_bf16_f32 v163, v161, v175
	v_mul_f32_e32 v192, v14, v164
	v_mul_f32_e32 v193, v15, v165
	v_mul_f32_e32 v196, v10, v164
	v_mul_f32_e32 v197, v11, v165
	v_cvt_pk_bf16_f32 v164, v186, v187
	v_cvt_pk_bf16_f32 v165, v188, v189
	v_cvt_pk_bf16_f32 v186, v190, v191
	v_cvt_pk_bf16_f32 v187, v192, v193
	v_cvt_pk_bf16_f32 v188, v194, v195
	v_cvt_pk_bf16_f32 v189, v196, v197
	global_store_dwordx2 v[180:181], v[162:163], off offset:3072
	global_store_dwordx2 v[182:183], v[164:165], off offset:3072
	global_store_dwordx2 v[184:185], v[186:187], off offset:3072
	global_store_dwordx2 v[178:179], v[188:189], off offset:3072
	global_load_dwordx4 v[162:165], v[176:177], off
	v_bitop3_b32 v133, v136, s42, v168 bitop3:0xc8
	v_lshlrev_b32_e32 v152, 1, v133
	v_lshl_add_u64 v[176:177], s[12:13], 0, v[252:253]
	v_lshl_add_u64 v[156:157], v[176:177], 0, v[156:157]
	v_lshl_add_u64 v[154:155], v[176:177], 0, v[154:155]
	v_lshl_add_u64 v[144:145], v[176:177], 0, v[144:145]
	v_lshl_add_u64 v[130:131], v[176:177], 0, v[130:131]
	s_waitcnt vmcnt(0)
	v_mul_f32_e32 v133, v68, v162
	v_mul_f32_e32 v152, v69, v163
	v_mul_f32_e32 v161, v70, v164
	v_mul_f32_e32 v175, v71, v165
	v_mul_f32_e32 v176, v64, v162
	v_mul_f32_e32 v177, v65, v163
	v_mul_f32_e32 v178, v66, v164
	v_mul_f32_e32 v179, v67, v165
	v_mul_f32_e32 v180, v4, v162
	v_mul_f32_e32 v181, v5, v163
	v_mul_f32_e32 v184, v0, v162
	v_mul_f32_e32 v185, v1, v163
	v_cvt_pk_bf16_f32 v162, v133, v152
	v_cvt_pk_bf16_f32 v163, v161, v175
	v_mul_f32_e32 v182, v6, v164
	v_mul_f32_e32 v183, v7, v165
	v_mul_f32_e32 v186, v2, v164
	v_mul_f32_e32 v187, v3, v165
	v_cvt_pk_bf16_f32 v164, v176, v177
	v_cvt_pk_bf16_f32 v165, v178, v179
	v_cvt_pk_bf16_f32 v176, v180, v181
	v_cvt_pk_bf16_f32 v177, v182, v183
	v_cvt_pk_bf16_f32 v178, v184, v185
	v_cvt_pk_bf16_f32 v179, v186, v187
	global_store_dwordx2 v[156:157], v[162:163], off offset:3584
	global_store_dwordx2 v[154:155], v[164:165], off offset:3584
	global_store_dwordx2 v[144:145], v[176:177], off offset:3584
	global_store_dwordx2 v[130:131], v[178:179], off offset:3584
	s_cbranch_execnz .LBB0_206
	s_branch .LBB0_212

.LBB0_330:
	v_mov_b32_e32 v40, v220
	s_add_u32 s0, s72, s4
	v_ashrrev_i32_e32 v24, 2, v40
	v_min_i32_e32 v0, 0x7f, v24
	v_lshlrev_b32_e32 v1, 4, v40
	v_and_b32_e32 v6, 48, v1
	v_ashrrev_i32_e32 v1, 31, v0
	v_add_u32_e32 v26, 64, v24
	v_lshlrev_b64 v[0:1], 9, v[0:1]
	v_ashrrev_i32_e32 v25, 31, v24
	v_min_i32_e32 v2, 0x7f, v26
	s_addc_u32 s1, s73, s5
	v_lshrrev_b32_e32 v0, 4, v24
	v_lshlrev_b32_e32 v0, 13, v0
	v_lshl_or_b32 v0, v6, 4, v0
	v_and_b32_e32 v253, 15, v24
	v_lshl_or_b32 v0, v253, 4, v0
	v_add_u32_e32 v0, 0x1000, v0
	v_mov_b32_e32 v1, 0
	v_lshlrev_b64 v[4:5], 9, v[24:25]
	v_lshl_add_u64 v[0:1], s[0:1], 0, v[0:1]
	v_ashrrev_i32_e32 v3, 31, v2
	v_or_b32_e32 v4, v4, v6
	v_add_co_u32_e32 v0, vcc, s3, v0
	v_lshlrev_b64 v[2:3], 9, v[2:3]
	v_lshl_add_u64 v[4:5], s[0:1], 0, v[4:5]
	v_addc_co_u32_e32 v1, vcc, 0, v1, vcc
	v_lshrrev_b32_e32 v2, 4, v24
	v_lshlrev_b32_e32 v2, 13, v2
	v_lshl_or_b32 v2, v6, 4, v2
	v_and_b32_e32 v253, 15, v24
	v_lshl_or_b32 v2, v253, 4, v2
	v_add_u32_e32 v2, 0x9000, v2
	v_mov_b32_e32 v3, 0
	v_lshl_add_u64 v[6:7], s[0:1], 0, v[2:3]
	v_add_co_u32_e32 v2, vcc, s22, v4
	global_load_dwordx4 v[8:11], v[0:1], off offset:-4096
	s_nop 0
	v_addc_co_u32_e32 v3, vcc, 0, v5, vcc
	v_add_co_u32_e32 v4, vcc, s23, v4
	global_load_dwordx4 v[12:15], v[2:3], off
	s_nop 0
	v_addc_co_u32_e32 v5, vcc, 0, v5, vcc
	v_add_co_u32_e32 v6, vcc, s3, v6
	global_load_dwordx4 v[16:19], v[4:5], off
	s_nop 0
	v_addc_co_u32_e32 v7, vcc, 0, v7, vcc
	global_load_dwordx4 v[20:23], v[6:7], off offset:-4096
	v_lshrrev_b32_e32 v41, 4, v40
	v_sub_u32_e32 v25, 0, v41
	v_xor_b32_e32 v25, v40, v25
	v_lshlrev_b32_e32 v25, 4, v25
	v_and_b32_e32 v25, 48, v25
	v_lshl_or_b32 v148, v24, 6, v25
	v_lshl_or_b32 v149, v26, 6, v25
	global_load_dwordx4 v[24:27], v[2:3], off offset:64
	global_load_dwordx4 v[28:31], v[4:5], off offset:64
	global_load_dwordx4 v[32:35], v[0:1], off offset:-3072
	global_load_dwordx4 v[36:39], v[6:7], off offset:-3072
	v_lshrrev_b32_e32 v42, 2, v40
	v_sub_u32_e32 v42, 0, v42
	v_xor_b32_e32 v41, v41, v42
	v_and_b32_e32 v42, 15, v40
	v_lshrrev_b32_e32 v43, 1, v40
	v_lshlrev_b32_e32 v41, 4, v41
	v_and_or_b32 v42, v43, s24, v42
	v_and_b32_e32 v41, 48, v41
	v_lshlrev_b32_e32 v40, 6, v40
	v_lshl_or_b32 v140, v42, 6, v41
	v_and_or_b32 v144, v40, s25, v41
	s_waitcnt vmcnt(7)
	ds_write_b128 v148, v[8:11]
	s_waitcnt vmcnt(6)
	ds_write_b128 v148, v[12:15] offset:16384
	s_waitcnt vmcnt(5)
	ds_write_b128 v149, v[16:19] offset:16384
	s_waitcnt vmcnt(4)
	ds_write_b128 v149, v[20:23]
	s_waitcnt lgkmcnt(0)
	s_barrier
	global_load_dwordx4 v[8:11], v[0:1], off offset:-2048
	global_load_dwordx4 v[12:15], v[6:7], off offset:-2048
	global_load_dwordx4 v[16:19], v[2:3], off offset:128
	global_load_dwordx4 v[20:23], v[4:5], off offset:128
	ds_read_b128 v[40:43], v140
	ds_read_b128 v[44:47], v140 offset:1024
	ds_read_b128 v[48:51], v144 offset:16384
	ds_read_b128 v[52:55], v144 offset:17408
	ds_read_b128 v[56:59], v140 offset:2048
	ds_read_b128 v[60:63], v140 offset:3072
	ds_read_b128 v[68:71], v144 offset:18432
	ds_read_b128 v[72:75], v144 offset:19456
	s_waitcnt lgkmcnt(5)
	v_mfma_f32_16x16x32_bf16 v[76:79], v[48:51], v[40:43], 0
	s_waitcnt lgkmcnt(4)
	v_mfma_f32_16x16x32_bf16 v[80:83], v[52:55], v[40:43], 0
	s_waitcnt lgkmcnt(1)
	v_mfma_f32_16x16x32_bf16 v[84:87], v[68:71], v[40:43], 0
	s_waitcnt lgkmcnt(0)
	v_mfma_f32_16x16x32_bf16 v[40:43], v[72:75], v[40:43], 0
	v_mfma_f32_16x16x32_bf16 v[88:91], v[48:51], v[44:47], 0
	v_mfma_f32_16x16x32_bf16 v[92:95], v[52:55], v[44:47], 0
	v_mfma_f32_16x16x32_bf16 v[96:99], v[68:71], v[44:47], 0
	v_mfma_f32_16x16x32_bf16 v[44:47], v[72:75], v[44:47], 0
	v_mfma_f32_16x16x32_bf16 v[100:103], v[48:51], v[56:59], 0
	v_mfma_f32_16x16x32_bf16 v[104:107], v[52:55], v[56:59], 0
	v_mfma_f32_16x16x32_bf16 v[108:111], v[68:71], v[56:59], 0
	v_mfma_f32_16x16x32_bf16 v[56:59], v[72:75], v[56:59], 0
	v_mfma_f32_16x16x32_bf16 v[48:51], v[48:51], v[60:63], 0
	v_mfma_f32_16x16x32_bf16 v[52:55], v[52:55], v[60:63], 0
	v_mfma_f32_16x16x32_bf16 v[68:71], v[68:71], v[60:63], 0
	v_mfma_f32_16x16x32_bf16 v[60:63], v[72:75], v[60:63], 0
	s_waitcnt vmcnt(5)
	ds_write_b128 v148, v[32:35] offset:8192
	s_waitcnt vmcnt(4)
	ds_write_b128 v148, v[36:39] offset:12288
	ds_write_b128 v148, v[24:27] offset:24576
	ds_write_b128 v148, v[28:31] offset:28672
	s_waitcnt lgkmcnt(0)
	s_barrier
	global_load_dwordx4 v[24:27], v[0:1], off offset:-1024
	global_load_dwordx4 v[28:31], v[6:7], off offset:-1024
	global_load_dwordx4 v[32:35], v[2:3], off offset:192
	global_load_dwordx4 v[36:39], v[4:5], off offset:192
	ds_read_b128 v[72:75], v140 offset:8192
	ds_read_b128 v[112:115], v144 offset:24576
	ds_read_b128 v[116:119], v140 offset:9216
	ds_read_b128 v[120:123], v144 offset:25600
	ds_read_b128 v[124:127], v140 offset:10240
	ds_read_b128 v[128:131], v144 offset:26624
	ds_read_b128 v[132:135], v140 offset:11264
	ds_read_b128 v[136:139], v144 offset:27648
	s_waitcnt lgkmcnt(6)
	v_mfma_f32_16x16x32_bf16 v[76:79], v[112:115], v[72:75], v[76:79]
	s_waitcnt lgkmcnt(4)
	v_mfma_f32_16x16x32_bf16 v[80:83], v[120:123], v[72:75], v[80:83]
	s_waitcnt lgkmcnt(2)
	v_mfma_f32_16x16x32_bf16 v[84:87], v[128:131], v[72:75], v[84:87]
	s_waitcnt lgkmcnt(0)
	v_mfma_f32_16x16x32_bf16 v[40:43], v[136:139], v[72:75], v[40:43]
	v_mfma_f32_16x16x32_bf16 v[72:75], v[112:115], v[116:119], v[88:91]
	v_mfma_f32_16x16x32_bf16 v[88:91], v[120:123], v[116:119], v[92:95]
	v_mfma_f32_16x16x32_bf16 v[92:95], v[128:131], v[116:119], v[96:99]
	v_mfma_f32_16x16x32_bf16 v[44:47], v[136:139], v[116:119], v[44:47]
	v_mfma_f32_16x16x32_bf16 v[96:99], v[112:115], v[124:127], v[100:103]
	v_mfma_f32_16x16x32_bf16 v[100:103], v[120:123], v[124:127], v[104:107]
	v_mfma_f32_16x16x32_bf16 v[104:107], v[128:131], v[124:127], v[108:111]
	v_mfma_f32_16x16x32_bf16 v[56:59], v[136:139], v[124:127], v[56:59]
	v_mfma_f32_16x16x32_bf16 v[48:51], v[112:115], v[132:135], v[48:51]
	v_mfma_f32_16x16x32_bf16 v[52:55], v[120:123], v[132:135], v[52:55]
	v_mfma_f32_16x16x32_bf16 v[68:71], v[128:131], v[132:135], v[68:71]
	v_mfma_f32_16x16x32_bf16 v[60:63], v[136:139], v[132:135], v[60:63]
	s_waitcnt vmcnt(7)
	ds_write_b128 v148, v[8:11]
	s_waitcnt vmcnt(6)
	ds_write_b128 v149, v[12:15]
	s_waitcnt vmcnt(5)
	ds_write_b128 v148, v[16:19] offset:16384
	s_waitcnt vmcnt(4)
	ds_write_b128 v149, v[20:23] offset:16384
	s_waitcnt lgkmcnt(0)
	s_barrier
	global_load_dwordx4 v[8:11], v[0:1], off
	global_load_dwordx4 v[12:15], v[6:7], off
	global_load_dwordx4 v[16:19], v[2:3], off offset:256
	global_load_dwordx4 v[20:23], v[4:5], off offset:256
	ds_read_b128 v[108:111], v140
	ds_read_b128 v[112:115], v144 offset:16384
	ds_read_b128 v[116:119], v140 offset:1024
	ds_read_b128 v[120:123], v144 offset:17408
	ds_read_b128 v[124:127], v140 offset:2048
	ds_read_b128 v[128:131], v144 offset:18432
	ds_read_b128 v[132:135], v140 offset:3072
	ds_read_b128 v[136:139], v144 offset:19456
	s_waitcnt lgkmcnt(6)
	v_mfma_f32_16x16x32_bf16 v[76:79], v[112:115], v[108:111], v[76:79]
	s_waitcnt lgkmcnt(4)
	v_mfma_f32_16x16x32_bf16 v[80:83], v[120:123], v[108:111], v[80:83]
	s_waitcnt lgkmcnt(2)
	v_mfma_f32_16x16x32_bf16 v[84:87], v[128:131], v[108:111], v[84:87]
	s_waitcnt lgkmcnt(0)
	v_mfma_f32_16x16x32_bf16 v[40:43], v[136:139], v[108:111], v[40:43]
	v_mfma_f32_16x16x32_bf16 v[72:75], v[112:115], v[116:119], v[72:75]
	v_mfma_f32_16x16x32_bf16 v[88:91], v[120:123], v[116:119], v[88:91]
	v_mfma_f32_16x16x32_bf16 v[92:95], v[128:131], v[116:119], v[92:95]
	v_mfma_f32_16x16x32_bf16 v[44:47], v[136:139], v[116:119], v[44:47]
	v_mfma_f32_16x16x32_bf16 v[96:99], v[112:115], v[124:127], v[96:99]
	v_mfma_f32_16x16x32_bf16 v[100:103], v[120:123], v[124:127], v[100:103]
	v_mfma_f32_16x16x32_bf16 v[104:107], v[128:131], v[124:127], v[104:107]
	v_mfma_f32_16x16x32_bf16 v[56:59], v[136:139], v[124:127], v[56:59]
	v_mfma_f32_16x16x32_bf16 v[48:51], v[112:115], v[132:135], v[48:51]
	v_mfma_f32_16x16x32_bf16 v[52:55], v[120:123], v[132:135], v[52:55]
	v_mfma_f32_16x16x32_bf16 v[68:71], v[128:131], v[132:135], v[68:71]
	v_mfma_f32_16x16x32_bf16 v[60:63], v[136:139], v[132:135], v[60:63]
	s_waitcnt vmcnt(7)
	ds_write_b128 v148, v[24:27] offset:8192
	s_waitcnt vmcnt(6)
	ds_write_b128 v148, v[28:31] offset:12288
	s_waitcnt vmcnt(5)
	ds_write_b128 v148, v[32:35] offset:24576
	s_waitcnt vmcnt(4)
	ds_write_b128 v148, v[36:39] offset:28672
	s_waitcnt lgkmcnt(0)
	s_barrier
	global_load_dwordx4 v[24:27], v[0:1], off offset:1024
	global_load_dwordx4 v[28:31], v[6:7], off offset:1024
	global_load_dwordx4 v[32:35], v[2:3], off offset:320
	global_load_dwordx4 v[36:39], v[4:5], off offset:320
	ds_read_b128 v[108:111], v140 offset:8192
	ds_read_b128 v[112:115], v144 offset:24576
	ds_read_b128 v[116:119], v140 offset:9216
	ds_read_b128 v[120:123], v144 offset:25600
	ds_read_b128 v[124:127], v140 offset:10240
	ds_read_b128 v[128:131], v144 offset:26624
	ds_read_b128 v[132:135], v140 offset:11264
	ds_read_b128 v[136:139], v144 offset:27648
	s_waitcnt lgkmcnt(6)
	v_mfma_f32_16x16x32_bf16 v[76:79], v[112:115], v[108:111], v[76:79]
	s_waitcnt lgkmcnt(4)
	v_mfma_f32_16x16x32_bf16 v[80:83], v[120:123], v[108:111], v[80:83]
	s_waitcnt lgkmcnt(2)
	v_mfma_f32_16x16x32_bf16 v[84:87], v[128:131], v[108:111], v[84:87]
	s_waitcnt lgkmcnt(0)
	v_mfma_f32_16x16x32_bf16 v[40:43], v[136:139], v[108:111], v[40:43]
	v_mfma_f32_16x16x32_bf16 v[72:75], v[112:115], v[116:119], v[72:75]
	v_mfma_f32_16x16x32_bf16 v[88:91], v[120:123], v[116:119], v[88:91]
	v_mfma_f32_16x16x32_bf16 v[92:95], v[128:131], v[116:119], v[92:95]
	v_mfma_f32_16x16x32_bf16 v[44:47], v[136:139], v[116:119], v[44:47]
	v_mfma_f32_16x16x32_bf16 v[96:99], v[112:115], v[124:127], v[96:99]
	v_mfma_f32_16x16x32_bf16 v[100:103], v[120:123], v[124:127], v[100:103]
	v_mfma_f32_16x16x32_bf16 v[104:107], v[128:131], v[124:127], v[104:107]
	v_mfma_f32_16x16x32_bf16 v[56:59], v[136:139], v[124:127], v[56:59]
	v_mfma_f32_16x16x32_bf16 v[48:51], v[112:115], v[132:135], v[48:51]
	v_mfma_f32_16x16x32_bf16 v[52:55], v[120:123], v[132:135], v[52:55]
	v_mfma_f32_16x16x32_bf16 v[68:71], v[128:131], v[132:135], v[68:71]
	v_mfma_f32_16x16x32_bf16 v[60:63], v[136:139], v[132:135], v[60:63]
	s_waitcnt vmcnt(7)
	ds_write_b128 v148, v[8:11]
	s_waitcnt vmcnt(6)
	ds_write_b128 v149, v[12:15]
	s_waitcnt vmcnt(5)
	ds_write_b128 v148, v[16:19] offset:16384
	s_waitcnt vmcnt(4)
	ds_write_b128 v149, v[20:23] offset:16384
	s_waitcnt lgkmcnt(0)
	s_barrier
	global_load_dwordx4 v[8:11], v[0:1], off offset:2048
	global_load_dwordx4 v[12:15], v[6:7], off offset:2048
	global_load_dwordx4 v[16:19], v[2:3], off offset:384
	global_load_dwordx4 v[20:23], v[4:5], off offset:384
	ds_read_b128 v[108:111], v140
	ds_read_b128 v[112:115], v144 offset:16384
	ds_read_b128 v[116:119], v140 offset:1024
	ds_read_b128 v[120:123], v144 offset:17408
	ds_read_b128 v[124:127], v140 offset:2048
	ds_read_b128 v[128:131], v144 offset:18432
	ds_read_b128 v[132:135], v140 offset:3072
	ds_read_b128 v[136:139], v144 offset:19456
	s_waitcnt lgkmcnt(6)
	v_mfma_f32_16x16x32_bf16 v[76:79], v[112:115], v[108:111], v[76:79]
	s_waitcnt lgkmcnt(4)
	v_mfma_f32_16x16x32_bf16 v[80:83], v[120:123], v[108:111], v[80:83]
	s_waitcnt lgkmcnt(2)
	v_mfma_f32_16x16x32_bf16 v[84:87], v[128:131], v[108:111], v[84:87]
	s_waitcnt lgkmcnt(0)
	v_mfma_f32_16x16x32_bf16 v[40:43], v[136:139], v[108:111], v[40:43]
	v_mfma_f32_16x16x32_bf16 v[72:75], v[112:115], v[116:119], v[72:75]
	v_mfma_f32_16x16x32_bf16 v[88:91], v[120:123], v[116:119], v[88:91]
	v_mfma_f32_16x16x32_bf16 v[92:95], v[128:131], v[116:119], v[92:95]
	v_mfma_f32_16x16x32_bf16 v[44:47], v[136:139], v[116:119], v[44:47]
	v_mfma_f32_16x16x32_bf16 v[96:99], v[112:115], v[124:127], v[96:99]
	v_mfma_f32_16x16x32_bf16 v[100:103], v[120:123], v[124:127], v[100:103]
	v_mfma_f32_16x16x32_bf16 v[104:107], v[128:131], v[124:127], v[104:107]
	v_mfma_f32_16x16x32_bf16 v[56:59], v[136:139], v[124:127], v[56:59]
	v_mfma_f32_16x16x32_bf16 v[48:51], v[112:115], v[132:135], v[48:51]
	v_mfma_f32_16x16x32_bf16 v[52:55], v[120:123], v[132:135], v[52:55]
	v_mfma_f32_16x16x32_bf16 v[68:71], v[128:131], v[132:135], v[68:71]
	v_mfma_f32_16x16x32_bf16 v[60:63], v[136:139], v[132:135], v[60:63]
	s_waitcnt vmcnt(7)
	ds_write_b128 v148, v[24:27] offset:8192
	s_waitcnt vmcnt(6)
	ds_write_b128 v148, v[28:31] offset:12288
	s_waitcnt vmcnt(5)
	ds_write_b128 v148, v[32:35] offset:24576
	s_waitcnt vmcnt(4)
	ds_write_b128 v148, v[36:39] offset:28672
	s_waitcnt lgkmcnt(0)
	s_barrier
	global_load_dwordx4 v[24:27], v[0:1], off offset:3072
	global_load_dwordx4 v[28:31], v[6:7], off offset:3072
	global_load_dwordx4 v[32:35], v[2:3], off offset:448
	global_load_dwordx4 v[36:39], v[4:5], off offset:448
	ds_read_b128 v[108:111], v140 offset:8192
	ds_read_b128 v[112:115], v144 offset:24576
	ds_read_b128 v[116:119], v140 offset:9216
	ds_read_b128 v[120:123], v144 offset:25600
	ds_read_b128 v[124:127], v140 offset:10240
	ds_read_b128 v[128:131], v144 offset:26624
	ds_read_b128 v[132:135], v140 offset:11264
	ds_read_b128 v[136:139], v144 offset:27648
	s_waitcnt lgkmcnt(6)
	v_mfma_f32_16x16x32_bf16 v[76:79], v[112:115], v[108:111], v[76:79]
	s_waitcnt lgkmcnt(4)
	v_mfma_f32_16x16x32_bf16 v[80:83], v[120:123], v[108:111], v[80:83]
	s_waitcnt lgkmcnt(2)
	v_mfma_f32_16x16x32_bf16 v[84:87], v[128:131], v[108:111], v[84:87]
	s_waitcnt lgkmcnt(0)
	v_mfma_f32_16x16x32_bf16 v[40:43], v[136:139], v[108:111], v[40:43]
	v_mfma_f32_16x16x32_bf16 v[72:75], v[112:115], v[116:119], v[72:75]
	v_mfma_f32_16x16x32_bf16 v[88:91], v[120:123], v[116:119], v[88:91]
	v_mfma_f32_16x16x32_bf16 v[92:95], v[128:131], v[116:119], v[92:95]
	v_mfma_f32_16x16x32_bf16 v[44:47], v[136:139], v[116:119], v[44:47]
	v_mfma_f32_16x16x32_bf16 v[96:99], v[112:115], v[124:127], v[96:99]
	v_mfma_f32_16x16x32_bf16 v[100:103], v[120:123], v[124:127], v[100:103]
	v_mfma_f32_16x16x32_bf16 v[104:107], v[128:131], v[124:127], v[104:107]
	v_mfma_f32_16x16x32_bf16 v[56:59], v[136:139], v[124:127], v[56:59]
	v_mfma_f32_16x16x32_bf16 v[48:51], v[112:115], v[132:135], v[48:51]
	v_mfma_f32_16x16x32_bf16 v[52:55], v[120:123], v[132:135], v[52:55]
	v_mfma_f32_16x16x32_bf16 v[68:71], v[128:131], v[132:135], v[68:71]
	v_mfma_f32_16x16x32_bf16 v[60:63], v[136:139], v[132:135], v[60:63]
	s_waitcnt vmcnt(7)
	ds_write_b128 v148, v[8:11]
	s_waitcnt vmcnt(6)
	ds_write_b128 v149, v[12:15]
	s_waitcnt vmcnt(5)
	ds_write_b128 v148, v[16:19] offset:16384
	s_waitcnt vmcnt(4)
	ds_write_b128 v149, v[20:23] offset:16384
	s_waitcnt lgkmcnt(0)
	s_barrier
	global_load_dwordx4 v[108:111], v[0:1], off offset:3072
	global_load_dwordx4 v[112:115], v[6:7], off offset:3072
	global_load_dwordx4 v[116:119], v[2:3], off offset:448
	global_load_dwordx4 v[120:123], v[4:5], off offset:448
	ds_read_b128 v[0:3], v140
	ds_read_b128 v[4:7], v144 offset:16384
	ds_read_b128 v[8:11], v140 offset:1024
	ds_read_b128 v[12:15], v144 offset:17408
	ds_read_b128 v[16:19], v140 offset:2048
	ds_read_b128 v[20:23], v144 offset:18432
	ds_read_b128 v[124:127], v140 offset:3072
	ds_read_b128 v[128:131], v144 offset:19456
	s_waitcnt lgkmcnt(6)
	v_mfma_f32_16x16x32_bf16 v[76:79], v[4:7], v[0:3], v[76:79]
	s_waitcnt lgkmcnt(4)
	v_mfma_f32_16x16x32_bf16 v[80:83], v[12:15], v[0:3], v[80:83]
	s_waitcnt lgkmcnt(2)
	v_mfma_f32_16x16x32_bf16 v[84:87], v[20:23], v[0:3], v[84:87]
	s_waitcnt lgkmcnt(0)
	v_mfma_f32_16x16x32_bf16 v[0:3], v[128:131], v[0:3], v[40:43]
	v_mfma_f32_16x16x32_bf16 v[40:43], v[4:7], v[8:11], v[72:75]
	v_mfma_f32_16x16x32_bf16 v[72:75], v[12:15], v[8:11], v[88:91]
	v_mfma_f32_16x16x32_bf16 v[88:91], v[20:23], v[8:11], v[92:95]
	v_mfma_f32_16x16x32_bf16 v[8:11], v[128:131], v[8:11], v[44:47]
	v_mfma_f32_16x16x32_bf16 v[92:95], v[4:7], v[16:19], v[96:99]
	v_mfma_f32_16x16x32_bf16 v[96:99], v[12:15], v[16:19], v[100:103]
	v_mfma_f32_16x16x32_bf16 v[100:103], v[20:23], v[16:19], v[104:107]
	v_mfma_f32_16x16x32_bf16 v[16:19], v[128:131], v[16:19], v[56:59]
	v_mfma_f32_16x16x32_bf16 v[4:7], v[4:7], v[124:127], v[48:51]
	v_mfma_f32_16x16x32_bf16 v[104:107], v[12:15], v[124:127], v[52:55]
	v_mfma_f32_16x16x32_bf16 v[68:71], v[20:23], v[124:127], v[68:71]
	v_mfma_f32_16x16x32_bf16 v[60:63], v[128:131], v[124:127], v[60:63]
	s_waitcnt vmcnt(7)
	ds_write_b128 v148, v[24:27] offset:8192
	s_waitcnt vmcnt(6)
	ds_write_b128 v148, v[28:31] offset:12288
	s_waitcnt vmcnt(5)
	ds_write_b128 v148, v[32:35] offset:24576
	s_waitcnt vmcnt(4)
	ds_write_b128 v148, v[36:39] offset:28672
	s_waitcnt lgkmcnt(0)
	s_barrier
	ds_read_b128 v[12:15], v140 offset:8192
	ds_read_b128 v[124:127], v144 offset:24576
	ds_read_b128 v[20:23], v140 offset:9216
	ds_read_b128 v[128:131], v144 offset:25600
	ds_read_b128 v[132:135], v140 offset:10240
	ds_read_b128 v[136:139], v144 offset:26624
	ds_read_b128 v[140:143], v140 offset:11264
	ds_read_b128 v[144:147], v144 offset:27648
	s_waitcnt lgkmcnt(6)
	v_mfma_f32_16x16x32_bf16 v[76:79], v[124:127], v[12:15], v[76:79]
	s_waitcnt lgkmcnt(4)
	v_mfma_f32_16x16x32_bf16 v[56:59], v[128:131], v[12:15], v[80:83]
	s_waitcnt lgkmcnt(2)
	v_mfma_f32_16x16x32_bf16 v[52:55], v[136:139], v[12:15], v[84:87]
	s_waitcnt lgkmcnt(0)
	v_mfma_f32_16x16x32_bf16 v[48:51], v[144:147], v[12:15], v[0:3]
	v_mfma_f32_16x16x32_bf16 v[44:47], v[124:127], v[20:23], v[40:43]
	v_mfma_f32_16x16x32_bf16 v[40:43], v[128:131], v[20:23], v[72:75]
	v_mfma_f32_16x16x32_bf16 v[36:39], v[136:139], v[20:23], v[88:91]
	v_mfma_f32_16x16x32_bf16 v[32:35], v[144:147], v[20:23], v[8:11]
	v_mfma_f32_16x16x32_bf16 v[28:31], v[124:127], v[132:135], v[92:95]
	v_mfma_f32_16x16x32_bf16 v[24:27], v[128:131], v[132:135], v[96:99]
	v_mfma_f32_16x16x32_bf16 v[20:23], v[136:139], v[132:135], v[100:103]
	v_mfma_f32_16x16x32_bf16 v[16:19], v[144:147], v[132:135], v[16:19]
	v_mfma_f32_16x16x32_bf16 v[12:15], v[124:127], v[140:143], v[4:7]
	v_mfma_f32_16x16x32_bf16 v[8:11], v[128:131], v[140:143], v[104:107]
	v_mfma_f32_16x16x32_bf16 v[4:7], v[136:139], v[140:143], v[68:71]
	v_mfma_f32_16x16x32_bf16 v[0:3], v[144:147], v[140:143], v[60:63]
	s_nop 1
	v_mov_b32_e32 v60, v220
	s_waitcnt vmcnt(3)
	ds_write_b128 v148, v[108:111]
	s_waitcnt vmcnt(2)
	ds_write_b128 v149, v[112:115]
	s_waitcnt vmcnt(1)
	ds_write_b128 v148, v[116:119] offset:16384
	s_waitcnt vmcnt(0)
	ds_write_b128 v149, v[120:123] offset:16384
	s_waitcnt lgkmcnt(0)
	s_barrier
	s_bfe_u32 s0, s35, 0x20007
	v_and_b32_e32 v62, 15, v60
	v_and_b32_e32 v61, 64, v60
	v_ashrrev_i32_e32 v63, 1, v60
	v_lshrrev_b32_e32 v60, 2, v60
	v_and_or_b32 v71, v60, 12, v61
	v_cvt_f32_ubyte0_e32 v60, s0
	v_sub_f32_e32 v60, 0xc0a00000, v60
	v_cmp_gt_f32_e32 vcc, s27, v60
	s_and_b64 s[0:1], vcc, exec
	s_cselect_b32 s0, 0xffffffc0, 0
	v_cndmask_b32_e32 v61, 0, v64, vcc
	v_add_f32_e32 v60, v60, v61
	v_exp_f32_e32 v60, v60
	v_and_or_b32 v72, v63, s26, v62
	v_lshlrev_b32_e32 v63, 7, v63
	v_lshlrev_b32_e32 v62, 7, v62
	v_ldexp_f32 v68, v60, s0
	v_sub_f32_e32 v69, 1.0, v68
	v_add_f32_e32 v60, -1.0, v69
	v_sub_f32_e32 v61, v60, v69
	v_add_f32_e32 v61, 1.0, v61
	v_sub_f32_e64 v60, -v68, v60
	v_add_f32_e32 v70, v60, v61
	v_frexp_mant_f32_e32 v60, v69
	v_cmp_gt_f32_e32 vcc, s28, v60
	v_cvt_f64_f32_e32 v[60:61], v69
	v_frexp_exp_i32_f64_e32 v60, v[60:61]
	v_subbrev_co_u32_e32 v60, vcc, 0, v60, vcc
	v_sub_u32_e32 v61, 0, v60
	v_ldexp_f32 v69, v69, v61
	v_ldexp_f32 v61, v70, v61
	v_add_f32_e32 v70, -1.0, v69
	v_add_f32_e32 v73, 1.0, v70
	v_sub_f32_e32 v73, v69, v73
	v_add_f32_e32 v73, v61, v73
	v_add_f32_e32 v74, v70, v73
	v_sub_f32_e32 v70, v74, v70
	v_sub_f32_e32 v70, v73, v70
	v_add_f32_e32 v73, 1.0, v69
	v_add_f32_e32 v75, -1.0, v73
	v_sub_f32_e32 v69, v69, v75
	v_add_f32_e32 v61, v61, v69
	v_add_f32_e32 v69, v73, v61
	v_sub_f32_e32 v73, v69, v73
	v_sub_f32_e32 v61, v61, v73
	v_rcp_f32_e32 v73, v69
	v_cvt_f32_i32_e32 v60, v60
	v_cmp_nlt_f32_e32 vcc, 1.0, v68
	v_cmp_gt_i32_e64 s[0:1], v72, v71
	v_mul_f32_e32 v75, v74, v73
	v_mul_f32_e32 v80, v69, v75
	v_fma_f32 v81, v75, v69, -v80
	v_fmac_f32_e32 v81, v75, v61
	v_add_f32_e32 v82, v80, v81
	v_sub_f32_e32 v83, v74, v82
	v_sub_f32_e32 v74, v74, v83
	v_sub_f32_e32 v80, v82, v80
	v_sub_f32_e32 v74, v74, v82
	v_add_f32_e32 v70, v70, v74
	v_sub_f32_e32 v74, v80, v81
	v_add_f32_e32 v70, v74, v70
	v_add_f32_e32 v74, v83, v70
	v_mul_f32_e32 v80, v73, v74
	v_mul_f32_e32 v81, v69, v80
	v_fma_f32 v69, v80, v69, -v81
	v_fmac_f32_e32 v69, v80, v61
	v_sub_f32_e32 v61, v83, v74
	v_add_f32_e32 v61, v70, v61
	v_add_f32_e32 v70, v81, v69
	v_sub_f32_e32 v82, v74, v70
	v_sub_f32_e32 v74, v74, v82
	v_sub_f32_e32 v81, v70, v81
	v_sub_f32_e32 v70, v74, v70
	v_add_f32_e32 v61, v61, v70
	v_sub_f32_e32 v69, v81, v69
	v_add_f32_e32 v61, v69, v61
	v_add_f32_e32 v69, v75, v80
	v_add_f32_e32 v61, v82, v61
	v_sub_f32_e32 v70, v69, v75
	v_mul_f32_e32 v61, v73, v61
	v_sub_f32_e32 v70, v80, v70
	v_add_f32_e32 v61, v70, v61
	v_mul_f32_e32 v75, 0x3f317218, v60
	v_add_f32_e32 v70, v69, v61
	v_fma_f32 v80, v60, s29, -v75
	v_mul_f32_e32 v73, v70, v70
	v_fmac_f32_e32 v80, 0xb102e308, v60
	v_sub_f32_e32 v60, v70, v69
	v_fmamk_f32 v74, v73, 0x3e9b6dac, v65
	v_sub_f32_e32 v60, v61, v60
	v_add_f32_e32 v61, v75, v80
	v_fmaak_f32 v74, v73, v74, 0x3f2aaada
	v_sub_f32_e32 v69, v61, v75
	v_ldexp_f32 v75, v70, 1
	v_mul_f32_e32 v70, v70, v73
	v_mul_f32_e32 v70, v70, v74
	v_add_f32_e32 v73, v75, v70
	v_sub_f32_e32 v74, v73, v75
	v_ldexp_f32 v60, v60, 1
	v_sub_f32_e32 v70, v70, v74
	v_add_f32_e32 v60, v60, v70
	v_add_f32_e32 v70, v73, v60
	v_sub_f32_e32 v73, v70, v73
	v_sub_f32_e32 v60, v60, v73
	v_add_f32_e32 v73, v61, v70
	v_sub_f32_e32 v74, v73, v61
	v_sub_f32_e32 v75, v73, v74
	v_sub_f32_e32 v69, v80, v69
	v_sub_f32_e32 v61, v61, v75
	v_sub_f32_e32 v70, v70, v74
	v_add_f32_e32 v61, v70, v61
	v_add_f32_e32 v70, v69, v60
	v_sub_f32_e32 v74, v70, v69
	v_sub_f32_e32 v75, v70, v74
	v_sub_f32_e32 v69, v69, v75
	v_sub_f32_e32 v60, v60, v74
	v_add_f32_e32 v61, v70, v61
	v_add_f32_e32 v60, v60, v69
	v_add_f32_e32 v69, v73, v61
	v_sub_f32_e32 v70, v69, v73
	v_sub_f32_e32 v61, v61, v70
	v_add_f32_e32 v60, v60, v61
	v_add_f32_e32 v60, v69, v60
	v_cndmask_b32_e32 v60, v66, v60, vcc
	v_cmp_neq_f32_e32 vcc, 1.0, v68
	v_or_b32_e32 v75, 1, v71
	v_sub_u32_e32 v61, v72, v75
	v_cndmask_b32_e32 v60, v67, v60, vcc
	v_cmp_gt_f32_e32 vcc, s30, v68
	v_or_b32_e32 v73, 2, v71
	v_cvt_f32_i32_e32 v61, v61
	v_cndmask_b32_e64 v68, v60, -v68, vcc
	v_sub_u32_e32 v60, v72, v71
	v_cvt_f32_i32_e32 v60, v60
	v_sub_u32_e32 v70, v72, v73
	v_or_b32_e32 v74, 3, v71
	v_cvt_f32_i32_e32 v70, v70
	v_mul_f32_e32 v60, v68, v60
	v_mul_f32_e32 v60, 0x3fb8aa3b, v60
	v_exp_f32_e32 v69, v60
	v_mul_f32_e32 v61, v68, v61
	v_mul_f32_e32 v61, 0x3fb8aa3b, v61
	v_mul_f32_e32 v70, v68, v70
	v_mul_f32_e32 v60, v76, v69
	v_sub_u32_e32 v76, v72, v74
	v_cvt_f32_i32_e32 v76, v76
	v_exp_f32_e32 v61, v61
	v_mul_f32_e32 v70, 0x3fb8aa3b, v70
	v_exp_f32_e32 v70, v70
	v_mul_f32_e32 v76, v68, v76
	v_mul_f32_e32 v76, 0x3fb8aa3b, v76
	v_exp_f32_e32 v76, v76
	v_mul_f32_e32 v61, v77, v61
	v_cndmask_b32_e64 v61, 0, v61, s[0:1]
	v_mul_f32_e32 v70, v78, v70
	v_cmp_ge_i32_e64 s[0:1], v72, v73
	v_cmp_lt_i32_e32 vcc, v72, v71
	v_mul_f32_e32 v76, v79, v76
	v_cndmask_b32_e64 v70, 0, v70, s[0:1]
	v_cmp_ge_i32_e64 s[0:1], v72, v74
	v_and_b32_e32 v62, s31, v63
	v_cndmask_b32_e64 v60, v60, 0, vcc
	v_cndmask_b32_e64 v76, 0, v76, s[0:1]
	v_ashrrev_i32_e32 v63, 31, v62
	v_cvt_pk_bf16_f32 v60, v60, v61
	v_cvt_pk_bf16_f32 v61, v70, v76
	v_lshlrev_b64 v[62:63], 1, v[62:63]
	v_and_b32_e32 v76, 64, v71
	v_lshlrev_b32_e32 v76, 5, v76
	v_and_b32_e32 v253, 8, v71
	v_lshl_or_b32 v76, v253, 5, v76
	v_and_b32_e32 v253, 4, v71
	v_lshl_or_b32 v76, v253, 1, v76
	v_and_b32_e32 v253, 15, v72
	v_lshl_or_b32 v76, v253, 4, v76
	s_add_u32 s20, s72, s14
	v_or_b32_e32 v62, v62, v76
	s_addc_u32 s21, s73, s15
	v_lshl_add_u64 v[62:63], s[20:21], 0, v[62:63]
	v_add_co_u32_e64 v62, s[0:1], s34, v62
	v_or_b32_e32 v70, 16, v71
	s_nop 0
	v_addc_co_u32_e64 v63, s[0:1], 0, v63, s[0:1]
	global_store_dwordx2 v[62:63], v[60:61], off
	v_sub_u32_e32 v60, v72, v70
	v_cvt_f32_i32_e32 v60, v60
	v_or_b32_e32 v61, 17, v71
	v_cmp_ge_i32_e64 s[0:1], v72, v70
	v_mul_f32_e32 v40, v40, v69
	v_mul_f32_e32 v60, v68, v60
	v_mul_f32_e32 v60, 0x3fb8aa3b, v60
	v_exp_f32_e32 v60, v60
	v_cndmask_b32_e64 v40, v40, 0, vcc
	v_mul_f32_e32 v20, v20, v69
	v_cndmask_b32_e64 v20, v20, 0, vcc
	v_mul_f32_e32 v56, v56, v60
	v_sub_u32_e32 v60, v72, v61
	v_cvt_f32_i32_e32 v60, v60
	v_cndmask_b32_e64 v56, 0, v56, s[0:1]
	v_cmp_ge_i32_e64 s[0:1], v72, v61
	s_add_i32 s35, s35, s74
	v_mul_f32_e32 v60, v68, v60
	v_mul_f32_e32 v60, 0x3fb8aa3b, v60
	v_exp_f32_e32 v60, v60
	s_add_u32 s4, s4, s8
	v_mul_f32_e32 v0, v0, v69
	s_addc_u32 s5, s5, s9
	v_mul_f32_e32 v57, v57, v60
	v_or_b32_e32 v60, 18, v71
	v_sub_u32_e32 v77, v72, v60
	v_cvt_f32_i32_e32 v77, v77
	v_cndmask_b32_e64 v57, 0, v57, s[0:1]
	v_cmp_ge_i32_e64 s[0:1], v72, v60
	v_cvt_pk_bf16_f32 v56, v56, v57
	v_mul_f32_e32 v77, v68, v77
	v_mul_f32_e32 v77, 0x3fb8aa3b, v77
	v_exp_f32_e32 v77, v77
	v_cndmask_b32_e64 v0, v0, 0, vcc
	s_add_u32 s14, s14, s16
	s_addc_u32 s15, s15, s17
	v_mul_f32_e32 v58, v58, v77
	v_cndmask_b32_e64 v77, 0, v58, s[0:1]
	v_or_b32_e32 v58, 19, v71
	v_sub_u32_e32 v78, v72, v58
	v_cvt_f32_i32_e32 v78, v78
	v_cmp_ge_i32_e64 s[0:1], v72, v58
	s_cmpk_lt_i32 s35, 0x400
	v_mul_f32_e32 v78, v68, v78
	v_mul_f32_e32 v78, 0x3fb8aa3b, v78
	v_exp_f32_e32 v78, v78
	s_nop 0
	v_mul_f32_e32 v59, v59, v78
	v_cndmask_b32_e64 v59, 0, v59, s[0:1]
	v_cvt_pk_bf16_f32 v57, v77, v59
	global_store_dwordx2 v[62:63], v[56:57], off offset:512
	v_or_b32_e32 v57, 32, v71
	v_sub_u32_e32 v56, v72, v57
	v_cvt_f32_i32_e32 v56, v56
	v_cmp_ge_i32_e64 s[0:1], v72, v57
	v_mul_f32_e32 v56, v68, v56
	v_mul_f32_e32 v56, 0x3fb8aa3b, v56
	v_exp_f32_e32 v56, v56
	s_nop 0
	v_mul_f32_e32 v52, v52, v56
	v_or_b32_e32 v56, 33, v71
	v_cndmask_b32_e64 v59, 0, v52, s[0:1]
	v_sub_u32_e32 v52, v72, v56
	v_cvt_f32_i32_e32 v52, v52
	v_cmp_ge_i32_e64 s[0:1], v72, v56
	v_mul_f32_e32 v52, v68, v52
	v_mul_f32_e32 v52, 0x3fb8aa3b, v52
	v_exp_f32_e32 v52, v52
	s_nop 0
	v_mul_f32_e32 v52, v53, v52
	v_or_b32_e32 v53, 34, v71
	v_cndmask_b32_e64 v77, 0, v52, s[0:1]
	v_sub_u32_e32 v52, v72, v53
	v_cvt_f32_i32_e32 v52, v52
	v_cmp_ge_i32_e64 s[0:1], v72, v53
	v_mul_f32_e32 v52, v68, v52
	v_mul_f32_e32 v52, 0x3fb8aa3b, v52
	v_exp_f32_e32 v52, v52
	s_nop 0
	v_mul_f32_e32 v52, v54, v52
	v_cndmask_b32_e64 v78, 0, v52, s[0:1]
	v_or_b32_e32 v52, 35, v71
	v_sub_u32_e32 v54, v72, v52
	v_cvt_f32_i32_e32 v54, v54
	v_cmp_ge_i32_e64 s[0:1], v72, v52
	v_mul_f32_e32 v54, v68, v54
	v_mul_f32_e32 v54, 0x3fb8aa3b, v54
	v_exp_f32_e32 v54, v54
	s_nop 0
	v_mul_f32_e32 v54, v55, v54
	v_cndmask_b32_e64 v55, 0, v54, s[0:1]
	v_cvt_pk_bf16_f32 v55, v78, v55
	v_cvt_pk_bf16_f32 v54, v59, v77
	global_store_dwordx2 v[62:63], v[54:55], off offset:1024
	v_or_b32_e32 v55, 48, v71
	v_sub_u32_e32 v54, v72, v55
	v_cvt_f32_i32_e32 v54, v54
	v_cmp_ge_i32_e64 s[0:1], v72, v55
	v_mul_f32_e32 v54, v68, v54
	v_mul_f32_e32 v54, 0x3fb8aa3b, v54
	v_exp_f32_e32 v54, v54
	s_nop 0
	v_mul_f32_e32 v48, v48, v54
	v_or_b32_e32 v54, 49, v71
	v_cndmask_b32_e64 v59, 0, v48, s[0:1]
	v_sub_u32_e32 v48, v72, v54
	v_cvt_f32_i32_e32 v48, v48
	v_cmp_ge_i32_e64 s[0:1], v72, v54
	v_mul_f32_e32 v48, v68, v48
	v_mul_f32_e32 v48, 0x3fb8aa3b, v48
	v_exp_f32_e32 v48, v48
	s_nop 0
	v_mul_f32_e32 v48, v49, v48
	v_or_b32_e32 v49, 50, v71
	v_cndmask_b32_e64 v77, 0, v48, s[0:1]
	v_sub_u32_e32 v48, v72, v49
	v_cvt_f32_i32_e32 v48, v48
	v_cmp_ge_i32_e64 s[0:1], v72, v49
	v_mul_f32_e32 v48, v68, v48
	v_mul_f32_e32 v48, 0x3fb8aa3b, v48
	v_exp_f32_e32 v48, v48
	s_nop 0
	v_mul_f32_e32 v48, v50, v48
	v_cndmask_b32_e64 v78, 0, v48, s[0:1]
	v_or_b32_e32 v48, 51, v71
	v_sub_u32_e32 v50, v72, v48
	v_cvt_f32_i32_e32 v50, v50
	v_cmp_ge_i32_e64 s[0:1], v72, v48
	v_mul_f32_e32 v50, v68, v50
	v_mul_f32_e32 v50, 0x3fb8aa3b, v50
	v_exp_f32_e32 v50, v50
	s_nop 0
	v_mul_f32_e32 v50, v51, v50
	v_cndmask_b32_e64 v51, 0, v50, s[0:1]
	v_cvt_pk_bf16_f32 v50, v59, v77
	v_cvt_pk_bf16_f32 v51, v78, v51
	global_store_dwordx2 v[62:63], v[50:51], off offset:1536
	v_or_b32_e32 v50, 16, v72
	v_sub_u32_e32 v51, v50, v71
	v_cvt_f32_i32_e32 v51, v51
	v_cmp_ge_i32_e64 s[0:1], v50, v71
	v_mul_f32_e32 v51, v68, v51
	v_mul_f32_e32 v51, 0x3fb8aa3b, v51
	v_exp_f32_e32 v51, v51
	s_nop 0
	v_mul_f32_e32 v44, v44, v51
	v_sub_u32_e32 v51, v50, v75
	v_cvt_f32_i32_e32 v51, v51
	v_cndmask_b32_e64 v44, 0, v44, s[0:1]
	v_cmp_gt_i32_e64 s[0:1], v50, v71
	v_mul_f32_e32 v51, v68, v51
	v_mul_f32_e32 v51, 0x3fb8aa3b, v51
	v_exp_f32_e32 v51, v51
	s_nop 0
	v_mul_f32_e32 v45, v45, v51
	v_sub_u32_e32 v51, v50, v73
	v_cvt_f32_i32_e32 v51, v51
	v_cndmask_b32_e64 v45, 0, v45, s[0:1]
	v_cmp_ge_i32_e64 s[0:1], v50, v73
	v_cvt_pk_bf16_f32 v44, v44, v45
	v_mul_f32_e32 v51, v68, v51
	v_mul_f32_e32 v51, 0x3fb8aa3b, v51
	v_exp_f32_e32 v51, v51
	s_nop 0
	v_mul_f32_e32 v46, v46, v51
	v_sub_u32_e32 v51, v50, v74
	v_cvt_f32_i32_e32 v51, v51
	v_cndmask_b32_e64 v46, 0, v46, s[0:1]
	v_cmp_ge_i32_e64 s[0:1], v50, v74
	v_mul_f32_e32 v51, v68, v51
	v_mul_f32_e32 v51, 0x3fb8aa3b, v51
	v_exp_f32_e32 v51, v51
	s_nop 0
	v_mul_f32_e32 v47, v47, v51
	v_cndmask_b32_e64 v47, 0, v47, s[0:1]
	v_cvt_pk_bf16_f32 v45, v46, v47
	v_lshlrev_b32_e32 v46, 7, v50
	v_and_b32_e32 v46, 0xfffff87f, v46
	v_ashrrev_i32_e32 v47, 31, v46
	v_lshlrev_b64 v[46:47], 1, v[46:47]
	v_or_b32_e32 v46, v46, v76
	v_lshl_add_u64 v[46:47], s[20:21], 0, v[46:47]
	v_add_co_u32_e64 v46, s[0:1], s34, v46
	s_nop 1
	v_addc_co_u32_e64 v47, s[0:1], 0, v47, s[0:1]
	global_store_dwordx2 v[46:47], v[44:45], off
	v_sub_u32_e32 v44, v50, v61
	v_cvt_f32_i32_e32 v44, v44
	v_cmp_ge_i32_e64 s[0:1], v50, v61
	v_mul_f32_e32 v44, v68, v44
	v_mul_f32_e32 v44, 0x3fb8aa3b, v44
	v_exp_f32_e32 v44, v44
	s_nop 0
	v_mul_f32_e32 v41, v41, v44
	v_sub_u32_e32 v44, v50, v60
	v_cvt_f32_i32_e32 v44, v44
	v_cndmask_b32_e64 v41, 0, v41, s[0:1]
	v_cmp_ge_i32_e64 s[0:1], v50, v60
	v_cvt_pk_bf16_f32 v40, v40, v41
	v_mul_f32_e32 v44, v68, v44
	v_mul_f32_e32 v44, 0x3fb8aa3b, v44
	v_exp_f32_e32 v44, v44
	s_nop 0
	v_mul_f32_e32 v42, v42, v44
	v_sub_u32_e32 v44, v50, v58
	v_cvt_f32_i32_e32 v44, v44
	v_cndmask_b32_e64 v42, 0, v42, s[0:1]
	v_cmp_ge_i32_e64 s[0:1], v50, v58
	v_mul_f32_e32 v44, v68, v44
	v_mul_f32_e32 v44, 0x3fb8aa3b, v44
	v_exp_f32_e32 v44, v44
	s_nop 0
	v_mul_f32_e32 v43, v43, v44
	v_cndmask_b32_e64 v43, 0, v43, s[0:1]
	v_cvt_pk_bf16_f32 v41, v42, v43
	global_store_dwordx2 v[46:47], v[40:41], off offset:512
	v_sub_u32_e32 v40, v50, v57
	v_cvt_f32_i32_e32 v40, v40
	v_cmp_ge_i32_e64 s[0:1], v50, v57
	v_mul_f32_e32 v40, v68, v40
	v_mul_f32_e32 v40, 0x3fb8aa3b, v40
	v_exp_f32_e32 v40, v40
	s_nop 0
	v_mul_f32_e32 v36, v36, v40
	v_sub_u32_e32 v40, v50, v56
	v_cvt_f32_i32_e32 v40, v40
	v_cndmask_b32_e64 v36, 0, v36, s[0:1]
	v_cmp_ge_i32_e64 s[0:1], v50, v56
	v_mul_f32_e32 v40, v68, v40
	v_mul_f32_e32 v40, 0x3fb8aa3b, v40
	v_exp_f32_e32 v40, v40
	s_nop 0
	v_mul_f32_e32 v37, v37, v40
	v_sub_u32_e32 v40, v50, v53
	v_cvt_f32_i32_e32 v40, v40
	v_cndmask_b32_e64 v37, 0, v37, s[0:1]
	v_cmp_ge_i32_e64 s[0:1], v50, v53
	v_cvt_pk_bf16_f32 v36, v36, v37
	v_mul_f32_e32 v40, v68, v40
	v_mul_f32_e32 v40, 0x3fb8aa3b, v40
	v_exp_f32_e32 v40, v40
	s_nop 0
	v_mul_f32_e32 v38, v38, v40
	v_sub_u32_e32 v40, v50, v52
	v_cvt_f32_i32_e32 v40, v40
	v_cndmask_b32_e64 v38, 0, v38, s[0:1]
	v_cmp_ge_i32_e64 s[0:1], v50, v52
	v_mul_f32_e32 v40, v68, v40
	v_mul_f32_e32 v40, 0x3fb8aa3b, v40
	v_exp_f32_e32 v40, v40
	s_nop 0
	v_mul_f32_e32 v39, v39, v40
	v_cndmask_b32_e64 v39, 0, v39, s[0:1]
	v_cvt_pk_bf16_f32 v37, v38, v39
	global_store_dwordx2 v[46:47], v[36:37], off offset:1024
	v_sub_u32_e32 v36, v50, v55
	v_cvt_f32_i32_e32 v36, v36
	v_cmp_ge_i32_e64 s[0:1], v50, v55
	v_mul_f32_e32 v36, v68, v36
	v_mul_f32_e32 v36, 0x3fb8aa3b, v36
	v_exp_f32_e32 v36, v36
	s_nop 0
	v_mul_f32_e32 v32, v32, v36
	v_sub_u32_e32 v36, v50, v54
	v_cvt_f32_i32_e32 v36, v36
	v_cndmask_b32_e64 v32, 0, v32, s[0:1]
	v_cmp_ge_i32_e64 s[0:1], v50, v54
	v_mul_f32_e32 v36, v68, v36
	v_mul_f32_e32 v36, 0x3fb8aa3b, v36
	v_exp_f32_e32 v36, v36
	s_nop 0
	v_mul_f32_e32 v33, v33, v36
	v_sub_u32_e32 v36, v50, v49
	v_cvt_f32_i32_e32 v36, v36
	v_cndmask_b32_e64 v33, 0, v33, s[0:1]
	v_cmp_ge_i32_e64 s[0:1], v50, v49
	v_cvt_pk_bf16_f32 v32, v32, v33
	v_mul_f32_e32 v36, v68, v36
	v_mul_f32_e32 v36, 0x3fb8aa3b, v36
	v_exp_f32_e32 v36, v36
	s_nop 0
	v_mul_f32_e32 v34, v34, v36
	v_sub_u32_e32 v36, v50, v48
	v_cvt_f32_i32_e32 v36, v36
	v_cndmask_b32_e64 v34, 0, v34, s[0:1]
	v_cmp_ge_i32_e64 s[0:1], v50, v48
	v_mul_f32_e32 v36, v68, v36
	v_mul_f32_e32 v36, 0x3fb8aa3b, v36
	v_exp_f32_e32 v36, v36
	s_nop 0
	v_mul_f32_e32 v35, v35, v36
	v_cndmask_b32_e64 v35, 0, v35, s[0:1]
	v_cvt_pk_bf16_f32 v33, v34, v35
	global_store_dwordx2 v[46:47], v[32:33], off offset:1536
	v_or_b32_e32 v32, 32, v72
	v_sub_u32_e32 v33, v32, v71
	v_cvt_f32_i32_e32 v33, v33
	v_cmp_ge_i32_e64 s[0:1], v32, v71
	v_mul_f32_e32 v33, v68, v33
	v_mul_f32_e32 v33, 0x3fb8aa3b, v33
	v_exp_f32_e32 v33, v33
	s_nop 0
	v_mul_f32_e32 v28, v28, v33
	v_sub_u32_e32 v33, v32, v75
	v_cvt_f32_i32_e32 v33, v33
	v_cndmask_b32_e64 v28, 0, v28, s[0:1]
	v_cmp_gt_i32_e64 s[0:1], v32, v71
	v_mul_f32_e32 v33, v68, v33
	v_mul_f32_e32 v33, 0x3fb8aa3b, v33
	v_exp_f32_e32 v33, v33
	s_nop 0
	v_mul_f32_e32 v29, v29, v33
	v_sub_u32_e32 v33, v32, v73
	v_cvt_f32_i32_e32 v33, v33
	v_cndmask_b32_e64 v29, 0, v29, s[0:1]
	v_cmp_ge_i32_e64 s[0:1], v32, v73
	v_cvt_pk_bf16_f32 v28, v28, v29
	v_mul_f32_e32 v33, v68, v33
	v_mul_f32_e32 v33, 0x3fb8aa3b, v33
	v_exp_f32_e32 v33, v33
	s_nop 0
	v_mul_f32_e32 v30, v30, v33
	v_sub_u32_e32 v33, v32, v74
	v_cvt_f32_i32_e32 v33, v33
	v_cndmask_b32_e64 v30, 0, v30, s[0:1]
	v_cmp_ge_i32_e64 s[0:1], v32, v74
	v_mul_f32_e32 v33, v68, v33
	v_mul_f32_e32 v33, 0x3fb8aa3b, v33
	v_exp_f32_e32 v33, v33
	s_nop 0
	v_mul_f32_e32 v31, v31, v33
	v_cndmask_b32_e64 v31, 0, v31, s[0:1]
	v_cvt_pk_bf16_f32 v29, v30, v31
	v_lshlrev_b32_e32 v30, 7, v32
	v_and_b32_e32 v30, 0xfffff87f, v30
	v_ashrrev_i32_e32 v31, 31, v30
	v_lshlrev_b64 v[30:31], 1, v[30:31]
	v_or_b32_e32 v30, v30, v76
	v_lshl_add_u64 v[30:31], s[20:21], 0, v[30:31]
	v_add_co_u32_e64 v30, s[0:1], s34, v30
	s_nop 1
	v_addc_co_u32_e64 v31, s[0:1], 0, v31, s[0:1]
	global_store_dwordx2 v[30:31], v[28:29], off
	v_sub_u32_e32 v28, v32, v70
	v_cvt_f32_i32_e32 v28, v28
	v_cmp_ge_i32_e64 s[0:1], v32, v70
	v_mul_f32_e32 v28, v68, v28
	v_mul_f32_e32 v28, 0x3fb8aa3b, v28
	v_exp_f32_e32 v28, v28
	s_nop 0
	v_mul_f32_e32 v24, v24, v28
	v_sub_u32_e32 v28, v32, v61
	v_cvt_f32_i32_e32 v28, v28
	v_cndmask_b32_e64 v24, 0, v24, s[0:1]
	v_cmp_ge_i32_e64 s[0:1], v32, v61
	v_mul_f32_e32 v28, v68, v28
	v_mul_f32_e32 v28, 0x3fb8aa3b, v28
	v_exp_f32_e32 v28, v28
	s_nop 0
	v_mul_f32_e32 v25, v25, v28
	v_sub_u32_e32 v28, v32, v60
	v_cvt_f32_i32_e32 v28, v28
	v_cndmask_b32_e64 v25, 0, v25, s[0:1]
	v_cmp_ge_i32_e64 s[0:1], v32, v60
	v_cvt_pk_bf16_f32 v24, v24, v25
	v_mul_f32_e32 v28, v68, v28
	v_mul_f32_e32 v28, 0x3fb8aa3b, v28
	v_exp_f32_e32 v28, v28
	s_nop 0
	v_mul_f32_e32 v26, v26, v28
	v_sub_u32_e32 v28, v32, v58
	v_cvt_f32_i32_e32 v28, v28
	v_cndmask_b32_e64 v26, 0, v26, s[0:1]
	v_cmp_ge_i32_e64 s[0:1], v32, v58
	v_mul_f32_e32 v28, v68, v28
	v_mul_f32_e32 v28, 0x3fb8aa3b, v28
	v_exp_f32_e32 v28, v28
	s_nop 0
	v_mul_f32_e32 v27, v27, v28
	v_cndmask_b32_e64 v27, 0, v27, s[0:1]
	v_cvt_pk_bf16_f32 v25, v26, v27
	global_store_dwordx2 v[30:31], v[24:25], off offset:512
	v_sub_u32_e32 v24, v32, v56
	v_cvt_f32_i32_e32 v24, v24
	v_cmp_ge_i32_e64 s[0:1], v32, v56
	v_mul_f32_e32 v24, v68, v24
	v_mul_f32_e32 v24, 0x3fb8aa3b, v24
	v_exp_f32_e32 v24, v24
	s_nop 0
	v_mul_f32_e32 v21, v21, v24
	v_sub_u32_e32 v24, v32, v53
	v_cvt_f32_i32_e32 v24, v24
	v_cndmask_b32_e64 v21, 0, v21, s[0:1]
	v_cmp_ge_i32_e64 s[0:1], v32, v53
	v_cvt_pk_bf16_f32 v20, v20, v21
	v_mul_f32_e32 v24, v68, v24
	v_mul_f32_e32 v24, 0x3fb8aa3b, v24
	v_exp_f32_e32 v24, v24
	s_nop 0
	v_mul_f32_e32 v22, v22, v24
	v_sub_u32_e32 v24, v32, v52
	v_cvt_f32_i32_e32 v24, v24
	v_cndmask_b32_e64 v22, 0, v22, s[0:1]
	v_cmp_ge_i32_e64 s[0:1], v32, v52
	v_mul_f32_e32 v24, v68, v24
	v_mul_f32_e32 v24, 0x3fb8aa3b, v24
	v_exp_f32_e32 v24, v24
	s_nop 0
	v_mul_f32_e32 v23, v23, v24
	v_cndmask_b32_e64 v23, 0, v23, s[0:1]
	v_cvt_pk_bf16_f32 v21, v22, v23
	global_store_dwordx2 v[30:31], v[20:21], off offset:1024
	v_sub_u32_e32 v20, v32, v55
	v_cvt_f32_i32_e32 v20, v20
	v_cmp_ge_i32_e64 s[0:1], v32, v55
	v_mul_f32_e32 v20, v68, v20
	v_mul_f32_e32 v20, 0x3fb8aa3b, v20
	v_exp_f32_e32 v20, v20
	s_nop 0
	v_mul_f32_e32 v16, v16, v20
	v_sub_u32_e32 v20, v32, v54
	v_cvt_f32_i32_e32 v20, v20
	v_cndmask_b32_e64 v16, 0, v16, s[0:1]
	v_cmp_ge_i32_e64 s[0:1], v32, v54
	v_mul_f32_e32 v20, v68, v20
	v_mul_f32_e32 v20, 0x3fb8aa3b, v20
	v_exp_f32_e32 v20, v20
	s_nop 0
	v_mul_f32_e32 v17, v17, v20
	v_sub_u32_e32 v20, v32, v49
	v_cvt_f32_i32_e32 v20, v20
	v_cndmask_b32_e64 v17, 0, v17, s[0:1]
	v_cmp_ge_i32_e64 s[0:1], v32, v49
	v_cvt_pk_bf16_f32 v16, v16, v17
	v_mul_f32_e32 v20, v68, v20
	v_mul_f32_e32 v20, 0x3fb8aa3b, v20
	v_exp_f32_e32 v20, v20
	s_nop 0
	v_mul_f32_e32 v18, v18, v20
	v_sub_u32_e32 v20, v32, v48
	v_cvt_f32_i32_e32 v20, v20
	v_cndmask_b32_e64 v18, 0, v18, s[0:1]
	v_cmp_ge_i32_e64 s[0:1], v32, v48
	v_mul_f32_e32 v20, v68, v20
	v_mul_f32_e32 v20, 0x3fb8aa3b, v20
	v_exp_f32_e32 v20, v20
	s_nop 0
	v_mul_f32_e32 v19, v19, v20
	v_cndmask_b32_e64 v19, 0, v19, s[0:1]
	v_cvt_pk_bf16_f32 v17, v18, v19
	global_store_dwordx2 v[30:31], v[16:17], off offset:1536
	v_or_b32_e32 v16, 48, v72
	v_sub_u32_e32 v17, v16, v71
	v_cvt_f32_i32_e32 v17, v17
	v_cmp_ge_i32_e64 s[0:1], v16, v71
	v_cmp_ge_i32_e32 vcc, v16, v54
	v_mul_f32_e32 v17, v68, v17
	v_mul_f32_e32 v17, 0x3fb8aa3b, v17
	v_exp_f32_e32 v17, v17
	s_nop 0
	v_mul_f32_e32 v12, v12, v17
	v_sub_u32_e32 v17, v16, v75
	v_cvt_f32_i32_e32 v17, v17
	v_cndmask_b32_e64 v12, 0, v12, s[0:1]
	v_cmp_gt_i32_e64 s[0:1], v16, v71
	v_mul_f32_e32 v17, v68, v17
	v_mul_f32_e32 v17, 0x3fb8aa3b, v17
	v_exp_f32_e32 v17, v17
	s_nop 0
	v_mul_f32_e32 v13, v13, v17
	v_sub_u32_e32 v17, v16, v73
	v_cvt_f32_i32_e32 v17, v17
	v_cndmask_b32_e64 v13, 0, v13, s[0:1]
	v_cmp_ge_i32_e64 s[0:1], v16, v73
	v_mul_f32_e32 v17, v68, v17
	v_mul_f32_e32 v17, 0x3fb8aa3b, v17
	v_exp_f32_e32 v17, v17
	s_nop 0
	v_mul_f32_e32 v14, v14, v17
	v_cndmask_b32_e64 v17, 0, v14, s[0:1]
	v_sub_u32_e32 v14, v16, v74
	v_cvt_f32_i32_e32 v14, v14
	v_cmp_ge_i32_e64 s[0:1], v16, v74
	v_mul_f32_e32 v14, v68, v14
	v_mul_f32_e32 v14, 0x3fb8aa3b, v14
	v_exp_f32_e32 v14, v14
	s_nop 0
	v_mul_f32_e32 v14, v15, v14
	v_cndmask_b32_e64 v15, 0, v14, s[0:1]
	v_cvt_pk_bf16_f32 v14, v12, v13
	v_lshlrev_b32_e32 v12, 7, v16
	v_and_b32_e32 v12, 0xfffff87f, v12
	v_ashrrev_i32_e32 v13, 31, v12
	v_lshlrev_b64 v[12:13], 1, v[12:13]
	v_or_b32_e32 v12, v12, v76
	v_lshl_add_u64 v[12:13], s[20:21], 0, v[12:13]
	v_add_co_u32_e64 v12, s[0:1], s34, v12
	v_cvt_pk_bf16_f32 v15, v17, v15
	s_nop 1
	v_addc_co_u32_e64 v13, s[0:1], 0, v13, s[0:1]
	global_store_dwordx2 v[12:13], v[14:15], off
	v_sub_u32_e32 v14, v16, v70
	v_cvt_f32_i32_e32 v14, v14
	v_cmp_ge_i32_e64 s[0:1], v16, v70
	v_mul_f32_e32 v14, v68, v14
	v_mul_f32_e32 v14, 0x3fb8aa3b, v14
	v_exp_f32_e32 v14, v14
	s_nop 0
	v_mul_f32_e32 v8, v8, v14
	v_sub_u32_e32 v14, v16, v61
	v_cvt_f32_i32_e32 v14, v14
	v_cndmask_b32_e64 v8, 0, v8, s[0:1]
	v_cmp_ge_i32_e64 s[0:1], v16, v61
	v_mul_f32_e32 v14, v68, v14
	v_mul_f32_e32 v14, 0x3fb8aa3b, v14
	v_exp_f32_e32 v14, v14
	s_nop 0
	v_mul_f32_e32 v9, v9, v14
	v_sub_u32_e32 v14, v16, v60
	v_cvt_f32_i32_e32 v14, v14
	v_cndmask_b32_e64 v9, 0, v9, s[0:1]
	v_cmp_ge_i32_e64 s[0:1], v16, v60
	v_cvt_pk_bf16_f32 v8, v8, v9
	v_mul_f32_e32 v14, v68, v14
	v_mul_f32_e32 v14, 0x3fb8aa3b, v14
	v_exp_f32_e32 v14, v14
	s_nop 0
	v_mul_f32_e32 v10, v10, v14
	v_sub_u32_e32 v14, v16, v58
	v_cvt_f32_i32_e32 v14, v14
	v_cndmask_b32_e64 v10, 0, v10, s[0:1]
	v_cmp_ge_i32_e64 s[0:1], v16, v58
	v_mul_f32_e32 v14, v68, v14
	v_mul_f32_e32 v14, 0x3fb8aa3b, v14
	v_exp_f32_e32 v14, v14
	s_nop 0
	v_mul_f32_e32 v11, v11, v14
	v_cndmask_b32_e64 v11, 0, v11, s[0:1]
	v_cvt_pk_bf16_f32 v9, v10, v11
	global_store_dwordx2 v[12:13], v[8:9], off offset:512
	v_sub_u32_e32 v8, v16, v57
	v_cvt_f32_i32_e32 v8, v8
	v_cmp_ge_i32_e64 s[0:1], v16, v57
	v_mul_f32_e32 v8, v68, v8
	v_mul_f32_e32 v8, 0x3fb8aa3b, v8
	v_exp_f32_e32 v8, v8
	s_nop 0
	v_mul_f32_e32 v4, v4, v8
	v_sub_u32_e32 v8, v16, v56
	v_cvt_f32_i32_e32 v8, v8
	v_cndmask_b32_e64 v4, 0, v4, s[0:1]
	v_cmp_ge_i32_e64 s[0:1], v16, v56
	v_mul_f32_e32 v8, v68, v8
	v_mul_f32_e32 v8, 0x3fb8aa3b, v8
	v_exp_f32_e32 v8, v8
	s_nop 0
	v_mul_f32_e32 v5, v5, v8
	v_sub_u32_e32 v8, v16, v53
	v_cvt_f32_i32_e32 v8, v8
	v_cndmask_b32_e64 v5, 0, v5, s[0:1]
	v_cmp_ge_i32_e64 s[0:1], v16, v53
	v_cvt_pk_bf16_f32 v4, v4, v5
	v_mul_f32_e32 v8, v68, v8
	v_mul_f32_e32 v8, 0x3fb8aa3b, v8
	v_exp_f32_e32 v8, v8
	s_nop 0
	v_mul_f32_e32 v6, v6, v8
	v_sub_u32_e32 v8, v16, v52
	v_cvt_f32_i32_e32 v8, v8
	v_cndmask_b32_e64 v6, 0, v6, s[0:1]
	v_cmp_ge_i32_e64 s[0:1], v16, v52
	v_mul_f32_e32 v8, v68, v8
	v_mul_f32_e32 v8, 0x3fb8aa3b, v8
	v_exp_f32_e32 v8, v8
	s_nop 0
	v_mul_f32_e32 v7, v7, v8
	v_cndmask_b32_e64 v7, 0, v7, s[0:1]
	v_cvt_pk_bf16_f32 v5, v6, v7
	global_store_dwordx2 v[12:13], v[4:5], off offset:1024
	v_sub_u32_e32 v4, v16, v54
	v_cvt_f32_i32_e32 v4, v4
	v_mul_f32_e32 v4, v68, v4
	v_mul_f32_e32 v4, 0x3fb8aa3b, v4
	v_exp_f32_e32 v4, v4
	s_nop 0
	v_mul_f32_e32 v1, v1, v4
	v_sub_u32_e32 v4, v16, v49
	v_cvt_f32_i32_e32 v4, v4
	v_cndmask_b32_e32 v1, 0, v1, vcc
	v_cmp_ge_i32_e32 vcc, v16, v49
	v_cvt_pk_bf16_f32 v0, v0, v1
	v_mul_f32_e32 v4, v68, v4
	v_mul_f32_e32 v4, 0x3fb8aa3b, v4
	v_exp_f32_e32 v4, v4
	s_nop 0
	v_mul_f32_e32 v2, v2, v4
	v_sub_u32_e32 v4, v16, v48
	v_cvt_f32_i32_e32 v4, v4
	v_cndmask_b32_e32 v2, 0, v2, vcc
	v_cmp_ge_i32_e32 vcc, v16, v48
	v_mul_f32_e32 v4, v68, v4
	v_mul_f32_e32 v4, 0x3fb8aa3b, v4
	v_exp_f32_e32 v4, v4
	s_nop 0
	v_mul_f32_e32 v3, v3, v4
	v_cndmask_b32_e32 v3, 0, v3, vcc
	v_cvt_pk_bf16_f32 v1, v2, v3
	global_store_dwordx2 v[12:13], v[0:1], off offset:1536
	s_cbranch_scc1 .LBB0_330

.LBB0_503:
	s_add_i32 s37, s36, 64
	s_min_u32 s14, s37, 0x3e0
	s_lshl_b32 s14, s14, 1
	v_lshl_add_u64 v[170:171], v[154:155], 0, s[14:15]
	v_lshl_add_u64 v[174:175], v[158:159], 0, s[14:15]
	v_lshl_add_u64 v[178:179], v[160:161], 0, s[14:15]
	v_lshl_add_u64 v[182:183], v[162:163], 0, s[14:15]
	v_lshl_add_u64 v[186:187], v[156:157], 0, s[14:15]
	v_lshl_add_u64 v[190:191], v[164:165], 0, s[14:15]
	global_load_dwordx4 v[170:173], v[170:171], off
	ds_read_b128 v[196:199], v169 offset:32768
	global_load_dwordx4 v[174:177], v[174:175], off
	ds_read_b128 v[200:203], v169 offset:33792
	global_load_dwordx4 v[178:181], v[178:179], off
	ds_read_b128 v[204:207], v169 offset:34816
	global_load_dwordx4 v[182:185], v[182:183], off
	ds_read_b128 v[208:211], v169 offset:35840
	global_load_dwordx4 v[186:189], v[186:187], off
	ds_read_b128 v[212:215], v167
	global_load_dwordx4 v[190:193], v[190:191], off
	ds_read_b128 v[216:219], v167 offset:1024
	ds_read_b128 v[222:225], v167 offset:2048
	ds_read_b128 v[226:229], v167 offset:3072
	ds_read_b128 v[230:233], v167 offset:4096
	ds_read_b128 v[234:237], v167 offset:5120
	ds_read_b128 v[238:241], v167 offset:6144
	ds_read_b128 v[242:245], v167 offset:7168
	s_waitcnt lgkmcnt(7)
	v_mfma_f32_16x16x32_bf16 v[148:151], v[196:199], v[212:215], v[148:151]
	v_mfma_f32_16x16x32_bf16 v[136:139], v[200:203], v[212:215], v[136:139]
	v_mfma_f32_16x16x32_bf16 v[132:135], v[204:207], v[212:215], v[132:135]
	v_mfma_f32_16x16x32_bf16 v[128:131], v[208:211], v[212:215], v[128:131]
	s_waitcnt vmcnt(11)
	ds_write_b128 v152, v[44:47] offset:16384
	s_waitcnt lgkmcnt(7)
	v_mfma_f32_16x16x32_bf16 v[124:127], v[196:199], v[216:219], v[124:127]
	v_mfma_f32_16x16x32_bf16 v[120:123], v[200:203], v[216:219], v[120:123]
	v_mfma_f32_16x16x32_bf16 v[116:119], v[204:207], v[216:219], v[116:119]
	v_mfma_f32_16x16x32_bf16 v[112:115], v[208:211], v[216:219], v[112:115]
	s_waitcnt vmcnt(9)
	ds_write_b128 v152, v[60:63] offset:20480
	s_waitcnt lgkmcnt(7)
	v_mfma_f32_16x16x32_bf16 v[108:111], v[196:199], v[222:225], v[108:111]
	v_mfma_f32_16x16x32_bf16 v[104:107], v[200:203], v[222:225], v[104:107]
	v_mfma_f32_16x16x32_bf16 v[100:103], v[204:207], v[222:225], v[100:103]
	v_mfma_f32_16x16x32_bf16 v[96:99], v[208:211], v[222:225], v[96:99]
	s_waitcnt vmcnt(8)
	ds_write_b128 v152, v[68:71] offset:24576
	s_waitcnt lgkmcnt(7)
	v_mfma_f32_16x16x32_bf16 v[92:95], v[196:199], v[226:229], v[92:95]
	v_mfma_f32_16x16x32_bf16 v[88:91], v[200:203], v[226:229], v[88:91]
	v_mfma_f32_16x16x32_bf16 v[84:87], v[204:207], v[226:229], v[84:87]
	v_mfma_f32_16x16x32_bf16 v[80:83], v[208:211], v[226:229], v[80:83]
	s_waitcnt vmcnt(7)
	ds_write_b128 v152, v[140:143] offset:28672
	s_waitcnt lgkmcnt(7)
	v_mfma_f32_16x16x32_bf16 v[76:79], v[196:199], v[230:233], v[76:79]
	v_mfma_f32_16x16x32_bf16 v[72:75], v[200:203], v[230:233], v[72:75]
	v_mfma_f32_16x16x32_bf16 v[64:67], v[204:207], v[230:233], v[64:67]
	v_mfma_f32_16x16x32_bf16 v[56:59], v[208:211], v[230:233], v[56:59]
	s_waitcnt vmcnt(7)
	ds_write_b128 v152, v[52:55] offset:40960
	s_waitcnt lgkmcnt(7)
	v_mfma_f32_16x16x32_bf16 v[48:51], v[196:199], v[234:237], v[48:51]
	v_mfma_f32_16x16x32_bf16 v[40:43], v[200:203], v[234:237], v[40:43]
	v_mfma_f32_16x16x32_bf16 v[36:39], v[204:207], v[234:237], v[36:39]
	v_mfma_f32_16x16x32_bf16 v[32:35], v[208:211], v[234:237], v[32:35]
	s_waitcnt vmcnt(6)
	ds_write_b128 v152, v[144:147] offset:45056
	s_waitcnt lgkmcnt(7)
	v_mfma_f32_16x16x32_bf16 v[28:31], v[196:199], v[238:241], v[28:31]
	v_mfma_f32_16x16x32_bf16 v[24:27], v[200:203], v[238:241], v[24:27]
	v_mfma_f32_16x16x32_bf16 v[20:23], v[204:207], v[238:241], v[20:23]
	v_mfma_f32_16x16x32_bf16 v[16:19], v[208:211], v[238:241], v[16:19]
	s_waitcnt lgkmcnt(6)
	v_mfma_f32_16x16x32_bf16 v[12:15], v[196:199], v[242:245], v[12:15]
	v_mfma_f32_16x16x32_bf16 v[8:11], v[200:203], v[242:245], v[8:11]
	v_mfma_f32_16x16x32_bf16 v[4:7], v[204:207], v[242:245], v[4:7]
	v_mfma_f32_16x16x32_bf16 v[0:3], v[208:211], v[242:245], v[0:3]
	s_min_u32 s14, s36, 0x380
	s_lshl_b32 s14, s14, 1
	s_mov_b32 s39, s15
	s_add_i32 s38, s14, 0xc0
	v_lshl_add_u64 v[44:45], v[154:155], 0, s[14:15]
	v_lshl_add_u64 v[52:53], v[156:157], 0, s[14:15]
	v_lshl_add_u64 v[60:61], v[158:159], 0, s[38:39]
	v_lshl_add_u64 v[68:69], v[160:161], 0, s[38:39]
	v_lshl_add_u64 v[140:141], v[162:163], 0, s[38:39]
	v_lshl_add_u64 v[144:145], v[164:165], 0, s[38:39]
	s_waitcnt lgkmcnt(0)
	s_barrier
	global_load_dwordx4 v[44:47], v[44:45], off offset:192
	ds_read_b128 v[196:199], v166 offset:40960
	global_load_dwordx4 v[52:55], v[52:53], off offset:192
	ds_read_b128 v[200:203], v166 offset:41984
	global_load_dwordx4 v[60:63], v[60:61], off
	ds_read_b128 v[204:207], v166 offset:43008
	global_load_dwordx4 v[68:71], v[68:69], off
	ds_read_b128 v[208:211], v166 offset:44032
	global_load_dwordx4 v[140:143], v[140:141], off
	ds_read_b128 v[212:215], v168
	global_load_dwordx4 v[144:147], v[144:145], off
	ds_read_b128 v[216:219], v168 offset:1024
	ds_read_b128 v[222:225], v168 offset:2048
	ds_read_b128 v[226:229], v168 offset:3072
	ds_read_b128 v[230:233], v168 offset:4096
	ds_read_b128 v[234:237], v168 offset:5120
	ds_read_b128 v[238:241], v168 offset:6144
	ds_read_b128 v[242:245], v168 offset:7168
	s_waitcnt lgkmcnt(7)
	v_mfma_f32_16x16x32_bf16 v[148:151], v[196:199], v[212:215], v[148:151]
	v_mfma_f32_16x16x32_bf16 v[136:139], v[200:203], v[212:215], v[136:139]
	v_mfma_f32_16x16x32_bf16 v[132:135], v[204:207], v[212:215], v[132:135]
	v_mfma_f32_16x16x32_bf16 v[128:131], v[208:211], v[212:215], v[128:131]
	s_waitcnt vmcnt(11)
	ds_write_b128 v152, v[170:173]
	s_waitcnt lgkmcnt(7)
	v_mfma_f32_16x16x32_bf16 v[124:127], v[196:199], v[216:219], v[124:127]
	v_mfma_f32_16x16x32_bf16 v[120:123], v[200:203], v[216:219], v[120:123]
	v_mfma_f32_16x16x32_bf16 v[116:119], v[204:207], v[216:219], v[116:119]
	v_mfma_f32_16x16x32_bf16 v[112:115], v[208:211], v[216:219], v[112:115]
	s_waitcnt vmcnt(10)
	ds_write_b128 v152, v[174:177] offset:4096
	s_waitcnt lgkmcnt(7)
	v_mfma_f32_16x16x32_bf16 v[108:111], v[196:199], v[222:225], v[108:111]
	v_mfma_f32_16x16x32_bf16 v[104:107], v[200:203], v[222:225], v[104:107]
	v_mfma_f32_16x16x32_bf16 v[100:103], v[204:207], v[222:225], v[100:103]
	v_mfma_f32_16x16x32_bf16 v[96:99], v[208:211], v[222:225], v[96:99]
	s_waitcnt vmcnt(9)
	ds_write_b128 v152, v[178:181] offset:8192
	s_waitcnt lgkmcnt(7)
	v_mfma_f32_16x16x32_bf16 v[92:95], v[196:199], v[226:229], v[92:95]
	v_mfma_f32_16x16x32_bf16 v[88:91], v[200:203], v[226:229], v[88:91]
	v_mfma_f32_16x16x32_bf16 v[84:87], v[204:207], v[226:229], v[84:87]
	v_mfma_f32_16x16x32_bf16 v[80:83], v[208:211], v[226:229], v[80:83]
	s_waitcnt vmcnt(8)
	ds_write_b128 v152, v[182:185] offset:12288
	s_waitcnt lgkmcnt(7)
	v_mfma_f32_16x16x32_bf16 v[76:79], v[196:199], v[230:233], v[76:79]
	v_mfma_f32_16x16x32_bf16 v[72:75], v[200:203], v[230:233], v[72:75]
	v_mfma_f32_16x16x32_bf16 v[64:67], v[204:207], v[230:233], v[64:67]
	v_mfma_f32_16x16x32_bf16 v[56:59], v[208:211], v[230:233], v[56:59]
	s_waitcnt vmcnt(7)
	ds_write_b128 v152, v[186:189] offset:32768
	s_waitcnt lgkmcnt(7)
	v_mfma_f32_16x16x32_bf16 v[48:51], v[196:199], v[234:237], v[48:51]
	v_mfma_f32_16x16x32_bf16 v[40:43], v[200:203], v[234:237], v[40:43]
	v_mfma_f32_16x16x32_bf16 v[36:39], v[204:207], v[234:237], v[36:39]
	v_mfma_f32_16x16x32_bf16 v[32:35], v[208:211], v[234:237], v[32:35]
	s_waitcnt vmcnt(6)
	ds_write_b128 v152, v[190:193] offset:36864
	s_waitcnt lgkmcnt(7)
	v_mfma_f32_16x16x32_bf16 v[28:31], v[196:199], v[238:241], v[28:31]
	v_mfma_f32_16x16x32_bf16 v[24:27], v[200:203], v[238:241], v[24:27]
	v_mfma_f32_16x16x32_bf16 v[20:23], v[204:207], v[238:241], v[20:23]
	v_mfma_f32_16x16x32_bf16 v[16:19], v[208:211], v[238:241], v[16:19]
	s_waitcnt lgkmcnt(6)
	v_mfma_f32_16x16x32_bf16 v[12:15], v[196:199], v[242:245], v[12:15]
	v_mfma_f32_16x16x32_bf16 v[8:11], v[200:203], v[242:245], v[8:11]
	v_mfma_f32_16x16x32_bf16 v[4:7], v[204:207], v[242:245], v[4:7]
	v_mfma_f32_16x16x32_bf16 v[0:3], v[208:211], v[242:245], v[0:3]
	s_add_i32 s29, s29, 2
	s_cmp_lt_u32 s29, 30
	s_mov_b32 s36, s37
	s_waitcnt lgkmcnt(0)
	s_barrier
	s_cbranch_scc1 .LBB0_503
	s_waitcnt vmcnt(1)
	v_mov_b32_e32 v142, v220
	v_readlane_b32 s36, v254, 6
	v_and_b32_e32 v45, 0xffffff80, v142
	v_add_u32_e32 v143, s28, v45
	v_lshrrev_b32_e32 v45, 2, v142
	v_and_b32_e32 v44, 64, v142
	v_and_b32_e32 v45, 12, v45
	s_ashr_i32 s28, s33, 2
	v_or3_b32 v140, v44, v45, s35
	s_ashr_i32 s29, s28, 31
	v_ashrrev_i32_e32 v141, 31, v140
	v_readlane_b32 s44, v254, 14
	v_readlane_b32 s45, v254, 15
	s_waitcnt vmcnt(0)
	v_and_or_b32 v144, v142, 15, v143
	s_lshl_b64 s[28:29], s[28:29], 3
	v_lshl_add_u64 v[44:45], v[140:141], 2, s[44:45]
	s_add_u32 s28, s5, s28
	v_lshlrev_b64 v[140:141], 1, v[140:141]
	v_ashrrev_i32_e32 v145, 31, v144
	s_addc_u32 s29, s26, s29
	v_lshl_add_u64 v[142:143], s[70:71], 0, v[140:141]
	v_lshl_add_u64 v[146:147], v[144:145], 2, s[6:7]
	v_lshlrev_b64 v[154:155], 5, v[144:145]
	v_lshlrev_b64 v[190:191], 12, v[144:145]
	global_load_dwordx4 v[68:71], v[44:45], off
	global_load_dwordx4 v[60:63], v[44:45], off offset:64
	global_load_dwordx4 v[52:55], v[44:45], off offset:128
	s_nop 0
	global_load_dwordx4 v[44:47], v[44:45], off offset:192
	v_lshl_add_u64 v[154:155], s[28:29], 0, v[154:155]
	global_load_dword v202, v[146:147], off
	global_load_dwordx2 v[184:185], v[154:155], off
	v_lshl_add_u64 v[146:147], v[142:143], 0, v[190:191]
	global_load_dwordx2 v[196:197], v[146:147], off
	global_load_dwordx2 v[198:199], v[146:147], off offset:32
	global_load_dwordx2 v[200:201], v[146:147], off offset:64
	global_load_dwordx2 v[192:193], v[146:147], off offset:96
	v_or_b32_e32 v146, 16, v144
	v_ashrrev_i32_e32 v147, 31, v146
	v_lshlrev_b64 v[188:189], 12, v[146:147]
	v_lshl_add_u64 v[154:155], v[146:147], 2, s[6:7]
	v_lshlrev_b64 v[156:157], 5, v[146:147]
	v_lshl_add_u64 v[146:147], v[142:143], 0, v[188:189]
	v_lshl_add_u64 v[156:157], s[28:29], 0, v[156:157]
	global_load_dword v195, v[154:155], off
	global_load_dwordx2 v[172:173], v[156:157], off
	global_load_dwordx2 v[186:187], v[146:147], off
	global_load_dwordx2 v[182:183], v[146:147], off offset:32
	global_load_dwordx2 v[180:181], v[146:147], off offset:64
	global_load_dwordx2 v[178:179], v[146:147], off offset:96
	v_or_b32_e32 v146, 32, v144
	v_ashrrev_i32_e32 v147, 31, v146
	v_lshl_add_u64 v[154:155], v[146:147], 2, s[6:7]
	v_lshlrev_b64 v[156:157], 5, v[146:147]
	v_lshl_add_u64 v[156:157], s[28:29], 0, v[156:157]
	global_load_dword v152, v[154:155], off
	global_load_dwordx2 v[160:161], v[156:157], off
	v_or_b32_e32 v154, 48, v144
	v_lshlrev_b64 v[176:177], 12, v[146:147]
	v_ashrrev_i32_e32 v155, 31, v154
	v_lshl_add_u64 v[146:147], v[142:143], 0, v[176:177]
	v_lshlrev_b64 v[156:157], 5, v[154:155]
	v_lshlrev_b64 v[164:165], 12, v[154:155]
	global_load_dwordx2 v[174:175], v[146:147], off
	global_load_dwordx2 v[170:171], v[146:147], off offset:32
	global_load_dwordx2 v[168:169], v[146:147], off offset:64
	global_load_dwordx2 v[166:167], v[146:147], off offset:96
	v_lshl_add_u64 v[146:147], v[154:155], 2, s[6:7]
	v_lshl_add_u64 v[156:157], s[28:29], 0, v[156:157]
	v_lshl_add_u64 v[154:155], v[142:143], 0, v[164:165]
	global_load_dword v145, v[146:147], off
	s_nop 0
	global_load_dwordx2 v[146:147], v[156:157], off
	global_load_dwordx2 v[162:163], v[154:155], off
	global_load_dwordx2 v[158:159], v[154:155], off offset:32
	s_nop 0
	global_load_dwordx2 v[156:157], v[154:155], off offset:64
	s_nop 0
	global_load_dwordx2 v[154:155], v[154:155], off offset:96
	v_readlane_b32 s37, v254, 7
	v_readlane_b32 s38, v254, 8
	v_readlane_b32 s39, v254, 9
	v_readlane_b32 s40, v254, 10
	v_readlane_b32 s41, v254, 11
	v_readlane_b32 s42, v254, 12
	v_readlane_b32 s43, v254, 13
	v_readlane_b32 s46, v254, 16
	v_readlane_b32 s47, v254, 17
	v_readlane_b32 s48, v254, 18
	v_readlane_b32 s49, v254, 19
	v_readlane_b32 s50, v254, 20
	v_readlane_b32 s51, v254, 21
	v_lshl_add_u64 v[140:141], s[8:9], 0, v[140:141]
	s_waitcnt vmcnt(23)
	v_mul_f32_e32 v148, v148, v202
	v_mul_f32_e32 v205, 0xbfb8aa3b, v148
	v_exp_f32_e32 v205, v205
	v_mul_f32_e32 v149, v149, v202
	v_mul_f32_e32 v206, 0xbfb8aa3b, v149
	v_exp_f32_e32 v206, v206
	v_add_f32_e32 v205, 1.0, v205
	v_rcp_f32_e32 v205, v205
	s_waitcnt vmcnt(21)
	v_lshlrev_b32_e32 v203, 16, v196
	v_mul_f32_e32 v150, v150, v202
	v_sub_f32_e32 v203, v203, v184
	v_mul_f32_e32 v148, v148, v205
	v_add_f32_e32 v205, 1.0, v206
	v_rcp_f32_e32 v205, v205
	v_mul_f32_e32 v148, v148, v203
	v_mul_f32_e32 v203, 0xbfb8aa3b, v150
	v_exp_f32_e32 v203, v203
	v_and_b32_e32 v196, 0xffff0000, v196
	v_mul_f32_e32 v151, v151, v202
	v_mul_f32_e32 v149, v149, v205
	v_sub_f32_e32 v196, v196, v184
	v_mul_f32_e32 v149, v149, v196
	v_add_f32_e32 v196, 1.0, v203
	v_mul_f32_e32 v203, 0xbfb8aa3b, v151
	v_exp_f32_e32 v203, v203
	v_rcp_f32_e32 v196, v196
	v_lshlrev_b32_e32 v204, 16, v197
	v_and_b32_e32 v197, 0xffff0000, v197
	v_add_f32_e32 v203, 1.0, v203
	v_rcp_f32_e32 v203, v203
	v_mul_f32_e32 v150, v150, v196
	v_sub_f32_e32 v196, v204, v184
	v_mul_f32_e32 v150, v150, v196
	v_mul_f32_e32 v151, v151, v203
	v_sub_f32_e32 v196, v197, v184
	v_mul_f32_e32 v151, v151, v196
	v_mul_f32_e32 v148, v185, v148
	v_mul_f32_e32 v149, v185, v149
	v_mul_f32_e32 v151, v185, v151
	v_mul_f32_e32 v148, v68, v148
	v_mul_f32_e32 v149, v69, v149
	v_mul_f32_e32 v150, v185, v150
	v_mul_f32_e32 v151, v71, v151
	v_mul_f32_e32 v136, v136, v202
	v_mul_f32_e32 v150, v70, v150
	v_cvt_pk_bf16_f32 v148, v148, v149
	v_cvt_pk_bf16_f32 v149, v150, v151
	v_mul_f32_e32 v151, 0xbfb8aa3b, v136
	v_exp_f32_e32 v151, v151
	v_mul_f32_e32 v137, v137, v202
	v_mul_f32_e32 v197, 0xbfb8aa3b, v137
	v_exp_f32_e32 v197, v197
	v_add_f32_e32 v151, 1.0, v151
	v_rcp_f32_e32 v151, v151
	v_lshl_add_u64 v[190:191], v[140:141], 0, v[190:191]
	global_store_dwordx2 v[190:191], v[148:149], off
	s_waitcnt vmcnt(21)
	v_lshlrev_b32_e32 v148, 16, v198
	v_mul_f32_e32 v136, v136, v151
	v_add_f32_e32 v151, 1.0, v197
	v_rcp_f32_e32 v151, v151
	v_and_b32_e32 v149, 0xffff0000, v198
	v_mul_f32_e32 v138, v138, v202
	v_sub_f32_e32 v148, v148, v184
	v_mul_f32_e32 v139, v139, v202
	v_mul_f32_e32 v136, v136, v148
	v_mul_f32_e32 v137, v137, v151
	v_mul_f32_e32 v148, 0xbfb8aa3b, v138
	v_sub_f32_e32 v149, v149, v184
	v_exp_f32_e32 v148, v148
	v_mul_f32_e32 v137, v137, v149
	v_mul_f32_e32 v149, 0xbfb8aa3b, v139
	v_exp_f32_e32 v149, v149
	v_add_f32_e32 v148, 1.0, v148
	v_rcp_f32_e32 v148, v148
	v_lshlrev_b32_e32 v150, 16, v199
	v_add_f32_e32 v149, 1.0, v149
	v_rcp_f32_e32 v149, v149
	v_and_b32_e32 v196, 0xffff0000, v199
	v_mul_f32_e32 v138, v138, v148
	v_sub_f32_e32 v148, v150, v184
	v_mul_f32_e32 v138, v138, v148
	v_mul_f32_e32 v139, v139, v149
	v_sub_f32_e32 v148, v196, v184
	v_mul_f32_e32 v139, v139, v148
	v_mul_f32_e32 v136, v185, v136
	v_mul_f32_e32 v137, v185, v137
	v_mul_f32_e32 v139, v185, v139
	v_mul_f32_e32 v136, v60, v136
	v_mul_f32_e32 v137, v61, v137
	v_mul_f32_e32 v138, v185, v138
	v_mul_f32_e32 v139, v63, v139
	v_mul_f32_e32 v132, v132, v202
	v_mul_f32_e32 v138, v62, v138
	v_cvt_pk_bf16_f32 v136, v136, v137
	v_cvt_pk_bf16_f32 v137, v138, v139
	v_mul_f32_e32 v139, 0xbfb8aa3b, v132
	v_exp_f32_e32 v139, v139
	v_mul_f32_e32 v133, v133, v202
	v_mul_f32_e32 v149, 0xbfb8aa3b, v133
	v_exp_f32_e32 v149, v149
	v_add_f32_e32 v139, 1.0, v139
	v_rcp_f32_e32 v139, v139
	global_store_dwordx2 v[190:191], v[136:137], off offset:32
	s_waitcnt vmcnt(21)
	v_lshlrev_b32_e32 v136, 16, v200
	v_and_b32_e32 v137, 0xffff0000, v200
	v_mul_f32_e32 v132, v132, v139
	v_add_f32_e32 v139, 1.0, v149
	v_rcp_f32_e32 v139, v139
	v_mul_f32_e32 v134, v134, v202
	v_sub_f32_e32 v136, v136, v184
	v_mul_f32_e32 v135, v135, v202
	v_mul_f32_e32 v132, v132, v136
	v_mul_f32_e32 v133, v133, v139
	v_mul_f32_e32 v136, 0xbfb8aa3b, v134
	v_sub_f32_e32 v137, v137, v184
	v_exp_f32_e32 v136, v136
	v_mul_f32_e32 v133, v133, v137
	v_mul_f32_e32 v137, 0xbfb8aa3b, v135
	v_exp_f32_e32 v137, v137
	v_add_f32_e32 v136, 1.0, v136
	v_rcp_f32_e32 v136, v136
	v_lshlrev_b32_e32 v138, 16, v201
	v_add_f32_e32 v137, 1.0, v137
	v_rcp_f32_e32 v137, v137
	v_and_b32_e32 v148, 0xffff0000, v201
	v_mul_f32_e32 v134, v134, v136
	v_sub_f32_e32 v136, v138, v184
	v_mul_f32_e32 v134, v134, v136
	v_mul_f32_e32 v135, v135, v137
	v_sub_f32_e32 v136, v148, v184
	v_mul_f32_e32 v135, v135, v136
	v_mul_f32_e32 v132, v185, v132
	v_mul_f32_e32 v133, v185, v133
	v_mul_f32_e32 v135, v185, v135
	v_mul_f32_e32 v132, v52, v132
	v_mul_f32_e32 v133, v53, v133
	v_mul_f32_e32 v134, v185, v134
	v_mul_f32_e32 v135, v55, v135
	v_mul_f32_e32 v128, v128, v202
	v_mul_f32_e32 v134, v54, v134
	v_cvt_pk_bf16_f32 v132, v132, v133
	v_cvt_pk_bf16_f32 v133, v134, v135
	v_mul_f32_e32 v135, 0xbfb8aa3b, v128
	v_exp_f32_e32 v135, v135
	v_mul_f32_e32 v129, v129, v202
	v_mul_f32_e32 v137, 0xbfb8aa3b, v129
	v_exp_f32_e32 v137, v137
	v_add_f32_e32 v135, 1.0, v135
	v_rcp_f32_e32 v135, v135
	global_store_dwordx2 v[190:191], v[132:133], off offset:64
	s_waitcnt vmcnt(21)
	v_and_b32_e32 v133, 0xffff0000, v192
	v_mul_f32_e32 v131, v131, v202
	v_mul_f32_e32 v128, v128, v135
	v_add_f32_e32 v135, 1.0, v137
	v_rcp_f32_e32 v135, v135
	v_sub_f32_e32 v133, v133, v184
	v_lshlrev_b32_e32 v132, 16, v192
	v_mul_f32_e32 v130, v130, v202
	v_mul_f32_e32 v129, v129, v135
	v_mul_f32_e32 v129, v129, v133
	v_mul_f32_e32 v133, 0xbfb8aa3b, v131
	v_exp_f32_e32 v133, v133
	v_sub_f32_e32 v132, v132, v184
	v_mul_f32_e32 v128, v128, v132
	v_mul_f32_e32 v132, 0xbfb8aa3b, v130
	v_add_f32_e32 v133, 1.0, v133
	v_rcp_f32_e32 v133, v133
	s_waitcnt vmcnt(20)
	v_mul_f32_e32 v124, v124, v195
	v_exp_f32_e32 v132, v132
	v_mul_f32_e32 v125, v125, v195
	v_mul_f32_e32 v131, v131, v133
	v_mul_f32_e32 v133, 0xbfb8aa3b, v124
	v_exp_f32_e32 v133, v133
	v_add_f32_e32 v132, 1.0, v132
	v_rcp_f32_e32 v132, v132
	v_mul_f32_e32 v135, 0xbfb8aa3b, v125
	v_add_f32_e32 v133, 1.0, v133
	v_rcp_f32_e32 v133, v133
	v_exp_f32_e32 v135, v135
	v_lshlrev_b32_e32 v134, 16, v193
	v_and_b32_e32 v136, 0xffff0000, v193
	v_mul_f32_e32 v130, v130, v132
	v_sub_f32_e32 v132, v134, v184
	v_mul_f32_e32 v130, v130, v132
	v_sub_f32_e32 v132, v136, v184
	v_mul_f32_e32 v124, v124, v133
	v_add_f32_e32 v133, 1.0, v135
	v_mul_f32_e32 v128, v185, v128
	v_mul_f32_e32 v129, v185, v129
	v_mul_f32_e32 v130, v185, v130
	v_mul_f32_e32 v131, v131, v132
	v_rcp_f32_e32 v133, v133
	v_mul_f32_e32 v128, v44, v128
	v_mul_f32_e32 v129, v45, v129
	v_mul_f32_e32 v130, v46, v130
	v_mul_f32_e32 v131, v185, v131
	v_mul_f32_e32 v131, v47, v131
	v_cvt_pk_bf16_f32 v128, v128, v129
	v_cvt_pk_bf16_f32 v129, v130, v131
	s_waitcnt vmcnt(18)
	v_lshlrev_b32_e32 v130, 16, v186
	v_and_b32_e32 v131, 0xffff0000, v186
	v_mul_f32_e32 v126, v126, v195
	v_sub_f32_e32 v130, v130, v172
	v_mul_f32_e32 v127, v127, v195
	v_mul_f32_e32 v124, v124, v130
	v_mul_f32_e32 v125, v125, v133
	v_mul_f32_e32 v130, 0xbfb8aa3b, v126
	v_sub_f32_e32 v131, v131, v172
	v_exp_f32_e32 v130, v130
	v_mul_f32_e32 v125, v125, v131
	v_mul_f32_e32 v131, 0xbfb8aa3b, v127
	v_exp_f32_e32 v131, v131
	v_add_f32_e32 v130, 1.0, v130
	v_rcp_f32_e32 v130, v130
	v_lshlrev_b32_e32 v132, 16, v187
	v_add_f32_e32 v131, 1.0, v131
	v_rcp_f32_e32 v131, v131
	v_and_b32_e32 v134, 0xffff0000, v187
	v_mul_f32_e32 v126, v126, v130
	v_sub_f32_e32 v130, v132, v172
	v_mul_f32_e32 v126, v126, v130
	v_mul_f32_e32 v127, v127, v131
	v_sub_f32_e32 v130, v134, v172
	v_mul_f32_e32 v127, v127, v130
	v_mul_f32_e32 v124, v173, v124
	v_mul_f32_e32 v125, v173, v125
	v_mul_f32_e32 v127, v173, v127
	v_mul_f32_e32 v124, v68, v124
	v_mul_f32_e32 v125, v69, v125
	v_mul_f32_e32 v126, v173, v126
	v_mul_f32_e32 v127, v71, v127
	v_mul_f32_e32 v120, v120, v195
	v_mul_f32_e32 v126, v70, v126
	v_cvt_pk_bf16_f32 v124, v124, v125
	v_cvt_pk_bf16_f32 v125, v126, v127
	v_mul_f32_e32 v127, 0xbfb8aa3b, v120
	v_exp_f32_e32 v127, v127
	v_mul_f32_e32 v121, v121, v195
	v_mul_f32_e32 v131, 0xbfb8aa3b, v121
	v_exp_f32_e32 v131, v131
	v_add_f32_e32 v127, 1.0, v127
	v_rcp_f32_e32 v127, v127
	global_store_dwordx2 v[190:191], v[128:129], off offset:96
	v_lshl_add_u64 v[128:129], v[140:141], 0, v[188:189]
	global_store_dwordx2 v[128:129], v[124:125], off
	v_mul_f32_e32 v120, v120, v127
	v_add_f32_e32 v127, 1.0, v131
	v_rcp_f32_e32 v127, v127
	s_waitcnt vmcnt(19)
	v_lshlrev_b32_e32 v124, 16, v182
	v_and_b32_e32 v125, 0xffff0000, v182
	v_mul_f32_e32 v122, v122, v195
	v_sub_f32_e32 v124, v124, v172
	v_mul_f32_e32 v123, v123, v195
	v_mul_f32_e32 v120, v120, v124
	v_mul_f32_e32 v121, v121, v127
	v_mul_f32_e32 v124, 0xbfb8aa3b, v122
	v_sub_f32_e32 v125, v125, v172
	v_exp_f32_e32 v124, v124
	v_mul_f32_e32 v121, v121, v125
	v_mul_f32_e32 v125, 0xbfb8aa3b, v123
	v_exp_f32_e32 v125, v125
	v_add_f32_e32 v124, 1.0, v124
	v_rcp_f32_e32 v124, v124
	v_lshlrev_b32_e32 v126, 16, v183
	v_add_f32_e32 v125, 1.0, v125
	v_rcp_f32_e32 v125, v125
	v_and_b32_e32 v130, 0xffff0000, v183
	v_mul_f32_e32 v122, v122, v124
	v_sub_f32_e32 v124, v126, v172
	v_mul_f32_e32 v122, v122, v124
	v_mul_f32_e32 v123, v123, v125
	v_sub_f32_e32 v124, v130, v172
	v_mul_f32_e32 v123, v123, v124
	v_mul_f32_e32 v120, v173, v120
	v_mul_f32_e32 v121, v173, v121
	v_mul_f32_e32 v123, v173, v123
	v_mul_f32_e32 v120, v60, v120
	v_mul_f32_e32 v121, v61, v121
	v_mul_f32_e32 v122, v173, v122
	v_mul_f32_e32 v123, v63, v123
	v_mul_f32_e32 v116, v116, v195
	v_mul_f32_e32 v122, v62, v122
	v_cvt_pk_bf16_f32 v120, v120, v121
	v_cvt_pk_bf16_f32 v121, v122, v123
	v_mul_f32_e32 v123, 0xbfb8aa3b, v116
	v_exp_f32_e32 v123, v123
	v_mul_f32_e32 v117, v117, v195
	v_mul_f32_e32 v125, 0xbfb8aa3b, v117
	v_exp_f32_e32 v125, v125
	v_add_f32_e32 v123, 1.0, v123
	v_rcp_f32_e32 v123, v123
	global_store_dwordx2 v[128:129], v[120:121], off offset:32
	s_waitcnt vmcnt(19)
	v_lshlrev_b32_e32 v120, 16, v180
	v_and_b32_e32 v121, 0xffff0000, v180
	v_mul_f32_e32 v116, v116, v123
	v_add_f32_e32 v123, 1.0, v125
	v_rcp_f32_e32 v123, v123
	v_mul_f32_e32 v118, v118, v195
	v_sub_f32_e32 v120, v120, v172
	v_mul_f32_e32 v119, v119, v195
	v_mul_f32_e32 v116, v116, v120
	v_mul_f32_e32 v117, v117, v123
	v_mul_f32_e32 v120, 0xbfb8aa3b, v118
	v_sub_f32_e32 v121, v121, v172
	v_exp_f32_e32 v120, v120
	v_mul_f32_e32 v117, v117, v121
	v_mul_f32_e32 v121, 0xbfb8aa3b, v119
	v_exp_f32_e32 v121, v121
	v_add_f32_e32 v120, 1.0, v120
	v_rcp_f32_e32 v120, v120
	v_lshlrev_b32_e32 v122, 16, v181
	v_add_f32_e32 v121, 1.0, v121
	v_rcp_f32_e32 v121, v121
	v_and_b32_e32 v124, 0xffff0000, v181
	v_mul_f32_e32 v118, v118, v120
	v_sub_f32_e32 v120, v122, v172
	v_mul_f32_e32 v118, v118, v120
	v_mul_f32_e32 v119, v119, v121
	v_sub_f32_e32 v120, v124, v172
	v_mul_f32_e32 v119, v119, v120
	v_mul_f32_e32 v116, v173, v116
	v_mul_f32_e32 v117, v173, v117
	v_mul_f32_e32 v119, v173, v119
	v_mul_f32_e32 v116, v52, v116
	v_mul_f32_e32 v117, v53, v117
	v_mul_f32_e32 v118, v173, v118
	v_mul_f32_e32 v119, v55, v119
	v_mul_f32_e32 v112, v112, v195
	v_mul_f32_e32 v118, v54, v118
	v_cvt_pk_bf16_f32 v116, v116, v117
	v_cvt_pk_bf16_f32 v117, v118, v119
	v_mul_f32_e32 v119, 0xbfb8aa3b, v112
	v_exp_f32_e32 v119, v119
	v_mul_f32_e32 v113, v113, v195
	v_mul_f32_e32 v121, 0xbfb8aa3b, v113
	v_exp_f32_e32 v121, v121
	v_add_f32_e32 v119, 1.0, v119
	v_rcp_f32_e32 v119, v119
	global_store_dwordx2 v[128:129], v[116:117], off offset:64
	s_waitcnt vmcnt(19)
	v_and_b32_e32 v117, 0xffff0000, v178
	v_mul_f32_e32 v115, v115, v195
	v_mul_f32_e32 v112, v112, v119
	v_add_f32_e32 v119, 1.0, v121
	v_rcp_f32_e32 v119, v119
	v_sub_f32_e32 v117, v117, v172
	v_lshlrev_b32_e32 v116, 16, v178
	v_mul_f32_e32 v114, v114, v195
	v_mul_f32_e32 v113, v113, v119
	v_mul_f32_e32 v113, v113, v117
	v_mul_f32_e32 v117, 0xbfb8aa3b, v115
	v_exp_f32_e32 v117, v117
	v_sub_f32_e32 v116, v116, v172
	v_mul_f32_e32 v112, v112, v116
	v_mul_f32_e32 v116, 0xbfb8aa3b, v114
	v_add_f32_e32 v117, 1.0, v117
	v_rcp_f32_e32 v117, v117
	s_waitcnt vmcnt(18)
	v_mul_f32_e32 v108, v108, v152
	v_exp_f32_e32 v116, v116
	v_mul_f32_e32 v109, v109, v152
	v_mul_f32_e32 v115, v115, v117
	v_mul_f32_e32 v117, 0xbfb8aa3b, v108
	v_exp_f32_e32 v117, v117
	v_add_f32_e32 v116, 1.0, v116
	v_rcp_f32_e32 v116, v116
	v_mul_f32_e32 v119, 0xbfb8aa3b, v109
	v_add_f32_e32 v117, 1.0, v117
	v_rcp_f32_e32 v117, v117
	v_exp_f32_e32 v119, v119
	v_lshlrev_b32_e32 v118, 16, v179
	v_and_b32_e32 v120, 0xffff0000, v179
	v_mul_f32_e32 v114, v114, v116
	v_sub_f32_e32 v116, v118, v172
	v_mul_f32_e32 v114, v114, v116
	v_sub_f32_e32 v116, v120, v172
	v_mul_f32_e32 v108, v108, v117
	v_add_f32_e32 v117, 1.0, v119
	v_mul_f32_e32 v112, v173, v112
	v_mul_f32_e32 v113, v173, v113
	v_mul_f32_e32 v114, v173, v114
	v_mul_f32_e32 v115, v115, v116
	v_rcp_f32_e32 v117, v117
	v_mul_f32_e32 v112, v44, v112
	v_mul_f32_e32 v113, v45, v113
	v_mul_f32_e32 v114, v46, v114
	v_mul_f32_e32 v115, v173, v115
	v_mul_f32_e32 v115, v47, v115
	v_cvt_pk_bf16_f32 v112, v112, v113
	v_cvt_pk_bf16_f32 v113, v114, v115
	s_waitcnt vmcnt(16)
	v_lshlrev_b32_e32 v114, 16, v174
	v_and_b32_e32 v115, 0xffff0000, v174
	v_mul_f32_e32 v110, v110, v152
	v_sub_f32_e32 v114, v114, v160
	v_mul_f32_e32 v111, v111, v152
	v_mul_f32_e32 v108, v108, v114
	v_mul_f32_e32 v109, v109, v117
	v_mul_f32_e32 v114, 0xbfb8aa3b, v110
	v_sub_f32_e32 v115, v115, v160
	v_exp_f32_e32 v114, v114
	v_mul_f32_e32 v109, v109, v115
	v_mul_f32_e32 v115, 0xbfb8aa3b, v111
	v_exp_f32_e32 v115, v115
	v_add_f32_e32 v114, 1.0, v114
	v_rcp_f32_e32 v114, v114
	v_lshlrev_b32_e32 v116, 16, v175
	v_add_f32_e32 v115, 1.0, v115
	v_rcp_f32_e32 v115, v115
	v_and_b32_e32 v118, 0xffff0000, v175
	v_mul_f32_e32 v110, v110, v114
	v_sub_f32_e32 v114, v116, v160
	v_mul_f32_e32 v110, v110, v114
	v_mul_f32_e32 v111, v111, v115
	v_sub_f32_e32 v114, v118, v160
	v_mul_f32_e32 v111, v111, v114
	v_mul_f32_e32 v108, v161, v108
	v_mul_f32_e32 v109, v161, v109
	v_mul_f32_e32 v111, v161, v111
	v_mul_f32_e32 v108, v68, v108
	v_mul_f32_e32 v109, v69, v109
	v_mul_f32_e32 v110, v161, v110
	v_mul_f32_e32 v111, v71, v111
	v_mul_f32_e32 v104, v104, v152
	v_mul_f32_e32 v110, v70, v110
	v_cvt_pk_bf16_f32 v108, v108, v109
	v_cvt_pk_bf16_f32 v109, v110, v111
	v_mul_f32_e32 v111, 0xbfb8aa3b, v104
	v_exp_f32_e32 v111, v111
	v_mul_f32_e32 v105, v105, v152
	v_mul_f32_e32 v115, 0xbfb8aa3b, v105
	v_exp_f32_e32 v115, v115
	v_add_f32_e32 v111, 1.0, v111
	v_rcp_f32_e32 v111, v111
	global_store_dwordx2 v[128:129], v[112:113], off offset:96
	v_lshl_add_u64 v[112:113], v[140:141], 0, v[176:177]
	global_store_dwordx2 v[112:113], v[108:109], off
	v_mul_f32_e32 v104, v104, v111
	v_add_f32_e32 v111, 1.0, v115
	v_rcp_f32_e32 v111, v111
	s_waitcnt vmcnt(17)
	v_lshlrev_b32_e32 v108, 16, v170
	v_and_b32_e32 v109, 0xffff0000, v170
	v_mul_f32_e32 v106, v106, v152
	v_sub_f32_e32 v108, v108, v160
	v_mul_f32_e32 v107, v107, v152
	v_mul_f32_e32 v104, v104, v108
	v_mul_f32_e32 v105, v105, v111
	v_mul_f32_e32 v108, 0xbfb8aa3b, v106
	v_sub_f32_e32 v109, v109, v160
	v_exp_f32_e32 v108, v108
	v_mul_f32_e32 v105, v105, v109
	v_mul_f32_e32 v109, 0xbfb8aa3b, v107
	v_exp_f32_e32 v109, v109
	v_add_f32_e32 v108, 1.0, v108
	v_rcp_f32_e32 v108, v108
	v_lshlrev_b32_e32 v110, 16, v171
	v_add_f32_e32 v109, 1.0, v109
	v_rcp_f32_e32 v109, v109
	v_and_b32_e32 v114, 0xffff0000, v171
	v_mul_f32_e32 v106, v106, v108
	v_sub_f32_e32 v108, v110, v160
	v_mul_f32_e32 v106, v106, v108
	v_mul_f32_e32 v107, v107, v109
	v_sub_f32_e32 v108, v114, v160
	v_mul_f32_e32 v107, v107, v108
	v_mul_f32_e32 v104, v161, v104
	v_mul_f32_e32 v105, v161, v105
	v_mul_f32_e32 v107, v161, v107
	v_mul_f32_e32 v104, v60, v104
	v_mul_f32_e32 v105, v61, v105
	v_mul_f32_e32 v106, v161, v106
	v_mul_f32_e32 v107, v63, v107
	v_mul_f32_e32 v100, v100, v152
	v_mul_f32_e32 v106, v62, v106
	v_cvt_pk_bf16_f32 v104, v104, v105
	v_cvt_pk_bf16_f32 v105, v106, v107
	v_mul_f32_e32 v107, 0xbfb8aa3b, v100
	v_exp_f32_e32 v107, v107
	v_mul_f32_e32 v101, v101, v152
	v_mul_f32_e32 v109, 0xbfb8aa3b, v101
	v_exp_f32_e32 v109, v109
	v_add_f32_e32 v107, 1.0, v107
	v_rcp_f32_e32 v107, v107
	global_store_dwordx2 v[112:113], v[104:105], off offset:32
	s_waitcnt vmcnt(17)
	v_lshlrev_b32_e32 v104, 16, v168
	v_and_b32_e32 v105, 0xffff0000, v168
	v_mul_f32_e32 v100, v100, v107
	v_add_f32_e32 v107, 1.0, v109
	v_rcp_f32_e32 v107, v107
	v_mul_f32_e32 v102, v102, v152
	v_sub_f32_e32 v104, v104, v160
	v_mul_f32_e32 v103, v103, v152
	v_mul_f32_e32 v100, v100, v104
	v_mul_f32_e32 v101, v101, v107
	v_mul_f32_e32 v104, 0xbfb8aa3b, v102
	v_sub_f32_e32 v105, v105, v160
	v_exp_f32_e32 v104, v104
	v_mul_f32_e32 v101, v101, v105
	v_mul_f32_e32 v105, 0xbfb8aa3b, v103
	v_exp_f32_e32 v105, v105
	v_add_f32_e32 v104, 1.0, v104
	v_rcp_f32_e32 v104, v104
	v_lshlrev_b32_e32 v106, 16, v169
	v_add_f32_e32 v105, 1.0, v105
	v_rcp_f32_e32 v105, v105
	v_and_b32_e32 v108, 0xffff0000, v169
	v_mul_f32_e32 v102, v102, v104
	v_sub_f32_e32 v104, v106, v160
	v_mul_f32_e32 v102, v102, v104
	v_mul_f32_e32 v103, v103, v105
	v_sub_f32_e32 v104, v108, v160
	v_mul_f32_e32 v103, v103, v104
	v_mul_f32_e32 v100, v161, v100
	v_mul_f32_e32 v101, v161, v101
	v_mul_f32_e32 v103, v161, v103
	v_mul_f32_e32 v100, v52, v100
	v_mul_f32_e32 v101, v53, v101
	v_mul_f32_e32 v102, v161, v102
	v_mul_f32_e32 v103, v55, v103
	v_mul_f32_e32 v96, v96, v152
	v_mul_f32_e32 v102, v54, v102
	v_cvt_pk_bf16_f32 v100, v100, v101
	v_cvt_pk_bf16_f32 v101, v102, v103
	v_mul_f32_e32 v103, 0xbfb8aa3b, v96
	v_exp_f32_e32 v103, v103
	v_mul_f32_e32 v97, v97, v152
	v_mul_f32_e32 v105, 0xbfb8aa3b, v97
	v_exp_f32_e32 v105, v105
	v_add_f32_e32 v103, 1.0, v103
	v_rcp_f32_e32 v103, v103
	global_store_dwordx2 v[112:113], v[100:101], off offset:64
	s_waitcnt vmcnt(17)
	v_and_b32_e32 v101, 0xffff0000, v166
	v_mul_f32_e32 v99, v99, v152
	v_mul_f32_e32 v96, v96, v103
	v_add_f32_e32 v103, 1.0, v105
	v_rcp_f32_e32 v103, v103
	v_sub_f32_e32 v101, v101, v160
	v_lshlrev_b32_e32 v100, 16, v166
	v_mul_f32_e32 v98, v98, v152
	v_mul_f32_e32 v97, v97, v103
	v_mul_f32_e32 v97, v97, v101
	v_mul_f32_e32 v101, 0xbfb8aa3b, v99
	v_exp_f32_e32 v101, v101
	v_sub_f32_e32 v100, v100, v160
	v_mul_f32_e32 v96, v96, v100
	v_mul_f32_e32 v100, 0xbfb8aa3b, v98
	v_add_f32_e32 v101, 1.0, v101
	v_rcp_f32_e32 v101, v101
	s_waitcnt vmcnt(16)
	v_mul_f32_e32 v92, v92, v145
	v_exp_f32_e32 v100, v100
	v_mul_f32_e32 v93, v93, v145
	v_mul_f32_e32 v99, v99, v101
	v_mul_f32_e32 v101, 0xbfb8aa3b, v92
	v_exp_f32_e32 v101, v101
	v_add_f32_e32 v100, 1.0, v100
	v_rcp_f32_e32 v100, v100
	v_mul_f32_e32 v103, 0xbfb8aa3b, v93
	v_add_f32_e32 v101, 1.0, v101
	v_rcp_f32_e32 v101, v101
	v_exp_f32_e32 v103, v103
	v_lshlrev_b32_e32 v102, 16, v167
	v_and_b32_e32 v104, 0xffff0000, v167
	v_mul_f32_e32 v98, v98, v100
	v_sub_f32_e32 v100, v102, v160
	v_mul_f32_e32 v98, v98, v100
	v_sub_f32_e32 v100, v104, v160
	v_mul_f32_e32 v92, v92, v101
	v_add_f32_e32 v101, 1.0, v103
	v_mul_f32_e32 v96, v161, v96
	v_mul_f32_e32 v97, v161, v97
	v_mul_f32_e32 v98, v161, v98
	v_mul_f32_e32 v99, v99, v100
	v_rcp_f32_e32 v101, v101
	v_mul_f32_e32 v96, v44, v96
	v_mul_f32_e32 v97, v45, v97
	v_mul_f32_e32 v98, v46, v98
	v_mul_f32_e32 v99, v161, v99
	v_mul_f32_e32 v99, v47, v99
	v_cvt_pk_bf16_f32 v96, v96, v97
	v_cvt_pk_bf16_f32 v97, v98, v99
	s_waitcnt vmcnt(14)
	v_lshlrev_b32_e32 v98, 16, v162
	v_and_b32_e32 v99, 0xffff0000, v162
	v_mul_f32_e32 v94, v94, v145
	v_sub_f32_e32 v98, v98, v146
	v_mul_f32_e32 v95, v95, v145
	v_mul_f32_e32 v92, v92, v98
	v_mul_f32_e32 v93, v93, v101
	v_mul_f32_e32 v98, 0xbfb8aa3b, v94
	v_sub_f32_e32 v99, v99, v146
	v_exp_f32_e32 v98, v98
	v_mul_f32_e32 v93, v93, v99
	v_mul_f32_e32 v99, 0xbfb8aa3b, v95
	v_exp_f32_e32 v99, v99
	v_add_f32_e32 v98, 1.0, v98
	v_rcp_f32_e32 v98, v98
	v_lshlrev_b32_e32 v100, 16, v163
	v_add_f32_e32 v99, 1.0, v99
	v_rcp_f32_e32 v99, v99
	v_and_b32_e32 v102, 0xffff0000, v163
	v_mul_f32_e32 v94, v94, v98
	v_sub_f32_e32 v98, v100, v146
	v_mul_f32_e32 v94, v94, v98
	v_mul_f32_e32 v95, v95, v99
	v_sub_f32_e32 v98, v102, v146
	v_mul_f32_e32 v95, v95, v98
	v_mul_f32_e32 v92, v147, v92
	v_mul_f32_e32 v93, v147, v93
	v_mul_f32_e32 v95, v147, v95
	v_mul_f32_e32 v92, v68, v92
	v_mul_f32_e32 v93, v69, v93
	v_mul_f32_e32 v94, v147, v94
	v_mul_f32_e32 v95, v71, v95
	v_mul_f32_e32 v88, v88, v145
	v_mul_f32_e32 v94, v70, v94
	v_cvt_pk_bf16_f32 v92, v92, v93
	v_cvt_pk_bf16_f32 v93, v94, v95
	v_mul_f32_e32 v95, 0xbfb8aa3b, v88
	v_exp_f32_e32 v95, v95
	v_mul_f32_e32 v89, v89, v145
	v_mul_f32_e32 v99, 0xbfb8aa3b, v89
	v_exp_f32_e32 v99, v99
	v_add_f32_e32 v95, 1.0, v95
	v_rcp_f32_e32 v95, v95
	global_store_dwordx2 v[112:113], v[96:97], off offset:96
	v_lshl_add_u64 v[96:97], v[140:141], 0, v[164:165]
	global_store_dwordx2 v[96:97], v[92:93], off
	v_mul_f32_e32 v88, v88, v95
	v_add_f32_e32 v95, 1.0, v99
	v_rcp_f32_e32 v95, v95
	s_waitcnt vmcnt(15)
	v_lshlrev_b32_e32 v92, 16, v158
	v_and_b32_e32 v93, 0xffff0000, v158
	v_mul_f32_e32 v90, v90, v145
	v_sub_f32_e32 v92, v92, v146
	v_mul_f32_e32 v91, v91, v145
	v_mul_f32_e32 v88, v88, v92
	v_mul_f32_e32 v89, v89, v95
	v_mul_f32_e32 v92, 0xbfb8aa3b, v90
	v_sub_f32_e32 v93, v93, v146
	v_exp_f32_e32 v92, v92
	v_mul_f32_e32 v89, v89, v93
	v_mul_f32_e32 v93, 0xbfb8aa3b, v91
	v_exp_f32_e32 v93, v93
	v_add_f32_e32 v92, 1.0, v92
	v_rcp_f32_e32 v92, v92
	v_lshlrev_b32_e32 v94, 16, v159
	v_add_f32_e32 v93, 1.0, v93
	v_rcp_f32_e32 v93, v93
	v_and_b32_e32 v98, 0xffff0000, v159
	v_mul_f32_e32 v90, v90, v92
	v_sub_f32_e32 v92, v94, v146
	v_mul_f32_e32 v90, v90, v92
	v_mul_f32_e32 v91, v91, v93
	v_sub_f32_e32 v92, v98, v146
	v_mul_f32_e32 v91, v91, v92
	v_mul_f32_e32 v88, v147, v88
	v_mul_f32_e32 v89, v147, v89
	v_mul_f32_e32 v91, v147, v91
	v_mul_f32_e32 v88, v60, v88
	v_mul_f32_e32 v89, v61, v89
	v_mul_f32_e32 v90, v147, v90
	v_mul_f32_e32 v91, v63, v91
	v_mul_f32_e32 v84, v84, v145
	v_mul_f32_e32 v90, v62, v90
	v_cvt_pk_bf16_f32 v88, v88, v89
	v_cvt_pk_bf16_f32 v89, v90, v91
	v_mul_f32_e32 v91, 0xbfb8aa3b, v84
	v_exp_f32_e32 v91, v91
	v_mul_f32_e32 v85, v85, v145
	v_mul_f32_e32 v93, 0xbfb8aa3b, v85
	v_exp_f32_e32 v93, v93
	v_add_f32_e32 v91, 1.0, v91
	v_rcp_f32_e32 v91, v91
	global_store_dwordx2 v[96:97], v[88:89], off offset:32
	s_waitcnt vmcnt(15)
	v_lshlrev_b32_e32 v88, 16, v156
	v_and_b32_e32 v89, 0xffff0000, v156
	v_mul_f32_e32 v84, v84, v91
	v_add_f32_e32 v91, 1.0, v93
	v_rcp_f32_e32 v91, v91
	v_mul_f32_e32 v86, v86, v145
	v_sub_f32_e32 v88, v88, v146
	v_mul_f32_e32 v87, v87, v145
	v_mul_f32_e32 v84, v84, v88
	v_mul_f32_e32 v85, v85, v91
	v_mul_f32_e32 v88, 0xbfb8aa3b, v86
	v_sub_f32_e32 v89, v89, v146
	v_exp_f32_e32 v88, v88
	v_mul_f32_e32 v85, v85, v89
	v_mul_f32_e32 v89, 0xbfb8aa3b, v87
	v_exp_f32_e32 v89, v89
	v_add_f32_e32 v88, 1.0, v88
	v_rcp_f32_e32 v88, v88
	v_lshlrev_b32_e32 v90, 16, v157
	v_add_f32_e32 v89, 1.0, v89
	v_rcp_f32_e32 v89, v89
	v_and_b32_e32 v92, 0xffff0000, v157
	v_mul_f32_e32 v86, v86, v88
	v_sub_f32_e32 v88, v90, v146
	v_mul_f32_e32 v86, v86, v88
	v_mul_f32_e32 v87, v87, v89
	v_sub_f32_e32 v88, v92, v146
	v_mul_f32_e32 v87, v87, v88
	v_mul_f32_e32 v84, v147, v84
	v_mul_f32_e32 v85, v147, v85
	v_mul_f32_e32 v87, v147, v87
	v_mul_f32_e32 v84, v52, v84
	v_mul_f32_e32 v85, v53, v85
	v_mul_f32_e32 v86, v147, v86
	v_mul_f32_e32 v87, v55, v87
	v_mul_f32_e32 v80, v80, v145
	v_mul_f32_e32 v86, v54, v86
	v_cvt_pk_bf16_f32 v84, v84, v85
	v_cvt_pk_bf16_f32 v85, v86, v87
	v_mul_f32_e32 v87, 0xbfb8aa3b, v80
	v_exp_f32_e32 v87, v87
	v_mul_f32_e32 v81, v81, v145
	v_mul_f32_e32 v89, 0xbfb8aa3b, v81
	v_exp_f32_e32 v89, v89
	v_add_f32_e32 v87, 1.0, v87
	v_rcp_f32_e32 v87, v87
	global_store_dwordx2 v[96:97], v[84:85], off offset:64
	s_waitcnt vmcnt(15)
	v_lshlrev_b32_e32 v84, 16, v154
	v_and_b32_e32 v85, 0xffff0000, v154
	v_mul_f32_e32 v80, v80, v87
	v_add_f32_e32 v87, 1.0, v89
	v_rcp_f32_e32 v87, v87
	v_mul_f32_e32 v82, v82, v145
	v_sub_f32_e32 v84, v84, v146
	v_mul_f32_e32 v83, v83, v145
	v_mul_f32_e32 v80, v80, v84
	v_mul_f32_e32 v81, v81, v87
	v_mul_f32_e32 v84, 0xbfb8aa3b, v82
	v_sub_f32_e32 v85, v85, v146
	v_exp_f32_e32 v84, v84
	v_mul_f32_e32 v81, v81, v85
	v_mul_f32_e32 v85, 0xbfb8aa3b, v83
	v_exp_f32_e32 v85, v85
	v_add_f32_e32 v84, 1.0, v84
	v_rcp_f32_e32 v84, v84
	v_lshlrev_b32_e32 v86, 16, v155
	v_add_f32_e32 v85, 1.0, v85
	v_rcp_f32_e32 v85, v85
	v_and_b32_e32 v88, 0xffff0000, v155
	v_mul_f32_e32 v82, v82, v84
	v_sub_f32_e32 v84, v86, v146
	v_mul_f32_e32 v82, v82, v84
	v_mul_f32_e32 v83, v83, v85
	v_sub_f32_e32 v84, v88, v146
	v_mul_f32_e32 v80, v147, v80
	v_mul_f32_e32 v81, v147, v81
	v_mul_f32_e32 v83, v83, v84
	v_mul_f32_e32 v80, v44, v80
	v_mul_f32_e32 v81, v45, v81
	v_mul_f32_e32 v82, v147, v82
	v_mul_f32_e32 v83, v147, v83
	v_mul_f32_e32 v82, v46, v82
	v_mul_f32_e32 v83, v47, v83
	v_cvt_pk_bf16_f32 v80, v80, v81
	v_cvt_pk_bf16_f32 v81, v82, v83
	global_store_dwordx2 v[96:97], v[80:81], off offset:96
	v_or_b32_e32 v80, 64, v144
	v_ashrrev_i32_e32 v81, 31, v80
	v_lshlrev_b64 v[118:119], 12, v[80:81]
	v_lshl_add_u64 v[82:83], v[80:81], 2, s[6:7]
	v_lshlrev_b64 v[84:85], 5, v[80:81]
	v_lshl_add_u64 v[80:81], v[142:143], 0, v[118:119]
	v_lshl_add_u64 v[84:85], s[28:29], 0, v[84:85]
	global_load_dword v125, v[82:83], off
	global_load_dwordx2 v[112:113], v[84:85], off
	global_load_dwordx2 v[126:127], v[80:81], off
	global_load_dwordx2 v[128:129], v[80:81], off offset:32
	global_load_dwordx2 v[130:131], v[80:81], off offset:64
	global_load_dwordx2 v[120:121], v[80:81], off offset:96
	v_or_b32_e32 v80, 0x50, v144
	v_ashrrev_i32_e32 v81, 31, v80
	v_lshlrev_b64 v[116:117], 12, v[80:81]
	v_lshl_add_u64 v[82:83], v[80:81], 2, s[6:7]
	v_lshlrev_b64 v[84:85], 5, v[80:81]
	v_lshl_add_u64 v[80:81], v[142:143], 0, v[116:117]
	v_lshl_add_u64 v[84:85], s[28:29], 0, v[84:85]
	global_load_dword v124, v[82:83], off
	global_load_dwordx2 v[100:101], v[84:85], off
	global_load_dwordx2 v[114:115], v[80:81], off
	global_load_dwordx2 v[110:111], v[80:81], off offset:32
	global_load_dwordx2 v[108:109], v[80:81], off offset:64
	global_load_dwordx2 v[106:107], v[80:81], off offset:96
	v_or_b32_e32 v80, 0x60, v144
	v_ashrrev_i32_e32 v81, 31, v80
	v_lshl_add_u64 v[82:83], v[80:81], 2, s[6:7]
	v_lshlrev_b64 v[84:85], 5, v[80:81]
	v_lshl_add_u64 v[84:85], s[28:29], 0, v[84:85]
	global_load_dword v123, v[82:83], off
	global_load_dwordx2 v[88:89], v[84:85], off
	v_or_b32_e32 v82, 0x70, v144
	v_lshlrev_b64 v[104:105], 12, v[80:81]
	v_ashrrev_i32_e32 v83, 31, v82
	v_lshl_add_u64 v[80:81], v[142:143], 0, v[104:105]
	v_lshlrev_b64 v[84:85], 5, v[82:83]
	v_lshlrev_b64 v[92:93], 12, v[82:83]
	global_load_dwordx2 v[102:103], v[80:81], off
	global_load_dwordx2 v[98:99], v[80:81], off offset:32
	global_load_dwordx2 v[96:97], v[80:81], off offset:64
	global_load_dwordx2 v[94:95], v[80:81], off offset:96
	v_lshl_add_u64 v[80:81], v[82:83], 2, s[6:7]
	v_lshl_add_u64 v[84:85], s[28:29], 0, v[84:85]
	v_lshl_add_u64 v[82:83], v[142:143], 0, v[92:93]
	global_load_dword v122, v[80:81], off
	s_nop 0
	global_load_dwordx2 v[80:81], v[84:85], off
	global_load_dwordx2 v[90:91], v[82:83], off
	global_load_dwordx2 v[86:87], v[82:83], off offset:32
	s_nop 0
	global_load_dwordx2 v[84:85], v[82:83], off offset:64
	s_nop 0
	global_load_dwordx2 v[82:83], v[82:83], off offset:96
	s_waitcnt vmcnt(23)
	v_mul_f32_e32 v76, v76, v125
	v_mul_f32_e32 v134, 0xbfb8aa3b, v76
	v_exp_f32_e32 v134, v134
	v_mul_f32_e32 v77, v77, v125
	v_mul_f32_e32 v135, 0xbfb8aa3b, v77
	v_exp_f32_e32 v135, v135
	v_add_f32_e32 v134, 1.0, v134
	v_rcp_f32_e32 v134, v134
	s_waitcnt vmcnt(21)
	v_lshlrev_b32_e32 v132, 16, v126
	v_mul_f32_e32 v78, v78, v125
	v_sub_f32_e32 v132, v132, v112
	v_mul_f32_e32 v76, v76, v134
	v_add_f32_e32 v134, 1.0, v135
	v_rcp_f32_e32 v134, v134
	v_mul_f32_e32 v76, v76, v132
	v_mul_f32_e32 v132, 0xbfb8aa3b, v78
	v_exp_f32_e32 v132, v132
	v_and_b32_e32 v126, 0xffff0000, v126
	v_mul_f32_e32 v79, v79, v125
	v_mul_f32_e32 v77, v77, v134
	v_sub_f32_e32 v126, v126, v112
	v_mul_f32_e32 v77, v77, v126
	v_add_f32_e32 v126, 1.0, v132
	v_mul_f32_e32 v132, 0xbfb8aa3b, v79
	v_exp_f32_e32 v132, v132
	v_rcp_f32_e32 v126, v126
	v_lshlrev_b32_e32 v133, 16, v127
	v_and_b32_e32 v127, 0xffff0000, v127
	v_add_f32_e32 v132, 1.0, v132
	v_rcp_f32_e32 v132, v132
	v_mul_f32_e32 v78, v78, v126
	v_sub_f32_e32 v126, v133, v112
	v_mul_f32_e32 v78, v78, v126
	v_mul_f32_e32 v79, v79, v132
	v_sub_f32_e32 v126, v127, v112
	v_mul_f32_e32 v79, v79, v126
	v_mul_f32_e32 v76, v113, v76
	v_mul_f32_e32 v77, v113, v77
	v_mul_f32_e32 v79, v113, v79
	v_mul_f32_e32 v76, v68, v76
	v_mul_f32_e32 v77, v69, v77
	v_mul_f32_e32 v78, v113, v78
	v_mul_f32_e32 v79, v71, v79
	v_mul_f32_e32 v72, v72, v125
	v_mul_f32_e32 v78, v70, v78
	v_cvt_pk_bf16_f32 v76, v76, v77
	v_cvt_pk_bf16_f32 v77, v78, v79
	v_mul_f32_e32 v79, 0xbfb8aa3b, v72
	v_exp_f32_e32 v79, v79
	v_mul_f32_e32 v73, v73, v125
	v_mul_f32_e32 v127, 0xbfb8aa3b, v73
	v_exp_f32_e32 v127, v127
	v_add_f32_e32 v79, 1.0, v79
	v_rcp_f32_e32 v79, v79
	v_lshl_add_u64 v[118:119], v[140:141], 0, v[118:119]
	global_store_dwordx2 v[118:119], v[76:77], off
	s_waitcnt vmcnt(21)
	v_lshlrev_b32_e32 v76, 16, v128
	v_mul_f32_e32 v72, v72, v79
	v_add_f32_e32 v79, 1.0, v127
	v_rcp_f32_e32 v79, v79
	v_and_b32_e32 v77, 0xffff0000, v128
	v_mul_f32_e32 v74, v74, v125
	v_sub_f32_e32 v76, v76, v112
	v_mul_f32_e32 v75, v75, v125
	v_mul_f32_e32 v72, v72, v76
	v_mul_f32_e32 v73, v73, v79
	v_mul_f32_e32 v76, 0xbfb8aa3b, v74
	v_sub_f32_e32 v77, v77, v112
	v_exp_f32_e32 v76, v76
	v_mul_f32_e32 v73, v73, v77
	v_mul_f32_e32 v77, 0xbfb8aa3b, v75
	v_exp_f32_e32 v77, v77
	v_add_f32_e32 v76, 1.0, v76
	v_rcp_f32_e32 v76, v76
	v_lshlrev_b32_e32 v78, 16, v129
	v_add_f32_e32 v77, 1.0, v77
	v_rcp_f32_e32 v77, v77
	v_and_b32_e32 v126, 0xffff0000, v129
	v_mul_f32_e32 v74, v74, v76
	v_sub_f32_e32 v76, v78, v112
	v_mul_f32_e32 v74, v74, v76
	v_mul_f32_e32 v75, v75, v77
	v_sub_f32_e32 v76, v126, v112
	v_mul_f32_e32 v75, v75, v76
	v_mul_f32_e32 v72, v113, v72
	v_mul_f32_e32 v73, v113, v73
	v_mul_f32_e32 v75, v113, v75
	v_mul_f32_e32 v72, v60, v72
	v_mul_f32_e32 v73, v61, v73
	v_mul_f32_e32 v74, v113, v74
	v_mul_f32_e32 v75, v63, v75
	v_mul_f32_e32 v64, v64, v125
	v_mul_f32_e32 v74, v62, v74
	v_cvt_pk_bf16_f32 v72, v72, v73
	v_cvt_pk_bf16_f32 v73, v74, v75
	v_mul_f32_e32 v75, 0xbfb8aa3b, v64
	v_exp_f32_e32 v75, v75
	v_mul_f32_e32 v65, v65, v125
	v_mul_f32_e32 v77, 0xbfb8aa3b, v65
	v_exp_f32_e32 v77, v77
	v_add_f32_e32 v75, 1.0, v75
	v_rcp_f32_e32 v75, v75
	global_store_dwordx2 v[118:119], v[72:73], off offset:32
	s_waitcnt vmcnt(21)
	v_lshlrev_b32_e32 v72, 16, v130
	v_and_b32_e32 v73, 0xffff0000, v130
	v_mul_f32_e32 v64, v64, v75
	v_add_f32_e32 v75, 1.0, v77
	v_rcp_f32_e32 v75, v75
	v_mul_f32_e32 v66, v66, v125
	v_sub_f32_e32 v72, v72, v112
	v_mul_f32_e32 v67, v67, v125
	v_mul_f32_e32 v64, v64, v72
	v_mul_f32_e32 v65, v65, v75
	v_mul_f32_e32 v72, 0xbfb8aa3b, v66
	v_sub_f32_e32 v73, v73, v112
	v_exp_f32_e32 v72, v72
	v_mul_f32_e32 v65, v65, v73
	v_mul_f32_e32 v73, 0xbfb8aa3b, v67
	v_exp_f32_e32 v73, v73
	v_add_f32_e32 v72, 1.0, v72
	v_rcp_f32_e32 v72, v72
	v_lshlrev_b32_e32 v74, 16, v131
	v_add_f32_e32 v73, 1.0, v73
	v_rcp_f32_e32 v73, v73
	v_and_b32_e32 v76, 0xffff0000, v131
	v_mul_f32_e32 v66, v66, v72
	v_sub_f32_e32 v72, v74, v112
	v_mul_f32_e32 v66, v66, v72
	v_mul_f32_e32 v67, v67, v73
	v_sub_f32_e32 v72, v76, v112
	v_mul_f32_e32 v67, v67, v72
	v_mul_f32_e32 v64, v113, v64
	v_mul_f32_e32 v65, v113, v65
	v_mul_f32_e32 v67, v113, v67
	v_mul_f32_e32 v64, v52, v64
	v_mul_f32_e32 v65, v53, v65
	v_mul_f32_e32 v66, v113, v66
	v_mul_f32_e32 v67, v55, v67
	v_mul_f32_e32 v56, v56, v125
	v_mul_f32_e32 v66, v54, v66
	v_cvt_pk_bf16_f32 v64, v64, v65
	v_cvt_pk_bf16_f32 v65, v66, v67
	v_mul_f32_e32 v67, 0xbfb8aa3b, v56
	v_exp_f32_e32 v67, v67
	v_mul_f32_e32 v57, v57, v125
	v_mul_f32_e32 v73, 0xbfb8aa3b, v57
	v_exp_f32_e32 v73, v73
	v_add_f32_e32 v67, 1.0, v67
	v_rcp_f32_e32 v67, v67
	global_store_dwordx2 v[118:119], v[64:65], off offset:64
	s_waitcnt vmcnt(21)
	v_and_b32_e32 v65, 0xffff0000, v120
	v_mul_f32_e32 v59, v59, v125
	v_mul_f32_e32 v56, v56, v67
	v_add_f32_e32 v67, 1.0, v73
	v_rcp_f32_e32 v67, v67
	v_sub_f32_e32 v65, v65, v112
	v_lshlrev_b32_e32 v64, 16, v120
	v_mul_f32_e32 v58, v58, v125
	v_mul_f32_e32 v57, v57, v67
	v_mul_f32_e32 v57, v57, v65
	v_mul_f32_e32 v65, 0xbfb8aa3b, v59
	v_exp_f32_e32 v65, v65
	v_sub_f32_e32 v64, v64, v112
	v_mul_f32_e32 v56, v56, v64
	v_mul_f32_e32 v64, 0xbfb8aa3b, v58
	v_add_f32_e32 v65, 1.0, v65
	v_rcp_f32_e32 v65, v65
	s_waitcnt vmcnt(20)
	v_mul_f32_e32 v48, v48, v124
	v_exp_f32_e32 v64, v64
	v_mul_f32_e32 v49, v49, v124
	v_mul_f32_e32 v59, v59, v65
	v_mul_f32_e32 v65, 0xbfb8aa3b, v48
	v_exp_f32_e32 v65, v65
	v_add_f32_e32 v64, 1.0, v64
	v_rcp_f32_e32 v64, v64
	v_mul_f32_e32 v67, 0xbfb8aa3b, v49
	v_add_f32_e32 v65, 1.0, v65
	v_rcp_f32_e32 v65, v65
	v_exp_f32_e32 v67, v67
	v_lshlrev_b32_e32 v66, 16, v121
	v_and_b32_e32 v72, 0xffff0000, v121
	v_mul_f32_e32 v58, v58, v64
	v_sub_f32_e32 v64, v66, v112
	v_mul_f32_e32 v58, v58, v64
	v_sub_f32_e32 v64, v72, v112
	v_mul_f32_e32 v48, v48, v65
	v_add_f32_e32 v65, 1.0, v67
	v_mul_f32_e32 v56, v113, v56
	v_mul_f32_e32 v57, v113, v57
	v_mul_f32_e32 v58, v113, v58
	v_mul_f32_e32 v59, v59, v64
	v_rcp_f32_e32 v65, v65
	v_mul_f32_e32 v56, v44, v56
	v_mul_f32_e32 v57, v45, v57
	v_mul_f32_e32 v58, v46, v58
	v_mul_f32_e32 v59, v113, v59
	v_mul_f32_e32 v59, v47, v59
	v_cvt_pk_bf16_f32 v56, v56, v57
	v_cvt_pk_bf16_f32 v57, v58, v59
	s_waitcnt vmcnt(18)
	v_lshlrev_b32_e32 v58, 16, v114
	v_and_b32_e32 v59, 0xffff0000, v114
	v_mul_f32_e32 v50, v50, v124
	v_sub_f32_e32 v58, v58, v100
	v_mul_f32_e32 v51, v51, v124
	v_mul_f32_e32 v48, v48, v58
	v_mul_f32_e32 v49, v49, v65
	v_mul_f32_e32 v58, 0xbfb8aa3b, v50
	v_sub_f32_e32 v59, v59, v100
	v_exp_f32_e32 v58, v58
	v_mul_f32_e32 v49, v49, v59
	v_mul_f32_e32 v59, 0xbfb8aa3b, v51
	v_exp_f32_e32 v59, v59
	v_add_f32_e32 v58, 1.0, v58
	v_rcp_f32_e32 v58, v58
	v_lshlrev_b32_e32 v64, 16, v115
	v_add_f32_e32 v59, 1.0, v59
	v_rcp_f32_e32 v59, v59
	v_and_b32_e32 v66, 0xffff0000, v115
	v_mul_f32_e32 v50, v50, v58
	v_sub_f32_e32 v58, v64, v100
	v_mul_f32_e32 v50, v50, v58
	v_mul_f32_e32 v51, v51, v59
	v_sub_f32_e32 v58, v66, v100
	v_mul_f32_e32 v51, v51, v58
	v_mul_f32_e32 v48, v101, v48
	v_mul_f32_e32 v49, v101, v49
	v_mul_f32_e32 v51, v101, v51
	v_mul_f32_e32 v48, v68, v48
	v_mul_f32_e32 v49, v69, v49
	v_mul_f32_e32 v50, v101, v50
	v_mul_f32_e32 v51, v71, v51
	v_mul_f32_e32 v40, v40, v124
	v_mul_f32_e32 v50, v70, v50
	v_cvt_pk_bf16_f32 v48, v48, v49
	v_cvt_pk_bf16_f32 v49, v50, v51
	v_mul_f32_e32 v51, 0xbfb8aa3b, v40
	v_exp_f32_e32 v51, v51
	v_mul_f32_e32 v41, v41, v124
	v_mul_f32_e32 v59, 0xbfb8aa3b, v41
	v_exp_f32_e32 v59, v59
	v_add_f32_e32 v51, 1.0, v51
	v_rcp_f32_e32 v51, v51
	global_store_dwordx2 v[118:119], v[56:57], off offset:96
	v_lshl_add_u64 v[56:57], v[140:141], 0, v[116:117]
	global_store_dwordx2 v[56:57], v[48:49], off
	v_mul_f32_e32 v40, v40, v51
	v_add_f32_e32 v51, 1.0, v59
	v_rcp_f32_e32 v51, v51
	s_waitcnt vmcnt(19)
	v_lshlrev_b32_e32 v48, 16, v110
	v_and_b32_e32 v49, 0xffff0000, v110
	v_mul_f32_e32 v42, v42, v124
	v_sub_f32_e32 v48, v48, v100
	v_mul_f32_e32 v43, v43, v124
	v_mul_f32_e32 v40, v40, v48
	v_mul_f32_e32 v41, v41, v51
	v_mul_f32_e32 v48, 0xbfb8aa3b, v42
	v_sub_f32_e32 v49, v49, v100
	v_exp_f32_e32 v48, v48
	v_mul_f32_e32 v41, v41, v49
	v_mul_f32_e32 v49, 0xbfb8aa3b, v43
	v_exp_f32_e32 v49, v49
	v_add_f32_e32 v48, 1.0, v48
	v_rcp_f32_e32 v48, v48
	v_lshlrev_b32_e32 v50, 16, v111
	v_add_f32_e32 v49, 1.0, v49
	v_rcp_f32_e32 v49, v49
	v_and_b32_e32 v58, 0xffff0000, v111
	v_mul_f32_e32 v42, v42, v48
	v_sub_f32_e32 v48, v50, v100
	v_mul_f32_e32 v42, v42, v48
	v_mul_f32_e32 v43, v43, v49
	v_sub_f32_e32 v48, v58, v100
	v_mul_f32_e32 v43, v43, v48
	v_mul_f32_e32 v40, v101, v40
	v_mul_f32_e32 v41, v101, v41
	v_mul_f32_e32 v43, v101, v43
	v_mul_f32_e32 v40, v60, v40
	v_mul_f32_e32 v41, v61, v41
	v_mul_f32_e32 v42, v101, v42
	v_mul_f32_e32 v43, v63, v43
	v_mul_f32_e32 v36, v36, v124
	v_mul_f32_e32 v42, v62, v42
	v_cvt_pk_bf16_f32 v40, v40, v41
	v_cvt_pk_bf16_f32 v41, v42, v43
	v_mul_f32_e32 v43, 0xbfb8aa3b, v36
	v_exp_f32_e32 v43, v43
	v_mul_f32_e32 v37, v37, v124
	v_mul_f32_e32 v49, 0xbfb8aa3b, v37
	v_exp_f32_e32 v49, v49
	v_add_f32_e32 v43, 1.0, v43
	v_rcp_f32_e32 v43, v43
	global_store_dwordx2 v[56:57], v[40:41], off offset:32
	s_waitcnt vmcnt(19)
	v_lshlrev_b32_e32 v40, 16, v108
	v_and_b32_e32 v41, 0xffff0000, v108
	v_mul_f32_e32 v36, v36, v43
	v_add_f32_e32 v43, 1.0, v49
	v_rcp_f32_e32 v43, v43
	v_mul_f32_e32 v38, v38, v124
	v_sub_f32_e32 v40, v40, v100
	v_mul_f32_e32 v39, v39, v124
	v_mul_f32_e32 v36, v36, v40
	v_mul_f32_e32 v37, v37, v43
	v_mul_f32_e32 v40, 0xbfb8aa3b, v38
	v_sub_f32_e32 v41, v41, v100
	v_exp_f32_e32 v40, v40
	v_mul_f32_e32 v37, v37, v41
	v_mul_f32_e32 v41, 0xbfb8aa3b, v39
	v_exp_f32_e32 v41, v41
	v_add_f32_e32 v40, 1.0, v40
	v_rcp_f32_e32 v40, v40
	v_lshlrev_b32_e32 v42, 16, v109
	v_add_f32_e32 v41, 1.0, v41
	v_rcp_f32_e32 v41, v41
	v_and_b32_e32 v48, 0xffff0000, v109
	v_mul_f32_e32 v38, v38, v40
	v_sub_f32_e32 v40, v42, v100
	v_mul_f32_e32 v38, v38, v40
	v_mul_f32_e32 v39, v39, v41
	v_sub_f32_e32 v40, v48, v100
	v_mul_f32_e32 v39, v39, v40
	v_mul_f32_e32 v36, v101, v36
	v_mul_f32_e32 v37, v101, v37
	v_mul_f32_e32 v39, v101, v39
	v_mul_f32_e32 v36, v52, v36
	v_mul_f32_e32 v37, v53, v37
	v_mul_f32_e32 v38, v101, v38
	v_mul_f32_e32 v39, v55, v39
	v_mul_f32_e32 v32, v32, v124
	v_mul_f32_e32 v38, v54, v38
	v_cvt_pk_bf16_f32 v36, v36, v37
	v_cvt_pk_bf16_f32 v37, v38, v39
	v_mul_f32_e32 v39, 0xbfb8aa3b, v32
	v_exp_f32_e32 v39, v39
	v_mul_f32_e32 v33, v33, v124
	v_mul_f32_e32 v41, 0xbfb8aa3b, v33
	v_exp_f32_e32 v41, v41
	v_add_f32_e32 v39, 1.0, v39
	v_rcp_f32_e32 v39, v39
	global_store_dwordx2 v[56:57], v[36:37], off offset:64
	s_waitcnt vmcnt(19)
	v_and_b32_e32 v37, 0xffff0000, v106
	v_mul_f32_e32 v35, v35, v124
	v_mul_f32_e32 v32, v32, v39
	v_add_f32_e32 v39, 1.0, v41
	v_rcp_f32_e32 v39, v39
	v_sub_f32_e32 v37, v37, v100
	v_lshlrev_b32_e32 v36, 16, v106
	v_mul_f32_e32 v34, v34, v124
	v_mul_f32_e32 v33, v33, v39
	v_mul_f32_e32 v33, v33, v37
	v_mul_f32_e32 v37, 0xbfb8aa3b, v35
	v_exp_f32_e32 v37, v37
	v_sub_f32_e32 v36, v36, v100
	v_mul_f32_e32 v32, v32, v36
	v_mul_f32_e32 v36, 0xbfb8aa3b, v34
	v_add_f32_e32 v37, 1.0, v37
	v_rcp_f32_e32 v37, v37
	s_waitcnt vmcnt(18)
	v_mul_f32_e32 v28, v28, v123
	v_exp_f32_e32 v36, v36
	v_mul_f32_e32 v29, v29, v123
	v_mul_f32_e32 v35, v35, v37
	v_mul_f32_e32 v37, 0xbfb8aa3b, v28
	v_exp_f32_e32 v37, v37
	v_add_f32_e32 v36, 1.0, v36
	v_rcp_f32_e32 v36, v36
	v_mul_f32_e32 v39, 0xbfb8aa3b, v29
	v_add_f32_e32 v37, 1.0, v37
	v_rcp_f32_e32 v37, v37
	v_exp_f32_e32 v39, v39
	v_lshlrev_b32_e32 v38, 16, v107
	v_and_b32_e32 v40, 0xffff0000, v107
	v_mul_f32_e32 v34, v34, v36
	v_sub_f32_e32 v36, v38, v100
	v_mul_f32_e32 v34, v34, v36
	v_sub_f32_e32 v36, v40, v100
	v_mul_f32_e32 v28, v28, v37
	v_add_f32_e32 v37, 1.0, v39
	v_mul_f32_e32 v32, v101, v32
	v_mul_f32_e32 v33, v101, v33
	v_mul_f32_e32 v34, v101, v34
	v_mul_f32_e32 v35, v35, v36
	v_rcp_f32_e32 v37, v37
	v_mul_f32_e32 v32, v44, v32
	v_mul_f32_e32 v33, v45, v33
	v_mul_f32_e32 v34, v46, v34
	v_mul_f32_e32 v35, v101, v35
	v_mul_f32_e32 v35, v47, v35
	v_cvt_pk_bf16_f32 v32, v32, v33
	v_cvt_pk_bf16_f32 v33, v34, v35
	s_waitcnt vmcnt(16)
	v_lshlrev_b32_e32 v34, 16, v102
	v_and_b32_e32 v35, 0xffff0000, v102
	v_mul_f32_e32 v30, v30, v123
	v_sub_f32_e32 v34, v34, v88
	v_mul_f32_e32 v31, v31, v123
	v_mul_f32_e32 v28, v28, v34
	v_mul_f32_e32 v29, v29, v37
	v_mul_f32_e32 v34, 0xbfb8aa3b, v30
	v_sub_f32_e32 v35, v35, v88
	v_exp_f32_e32 v34, v34
	v_mul_f32_e32 v29, v29, v35
	v_mul_f32_e32 v35, 0xbfb8aa3b, v31
	v_exp_f32_e32 v35, v35
	v_add_f32_e32 v34, 1.0, v34
	v_rcp_f32_e32 v34, v34
	v_lshlrev_b32_e32 v36, 16, v103
	v_add_f32_e32 v35, 1.0, v35
	v_rcp_f32_e32 v35, v35
	v_and_b32_e32 v38, 0xffff0000, v103
	v_mul_f32_e32 v30, v30, v34
	v_sub_f32_e32 v34, v36, v88
	v_mul_f32_e32 v30, v30, v34
	v_mul_f32_e32 v31, v31, v35
	v_sub_f32_e32 v34, v38, v88
	v_mul_f32_e32 v31, v31, v34
	v_mul_f32_e32 v28, v89, v28
	v_mul_f32_e32 v29, v89, v29
	v_mul_f32_e32 v31, v89, v31
	v_mul_f32_e32 v28, v68, v28
	v_mul_f32_e32 v29, v69, v29
	v_mul_f32_e32 v30, v89, v30
	v_mul_f32_e32 v31, v71, v31
	v_mul_f32_e32 v24, v24, v123
	v_mul_f32_e32 v30, v70, v30
	v_cvt_pk_bf16_f32 v28, v28, v29
	v_cvt_pk_bf16_f32 v29, v30, v31
	v_mul_f32_e32 v31, 0xbfb8aa3b, v24
	v_exp_f32_e32 v31, v31
	v_mul_f32_e32 v25, v25, v123
	v_mul_f32_e32 v35, 0xbfb8aa3b, v25
	v_exp_f32_e32 v35, v35
	v_add_f32_e32 v31, 1.0, v31
	v_rcp_f32_e32 v31, v31
	global_store_dwordx2 v[56:57], v[32:33], off offset:96
	v_lshl_add_u64 v[32:33], v[140:141], 0, v[104:105]
	global_store_dwordx2 v[32:33], v[28:29], off
	v_mul_f32_e32 v24, v24, v31
	v_add_f32_e32 v31, 1.0, v35
	v_rcp_f32_e32 v31, v31
	s_waitcnt vmcnt(17)
	v_lshlrev_b32_e32 v28, 16, v98
	v_and_b32_e32 v29, 0xffff0000, v98
	v_mul_f32_e32 v26, v26, v123
	v_sub_f32_e32 v28, v28, v88
	v_mul_f32_e32 v27, v27, v123
	v_mul_f32_e32 v24, v24, v28
	v_mul_f32_e32 v25, v25, v31
	v_mul_f32_e32 v28, 0xbfb8aa3b, v26
	v_sub_f32_e32 v29, v29, v88
	v_exp_f32_e32 v28, v28
	v_mul_f32_e32 v25, v25, v29
	v_mul_f32_e32 v29, 0xbfb8aa3b, v27
	v_exp_f32_e32 v29, v29
	v_add_f32_e32 v28, 1.0, v28
	v_rcp_f32_e32 v28, v28
	v_lshlrev_b32_e32 v30, 16, v99
	v_add_f32_e32 v29, 1.0, v29
	v_rcp_f32_e32 v29, v29
	v_and_b32_e32 v34, 0xffff0000, v99
	v_mul_f32_e32 v26, v26, v28
	v_sub_f32_e32 v28, v30, v88
	v_mul_f32_e32 v26, v26, v28
	v_mul_f32_e32 v27, v27, v29
	v_sub_f32_e32 v28, v34, v88
	v_mul_f32_e32 v27, v27, v28
	v_mul_f32_e32 v24, v89, v24
	v_mul_f32_e32 v25, v89, v25
	v_mul_f32_e32 v27, v89, v27
	v_mul_f32_e32 v24, v60, v24
	v_mul_f32_e32 v25, v61, v25
	v_mul_f32_e32 v26, v89, v26
	v_mul_f32_e32 v27, v63, v27
	v_mul_f32_e32 v20, v20, v123
	v_mul_f32_e32 v26, v62, v26
	v_cvt_pk_bf16_f32 v24, v24, v25
	v_cvt_pk_bf16_f32 v25, v26, v27
	v_mul_f32_e32 v27, 0xbfb8aa3b, v20
	v_exp_f32_e32 v27, v27
	v_mul_f32_e32 v21, v21, v123
	v_mul_f32_e32 v29, 0xbfb8aa3b, v21
	v_exp_f32_e32 v29, v29
	v_add_f32_e32 v27, 1.0, v27
	v_rcp_f32_e32 v27, v27
	global_store_dwordx2 v[32:33], v[24:25], off offset:32
	s_waitcnt vmcnt(17)
	v_lshlrev_b32_e32 v24, 16, v96
	v_and_b32_e32 v25, 0xffff0000, v96
	v_mul_f32_e32 v20, v20, v27
	v_add_f32_e32 v27, 1.0, v29
	v_rcp_f32_e32 v27, v27
	v_mul_f32_e32 v22, v22, v123
	v_sub_f32_e32 v24, v24, v88
	v_mul_f32_e32 v23, v23, v123
	v_mul_f32_e32 v20, v20, v24
	v_mul_f32_e32 v21, v21, v27
	v_mul_f32_e32 v24, 0xbfb8aa3b, v22
	v_sub_f32_e32 v25, v25, v88
	v_exp_f32_e32 v24, v24
	v_mul_f32_e32 v21, v21, v25
	v_mul_f32_e32 v25, 0xbfb8aa3b, v23
	v_exp_f32_e32 v25, v25
	v_add_f32_e32 v24, 1.0, v24
	v_rcp_f32_e32 v24, v24
	v_lshlrev_b32_e32 v26, 16, v97
	v_add_f32_e32 v25, 1.0, v25
	v_rcp_f32_e32 v25, v25
	v_and_b32_e32 v28, 0xffff0000, v97
	v_mul_f32_e32 v22, v22, v24
	v_sub_f32_e32 v24, v26, v88
	v_mul_f32_e32 v22, v22, v24
	v_mul_f32_e32 v23, v23, v25
	v_sub_f32_e32 v24, v28, v88
	v_mul_f32_e32 v23, v23, v24
	v_mul_f32_e32 v20, v89, v20
	v_mul_f32_e32 v21, v89, v21
	v_mul_f32_e32 v23, v89, v23
	v_mul_f32_e32 v20, v52, v20
	v_mul_f32_e32 v21, v53, v21
	v_mul_f32_e32 v22, v89, v22
	v_mul_f32_e32 v23, v55, v23
	v_mul_f32_e32 v16, v16, v123
	v_mul_f32_e32 v22, v54, v22
	v_cvt_pk_bf16_f32 v20, v20, v21
	v_cvt_pk_bf16_f32 v21, v22, v23
	v_mul_f32_e32 v23, 0xbfb8aa3b, v16
	v_exp_f32_e32 v23, v23
	v_mul_f32_e32 v17, v17, v123
	v_mul_f32_e32 v25, 0xbfb8aa3b, v17
	v_exp_f32_e32 v25, v25
	v_add_f32_e32 v23, 1.0, v23
	v_rcp_f32_e32 v23, v23
	global_store_dwordx2 v[32:33], v[20:21], off offset:64
	s_waitcnt vmcnt(17)
	v_and_b32_e32 v21, 0xffff0000, v94
	v_mul_f32_e32 v19, v19, v123
	v_mul_f32_e32 v16, v16, v23
	v_add_f32_e32 v23, 1.0, v25
	v_rcp_f32_e32 v23, v23
	v_sub_f32_e32 v21, v21, v88
	v_lshlrev_b32_e32 v20, 16, v94
	v_mul_f32_e32 v18, v18, v123
	v_mul_f32_e32 v17, v17, v23
	v_mul_f32_e32 v17, v17, v21
	v_mul_f32_e32 v21, 0xbfb8aa3b, v19
	v_exp_f32_e32 v21, v21
	v_sub_f32_e32 v20, v20, v88
	v_mul_f32_e32 v16, v16, v20
	v_mul_f32_e32 v20, 0xbfb8aa3b, v18
	v_add_f32_e32 v21, 1.0, v21
	v_rcp_f32_e32 v21, v21
	s_waitcnt vmcnt(16)
	v_mul_f32_e32 v12, v12, v122
	v_exp_f32_e32 v20, v20
	v_mul_f32_e32 v13, v13, v122
	v_mul_f32_e32 v19, v19, v21
	v_mul_f32_e32 v21, 0xbfb8aa3b, v12
	v_exp_f32_e32 v21, v21
	v_add_f32_e32 v20, 1.0, v20
	v_rcp_f32_e32 v20, v20
	v_mul_f32_e32 v23, 0xbfb8aa3b, v13
	v_add_f32_e32 v21, 1.0, v21
	v_rcp_f32_e32 v21, v21
	v_exp_f32_e32 v23, v23
	v_lshlrev_b32_e32 v22, 16, v95
	v_and_b32_e32 v24, 0xffff0000, v95
	v_mul_f32_e32 v18, v18, v20
	v_sub_f32_e32 v20, v22, v88
	v_mul_f32_e32 v18, v18, v20
	v_sub_f32_e32 v20, v24, v88
	v_mul_f32_e32 v12, v12, v21
	v_add_f32_e32 v21, 1.0, v23
	v_mul_f32_e32 v16, v89, v16
	v_mul_f32_e32 v17, v89, v17
	v_mul_f32_e32 v18, v89, v18
	v_mul_f32_e32 v19, v19, v20
	v_rcp_f32_e32 v21, v21
	v_mul_f32_e32 v16, v44, v16
	v_mul_f32_e32 v17, v45, v17
	v_mul_f32_e32 v18, v46, v18
	v_mul_f32_e32 v19, v89, v19
	v_mul_f32_e32 v19, v47, v19
	v_cvt_pk_bf16_f32 v16, v16, v17
	v_cvt_pk_bf16_f32 v17, v18, v19
	s_waitcnt vmcnt(14)
	v_lshlrev_b32_e32 v18, 16, v90
	v_and_b32_e32 v19, 0xffff0000, v90
	v_mul_f32_e32 v14, v14, v122
	v_sub_f32_e32 v18, v18, v80
	v_mul_f32_e32 v15, v15, v122
	v_mul_f32_e32 v12, v12, v18
	v_mul_f32_e32 v13, v13, v21
	v_mul_f32_e32 v18, 0xbfb8aa3b, v14
	v_sub_f32_e32 v19, v19, v80
	v_exp_f32_e32 v18, v18
	v_mul_f32_e32 v13, v13, v19
	v_mul_f32_e32 v19, 0xbfb8aa3b, v15
	v_exp_f32_e32 v19, v19
	v_add_f32_e32 v18, 1.0, v18
	v_rcp_f32_e32 v18, v18
	v_lshlrev_b32_e32 v20, 16, v91
	v_add_f32_e32 v19, 1.0, v19
	v_rcp_f32_e32 v19, v19
	v_and_b32_e32 v22, 0xffff0000, v91
	v_mul_f32_e32 v14, v14, v18
	v_sub_f32_e32 v18, v20, v80
	v_mul_f32_e32 v14, v14, v18
	v_mul_f32_e32 v15, v15, v19
	v_sub_f32_e32 v18, v22, v80
	v_mul_f32_e32 v15, v15, v18
	v_mul_f32_e32 v12, v81, v12
	v_mul_f32_e32 v13, v81, v13
	v_mul_f32_e32 v15, v81, v15
	v_mul_f32_e32 v12, v68, v12
	v_mul_f32_e32 v13, v69, v13
	v_mul_f32_e32 v14, v81, v14
	v_mul_f32_e32 v15, v71, v15
	v_mul_f32_e32 v8, v8, v122
	v_mul_f32_e32 v14, v70, v14
	v_cvt_pk_bf16_f32 v12, v12, v13
	v_cvt_pk_bf16_f32 v13, v14, v15
	v_mul_f32_e32 v15, 0xbfb8aa3b, v8
	v_exp_f32_e32 v15, v15
	v_mul_f32_e32 v9, v9, v122
	v_mul_f32_e32 v19, 0xbfb8aa3b, v9
	v_exp_f32_e32 v19, v19
	v_add_f32_e32 v15, 1.0, v15
	v_rcp_f32_e32 v15, v15
	global_store_dwordx2 v[32:33], v[16:17], off offset:96
	v_lshl_add_u64 v[16:17], v[140:141], 0, v[92:93]
	global_store_dwordx2 v[16:17], v[12:13], off
	v_mul_f32_e32 v8, v8, v15
	v_add_f32_e32 v15, 1.0, v19
	v_rcp_f32_e32 v15, v15
	s_waitcnt vmcnt(15)
	v_lshlrev_b32_e32 v12, 16, v86
	v_and_b32_e32 v13, 0xffff0000, v86
	v_mul_f32_e32 v10, v10, v122
	v_sub_f32_e32 v12, v12, v80
	v_mul_f32_e32 v11, v11, v122
	v_mul_f32_e32 v8, v8, v12
	v_mul_f32_e32 v9, v9, v15
	v_mul_f32_e32 v12, 0xbfb8aa3b, v10
	v_sub_f32_e32 v13, v13, v80
	v_exp_f32_e32 v12, v12
	v_mul_f32_e32 v9, v9, v13
	v_mul_f32_e32 v13, 0xbfb8aa3b, v11
	v_exp_f32_e32 v13, v13
	v_add_f32_e32 v12, 1.0, v12
	v_rcp_f32_e32 v12, v12
	v_lshlrev_b32_e32 v14, 16, v87
	v_add_f32_e32 v13, 1.0, v13
	v_rcp_f32_e32 v13, v13
	v_and_b32_e32 v18, 0xffff0000, v87
	v_mul_f32_e32 v10, v10, v12
	v_sub_f32_e32 v12, v14, v80
	v_mul_f32_e32 v10, v10, v12
	v_mul_f32_e32 v11, v11, v13
	v_sub_f32_e32 v12, v18, v80
	v_mul_f32_e32 v11, v11, v12
	v_mul_f32_e32 v8, v81, v8
	v_mul_f32_e32 v9, v81, v9
	v_mul_f32_e32 v11, v81, v11
	v_mul_f32_e32 v8, v60, v8
	v_mul_f32_e32 v9, v61, v9
	v_mul_f32_e32 v10, v81, v10
	v_mul_f32_e32 v11, v63, v11
	v_mul_f32_e32 v4, v4, v122
	v_mul_f32_e32 v10, v62, v10
	v_cvt_pk_bf16_f32 v8, v8, v9
	v_cvt_pk_bf16_f32 v9, v10, v11
	v_mul_f32_e32 v11, 0xbfb8aa3b, v4
	v_exp_f32_e32 v11, v11
	v_mul_f32_e32 v5, v5, v122
	v_mul_f32_e32 v13, 0xbfb8aa3b, v5
	v_exp_f32_e32 v13, v13
	v_add_f32_e32 v11, 1.0, v11
	v_rcp_f32_e32 v11, v11
	global_store_dwordx2 v[16:17], v[8:9], off offset:32
	s_waitcnt vmcnt(15)
	v_lshlrev_b32_e32 v8, 16, v84
	v_and_b32_e32 v9, 0xffff0000, v84
	v_mul_f32_e32 v4, v4, v11
	v_add_f32_e32 v11, 1.0, v13
	v_rcp_f32_e32 v11, v11
	v_mul_f32_e32 v6, v6, v122
	v_sub_f32_e32 v8, v8, v80
	v_mul_f32_e32 v7, v7, v122
	v_mul_f32_e32 v4, v4, v8
	v_mul_f32_e32 v5, v5, v11
	v_mul_f32_e32 v8, 0xbfb8aa3b, v6
	v_sub_f32_e32 v9, v9, v80
	v_exp_f32_e32 v8, v8
	v_mul_f32_e32 v5, v5, v9
	v_mul_f32_e32 v9, 0xbfb8aa3b, v7
	v_exp_f32_e32 v9, v9
	v_add_f32_e32 v8, 1.0, v8
	v_rcp_f32_e32 v8, v8
	v_lshlrev_b32_e32 v10, 16, v85
	v_add_f32_e32 v9, 1.0, v9
	v_rcp_f32_e32 v9, v9
	v_and_b32_e32 v12, 0xffff0000, v85
	v_mul_f32_e32 v6, v6, v8
	v_sub_f32_e32 v8, v10, v80
	v_mul_f32_e32 v6, v6, v8
	v_mul_f32_e32 v7, v7, v9
	v_sub_f32_e32 v8, v12, v80
	v_mul_f32_e32 v7, v7, v8
	v_mul_f32_e32 v4, v81, v4
	v_mul_f32_e32 v5, v81, v5
	v_mul_f32_e32 v7, v81, v7
	v_mul_f32_e32 v4, v52, v4
	v_mul_f32_e32 v5, v53, v5
	v_mul_f32_e32 v6, v81, v6
	v_mul_f32_e32 v7, v55, v7
	v_mul_f32_e32 v0, v0, v122
	v_mul_f32_e32 v6, v54, v6
	v_cvt_pk_bf16_f32 v4, v4, v5
	v_cvt_pk_bf16_f32 v5, v6, v7
	v_mul_f32_e32 v7, 0xbfb8aa3b, v0
	v_exp_f32_e32 v7, v7
	v_mul_f32_e32 v1, v1, v122
	v_mul_f32_e32 v9, 0xbfb8aa3b, v1
	v_exp_f32_e32 v9, v9
	v_add_f32_e32 v7, 1.0, v7
	v_rcp_f32_e32 v7, v7
	global_store_dwordx2 v[16:17], v[4:5], off offset:64
	s_waitcnt vmcnt(15)
	v_lshlrev_b32_e32 v4, 16, v82
	v_and_b32_e32 v5, 0xffff0000, v82
	v_mul_f32_e32 v0, v0, v7
	v_add_f32_e32 v7, 1.0, v9
	v_rcp_f32_e32 v7, v7
	v_mul_f32_e32 v2, v2, v122
	v_sub_f32_e32 v4, v4, v80
	v_mul_f32_e32 v3, v3, v122
	v_mul_f32_e32 v0, v0, v4
	v_mul_f32_e32 v1, v1, v7
	v_mul_f32_e32 v4, 0xbfb8aa3b, v2
	v_sub_f32_e32 v5, v5, v80
	v_exp_f32_e32 v4, v4
	v_mul_f32_e32 v1, v1, v5
	v_mul_f32_e32 v5, 0xbfb8aa3b, v3
	v_exp_f32_e32 v5, v5
	v_add_f32_e32 v4, 1.0, v4
	v_rcp_f32_e32 v4, v4
	v_lshlrev_b32_e32 v6, 16, v83
	v_add_f32_e32 v5, 1.0, v5
	v_rcp_f32_e32 v5, v5
	v_and_b32_e32 v8, 0xffff0000, v83
	v_mul_f32_e32 v2, v2, v4
	v_sub_f32_e32 v4, v6, v80
	v_mul_f32_e32 v2, v2, v4
	v_mul_f32_e32 v3, v3, v5
	v_sub_f32_e32 v4, v8, v80
	v_mul_f32_e32 v0, v81, v0
	v_mul_f32_e32 v1, v81, v1
	v_mul_f32_e32 v3, v3, v4
	v_mul_f32_e32 v0, v44, v0
	v_mul_f32_e32 v1, v45, v1
	v_mul_f32_e32 v2, v81, v2
	v_mul_f32_e32 v3, v81, v3
	v_mul_f32_e32 v2, v46, v2
	v_mul_f32_e32 v3, v47, v3
	v_cvt_pk_bf16_f32 v0, v0, v1
	v_cvt_pk_bf16_f32 v1, v2, v3
	global_store_dwordx2 v[16:17], v[0:1], off offset:96
	s_add_i32 s34, s34, s74
	s_cmpk_lt_i32 s34, 0x800
	s_cbranch_scc1 .LBB0_502

.LBB0_561:
	s_add_i32 s31, s29, 64
	s_min_u32 s22, s31, 0x7e0
	s_lshl_b32 s22, s22, 1
	v_lshl_add_u64 v[174:175], v[156:157], 0, s[22:23]
	global_load_dwordx4 v[178:181], v[174:175], off
	v_lshl_add_u64 v[174:175], v[158:159], 0, s[22:23]
	v_lshl_add_u64 v[170:171], v[152:153], 0, s[22:23]
	v_lshl_add_u64 v[186:187], v[160:161], 0, s[22:23]
	global_load_dwordx4 v[182:185], v[174:175], off
	v_lshl_add_u64 v[174:175], v[154:155], 0, s[22:23]
	v_lshl_add_u64 v[194:195], v[162:163], 0, s[22:23]
	global_load_dwordx4 v[170:173], v[170:171], off
	ds_read_b128 v[202:205], v168 offset:32768
	global_load_dwordx4 v[186:189], v[186:187], off
	ds_read_b128 v[206:209], v168 offset:33792
	global_load_dwordx4 v[190:193], v[174:175], off
	global_load_dwordx4 v[198:201], v[194:195], off
	ds_read_b128 v[210:213], v168 offset:34816
	ds_read_b128 v[214:217], v168 offset:35840
	ds_read_b128 v[222:225], v166
	ds_read_b128 v[226:229], v166 offset:1024
	ds_read_b128 v[230:233], v166 offset:2048
	ds_read_b128 v[234:237], v166 offset:3072
	ds_read_b128 v[238:241], v166 offset:4096
	ds_read_b128 v[242:245], v166 offset:5120
	ds_read_b128 v[246:249], v166 offset:6144
	ds_read_b128 v[250:253], v166 offset:7168
	s_waitcnt lgkmcnt(7)
	v_mfma_f32_16x16x32_bf16 v[148:151], v[202:205], v[222:225], v[148:151]
	v_mfma_f32_16x16x32_bf16 v[144:147], v[206:209], v[222:225], v[144:147]
	v_mfma_f32_16x16x32_bf16 v[140:143], v[210:213], v[222:225], v[140:143]
	v_mfma_f32_16x16x32_bf16 v[136:139], v[214:217], v[222:225], v[136:139]
	s_waitcnt vmcnt(11)
	ds_write_b128 v164, v[112:115] offset:16384
	s_waitcnt lgkmcnt(7)
	v_mfma_f32_16x16x32_bf16 v[108:111], v[202:205], v[226:229], v[108:111]
	v_mfma_f32_16x16x32_bf16 v[104:107], v[206:209], v[226:229], v[104:107]
	v_mfma_f32_16x16x32_bf16 v[100:103], v[210:213], v[226:229], v[100:103]
	v_mfma_f32_16x16x32_bf16 v[96:99], v[214:217], v[226:229], v[96:99]
	s_waitcnt vmcnt(9)
	ds_write_b128 v164, v[120:123] offset:20480
	s_waitcnt lgkmcnt(7)
	v_mfma_f32_16x16x32_bf16 v[92:95], v[202:205], v[230:233], v[92:95]
	v_mfma_f32_16x16x32_bf16 v[88:91], v[206:209], v[230:233], v[88:91]
	v_mfma_f32_16x16x32_bf16 v[84:87], v[210:213], v[230:233], v[84:87]
	v_mfma_f32_16x16x32_bf16 v[80:83], v[214:217], v[230:233], v[80:83]
	s_waitcnt vmcnt(8)
	ds_write_b128 v164, v[124:127] offset:24576
	s_waitcnt lgkmcnt(7)
	v_mfma_f32_16x16x32_bf16 v[76:79], v[202:205], v[234:237], v[76:79]
	v_mfma_f32_16x16x32_bf16 v[72:75], v[206:209], v[234:237], v[72:75]
	v_mfma_f32_16x16x32_bf16 v[68:71], v[210:213], v[234:237], v[68:71]
	v_mfma_f32_16x16x32_bf16 v[64:67], v[214:217], v[234:237], v[64:67]
	s_waitcnt vmcnt(7)
	ds_write_b128 v164, v[128:131] offset:28672
	s_waitcnt lgkmcnt(7)
	v_mfma_f32_16x16x32_bf16 v[60:63], v[202:205], v[238:241], v[60:63]
	v_mfma_f32_16x16x32_bf16 v[56:59], v[206:209], v[238:241], v[56:59]
	v_mfma_f32_16x16x32_bf16 v[52:55], v[210:213], v[238:241], v[52:55]
	v_mfma_f32_16x16x32_bf16 v[48:51], v[214:217], v[238:241], v[48:51]
	s_waitcnt vmcnt(7)
	ds_write_b128 v164, v[116:119] offset:40960
	s_waitcnt lgkmcnt(7)
	v_mfma_f32_16x16x32_bf16 v[44:47], v[202:205], v[242:245], v[44:47]
	v_mfma_f32_16x16x32_bf16 v[40:43], v[206:209], v[242:245], v[40:43]
	v_mfma_f32_16x16x32_bf16 v[36:39], v[210:213], v[242:245], v[36:39]
	v_mfma_f32_16x16x32_bf16 v[32:35], v[214:217], v[242:245], v[32:35]
	s_waitcnt vmcnt(6)
	ds_write_b128 v164, v[132:135] offset:45056
	s_waitcnt lgkmcnt(7)
	v_mfma_f32_16x16x32_bf16 v[28:31], v[202:205], v[246:249], v[28:31]
	v_mfma_f32_16x16x32_bf16 v[24:27], v[206:209], v[246:249], v[24:27]
	v_mfma_f32_16x16x32_bf16 v[20:23], v[210:213], v[246:249], v[20:23]
	v_mfma_f32_16x16x32_bf16 v[16:19], v[214:217], v[246:249], v[16:19]
	s_waitcnt lgkmcnt(6)
	v_mfma_f32_16x16x32_bf16 v[12:15], v[202:205], v[250:253], v[12:15]
	v_mfma_f32_16x16x32_bf16 v[8:11], v[206:209], v[250:253], v[8:11]
	v_mfma_f32_16x16x32_bf16 v[4:7], v[210:213], v[250:253], v[4:7]
	v_mfma_f32_16x16x32_bf16 v[0:3], v[214:217], v[250:253], v[0:3]
	s_min_u32 s22, s29, 0x780
	s_lshl_b32 s22, s22, 1
	s_mov_b32 s35, s23
	s_add_i32 s34, s22, 0xc0
	v_lshl_add_u64 v[112:113], v[152:153], 0, s[22:23]
	v_lshl_add_u64 v[116:117], v[154:155], 0, s[22:23]
	v_lshl_add_u64 v[120:121], v[156:157], 0, s[34:35]
	v_lshl_add_u64 v[124:125], v[158:159], 0, s[34:35]
	v_lshl_add_u64 v[128:129], v[160:161], 0, s[34:35]
	v_lshl_add_u64 v[132:133], v[162:163], 0, s[34:35]
	s_waitcnt lgkmcnt(0)
	s_barrier
	global_load_dwordx4 v[112:115], v[112:113], off offset:192
	ds_read_b128 v[202:205], v165 offset:40960
	global_load_dwordx4 v[116:119], v[116:117], off offset:192
	ds_read_b128 v[206:209], v165 offset:41984
	global_load_dwordx4 v[120:123], v[120:121], off
	ds_read_b128 v[210:213], v165 offset:43008
	global_load_dwordx4 v[124:127], v[124:125], off
	ds_read_b128 v[214:217], v165 offset:44032
	global_load_dwordx4 v[128:131], v[128:129], off
	ds_read_b128 v[222:225], v167
	global_load_dwordx4 v[132:135], v[132:133], off
	ds_read_b128 v[226:229], v167 offset:1024
	ds_read_b128 v[230:233], v167 offset:2048
	ds_read_b128 v[234:237], v167 offset:3072
	ds_read_b128 v[238:241], v167 offset:4096
	ds_read_b128 v[242:245], v167 offset:5120
	ds_read_b128 v[246:249], v167 offset:6144
	ds_read_b128 v[250:253], v167 offset:7168
	s_waitcnt lgkmcnt(7)
	v_mfma_f32_16x16x32_bf16 v[148:151], v[202:205], v[222:225], v[148:151]
	v_mfma_f32_16x16x32_bf16 v[144:147], v[206:209], v[222:225], v[144:147]
	v_mfma_f32_16x16x32_bf16 v[140:143], v[210:213], v[222:225], v[140:143]
	v_mfma_f32_16x16x32_bf16 v[136:139], v[214:217], v[222:225], v[136:139]
	s_waitcnt vmcnt(9)
	ds_write_b128 v164, v[170:173]
	s_waitcnt lgkmcnt(7)
	v_mfma_f32_16x16x32_bf16 v[108:111], v[202:205], v[226:229], v[108:111]
	v_mfma_f32_16x16x32_bf16 v[104:107], v[206:209], v[226:229], v[104:107]
	v_mfma_f32_16x16x32_bf16 v[100:103], v[210:213], v[226:229], v[100:103]
	v_mfma_f32_16x16x32_bf16 v[96:99], v[214:217], v[226:229], v[96:99]
	ds_write_b128 v164, v[178:181] offset:4096
	s_waitcnt lgkmcnt(7)
	v_mfma_f32_16x16x32_bf16 v[92:95], v[202:205], v[230:233], v[92:95]
	v_mfma_f32_16x16x32_bf16 v[88:91], v[206:209], v[230:233], v[88:91]
	v_mfma_f32_16x16x32_bf16 v[84:87], v[210:213], v[230:233], v[84:87]
	v_mfma_f32_16x16x32_bf16 v[80:83], v[214:217], v[230:233], v[80:83]
	ds_write_b128 v164, v[182:185] offset:8192
	s_waitcnt lgkmcnt(7)
	v_mfma_f32_16x16x32_bf16 v[76:79], v[202:205], v[234:237], v[76:79]
	v_mfma_f32_16x16x32_bf16 v[72:75], v[206:209], v[234:237], v[72:75]
	v_mfma_f32_16x16x32_bf16 v[68:71], v[210:213], v[234:237], v[68:71]
	v_mfma_f32_16x16x32_bf16 v[64:67], v[214:217], v[234:237], v[64:67]
	s_waitcnt vmcnt(8)
	ds_write_b128 v164, v[186:189] offset:12288
	s_waitcnt lgkmcnt(7)
	v_mfma_f32_16x16x32_bf16 v[60:63], v[202:205], v[238:241], v[60:63]
	v_mfma_f32_16x16x32_bf16 v[56:59], v[206:209], v[238:241], v[56:59]
	v_mfma_f32_16x16x32_bf16 v[52:55], v[210:213], v[238:241], v[52:55]
	v_mfma_f32_16x16x32_bf16 v[48:51], v[214:217], v[238:241], v[48:51]
	s_waitcnt vmcnt(7)
	ds_write_b128 v164, v[190:193] offset:32768
	s_waitcnt lgkmcnt(7)
	v_mfma_f32_16x16x32_bf16 v[44:47], v[202:205], v[242:245], v[44:47]
	v_mfma_f32_16x16x32_bf16 v[40:43], v[206:209], v[242:245], v[40:43]
	v_mfma_f32_16x16x32_bf16 v[36:39], v[210:213], v[242:245], v[36:39]
	v_mfma_f32_16x16x32_bf16 v[32:35], v[214:217], v[242:245], v[32:35]
	s_waitcnt vmcnt(6)
	ds_write_b128 v164, v[198:201] offset:36864
	s_waitcnt lgkmcnt(7)
	v_mfma_f32_16x16x32_bf16 v[28:31], v[202:205], v[246:249], v[28:31]
	v_mfma_f32_16x16x32_bf16 v[24:27], v[206:209], v[246:249], v[24:27]
	v_mfma_f32_16x16x32_bf16 v[20:23], v[210:213], v[246:249], v[20:23]
	v_mfma_f32_16x16x32_bf16 v[16:19], v[214:217], v[246:249], v[16:19]
	s_waitcnt lgkmcnt(6)
	v_mfma_f32_16x16x32_bf16 v[12:15], v[202:205], v[250:253], v[12:15]
	v_mfma_f32_16x16x32_bf16 v[8:11], v[206:209], v[250:253], v[8:11]
	v_mfma_f32_16x16x32_bf16 v[4:7], v[210:213], v[250:253], v[4:7]
	v_mfma_f32_16x16x32_bf16 v[0:3], v[214:217], v[250:253], v[0:3]
	s_add_i32 s25, s25, 2
	s_cmp_lt_u32 s25, 62
	s_mov_b32 s29, s31
	s_waitcnt lgkmcnt(0)
	s_barrier
	s_cbranch_scc1 .LBB0_561
	s_waitcnt vmcnt(5)
	v_mov_b32_e32 v112, v220
	v_readlane_b32 s36, v254, 6
	v_and_b32_e32 v114, 0xffffff80, v112
	v_bfe_u32 v176, v112, 4, 2
	v_add_u32_e32 v114, s28, v114
	v_and_b32_e32 v113, 64, v112
	v_and_or_b32 v180, v112, 15, v114
	v_lshlrev_b32_e32 v112, 2, v176
	v_or3_b32 v178, v112, v113, s24
	v_ashrrev_i32_e32 v179, 31, v178
	v_lshlrev_b64 v[214:215], 2, v[178:179]
	v_readlane_b32 s37, v254, 7
	v_ashrrev_i32_e32 v181, 31, v180
	v_or_b32_e32 v190, 16, v180
	v_lshl_add_u64 v[182:183], s[36:37], 0, v[214:215]
	v_lshlrev_b64 v[216:217], 12, v[180:181]
	v_ashrrev_i32_e32 v191, 31, v190
	v_or_b32_e32 v186, 32, v180
	v_lshl_add_u64 v[112:113], v[182:183], 0, v[216:217]
	v_lshlrev_b64 v[194:195], 12, v[190:191]
	v_ashrrev_i32_e32 v187, 31, v186
	v_or_b32_e32 v184, 48, v180
	global_load_dwordx4 v[198:201], v[112:113], off nt
	global_load_dwordx4 v[202:205], v[112:113], off offset:64 nt
	global_load_dwordx4 v[206:209], v[112:113], off offset:128 nt
	global_load_dwordx4 v[210:213], v[112:113], off offset:192 nt
	v_lshl_add_u64 v[112:113], v[182:183], 0, v[194:195]
	v_lshlrev_b64 v[192:193], 12, v[186:187]
	v_ashrrev_i32_e32 v185, 31, v184
	global_load_dwordx4 v[172:175], v[112:113], off nt
	global_load_dwordx4 v[168:171], v[112:113], off offset:64 nt
	global_load_dwordx4 v[164:167], v[112:113], off offset:128 nt
	global_load_dwordx4 v[160:163], v[112:113], off offset:192 nt
	v_lshl_add_u64 v[112:113], v[182:183], 0, v[192:193]
	v_lshlrev_b64 v[188:189], 12, v[184:185]
	global_load_dwordx4 v[156:159], v[112:113], off nt
	global_load_dwordx4 v[152:155], v[112:113], off offset:64 nt
	global_load_dwordx4 v[132:135], v[112:113], off offset:128 nt
	global_load_dwordx4 v[128:131], v[112:113], off offset:192 nt
	v_lshl_add_u64 v[112:113], v[182:183], 0, v[188:189]
	global_load_dwordx4 v[124:127], v[112:113], off nt
	global_load_dwordx4 v[120:123], v[112:113], off offset:64 nt
	global_load_dwordx4 v[116:119], v[112:113], off offset:128 nt
	s_nop 0
	global_load_dwordx4 v[112:115], v[112:113], off offset:192 nt
	v_cmp_eq_u32_e32 vcc, 0, v176
	v_readlane_b32 s38, v254, 8
	v_readlane_b32 s39, v254, 9
	v_readlane_b32 s40, v254, 10
	v_readlane_b32 s41, v254, 11
	v_readlane_b32 s42, v254, 12
	v_readlane_b32 s43, v254, 13
	v_readlane_b32 s44, v254, 14
	v_readlane_b32 s45, v254, 15
	v_readlane_b32 s46, v254, 16
	v_readlane_b32 s47, v254, 17
	v_readlane_b32 s48, v254, 18
	v_readlane_b32 s49, v254, 19
	v_readlane_b32 s50, v254, 20
	v_readlane_b32 s51, v254, 21
	v_lshl_add_u64 v[216:217], s[70:71], 0, v[216:217]
	s_waitcnt vmcnt(15)
	v_pk_add_f32 v[148:149], v[148:149], v[198:199]
	v_lshl_add_u64 v[214:215], v[216:217], 0, v[214:215]
	v_pk_add_f32 v[150:151], v[150:151], v[200:201]
	v_mul_f32_e32 v176, v149, v149
	global_store_dwordx4 v[214:215], v[148:151], off
	v_cvt_pk_bf16_f32 v198, v148, v149
	v_lshlrev_b64 v[200:201], 11, v[180:181]
	v_cvt_pk_bf16_f32 v199, v150, v151
	v_lshl_add_u64 v[200:201], s[6:7], 0, v[200:201]
	v_pk_fma_f32 v[148:149], v[148:149], v[148:149], v[176:177] op_sel_hi:[1,1,0]
	v_lshl_add_u64 v[200:201], v[178:179], 1, v[200:201]
	v_pk_fma_f32 v[148:149], v[150:151], v[150:151], v[148:149]
	v_mul_f32_e32 v150, v151, v151
	v_pk_add_f32 v[148:149], v[150:151], v[148:149] op_sel_hi:[0,1]
	s_waitcnt vmcnt(15)
	v_pk_add_f32 v[146:147], v[146:147], v[204:205]
	v_pk_add_f32 v[144:145], v[144:145], v[202:203]
	global_store_dwordx2 v[200:201], v[198:199], off
	v_cvt_pk_bf16_f32 v150, v144, v145
	global_store_dwordx4 v[214:215], v[144:147], off offset:64
	v_cvt_pk_bf16_f32 v151, v146, v147
	global_store_dwordx2 v[200:201], v[150:151], off offset:32
	v_mul_f32_e32 v150, v145, v145
	v_pk_fma_f32 v[144:145], v[144:145], v[144:145], v[150:151] op_sel_hi:[1,1,0]
	s_waitcnt vmcnt(17)
	v_pk_add_f32 v[142:143], v[142:143], v[208:209]
	v_pk_fma_f32 v[144:145], v[146:147], v[146:147], v[144:145]
	v_mul_f32_e32 v146, v147, v147
	v_pk_add_f32 v[144:145], v[146:147], v[144:145] op_sel_hi:[0,1]
	v_pk_add_f32 v[140:141], v[140:141], v[206:207]
	global_store_dwordx4 v[214:215], v[140:143], off offset:128
	v_cvt_pk_bf16_f32 v146, v140, v141
	v_cvt_pk_bf16_f32 v147, v142, v143
	global_store_dwordx2 v[200:201], v[146:147], off offset:64
	v_mul_f32_e32 v146, v141, v141
	v_pk_fma_f32 v[140:141], v[140:141], v[140:141], v[146:147] op_sel_hi:[1,1,0]
	s_waitcnt vmcnt(18)
	v_pk_add_f32 v[138:139], v[138:139], v[212:213]
	v_pk_fma_f32 v[140:141], v[142:143], v[142:143], v[140:141]
	v_mul_f32_e32 v142, v143, v143
	v_pk_add_f32 v[140:141], v[142:143], v[140:141] op_sel_hi:[0,1]
	v_pk_add_f32 v[136:137], v[136:137], v[210:211]
	global_store_dwordx4 v[214:215], v[136:139], off offset:192
	v_cvt_pk_bf16_f32 v142, v136, v137
	v_cvt_pk_bf16_f32 v143, v138, v139
	global_store_dwordx2 v[200:201], v[142:143], off offset:96
	v_mul_f32_e32 v142, v137, v137
	v_pk_fma_f32 v[136:137], v[136:137], v[136:137], v[142:143] op_sel_hi:[1,1,0]
	v_pk_add_f32 v[144:145], v[148:149], v[144:145]
	v_pk_fma_f32 v[136:137], v[138:139], v[138:139], v[136:137]
	v_mul_f32_e32 v138, v139, v139
	v_pk_add_f32 v[140:141], v[144:145], v[140:141]
	v_pk_add_f32 v[136:137], v[138:139], v[136:137] op_sel_hi:[0,1]
	v_pk_add_f32 v[136:137], v[140:141], v[136:137]
	s_nop 0
	v_mov_b32_e32 v137, v136
	s_nop 1
	v_permlane32_swap_b32_e32 v136, v137
	v_add_f32_e32 v136, v136, v137
	v_mov_b32_e32 v137, v136
	s_nop 1
	v_permlane16_swap_b32_e32 v136, v137
	s_and_saveexec_b64 s[24:25], vcc
	s_cbranch_execz .LBB0_564
	v_lshl_add_u64 v[138:139], v[180:181], 2, s[10:11]
	v_add_f32_e32 v136, v136, v137
	global_atomic_add_f32 v[138:139], v136, off

.LBB0_634:
	s_min_u32 s31, s29, 0xe0
	s_lshl_b32 s16, s31, 2
	v_lshl_add_u64 v[58:59], v[42:43], 0, s[16:17]
	v_lshl_add_u64 v[92:93], v[48:49], 0, s[16:17]
	s_lshl_b32 s16, s31, 1
	global_load_dwordx4 v[64:67], v[58:59], off offset:16 nt
	global_load_dwordx4 v[68:71], v[58:59], off nt
	v_lshl_add_u64 v[58:59], v[34:35], 0, s[16:17]
	v_lshl_add_u64 v[100:101], v[40:41], 0, s[16:17]
	global_load_dwordx4 v[88:91], v[92:93], off offset:16 nt
	global_load_dwordx4 v[96:99], v[58:59], off
	s_and_b32 s16, s30, 0x80
	global_load_dwordx4 v[92:95], v[92:93], off nt
	v_add_u32_e32 v57, s16, v50
	global_load_dwordx4 v[100:103], v[100:101], off
	v_or_b32_e32 v58, s16, v56
	v_lshl_or_b32 v57, v57, 6, v51
	v_lshl_or_b32 v58, v58, 6, v51
	ds_read_b128 v[104:107], v57
	ds_read_b128 v[108:111], v57 offset:1024
	ds_read_b128 v[112:115], v58 offset:16384
	ds_read_b128 v[116:119], v58 offset:17408
	ds_read_b128 v[120:123], v57 offset:2048
	ds_read_b128 v[124:127], v57 offset:3072
	ds_read_b128 v[128:131], v58 offset:18432
	ds_read_b128 v[132:135], v58 offset:19456
	s_waitcnt lgkmcnt(5)
	v_mfma_f32_16x16x32_bf16 v[84:87], v[112:115], v[104:107], v[84:87]
	s_waitcnt lgkmcnt(4)
	v_mfma_f32_16x16x32_bf16 v[80:83], v[116:119], v[104:107], v[80:83]
	s_waitcnt lgkmcnt(1)
	v_mfma_f32_16x16x32_bf16 v[76:79], v[128:131], v[104:107], v[76:79]
	s_waitcnt lgkmcnt(0)
	v_mfma_f32_16x16x32_bf16 v[72:75], v[132:135], v[104:107], v[72:75]
	v_mfma_f32_16x16x32_bf16 v[60:63], v[112:115], v[108:111], v[60:63]
	v_mfma_f32_16x16x32_bf16 v[52:55], v[116:119], v[108:111], v[52:55]
	v_mfma_f32_16x16x32_bf16 v[44:47], v[128:131], v[108:111], v[44:47]
	v_mfma_f32_16x16x32_bf16 v[36:39], v[132:135], v[108:111], v[36:39]
	v_mfma_f32_16x16x32_bf16 v[28:31], v[112:115], v[120:123], v[28:31]
	v_mfma_f32_16x16x32_bf16 v[24:27], v[116:119], v[120:123], v[24:27]
	v_mfma_f32_16x16x32_bf16 v[20:23], v[128:131], v[120:123], v[20:23]
	v_mfma_f32_16x16x32_bf16 v[16:19], v[132:135], v[120:123], v[16:19]
	v_mfma_f32_16x16x32_bf16 v[12:15], v[112:115], v[124:127], v[12:15]
	v_mfma_f32_16x16x32_bf16 v[8:11], v[116:119], v[124:127], v[8:11]
	v_mfma_f32_16x16x32_bf16 v[4:7], v[128:131], v[124:127], v[4:7]
	v_mfma_f32_16x16x32_bf16 v[0:3], v[132:135], v[124:127], v[0:3]
	s_waitcnt vmcnt(4)
	v_and_b32_sdwa v58, v70, v199 dst_sel:DWORD dst_unused:UNUSED_PAD src0_sel:WORD_1 src1_sel:DWORD
	v_and_b32_sdwa v59, v68, v199 dst_sel:DWORD dst_unused:UNUSED_PAD src0_sel:WORD_1 src1_sel:DWORD
	v_add3_u32 v59, v68, v59, s9
	v_add3_u32 v58, v70, v58, s9
	v_and_b32_sdwa v68, v71, v199 dst_sel:DWORD dst_unused:UNUSED_PAD src0_sel:WORD_1 src1_sel:DWORD
	v_and_b32_sdwa v70, v69, v199 dst_sel:DWORD dst_unused:UNUSED_PAD src0_sel:WORD_1 src1_sel:DWORD
	v_add3_u32 v68, v71, v68, s9
	v_add3_u32 v69, v69, v70, s9
	v_and_b32_e32 v68, 0xffff0000, v68
	v_and_b32_e32 v70, 0xffff0000, v69
	v_or_b32_sdwa v69, v68, v58 dst_sel:DWORD dst_unused:UNUSED_PAD src0_sel:DWORD src1_sel:WORD_1
	v_or_b32_sdwa v68, v70, v59 dst_sel:DWORD dst_unused:UNUSED_PAD src0_sel:DWORD src1_sel:WORD_1
	v_and_b32_sdwa v58, v66, v199 dst_sel:DWORD dst_unused:UNUSED_PAD src0_sel:WORD_1 src1_sel:DWORD
	v_and_b32_sdwa v59, v64, v199 dst_sel:DWORD dst_unused:UNUSED_PAD src0_sel:WORD_1 src1_sel:DWORD
	v_add3_u32 v59, v64, v59, s9
	v_add3_u32 v58, v66, v58, s9
	v_and_b32_sdwa v64, v67, v199 dst_sel:DWORD dst_unused:UNUSED_PAD src0_sel:WORD_1 src1_sel:DWORD
	v_and_b32_sdwa v66, v65, v199 dst_sel:DWORD dst_unused:UNUSED_PAD src0_sel:WORD_1 src1_sel:DWORD
	v_add3_u32 v64, v67, v64, s9
	v_add3_u32 v65, v65, v66, s9
	v_and_b32_e32 v64, 0xffff0000, v64
	v_and_b32_e32 v65, 0xffff0000, v65
	v_or_b32_sdwa v71, v64, v58 dst_sel:DWORD dst_unused:UNUSED_PAD src0_sel:DWORD src1_sel:WORD_1
	v_or_b32_sdwa v70, v65, v59 dst_sel:DWORD dst_unused:UNUSED_PAD src0_sel:DWORD src1_sel:WORD_1
	s_waitcnt vmcnt(1)
	v_and_b32_sdwa v64, v95, v199 dst_sel:DWORD dst_unused:UNUSED_PAD src0_sel:WORD_1 src1_sel:DWORD
	v_and_b32_sdwa v65, v93, v199 dst_sel:DWORD dst_unused:UNUSED_PAD src0_sel:WORD_1 src1_sel:DWORD
	v_and_b32_sdwa v58, v94, v199 dst_sel:DWORD dst_unused:UNUSED_PAD src0_sel:WORD_1 src1_sel:DWORD
	v_and_b32_sdwa v59, v92, v199 dst_sel:DWORD dst_unused:UNUSED_PAD src0_sel:WORD_1 src1_sel:DWORD
	v_add3_u32 v64, v95, v64, s9
	v_add3_u32 v65, v93, v65, s9
	s_xor_b32 s16, s16, 0x80
	v_add3_u32 v59, v92, v59, s9
	v_add3_u32 v58, v94, v58, s9
	v_and_b32_e32 v64, 0xffff0000, v64
	v_and_b32_e32 v66, 0xffff0000, v65
	v_add_u32_e32 v57, s16, v32
	v_or_b32_sdwa v65, v64, v58 dst_sel:DWORD dst_unused:UNUSED_PAD src0_sel:DWORD src1_sel:WORD_1
	v_or_b32_sdwa v64, v66, v59 dst_sel:DWORD dst_unused:UNUSED_PAD src0_sel:DWORD src1_sel:WORD_1
	v_and_b32_sdwa v66, v91, v199 dst_sel:DWORD dst_unused:UNUSED_PAD src0_sel:WORD_1 src1_sel:DWORD
	v_and_b32_sdwa v67, v89, v199 dst_sel:DWORD dst_unused:UNUSED_PAD src0_sel:WORD_1 src1_sel:DWORD
	v_lshl_or_b32 v57, v57, 6, v33
	v_and_b32_sdwa v58, v90, v199 dst_sel:DWORD dst_unused:UNUSED_PAD src0_sel:WORD_1 src1_sel:DWORD
	v_and_b32_sdwa v59, v88, v199 dst_sel:DWORD dst_unused:UNUSED_PAD src0_sel:WORD_1 src1_sel:DWORD
	v_add3_u32 v66, v91, v66, s9
	v_add3_u32 v67, v89, v67, s9
	ds_write_b128 v57, v[68:71]
	v_add3_u32 v59, v88, v59, s9
	v_add3_u32 v58, v90, v58, s9
	v_and_b32_e32 v66, 0xffff0000, v66
	v_and_b32_e32 v68, 0xffff0000, v67
	s_addk_i32 s30, 0x80
	s_add_i32 s29, s29, 32
	v_or_b32_sdwa v67, v66, v58 dst_sel:DWORD dst_unused:UNUSED_PAD src0_sel:DWORD src1_sel:WORD_1
	v_or_b32_sdwa v66, v68, v59 dst_sel:DWORD dst_unused:UNUSED_PAD src0_sel:DWORD src1_sel:WORD_1
	s_cmpk_lg_i32 s30, 0x400
	ds_write_b128 v57, v[64:67] offset:4096
	ds_write_b128 v57, v[96:99] offset:16384
	s_waitcnt vmcnt(0)
	ds_write_b128 v57, v[100:103] offset:20480
	s_waitcnt lgkmcnt(0)
	s_barrier
	s_cbranch_scc1 .LBB0_634
	s_lshl_b64 s[30:31], s[22:23], 11
	v_mov_b32_e32 v118, v220
	s_add_u32 s30, s5, s30
	s_addc_u32 s31, s6, s31
	v_ashrrev_i32_e32 v70, 2, v118
	s_lshl_b64 s[34:35], s[0:1], 11
	v_add_u32_e32 v116, 64, v70
	s_add_u32 s34, s7, s34
	v_ashrrev_i32_e32 v117, 31, v116
	s_addc_u32 s35, s8, s35
	v_lshlrev_b64 v[32:33], 11, v[116:117]
	v_min_i32_e32 v34, 0x7f, v70
	v_lshlrev_b32_e32 v35, 4, v118
	v_lshl_add_u64 v[32:33], s[34:35], 0, v[32:33]
	v_and_b32_e32 v176, 48, v35
	v_ashrrev_i32_e32 v35, 31, v34
	v_ashrrev_i32_e32 v71, 31, v70
	v_min_i32_e32 v40, 0x7f, v116
	v_lshl_add_u64 v[130:131], v[32:33], 0, v[176:177]
	v_lshlrev_b64 v[32:33], 11, v[34:35]
	v_lshlrev_b64 v[42:43], 11, v[70:71]
	v_lshl_add_u64 v[32:33], s[30:31], 0, v[32:33]
	v_ashrrev_i32_e32 v41, 31, v40
	v_lshl_add_u64 v[42:43], s[34:35], 0, v[42:43]
	v_lshl_add_u64 v[132:133], v[32:33], 0, v[176:177]
	v_lshlrev_b64 v[32:33], 11, v[40:41]
	v_lshl_add_u64 v[128:129], v[42:43], 0, v[176:177]
	v_lshl_add_u64 v[32:33], s[30:31], 0, v[32:33]
	global_load_dwordx4 v[88:91], v[132:133], off
	global_load_dwordx4 v[92:95], v[128:129], off
	v_lshl_add_u64 v[134:135], v[32:33], 0, v[176:177]
	global_load_dwordx4 v[96:99], v[130:131], off
	global_load_dwordx4 v[108:111], v[134:135], off
	global_load_dwordx4 v[100:103], v[128:129], off offset:64
	global_load_dwordx4 v[104:107], v[132:133], off offset:64
	global_load_dwordx4 v[112:115], v[130:131], off offset:64
	global_load_dwordx4 v[120:123], v[134:135], off offset:64
	v_lshrrev_b32_e32 v71, 4, v118
	v_lshrrev_b32_e32 v117, 2, v118
	v_sub_u32_e32 v126, 0, v71
	v_and_b32_e32 v119, 15, v118
	v_lshrrev_b32_e32 v124, 1, v118
	v_lshlrev_b32_e32 v125, 6, v118
	v_sub_u32_e32 v117, 0, v117
	v_xor_b32_e32 v118, v118, v126
	v_and_or_b32 v119, v124, s25, v119
	v_xor_b32_e32 v71, v71, v117
	v_lshlrev_b32_e32 v117, 4, v118
	v_lshlrev_b32_e32 v145, 6, v119
	v_lshlrev_b32_e32 v71, 4, v71
	v_and_b32_e32 v117, 48, v117
	v_mov_b32_e32 v32, 0
	v_and_b32_e32 v144, 0x13c0, v125
	v_add_u32_e32 v118, 0x2000, v145
	v_and_b32_e32 v146, 48, v71
	v_lshl_or_b32 v147, v70, 6, v117
	s_mov_b32 s23, 0
	s_mov_b32 s1, -2
	v_mov_b32_e32 v33, v32
	v_mov_b32_e32 v34, v32
	v_mov_b32_e32 v35, v32
	v_mov_b32_e32 v40, v32
	v_mov_b32_e32 v41, v32
	v_mov_b32_e32 v42, v32
	v_mov_b32_e32 v43, v32
	v_mov_b32_e32 v48, v32
	v_mov_b32_e32 v49, v32
	v_mov_b32_e32 v50, v32
	v_mov_b32_e32 v51, v32
	v_mov_b32_e32 v56, v32
	v_mov_b32_e32 v57, v32
	v_mov_b32_e32 v58, v32
	v_mov_b32_e32 v59, v32
	v_mov_b32_e32 v64, v32
	v_mov_b32_e32 v65, v32
	v_mov_b32_e32 v66, v32
	v_mov_b32_e32 v67, v32
	v_mov_b32_e32 v68, v32
	v_mov_b32_e32 v69, v32
	v_lshl_or_b32 v156, v116, 6, v117
	v_or_b32_e32 v157, v146, v144
	v_add_u32_e32 v158, v146, v118
	v_mov_b32_e32 v70, v32
	v_mov_b32_e32 v71, v32
	v_mov_b32_e32 v116, v32
	v_mov_b32_e32 v117, v32
	v_mov_b32_e32 v118, v32
	v_mov_b32_e32 v119, v32
	v_mov_b32_e32 v124, v32
	v_mov_b32_e32 v125, v32
	v_mov_b32_e32 v126, v32
	v_mov_b32_e32 v127, v32
	v_mov_b32_e32 v136, v32
	s_waitcnt vmcnt(6)
	ds_write_b128 v147, v[92:95] offset:16384
	ds_write_b128 v147, v[88:91]
	s_waitcnt vmcnt(5)
	ds_write_b128 v156, v[96:99] offset:16384
	s_waitcnt vmcnt(4)
	ds_write_b128 v156, v[108:111]
	v_mov_b32_e32 v88, v32
	v_mov_b32_e32 v89, v32
	v_mov_b32_e32 v90, v32
	v_mov_b32_e32 v91, v32
	v_mov_b32_e32 v92, v32
	v_mov_b32_e32 v93, v32
	v_mov_b32_e32 v94, v32
	v_mov_b32_e32 v95, v32
	v_mov_b32_e32 v96, v32
	v_mov_b32_e32 v97, v32
	v_mov_b32_e32 v98, v32
	v_mov_b32_e32 v99, v32
	v_mov_b32_e32 v108, v32
	v_mov_b32_e32 v109, v32
	v_mov_b32_e32 v110, v32
	v_mov_b32_e32 v111, v32
	v_mov_b32_e32 v137, v32
	v_mov_b32_e32 v138, v32
	v_mov_b32_e32 v139, v32
	v_mov_b32_e32 v140, v32
	v_mov_b32_e32 v141, v32
	v_mov_b32_e32 v142, v32
	v_mov_b32_e32 v143, v32
	v_mov_b32_e32 v148, v32
	v_mov_b32_e32 v149, v32
	v_mov_b32_e32 v150, v32
	v_mov_b32_e32 v151, v32
	v_mov_b32_e32 v152, v32
	v_mov_b32_e32 v153, v32
	v_mov_b32_e32 v154, v32
	v_mov_b32_e32 v155, v32
	s_waitcnt lgkmcnt(0)
	s_barrier
.LBB0_636:
	s_add_i32 s29, s23, 64
	s_min_u32 s16, s29, 0x3e0
	s_lshl_b32 s16, s16, 1
	v_lshl_add_u64 v[160:161], v[132:133], 0, s[16:17]
	v_lshl_add_u64 v[164:165], v[134:135], 0, s[16:17]
	v_lshl_add_u64 v[168:169], v[128:129], 0, s[16:17]
	v_lshl_add_u64 v[172:173], v[130:131], 0, s[16:17]
	global_load_dwordx4 v[160:163], v[160:161], off
	v_add_u32_e32 v159, v146, v145
	global_load_dwordx4 v[164:167], v[164:165], off
	v_add_u32_e32 v176, v146, v144
	global_load_dwordx4 v[168:171], v[168:169], off
	ds_read_b128 v[178:181], v159
	global_load_dwordx4 v[172:175], v[172:173], off
	ds_read_b128 v[182:185], v159 offset:1024
	ds_read_b128 v[186:189], v176 offset:16384
	ds_read_b128 v[190:193], v176 offset:17408
	ds_read_b128 v[194:197], v159 offset:2048
	ds_read_b128 v[200:203], v159 offset:3072
	ds_read_b128 v[204:207], v176 offset:18432
	ds_read_b128 v[208:211], v176 offset:19456
	s_waitcnt lgkmcnt(5)
	v_mfma_f32_16x16x32_bf16 v[152:155], v[186:189], v[178:181], v[152:155]
	s_waitcnt lgkmcnt(4)
	v_mfma_f32_16x16x32_bf16 v[148:151], v[190:193], v[178:181], v[148:151]
	s_waitcnt lgkmcnt(1)
	v_mfma_f32_16x16x32_bf16 v[140:143], v[204:207], v[178:181], v[140:143]
	s_waitcnt lgkmcnt(0)
	v_mfma_f32_16x16x32_bf16 v[136:139], v[208:211], v[178:181], v[136:139]
	v_mfma_f32_16x16x32_bf16 v[124:127], v[186:189], v[182:185], v[124:127]
	v_mfma_f32_16x16x32_bf16 v[116:119], v[190:193], v[182:185], v[116:119]
	v_mfma_f32_16x16x32_bf16 v[108:111], v[204:207], v[182:185], v[108:111]
	v_mfma_f32_16x16x32_bf16 v[96:99], v[208:211], v[182:185], v[96:99]
	v_mfma_f32_16x16x32_bf16 v[92:95], v[186:189], v[194:197], v[92:95]
	v_mfma_f32_16x16x32_bf16 v[88:91], v[190:193], v[194:197], v[88:91]
	v_mfma_f32_16x16x32_bf16 v[68:71], v[204:207], v[194:197], v[68:71]
	v_mfma_f32_16x16x32_bf16 v[64:67], v[208:211], v[194:197], v[64:67]
	v_mfma_f32_16x16x32_bf16 v[56:59], v[186:189], v[200:203], v[56:59]
	v_mfma_f32_16x16x32_bf16 v[48:51], v[190:193], v[200:203], v[48:51]
	v_mfma_f32_16x16x32_bf16 v[40:43], v[204:207], v[200:203], v[40:43]
	v_mfma_f32_16x16x32_bf16 v[32:35], v[208:211], v[200:203], v[32:35]
	s_min_u32 s16, s23, 0x380
	s_lshl_b32 s16, s16, 1
	s_waitcnt vmcnt(5)
	ds_write_b128 v147, v[100:103] offset:24576
	s_waitcnt vmcnt(4)
	ds_write_b128 v147, v[112:115] offset:28672
	v_lshl_add_u64 v[100:101], v[132:133], 0, s[16:17]
	v_lshl_add_u64 v[102:103], v[134:135], 0, s[16:17]
	v_lshl_add_u64 v[112:113], v[128:129], 0, s[16:17]
	v_lshl_add_u64 v[114:115], v[130:131], 0, s[16:17]
	ds_write_b128 v147, v[104:107] offset:8192
	s_waitcnt vmcnt(4)
	ds_write_b128 v147, v[120:123] offset:12288
	s_waitcnt lgkmcnt(0)
	s_barrier
	global_load_dwordx4 v[104:107], v[100:101], off offset:192
	global_load_dwordx4 v[120:123], v[102:103], off offset:192
	ds_read_b128 v[178:181], v158
	global_load_dwordx4 v[100:103], v[112:113], off offset:192
	ds_read_b128 v[182:185], v157 offset:24576
	global_load_dwordx4 v[112:115], v[114:115], off offset:192
	ds_read_b128 v[186:189], v158 offset:1024
	ds_read_b128 v[190:193], v157 offset:25600
	ds_read_b128 v[194:197], v158 offset:2048
	ds_read_b128 v[200:203], v157 offset:26624
	ds_read_b128 v[204:207], v158 offset:3072
	ds_read_b128 v[208:211], v157 offset:27648
	s_waitcnt lgkmcnt(6)
	v_mfma_f32_16x16x32_bf16 v[152:155], v[182:185], v[178:181], v[152:155]
	s_waitcnt lgkmcnt(4)
	v_mfma_f32_16x16x32_bf16 v[148:151], v[190:193], v[178:181], v[148:151]
	s_waitcnt lgkmcnt(2)
	v_mfma_f32_16x16x32_bf16 v[140:143], v[200:203], v[178:181], v[140:143]
	s_waitcnt lgkmcnt(0)
	v_mfma_f32_16x16x32_bf16 v[136:139], v[208:211], v[178:181], v[136:139]
	v_mfma_f32_16x16x32_bf16 v[124:127], v[182:185], v[186:189], v[124:127]
	v_mfma_f32_16x16x32_bf16 v[116:119], v[190:193], v[186:189], v[116:119]
	v_mfma_f32_16x16x32_bf16 v[108:111], v[200:203], v[186:189], v[108:111]
	v_mfma_f32_16x16x32_bf16 v[96:99], v[208:211], v[186:189], v[96:99]
	v_mfma_f32_16x16x32_bf16 v[92:95], v[182:185], v[194:197], v[92:95]
	v_mfma_f32_16x16x32_bf16 v[88:91], v[190:193], v[194:197], v[88:91]
	v_mfma_f32_16x16x32_bf16 v[68:71], v[200:203], v[194:197], v[68:71]
	v_mfma_f32_16x16x32_bf16 v[64:67], v[208:211], v[194:197], v[64:67]
	v_mfma_f32_16x16x32_bf16 v[56:59], v[182:185], v[204:207], v[56:59]
	v_mfma_f32_16x16x32_bf16 v[48:51], v[190:193], v[204:207], v[48:51]
	v_mfma_f32_16x16x32_bf16 v[40:43], v[200:203], v[204:207], v[40:43]
	v_mfma_f32_16x16x32_bf16 v[32:35], v[208:211], v[204:207], v[32:35]
	s_add_i32 s1, s1, 2
	s_cmp_lt_u32 s1, 30
	s_mov_b32 s23, s29
	s_waitcnt vmcnt(7)
	ds_write_b128 v147, v[160:163]
	s_waitcnt vmcnt(6)
	ds_write_b128 v156, v[164:167]
	s_waitcnt vmcnt(5)
	ds_write_b128 v147, v[168:171] offset:16384
	s_waitcnt vmcnt(4)
	ds_write_b128 v156, v[172:175] offset:16384
	s_waitcnt lgkmcnt(0)
	s_barrier
	s_cbranch_scc1 .LBB0_636
	s_waitcnt vmcnt(1)
	v_mov_b32_e32 v102, v220
	s_nop 0
	v_ashrrev_i32_e32 v100, 1, v102
	v_and_b32_e32 v100, 0xffffffc0, v100
	v_add_u32_e32 v100, s22, v100
	v_and_or_b32 v192, v102, 15, v100
	v_ashrrev_i32_e32 v193, 31, v192
	v_lshl_add_u64 v[100:101], v[192:193], 2, s[10:11]
	global_load_dword v224, v[100:101], off
	v_bfe_u32 v100, v102, 4, 2
	v_and_b32_e32 v101, 64, v102
	v_lshlrev_b32_e32 v102, 2, v100
	v_or3_b32 v182, v102, v101, s0
	v_ashrrev_i32_e32 v183, 31, v182
	v_cmp_eq_u32_e32 vcc, 0, v100
	v_lshlrev_b64 v[100:101], 2, v[182:183]
	v_lshl_add_u64 v[102:103], s[70:71], 0, v[100:101]
	v_lshlrev_b64 v[104:105], 12, v[192:193]
	v_lshl_add_u64 v[106:107], v[102:103], 0, v[104:105]
	global_load_dwordx4 v[206:209], v[106:107], off offset:64
	global_load_dwordx4 v[202:205], v[106:107], off
	v_or_b32_e32 v188, 16, v192
	v_or_b32_e32 v184, 32, v192
	v_or_b32_e32 v178, 48, v192
	v_lshl_add_u64 v[104:105], s[70:71], 0, v[104:105]
	v_ashrrev_i32_e32 v189, 31, v188
	v_ashrrev_i32_e32 v185, 31, v184
	v_ashrrev_i32_e32 v179, 31, v178
	v_lshl_add_u64 v[196:197], v[104:105], 0, v[100:101]
	v_lshlrev_b64 v[218:219], 11, v[192:193]
	s_waitcnt vmcnt(3)
	v_lshl_add_u64 v[112:113], v[188:189], 2, s[10:11]
	v_lshlrev_b64 v[194:195], 12, v[188:189]
	v_lshl_add_u64 v[114:115], v[184:185], 2, s[10:11]
	v_lshlrev_b64 v[190:191], 12, v[184:185]
	v_lshlrev_b64 v[186:187], 12, v[178:179]
	v_lshlrev_b64 v[180:181], 1, v[182:183]
	v_lshl_add_u64 v[120:121], v[178:179], 2, s[10:11]
	v_lshl_add_u64 v[122:123], s[12:13], 0, v[218:219]
	global_load_dword v201, v[112:113], off
	v_lshl_add_u64 v[112:113], v[102:103], 0, v[194:195]
	global_load_dword v200, v[114:115], off
	v_lshl_add_u64 v[114:115], v[102:103], 0, v[190:191]
	v_lshl_add_u64 v[102:103], v[102:103], 0, v[186:187]
	global_load_dword v176, v[120:121], off
	v_lshl_add_u64 v[222:223], v[122:123], 0, v[180:181]
	global_load_dwordx4 v[210:213], v[106:107], off offset:128
	global_load_dwordx4 v[214:217], v[106:107], off offset:192
	global_load_dwordx4 v[172:175], v[112:113], off
	global_load_dwordx4 v[168:171], v[112:113], off offset:64
	global_load_dwordx4 v[164:167], v[112:113], off offset:128
	global_load_dwordx4 v[160:163], v[112:113], off offset:192
	global_load_dwordx4 v[156:159], v[114:115], off
	global_load_dwordx4 v[144:147], v[114:115], off offset:64
	global_load_dwordx4 v[132:135], v[114:115], off offset:128
	global_load_dwordx4 v[128:131], v[114:115], off offset:192
	s_waitcnt vmcnt(15)
	v_fmamk_f32 v100, v224, 0x3a800000, v198
	v_mul_f32_e32 v101, 0x4b800000, v100
	v_cmp_gt_f32_e64 s[0:1], s26, v100
	s_nop 1
	v_cndmask_b32_e64 v100, v100, v101, s[0:1]
	v_rsq_f32_e32 v224, v100
	global_load_dwordx4 v[120:123], v[102:103], off
	global_load_dwordx4 v[112:115], v[102:103], off offset:64
	global_load_dwordx4 v[104:107], v[102:103], off offset:128
	s_nop 0
	global_load_dwordx4 v[100:103], v[102:103], off offset:192
	v_mul_f32_e32 v225, 0x45800000, v224
	v_cndmask_b32_e64 v224, v224, v225, s[0:1]
	v_mul_f32_e32 v154, v154, v224
	v_mul_f32_e32 v155, v155, v224
	v_mul_f32_e32 v150, v150, v224
	v_mul_f32_e32 v151, v151, v224
	v_mul_f32_e32 v154, 0xbfb8aa3b, v154
	v_mul_f32_e32 v155, 0xbfb8aa3b, v155
	v_mul_f32_e32 v150, 0xbfb8aa3b, v150
	v_mul_f32_e32 v151, 0xbfb8aa3b, v151
	v_exp_f32_e32 v154, v154
	v_exp_f32_e32 v155, v155
	v_exp_f32_e32 v150, v150
	v_exp_f32_e32 v151, v151
	v_mul_f32_e32 v152, v152, v224
	v_mul_f32_e32 v153, v153, v224
	v_mul_f32_e32 v148, v148, v224
	v_mul_f32_e32 v149, v149, v224
	v_mul_f32_e32 v152, 0xbfb8aa3b, v152
	v_mul_f32_e32 v153, 0xbfb8aa3b, v153
	v_mul_f32_e32 v148, 0xbfb8aa3b, v148
	v_mul_f32_e32 v149, 0xbfb8aa3b, v149
	v_add_f32_e32 v154, 1.0, v154
	v_add_f32_e32 v155, 1.0, v155
	v_add_f32_e32 v227, 1.0, v150
	v_add_f32_e32 v228, 1.0, v151
	v_exp_f32_e32 v152, v152
	v_exp_f32_e32 v153, v153
	v_exp_f32_e32 v148, v148
	v_exp_f32_e32 v149, v149
	v_rcp_f32_e32 v150, v154
	v_rcp_f32_e32 v151, v155
	v_rcp_f32_e32 v154, v227
	v_rcp_f32_e32 v155, v228
	v_mul_f32_e32 v140, v140, v224
	v_mul_f32_e32 v140, 0xbfb8aa3b, v140
	v_add_f32_e32 v152, 1.0, v152
	v_add_f32_e32 v153, 1.0, v153
	v_add_f32_e32 v225, 1.0, v148
	v_add_f32_e32 v226, 1.0, v149
	s_waitcnt vmcnt(18)
	v_pk_fma_f32 v[82:83], v[82:83], v[154:155], v[208:209]
	v_exp_f32_e32 v154, v140
	v_mul_f32_e32 v140, v141, v224
	v_rcp_f32_e32 v148, v152
	v_rcp_f32_e32 v149, v153
	v_rcp_f32_e32 v152, v225
	v_rcp_f32_e32 v153, v226
	v_mul_f32_e32 v140, 0xbfb8aa3b, v140
	v_mul_f32_e32 v142, v142, v224
	v_exp_f32_e32 v141, v140
	v_mul_f32_e32 v142, 0xbfb8aa3b, v142
	v_mul_f32_e32 v143, v143, v224
	v_exp_f32_e32 v142, v142
	v_mul_f32_e32 v143, 0xbfb8aa3b, v143
	v_exp_f32_e32 v143, v143
	s_waitcnt vmcnt(17)
	v_pk_fma_f32 v[84:85], v[84:85], v[148:149], v[202:203]
	v_pk_fma_f32 v[80:81], v[80:81], v[152:153], v[206:207]
	v_mul_f32_e32 v148, v85, v85
	v_mul_f32_e32 v152, v81, v81
	v_add_f32_e32 v141, 1.0, v141
	v_pk_fma_f32 v[86:87], v[86:87], v[150:151], v[204:205]
	v_pk_fma_f32 v[148:149], v[84:85], v[84:85], v[148:149] op_sel_hi:[1,1,0]
	v_pk_fma_f32 v[152:153], v[80:81], v[80:81], v[152:153] op_sel_hi:[1,1,0]
	v_rcp_f32_e32 v155, v141
	v_add_f32_e32 v141, 1.0, v142
	v_mul_f32_e32 v150, v87, v87
	v_pk_fma_f32 v[148:149], v[86:87], v[86:87], v[148:149]
	v_pk_fma_f32 v[152:153], v[82:83], v[82:83], v[152:153]
	v_mul_f32_e32 v140, v83, v83
	v_rcp_f32_e32 v142, v141
	v_add_f32_e32 v141, 1.0, v143
	v_mul_f32_e32 v136, v136, v224
	v_pk_add_f32 v[148:149], v[150:151], v[148:149] op_sel_hi:[0,1]
	v_rcp_f32_e32 v143, v141
	v_pk_add_f32 v[140:141], v[140:141], v[152:153] op_sel_hi:[0,1]
	v_mul_f32_e32 v136, 0xbfb8aa3b, v136
	v_pk_add_f32 v[140:141], v[148:149], v[140:141]
	v_exp_f32_e32 v148, v136
	v_mul_f32_e32 v136, v137, v224
	v_mul_f32_e32 v136, 0xbfb8aa3b, v136
	v_mul_f32_e32 v138, v138, v224
	v_exp_f32_e32 v137, v136
	v_mul_f32_e32 v138, 0xbfb8aa3b, v138
	v_mul_f32_e32 v139, v139, v224
	v_add_f32_e32 v154, 1.0, v154
	v_exp_f32_e32 v138, v138
	v_mul_f32_e32 v139, 0xbfb8aa3b, v139
	v_rcp_f32_e32 v154, v154
	v_exp_f32_e32 v139, v139
	v_add_f32_e32 v137, 1.0, v137
	v_add_f32_e32 v148, 1.0, v148
	v_rcp_f32_e32 v149, v137
	v_add_f32_e32 v137, 1.0, v138
	s_waitcnt vmcnt(13)
	v_pk_fma_f32 v[76:77], v[76:77], v[154:155], v[210:211]
	v_rcp_f32_e32 v148, v148
	v_rcp_f32_e32 v138, v137
	v_add_f32_e32 v137, 1.0, v139
	v_pk_fma_f32 v[78:79], v[78:79], v[142:143], v[212:213]
	v_mul_f32_e32 v142, v77, v77
	v_rcp_f32_e32 v139, v137
	v_pk_fma_f32 v[142:143], v[76:77], v[76:77], v[142:143] op_sel_hi:[1,1,0]
	v_mul_f32_e32 v136, v79, v79
	v_pk_fma_f32 v[142:143], v[78:79], v[78:79], v[142:143]
	v_lshl_add_u64 v[150:151], s[72:73], 0, v[218:219]
	v_pk_add_f32 v[136:137], v[136:137], v[142:143] op_sel_hi:[0,1]
	s_waitcnt vmcnt(12)
	v_pk_fma_f32 v[72:73], v[72:73], v[148:149], v[214:215]
	v_lshl_add_u64 v[150:151], v[150:151], 0, v[180:181]
	v_pk_add_f32 v[136:137], v[136:137], v[140:141]
	v_pk_fma_f32 v[74:75], v[74:75], v[138:139], v[216:217]
	v_and_b32_sdwa v138, v86, v199 dst_sel:DWORD dst_unused:UNUSED_PAD src0_sel:WORD_1 src1_sel:DWORD
	v_and_b32_sdwa v139, v84, v199 dst_sel:DWORD dst_unused:UNUSED_PAD src0_sel:WORD_1 src1_sel:DWORD
	global_store_dwordx4 v[196:197], v[84:87], off
	s_nop 1
	v_add3_u32 v84, v84, v139, s9
	v_add3_u32 v86, v86, v138, s9
	v_and_b32_sdwa v138, v87, v199 dst_sel:DWORD dst_unused:UNUSED_PAD src0_sel:WORD_1 src1_sel:DWORD
	v_and_b32_sdwa v139, v85, v199 dst_sel:DWORD dst_unused:UNUSED_PAD src0_sel:WORD_1 src1_sel:DWORD
	v_add3_u32 v87, v87, v138, s9
	v_add3_u32 v85, v85, v139, s9
	v_and_b32_e32 v87, 0xffff0000, v87
	v_and_b32_e32 v138, 0xffff0000, v85
	v_or_b32_sdwa v85, v87, v86 dst_sel:DWORD dst_unused:UNUSED_PAD src0_sel:DWORD src1_sel:WORD_1
	v_or_b32_sdwa v84, v138, v84 dst_sel:DWORD dst_unused:UNUSED_PAD src0_sel:DWORD src1_sel:WORD_1
	global_store_dwordx2 v[222:223], v[84:85], off
	global_store_dwordx4 v[196:197], v[80:83], off offset:64
	v_and_b32_sdwa v84, v82, v199 dst_sel:DWORD dst_unused:UNUSED_PAD src0_sel:WORD_1 src1_sel:DWORD
	v_and_b32_sdwa v85, v80, v199 dst_sel:DWORD dst_unused:UNUSED_PAD src0_sel:WORD_1 src1_sel:DWORD
	v_add3_u32 v82, v82, v84, s9
	v_and_b32_sdwa v84, v83, v199 dst_sel:DWORD dst_unused:UNUSED_PAD src0_sel:WORD_1 src1_sel:DWORD
	v_add3_u32 v80, v80, v85, s9
	v_and_b32_sdwa v85, v81, v199 dst_sel:DWORD dst_unused:UNUSED_PAD src0_sel:WORD_1 src1_sel:DWORD
	v_add3_u32 v83, v83, v84, s9
	v_add3_u32 v81, v81, v85, s9
	v_and_b32_e32 v83, 0xffff0000, v83
	v_and_b32_e32 v84, 0xffff0000, v81
	v_or_b32_sdwa v81, v83, v82 dst_sel:DWORD dst_unused:UNUSED_PAD src0_sel:DWORD src1_sel:WORD_1
	v_add_co_u32_e64 v82, s[0:1], s27, v150
	v_or_b32_sdwa v80, v84, v80 dst_sel:DWORD dst_unused:UNUSED_PAD src0_sel:DWORD src1_sel:WORD_1
	s_nop 0
	v_addc_co_u32_e64 v83, s[0:1], 0, v151, s[0:1]
	global_store_dwordx2 v[82:83], v[80:81], off offset:32
	global_store_dwordx4 v[196:197], v[76:79], off offset:128
	v_and_b32_sdwa v80, v78, v199 dst_sel:DWORD dst_unused:UNUSED_PAD src0_sel:WORD_1 src1_sel:DWORD
	v_and_b32_sdwa v81, v76, v199 dst_sel:DWORD dst_unused:UNUSED_PAD src0_sel:WORD_1 src1_sel:DWORD
	v_add3_u32 v76, v76, v81, s9
	v_add3_u32 v78, v78, v80, s9
	v_and_b32_sdwa v80, v79, v199 dst_sel:DWORD dst_unused:UNUSED_PAD src0_sel:WORD_1 src1_sel:DWORD
	v_and_b32_sdwa v81, v77, v199 dst_sel:DWORD dst_unused:UNUSED_PAD src0_sel:WORD_1 src1_sel:DWORD
	v_add3_u32 v79, v79, v80, s9
	v_add3_u32 v77, v77, v81, s9
	v_and_b32_e32 v79, 0xffff0000, v79
	v_and_b32_e32 v80, 0xffff0000, v77
	v_or_b32_sdwa v77, v79, v78 dst_sel:DWORD dst_unused:UNUSED_PAD src0_sel:DWORD src1_sel:WORD_1
	v_or_b32_sdwa v76, v80, v76 dst_sel:DWORD dst_unused:UNUSED_PAD src0_sel:DWORD src1_sel:WORD_1
	global_store_dwordx2 v[82:83], v[76:77], off offset:64
	global_store_dwordx4 v[196:197], v[72:75], off offset:192
	v_and_b32_sdwa v77, v72, v199 dst_sel:DWORD dst_unused:UNUSED_PAD src0_sel:WORD_1 src1_sel:DWORD
	v_add3_u32 v78, v72, v77, s9
	v_and_b32_sdwa v77, v75, v199 dst_sel:DWORD dst_unused:UNUSED_PAD src0_sel:WORD_1 src1_sel:DWORD
	v_and_b32_sdwa v79, v73, v199 dst_sel:DWORD dst_unused:UNUSED_PAD src0_sel:WORD_1 src1_sel:DWORD
	v_and_b32_sdwa v76, v74, v199 dst_sel:DWORD dst_unused:UNUSED_PAD src0_sel:WORD_1 src1_sel:DWORD
	v_add3_u32 v77, v75, v77, s9
	v_add3_u32 v79, v73, v79, s9
	v_add3_u32 v76, v74, v76, s9
	v_and_b32_e32 v77, 0xffff0000, v77
	v_and_b32_e32 v79, 0xffff0000, v79
	v_or_b32_sdwa v77, v77, v76 dst_sel:DWORD dst_unused:UNUSED_PAD src0_sel:DWORD src1_sel:WORD_1
	v_or_b32_sdwa v76, v79, v78 dst_sel:DWORD dst_unused:UNUSED_PAD src0_sel:DWORD src1_sel:WORD_1
	global_store_dwordx2 v[82:83], v[76:77], off offset:96
	v_mul_f32_e32 v76, v73, v73
	v_pk_fma_f32 v[72:73], v[72:73], v[72:73], v[76:77] op_sel_hi:[1,1,0]
	s_nop 0
	v_pk_fma_f32 v[72:73], v[74:75], v[74:75], v[72:73]
	v_mul_f32_e32 v74, v75, v75
	v_pk_add_f32 v[72:73], v[74:75], v[72:73] op_sel_hi:[0,1]
	v_pk_add_f32 v[72:73], v[72:73], v[136:137]
	s_nop 0
	v_mov_b32_e32 v73, v72
	s_nop 1
	v_permlane32_swap_b32_e32 v72, v73
	v_add_f32_e32 v72, v72, v73
	v_mov_b32_e32 v73, v72
	s_nop 1
	v_permlane16_swap_b32_e32 v72, v73
	s_and_saveexec_b64 s[0:1], vcc
	s_cbranch_execz .LBB0_639
	v_lshl_add_u64 v[74:75], v[192:193], 2, s[14:15]
	v_add_f32_e32 v72, v72, v73
	global_atomic_add_f32 v[74:75], v72, off

.LBB0_706:
	s_add_i32 s11, s10, 64
	s_min_u32 s13, s11, 0x3e0
	s_lshl_b32 s16, s13, 1
	v_lshl_add_u64 v[172:173], v[154:155], 0, s[16:17]
	v_lshl_add_u64 v[176:177], v[158:159], 0, s[16:17]
	v_lshl_add_u64 v[180:181], v[160:161], 0, s[16:17]
	v_lshl_add_u64 v[184:185], v[162:163], 0, s[16:17]
	v_lshl_add_u64 v[188:189], v[156:157], 0, s[16:17]
	v_lshl_add_u64 v[192:193], v[164:165], 0, s[16:17]
	global_load_dwordx4 v[172:175], v[172:173], off
	ds_read_b128 v[196:199], v171 offset:32768
	global_load_dwordx4 v[176:179], v[176:177], off
	ds_read_b128 v[200:203], v171 offset:33792
	global_load_dwordx4 v[180:183], v[180:181], off
	ds_read_b128 v[204:207], v171 offset:34816
	global_load_dwordx4 v[184:187], v[184:185], off
	ds_read_b128 v[208:211], v171 offset:35840
	global_load_dwordx4 v[188:191], v[188:189], off
	ds_read_b128 v[212:215], v169
	global_load_dwordx4 v[192:195], v[192:193], off
	ds_read_b128 v[216:219], v169 offset:1024
	ds_read_b128 v[222:225], v169 offset:2048
	ds_read_b128 v[226:229], v169 offset:3072
	ds_read_b128 v[230:233], v169 offset:4096
	ds_read_b128 v[234:237], v169 offset:5120
	ds_read_b128 v[238:241], v169 offset:6144
	ds_read_b128 v[242:245], v169 offset:7168
	s_waitcnt lgkmcnt(7)
	v_mfma_f32_16x16x32_bf16 v[148:151], v[196:199], v[212:215], v[148:151]
	v_mfma_f32_16x16x32_bf16 v[144:147], v[200:203], v[212:215], v[144:147]
	v_mfma_f32_16x16x32_bf16 v[140:143], v[204:207], v[212:215], v[140:143]
	v_mfma_f32_16x16x32_bf16 v[136:139], v[208:211], v[212:215], v[136:139]
	s_waitcnt vmcnt(11)
	ds_write_b128 v152, v[112:115] offset:16384
	s_waitcnt lgkmcnt(7)
	v_mfma_f32_16x16x32_bf16 v[108:111], v[196:199], v[216:219], v[108:111]
	v_mfma_f32_16x16x32_bf16 v[104:107], v[200:203], v[216:219], v[104:107]
	v_mfma_f32_16x16x32_bf16 v[100:103], v[204:207], v[216:219], v[100:103]
	v_mfma_f32_16x16x32_bf16 v[96:99], v[208:211], v[216:219], v[96:99]
	s_waitcnt vmcnt(9)
	ds_write_b128 v152, v[120:123] offset:20480
	s_waitcnt lgkmcnt(7)
	v_mfma_f32_16x16x32_bf16 v[92:95], v[196:199], v[222:225], v[92:95]
	v_mfma_f32_16x16x32_bf16 v[88:91], v[200:203], v[222:225], v[88:91]
	v_mfma_f32_16x16x32_bf16 v[84:87], v[204:207], v[222:225], v[84:87]
	v_mfma_f32_16x16x32_bf16 v[80:83], v[208:211], v[222:225], v[80:83]
	s_waitcnt vmcnt(8)
	ds_write_b128 v152, v[124:127] offset:24576
	s_waitcnt lgkmcnt(7)
	v_mfma_f32_16x16x32_bf16 v[76:79], v[196:199], v[226:229], v[76:79]
	v_mfma_f32_16x16x32_bf16 v[72:75], v[200:203], v[226:229], v[72:75]
	v_mfma_f32_16x16x32_bf16 v[68:71], v[204:207], v[226:229], v[68:71]
	v_mfma_f32_16x16x32_bf16 v[64:67], v[208:211], v[226:229], v[64:67]
	s_waitcnt vmcnt(7)
	ds_write_b128 v152, v[128:131] offset:28672
	s_waitcnt lgkmcnt(7)
	v_mfma_f32_16x16x32_bf16 v[60:63], v[196:199], v[230:233], v[60:63]
	v_mfma_f32_16x16x32_bf16 v[56:59], v[200:203], v[230:233], v[56:59]
	v_mfma_f32_16x16x32_bf16 v[52:55], v[204:207], v[230:233], v[52:55]
	v_mfma_f32_16x16x32_bf16 v[48:51], v[208:211], v[230:233], v[48:51]
	s_waitcnt vmcnt(7)
	ds_write_b128 v152, v[116:119] offset:40960
	s_waitcnt lgkmcnt(7)
	v_mfma_f32_16x16x32_bf16 v[44:47], v[196:199], v[234:237], v[44:47]
	v_mfma_f32_16x16x32_bf16 v[40:43], v[200:203], v[234:237], v[40:43]
	v_mfma_f32_16x16x32_bf16 v[36:39], v[204:207], v[234:237], v[36:39]
	v_mfma_f32_16x16x32_bf16 v[32:35], v[208:211], v[234:237], v[32:35]
	s_waitcnt vmcnt(6)
	ds_write_b128 v152, v[132:135] offset:45056
	s_waitcnt lgkmcnt(7)
	v_mfma_f32_16x16x32_bf16 v[28:31], v[196:199], v[238:241], v[28:31]
	v_mfma_f32_16x16x32_bf16 v[24:27], v[200:203], v[238:241], v[24:27]
	v_mfma_f32_16x16x32_bf16 v[20:23], v[204:207], v[238:241], v[20:23]
	v_mfma_f32_16x16x32_bf16 v[16:19], v[208:211], v[238:241], v[16:19]
	s_waitcnt lgkmcnt(6)
	v_mfma_f32_16x16x32_bf16 v[12:15], v[196:199], v[242:245], v[12:15]
	v_mfma_f32_16x16x32_bf16 v[8:11], v[200:203], v[242:245], v[8:11]
	v_mfma_f32_16x16x32_bf16 v[4:7], v[204:207], v[242:245], v[4:7]
	v_mfma_f32_16x16x32_bf16 v[0:3], v[208:211], v[242:245], v[0:3]
	s_min_u32 s10, s10, 0x380
	s_lshl_b32 s16, s10, 1
	s_mov_b32 s27, s17
	s_add_i32 s26, s16, 0xc0
	v_lshl_add_u64 v[112:113], v[154:155], 0, s[16:17]
	v_lshl_add_u64 v[116:117], v[156:157], 0, s[16:17]
	v_lshl_add_u64 v[120:121], v[158:159], 0, s[26:27]
	v_lshl_add_u64 v[124:125], v[160:161], 0, s[26:27]
	v_lshl_add_u64 v[128:129], v[162:163], 0, s[26:27]
	v_lshl_add_u64 v[132:133], v[164:165], 0, s[26:27]
	s_waitcnt lgkmcnt(0)
	s_barrier
	global_load_dwordx4 v[112:115], v[112:113], off offset:192
	ds_read_b128 v[196:199], v168 offset:40960
	global_load_dwordx4 v[116:119], v[116:117], off offset:192
	ds_read_b128 v[200:203], v168 offset:41984
	global_load_dwordx4 v[120:123], v[120:121], off
	ds_read_b128 v[204:207], v168 offset:43008
	global_load_dwordx4 v[124:127], v[124:125], off
	ds_read_b128 v[208:211], v168 offset:44032
	global_load_dwordx4 v[128:131], v[128:129], off
	ds_read_b128 v[212:215], v170
	global_load_dwordx4 v[132:135], v[132:133], off
	ds_read_b128 v[216:219], v170 offset:1024
	ds_read_b128 v[222:225], v170 offset:2048
	ds_read_b128 v[226:229], v170 offset:3072
	ds_read_b128 v[230:233], v170 offset:4096
	ds_read_b128 v[234:237], v170 offset:5120
	ds_read_b128 v[238:241], v170 offset:6144
	ds_read_b128 v[242:245], v170 offset:7168
	s_waitcnt lgkmcnt(7)
	v_mfma_f32_16x16x32_bf16 v[148:151], v[196:199], v[212:215], v[148:151]
	v_mfma_f32_16x16x32_bf16 v[144:147], v[200:203], v[212:215], v[144:147]
	v_mfma_f32_16x16x32_bf16 v[140:143], v[204:207], v[212:215], v[140:143]
	v_mfma_f32_16x16x32_bf16 v[136:139], v[208:211], v[212:215], v[136:139]
	s_waitcnt vmcnt(11)
	ds_write_b128 v152, v[172:175]
	s_waitcnt lgkmcnt(7)
	v_mfma_f32_16x16x32_bf16 v[108:111], v[196:199], v[216:219], v[108:111]
	v_mfma_f32_16x16x32_bf16 v[104:107], v[200:203], v[216:219], v[104:107]
	v_mfma_f32_16x16x32_bf16 v[100:103], v[204:207], v[216:219], v[100:103]
	v_mfma_f32_16x16x32_bf16 v[96:99], v[208:211], v[216:219], v[96:99]
	s_waitcnt vmcnt(10)
	ds_write_b128 v152, v[176:179] offset:4096
	s_waitcnt lgkmcnt(7)
	v_mfma_f32_16x16x32_bf16 v[92:95], v[196:199], v[222:225], v[92:95]
	v_mfma_f32_16x16x32_bf16 v[88:91], v[200:203], v[222:225], v[88:91]
	v_mfma_f32_16x16x32_bf16 v[84:87], v[204:207], v[222:225], v[84:87]
	v_mfma_f32_16x16x32_bf16 v[80:83], v[208:211], v[222:225], v[80:83]
	s_waitcnt vmcnt(9)
	ds_write_b128 v152, v[180:183] offset:8192
	s_waitcnt lgkmcnt(7)
	v_mfma_f32_16x16x32_bf16 v[76:79], v[196:199], v[226:229], v[76:79]
	v_mfma_f32_16x16x32_bf16 v[72:75], v[200:203], v[226:229], v[72:75]
	v_mfma_f32_16x16x32_bf16 v[68:71], v[204:207], v[226:229], v[68:71]
	v_mfma_f32_16x16x32_bf16 v[64:67], v[208:211], v[226:229], v[64:67]
	s_waitcnt vmcnt(8)
	ds_write_b128 v152, v[184:187] offset:12288
	s_waitcnt lgkmcnt(7)
	v_mfma_f32_16x16x32_bf16 v[60:63], v[196:199], v[230:233], v[60:63]
	v_mfma_f32_16x16x32_bf16 v[56:59], v[200:203], v[230:233], v[56:59]
	v_mfma_f32_16x16x32_bf16 v[52:55], v[204:207], v[230:233], v[52:55]
	v_mfma_f32_16x16x32_bf16 v[48:51], v[208:211], v[230:233], v[48:51]
	s_waitcnt vmcnt(7)
	ds_write_b128 v152, v[188:191] offset:32768
	s_waitcnt lgkmcnt(7)
	v_mfma_f32_16x16x32_bf16 v[44:47], v[196:199], v[234:237], v[44:47]
	v_mfma_f32_16x16x32_bf16 v[40:43], v[200:203], v[234:237], v[40:43]
	v_mfma_f32_16x16x32_bf16 v[36:39], v[204:207], v[234:237], v[36:39]
	v_mfma_f32_16x16x32_bf16 v[32:35], v[208:211], v[234:237], v[32:35]
	s_waitcnt vmcnt(6)
	ds_write_b128 v152, v[192:195] offset:36864
	s_waitcnt lgkmcnt(7)
	v_mfma_f32_16x16x32_bf16 v[28:31], v[196:199], v[238:241], v[28:31]
	v_mfma_f32_16x16x32_bf16 v[24:27], v[200:203], v[238:241], v[24:27]
	v_mfma_f32_16x16x32_bf16 v[20:23], v[204:207], v[238:241], v[20:23]
	v_mfma_f32_16x16x32_bf16 v[16:19], v[208:211], v[238:241], v[16:19]
	s_waitcnt lgkmcnt(6)
	v_mfma_f32_16x16x32_bf16 v[12:15], v[196:199], v[242:245], v[12:15]
	v_mfma_f32_16x16x32_bf16 v[8:11], v[200:203], v[242:245], v[8:11]
	v_mfma_f32_16x16x32_bf16 v[4:7], v[204:207], v[242:245], v[4:7]
	v_mfma_f32_16x16x32_bf16 v[0:3], v[208:211], v[242:245], v[0:3]
	s_add_i32 s1, s1, 2
	s_cmp_lt_u32 s1, 30
	s_mov_b32 s10, s11
	s_waitcnt lgkmcnt(0)
	s_barrier
	s_cbranch_scc1 .LBB0_706
	s_waitcnt vmcnt(4)
	v_mov_b32_e32 v116, v220
	s_nop 0
	v_and_b32_e32 v112, 0xffffff80, v116
	v_add_u32_e32 v117, s0, v112
	v_and_or_b32 v114, v116, 15, v117
	v_ashrrev_i32_e32 v115, 31, v114
	v_lshl_add_u64 v[112:113], v[114:115], 2, s[14:15]
	global_load_dword v122, v[112:113], off
	v_and_b32_e32 v112, 64, v116
	v_lshrrev_b32_e32 v115, 1, v116
	v_ashrrev_i32_e32 v116, 14, v117
	v_ashrrev_i32_e32 v117, 31, v116
	v_lshlrev_b32_e32 v152, 1, v112
	v_or_b32_e32 v118, 16, v114
	v_lshlrev_b64 v[116:117], 16, v[116:117]
	v_lshl_add_u64 v[112:113], s[38:39], 0, v[152:153]
	v_and_b32_e32 v152, 24, v115
	v_ashrrev_i32_e32 v119, 31, v118
	v_lshl_or_b32 v115, s12, 14, v116
	s_waitcnt vmcnt(4)
	v_lshl_add_u64 v[120:121], v[118:119], 2, s[14:15]
	v_lshl_add_u64 v[112:113], v[112:113], 0, v[152:153]
	s_waitcnt vmcnt(0)
	v_fmamk_f32 v116, v122, 0x3a800000, v166
	v_mul_f32_e32 v119, 0x4b800000, v116
	v_cmp_gt_f32_e32 vcc, s40, v116
	s_nop 1
	v_cndmask_b32_e32 v116, v116, v119, vcc
	v_rsq_f32_e32 v119, v116
	v_and_or_b32 v116, v114, s41, v115
	v_lshlrev_b64 v[122:123], 8, v[116:117]
	v_lshl_add_u64 v[122:123], v[112:113], 0, v[122:123]
	v_mul_f32_e32 v116, 0x45800000, v119
	v_cndmask_b32_e32 v116, v119, v116, vcc
	v_mul_f32_e32 v124, v149, v116
	v_mul_f32_e32 v125, v150, v116
	v_mul_f32_e32 v119, v148, v116
	v_mul_f32_e32 v126, v151, v116
	v_mul_f32_e32 v127, v144, v116
	v_mul_f32_e32 v128, v145, v116
	v_mul_f32_e32 v129, v146, v116
	v_mul_f32_e32 v130, v147, v116
	v_mul_f32_e32 v131, v140, v116
	v_cvt_pk_bf16_f32 v124, v119, v124
	v_cvt_pk_bf16_f32 v125, v125, v126
	v_mul_f32_e32 v132, v141, v116
	v_mul_f32_e32 v133, v142, v116
	v_mul_f32_e32 v134, v143, v116
	v_mul_f32_e32 v135, v136, v116
	v_mul_f32_e32 v136, v137, v116
	v_mul_f32_e32 v137, v138, v116
	v_mul_f32_e32 v116, v139, v116
	v_cvt_pk_bf16_f32 v126, v127, v128
	v_cvt_pk_bf16_f32 v127, v129, v130
	v_cvt_pk_bf16_f32 v128, v131, v132
	v_cvt_pk_bf16_f32 v129, v133, v134
	v_cvt_pk_bf16_f32 v130, v135, v136
	v_cvt_pk_bf16_f32 v131, v137, v116
	global_store_dwordx2 v[122:123], v[124:125], off
	global_store_dwordx2 v[122:123], v[126:127], off offset:32
	global_store_dwordx2 v[122:123], v[128:129], off offset:64
	global_store_dwordx2 v[122:123], v[130:131], off offset:96
	global_load_dword v116, v[120:121], off
	v_or_b32_e32 v120, 32, v114
	v_ashrrev_i32_e32 v121, 31, v120
	v_lshl_add_u64 v[122:123], v[120:121], 2, s[14:15]
	s_waitcnt vmcnt(0)
	v_fmamk_f32 v116, v116, 0x3a800000, v166
	v_mul_f32_e32 v119, 0x4b800000, v116
	v_cmp_gt_f32_e32 vcc, s40, v116
	s_nop 1
	v_cndmask_b32_e32 v116, v116, v119, vcc
	v_rsq_f32_e32 v121, v116
	v_and_or_b32 v116, v118, s42, v115
	v_lshlrev_b64 v[118:119], 8, v[116:117]
	v_lshl_add_u64 v[118:119], v[112:113], 0, v[118:119]
	v_mul_f32_e32 v116, 0x45800000, v121
	v_cndmask_b32_e32 v116, v121, v116, vcc
	v_mul_f32_e32 v108, v108, v116
	v_mul_f32_e32 v109, v109, v116
	v_mul_f32_e32 v110, v110, v116
	v_mul_f32_e32 v111, v111, v116
	v_mul_f32_e32 v100, v100, v116
	v_mul_f32_e32 v101, v101, v116
	v_mul_f32_e32 v102, v102, v116
	v_mul_f32_e32 v103, v103, v116
	v_mul_f32_e32 v121, v96, v116
	v_mul_f32_e32 v124, v97, v116
	v_cvt_pk_bf16_f32 v96, v108, v109
	v_cvt_pk_bf16_f32 v97, v110, v111
	v_mul_f32_e32 v104, v104, v116
	v_mul_f32_e32 v105, v105, v116
	v_mul_f32_e32 v106, v106, v116
	v_mul_f32_e32 v107, v107, v116
	v_mul_f32_e32 v125, v98, v116
	v_mul_f32_e32 v116, v99, v116
	v_cvt_pk_bf16_f32 v98, v104, v105
	v_cvt_pk_bf16_f32 v99, v106, v107
	v_cvt_pk_bf16_f32 v100, v100, v101
	v_cvt_pk_bf16_f32 v101, v102, v103
	v_cvt_pk_bf16_f32 v102, v121, v124
	v_cvt_pk_bf16_f32 v103, v125, v116
	global_store_dwordx2 v[118:119], v[96:97], off
	global_store_dwordx2 v[118:119], v[98:99], off offset:32
	global_store_dwordx2 v[118:119], v[100:101], off offset:64
	global_store_dwordx2 v[118:119], v[102:103], off offset:96
	global_load_dword v100, v[122:123], off
	v_or_b32_e32 v96, 48, v114
	v_ashrrev_i32_e32 v97, 31, v96
	v_lshl_add_u64 v[98:99], v[96:97], 2, s[14:15]
	v_and_or_b32 v116, v120, s43, v115
	s_waitcnt vmcnt(0)
	v_fmamk_f32 v97, v100, 0x3a800000, v166
	v_mul_f32_e32 v100, 0x4b800000, v97
	v_cmp_gt_f32_e32 vcc, s40, v97
	s_nop 1
	v_cndmask_b32_e32 v97, v97, v100, vcc
	v_rsq_f32_e32 v97, v97
	v_lshlrev_b64 v[100:101], 8, v[116:117]
	v_lshl_add_u64 v[100:101], v[112:113], 0, v[100:101]
	v_and_or_b32 v116, v96, s44, v115
	v_mul_f32_e32 v102, 0x45800000, v97
	v_cndmask_b32_e32 v97, v97, v102, vcc
	v_mul_f32_e32 v92, v92, v97
	v_mul_f32_e32 v93, v93, v97
	v_mul_f32_e32 v94, v94, v97
	v_mul_f32_e32 v95, v95, v97
	v_mul_f32_e32 v84, v84, v97
	v_mul_f32_e32 v85, v85, v97
	v_mul_f32_e32 v86, v86, v97
	v_mul_f32_e32 v87, v87, v97
	v_mul_f32_e32 v102, v80, v97
	v_mul_f32_e32 v103, v81, v97
	v_cvt_pk_bf16_f32 v80, v92, v93
	v_cvt_pk_bf16_f32 v81, v94, v95
	v_mul_f32_e32 v88, v88, v97
	v_mul_f32_e32 v89, v89, v97
	v_mul_f32_e32 v90, v90, v97
	v_mul_f32_e32 v91, v91, v97
	v_mul_f32_e32 v104, v82, v97
	v_mul_f32_e32 v97, v83, v97
	v_cvt_pk_bf16_f32 v82, v88, v89
	v_cvt_pk_bf16_f32 v83, v90, v91
	v_cvt_pk_bf16_f32 v84, v84, v85
	v_cvt_pk_bf16_f32 v85, v86, v87
	v_cvt_pk_bf16_f32 v86, v102, v103
	v_cvt_pk_bf16_f32 v87, v104, v97
	global_store_dwordx2 v[100:101], v[80:81], off
	global_store_dwordx2 v[100:101], v[82:83], off offset:32
	global_store_dwordx2 v[100:101], v[84:85], off offset:64
	global_store_dwordx2 v[100:101], v[86:87], off offset:96
	global_load_dword v84, v[98:99], off
	v_or_b32_e32 v80, 64, v114
	v_ashrrev_i32_e32 v81, 31, v80
	v_lshl_add_u64 v[82:83], v[80:81], 2, s[14:15]
	s_waitcnt vmcnt(0)
	v_fmamk_f32 v81, v84, 0x3a800000, v166
	v_mul_f32_e32 v84, 0x4b800000, v81
	v_cmp_gt_f32_e32 vcc, s40, v81
	s_nop 1
	v_cndmask_b32_e32 v81, v81, v84, vcc
	v_rsq_f32_e32 v81, v81
	v_lshlrev_b64 v[84:85], 8, v[116:117]
	v_lshl_add_u64 v[84:85], v[112:113], 0, v[84:85]
	v_and_or_b32 v116, v80, s45, v115
	v_mul_f32_e32 v86, 0x45800000, v81
	v_cndmask_b32_e32 v81, v81, v86, vcc
	v_mul_f32_e32 v76, v76, v81
	v_mul_f32_e32 v77, v77, v81
	v_mul_f32_e32 v78, v78, v81
	v_mul_f32_e32 v79, v79, v81
	v_mul_f32_e32 v68, v68, v81
	v_mul_f32_e32 v69, v69, v81
	v_mul_f32_e32 v70, v70, v81
	v_mul_f32_e32 v71, v71, v81
	v_mul_f32_e32 v86, v64, v81
	v_mul_f32_e32 v87, v65, v81
	v_cvt_pk_bf16_f32 v64, v76, v77
	v_cvt_pk_bf16_f32 v65, v78, v79
	v_mul_f32_e32 v72, v72, v81
	v_mul_f32_e32 v73, v73, v81
	v_mul_f32_e32 v74, v74, v81
	v_mul_f32_e32 v75, v75, v81
	v_mul_f32_e32 v88, v66, v81
	v_mul_f32_e32 v81, v67, v81
	v_cvt_pk_bf16_f32 v66, v72, v73
	v_cvt_pk_bf16_f32 v67, v74, v75
	v_cvt_pk_bf16_f32 v68, v68, v69
	v_cvt_pk_bf16_f32 v69, v70, v71
	v_cvt_pk_bf16_f32 v70, v86, v87
	v_cvt_pk_bf16_f32 v71, v88, v81
	global_store_dwordx2 v[84:85], v[64:65], off
	global_store_dwordx2 v[84:85], v[66:67], off offset:32
	global_store_dwordx2 v[84:85], v[68:69], off offset:64
	global_store_dwordx2 v[84:85], v[70:71], off offset:96
	global_load_dword v68, v[82:83], off
	v_or_b32_e32 v64, 0x50, v114
	v_ashrrev_i32_e32 v65, 31, v64
	v_lshl_add_u64 v[66:67], v[64:65], 2, s[14:15]
	s_waitcnt vmcnt(0)
	v_fmamk_f32 v65, v68, 0x3a800000, v166
	v_mul_f32_e32 v68, 0x4b800000, v65
	v_cmp_gt_f32_e32 vcc, s40, v65
	s_nop 1
	v_cndmask_b32_e32 v65, v65, v68, vcc
	v_rsq_f32_e32 v65, v65
	v_lshlrev_b64 v[68:69], 8, v[116:117]
	v_lshl_add_u64 v[68:69], v[112:113], 0, v[68:69]
	v_and_or_b32 v116, v64, s46, v115
	v_mul_f32_e32 v70, 0x45800000, v65
	v_cndmask_b32_e32 v65, v65, v70, vcc
	v_mul_f32_e32 v60, v60, v65
	v_mul_f32_e32 v61, v61, v65
	v_mul_f32_e32 v62, v62, v65
	v_mul_f32_e32 v63, v63, v65
	v_mul_f32_e32 v52, v52, v65
	v_mul_f32_e32 v53, v53, v65
	v_mul_f32_e32 v54, v54, v65
	v_mul_f32_e32 v55, v55, v65
	v_mul_f32_e32 v70, v48, v65
	v_mul_f32_e32 v71, v49, v65
	v_cvt_pk_bf16_f32 v48, v60, v61
	v_cvt_pk_bf16_f32 v49, v62, v63
	v_mul_f32_e32 v56, v56, v65
	v_mul_f32_e32 v57, v57, v65
	v_mul_f32_e32 v58, v58, v65
	v_mul_f32_e32 v59, v59, v65
	v_mul_f32_e32 v72, v50, v65
	v_mul_f32_e32 v65, v51, v65
	v_cvt_pk_bf16_f32 v50, v56, v57
	v_cvt_pk_bf16_f32 v51, v58, v59
	v_cvt_pk_bf16_f32 v52, v52, v53
	v_cvt_pk_bf16_f32 v53, v54, v55
	v_cvt_pk_bf16_f32 v54, v70, v71
	v_cvt_pk_bf16_f32 v55, v72, v65
	global_store_dwordx2 v[68:69], v[48:49], off
	global_store_dwordx2 v[68:69], v[50:51], off offset:32
	global_store_dwordx2 v[68:69], v[52:53], off offset:64
	global_store_dwordx2 v[68:69], v[54:55], off offset:96
	global_load_dword v52, v[66:67], off
	v_or_b32_e32 v48, 0x60, v114
	v_ashrrev_i32_e32 v49, 31, v48
	v_lshl_add_u64 v[50:51], v[48:49], 2, s[14:15]
	s_waitcnt vmcnt(0)
	v_fmamk_f32 v49, v52, 0x3a800000, v166
	v_mul_f32_e32 v52, 0x4b800000, v49
	v_cmp_gt_f32_e32 vcc, s40, v49
	s_nop 1
	v_cndmask_b32_e32 v49, v49, v52, vcc
	v_rsq_f32_e32 v49, v49
	v_lshlrev_b64 v[52:53], 8, v[116:117]
	v_lshl_add_u64 v[52:53], v[112:113], 0, v[52:53]
	v_and_or_b32 v116, v48, s47, v115
	v_mul_f32_e32 v54, 0x45800000, v49
	v_cndmask_b32_e32 v49, v49, v54, vcc
	v_mul_f32_e32 v44, v44, v49
	v_mul_f32_e32 v45, v45, v49
	v_mul_f32_e32 v46, v46, v49
	v_mul_f32_e32 v47, v47, v49
	v_mul_f32_e32 v36, v36, v49
	v_mul_f32_e32 v37, v37, v49
	v_mul_f32_e32 v38, v38, v49
	v_mul_f32_e32 v39, v39, v49
	v_mul_f32_e32 v54, v32, v49
	v_mul_f32_e32 v55, v33, v49
	v_cvt_pk_bf16_f32 v32, v44, v45
	v_cvt_pk_bf16_f32 v33, v46, v47
	v_mul_f32_e32 v40, v40, v49
	v_mul_f32_e32 v41, v41, v49
	v_mul_f32_e32 v42, v42, v49
	v_mul_f32_e32 v43, v43, v49
	v_mul_f32_e32 v56, v34, v49
	v_mul_f32_e32 v49, v35, v49
	v_cvt_pk_bf16_f32 v34, v40, v41
	v_cvt_pk_bf16_f32 v35, v42, v43
	v_cvt_pk_bf16_f32 v36, v36, v37
	v_cvt_pk_bf16_f32 v37, v38, v39
	v_cvt_pk_bf16_f32 v38, v54, v55
	v_cvt_pk_bf16_f32 v39, v56, v49
	global_store_dwordx2 v[52:53], v[32:33], off
	global_store_dwordx2 v[52:53], v[34:35], off offset:32
	global_store_dwordx2 v[52:53], v[36:37], off offset:64
	global_store_dwordx2 v[52:53], v[38:39], off offset:96
	global_load_dword v36, v[50:51], off
	v_or_b32_e32 v32, 0x70, v114
	v_ashrrev_i32_e32 v33, 31, v32
	v_lshl_add_u64 v[34:35], v[32:33], 2, s[14:15]
	s_waitcnt vmcnt(0)
	v_fmamk_f32 v33, v36, 0x3a800000, v166
	v_mul_f32_e32 v36, 0x4b800000, v33
	v_cmp_gt_f32_e32 vcc, s40, v33
	s_nop 1
	v_cndmask_b32_e32 v33, v33, v36, vcc
	v_rsq_f32_e32 v33, v33
	v_lshlrev_b64 v[36:37], 8, v[116:117]
	v_lshl_add_u64 v[36:37], v[112:113], 0, v[36:37]
	v_and_or_b32 v116, v32, s48, v115
	v_mul_f32_e32 v38, 0x45800000, v33
	v_cndmask_b32_e32 v33, v33, v38, vcc
	v_mul_f32_e32 v28, v28, v33
	v_mul_f32_e32 v29, v29, v33
	v_mul_f32_e32 v30, v30, v33
	v_mul_f32_e32 v31, v31, v33
	v_mul_f32_e32 v20, v20, v33
	v_mul_f32_e32 v21, v21, v33
	v_mul_f32_e32 v22, v22, v33
	v_mul_f32_e32 v23, v23, v33
	v_mul_f32_e32 v38, v16, v33
	v_mul_f32_e32 v39, v17, v33
	v_cvt_pk_bf16_f32 v16, v28, v29
	v_cvt_pk_bf16_f32 v17, v30, v31
	v_mul_f32_e32 v24, v24, v33
	v_mul_f32_e32 v25, v25, v33
	v_mul_f32_e32 v26, v26, v33
	v_mul_f32_e32 v27, v27, v33
	v_mul_f32_e32 v40, v18, v33
	v_mul_f32_e32 v33, v19, v33
	v_cvt_pk_bf16_f32 v18, v24, v25
	v_cvt_pk_bf16_f32 v19, v26, v27
	v_cvt_pk_bf16_f32 v20, v20, v21
	v_cvt_pk_bf16_f32 v21, v22, v23
	v_cvt_pk_bf16_f32 v22, v38, v39
	v_cvt_pk_bf16_f32 v23, v40, v33
	global_store_dwordx2 v[36:37], v[16:17], off
	global_store_dwordx2 v[36:37], v[18:19], off offset:32
	global_store_dwordx2 v[36:37], v[20:21], off offset:64
	global_store_dwordx2 v[36:37], v[22:23], off offset:96
	global_load_dword v16, v[34:35], off
	s_waitcnt vmcnt(0)
	v_fmamk_f32 v16, v16, 0x3a800000, v166
	v_mul_f32_e32 v17, 0x4b800000, v16
	v_cmp_gt_f32_e32 vcc, s40, v16
	s_nop 1
	v_cndmask_b32_e32 v16, v16, v17, vcc
	v_rsq_f32_e32 v18, v16
	v_lshlrev_b64 v[16:17], 8, v[116:117]
	v_lshl_add_u64 v[16:17], v[112:113], 0, v[16:17]
	v_mul_f32_e32 v19, 0x45800000, v18
	v_cndmask_b32_e32 v18, v18, v19, vcc
	v_mul_f32_e32 v12, v12, v18
	v_mul_f32_e32 v13, v13, v18
	v_mul_f32_e32 v14, v14, v18
	v_mul_f32_e32 v15, v15, v18
	v_mul_f32_e32 v4, v4, v18
	v_mul_f32_e32 v5, v5, v18
	v_mul_f32_e32 v6, v6, v18
	v_mul_f32_e32 v7, v7, v18
	v_mul_f32_e32 v19, v0, v18
	v_mul_f32_e32 v20, v1, v18
	v_cvt_pk_bf16_f32 v0, v12, v13
	v_cvt_pk_bf16_f32 v1, v14, v15
	v_mul_f32_e32 v8, v8, v18
	v_mul_f32_e32 v9, v9, v18
	v_mul_f32_e32 v10, v10, v18
	v_mul_f32_e32 v11, v11, v18
	v_mul_f32_e32 v21, v2, v18
	v_mul_f32_e32 v18, v3, v18
	v_cvt_pk_bf16_f32 v2, v8, v9
	v_cvt_pk_bf16_f32 v3, v10, v11
	v_cvt_pk_bf16_f32 v4, v4, v5
	v_cvt_pk_bf16_f32 v5, v6, v7
	v_cvt_pk_bf16_f32 v6, v19, v20
	v_cvt_pk_bf16_f32 v7, v21, v18
	global_store_dwordx2 v[16:17], v[0:1], off
	global_store_dwordx2 v[16:17], v[2:3], off offset:32
	global_store_dwordx2 v[16:17], v[4:5], off offset:64
	global_store_dwordx2 v[16:17], v[6:7], off offset:96
	s_branch .LBB0_699

.LBB0_710:
	s_add_i32 s11, s10, 64
	s_min_u32 s13, s11, 0x3e0
	s_lshl_b32 s16, s13, 1
	v_lshl_add_u64 v[172:173], v[154:155], 0, s[16:17]
	v_lshl_add_u64 v[176:177], v[158:159], 0, s[16:17]
	v_lshl_add_u64 v[180:181], v[160:161], 0, s[16:17]
	v_lshl_add_u64 v[184:185], v[162:163], 0, s[16:17]
	v_lshl_add_u64 v[188:189], v[156:157], 0, s[16:17]
	v_lshl_add_u64 v[192:193], v[164:165], 0, s[16:17]
	global_load_dwordx4 v[172:175], v[172:173], off
	ds_read_b128 v[196:199], v171 offset:32768
	global_load_dwordx4 v[176:179], v[176:177], off
	ds_read_b128 v[200:203], v171 offset:33792
	global_load_dwordx4 v[180:183], v[180:181], off
	ds_read_b128 v[204:207], v171 offset:34816
	global_load_dwordx4 v[184:187], v[184:185], off
	ds_read_b128 v[208:211], v171 offset:35840
	global_load_dwordx4 v[188:191], v[188:189], off
	ds_read_b128 v[212:215], v169
	global_load_dwordx4 v[192:195], v[192:193], off
	ds_read_b128 v[216:219], v169 offset:1024
	ds_read_b128 v[222:225], v169 offset:2048
	ds_read_b128 v[226:229], v169 offset:3072
	ds_read_b128 v[230:233], v169 offset:4096
	ds_read_b128 v[234:237], v169 offset:5120
	ds_read_b128 v[238:241], v169 offset:6144
	ds_read_b128 v[242:245], v169 offset:7168
	s_waitcnt lgkmcnt(7)
	v_mfma_f32_16x16x32_bf16 v[148:151], v[212:215], v[196:199], v[148:151]
	v_mfma_f32_16x16x32_bf16 v[144:147], v[212:215], v[200:203], v[144:147]
	v_mfma_f32_16x16x32_bf16 v[140:143], v[212:215], v[204:207], v[140:143]
	v_mfma_f32_16x16x32_bf16 v[128:131], v[212:215], v[208:211], v[128:131]
	s_waitcnt vmcnt(11)
	ds_write_b128 v152, v[112:115] offset:16384
	s_waitcnt lgkmcnt(7)
	v_mfma_f32_16x16x32_bf16 v[108:111], v[216:219], v[196:199], v[108:111]
	v_mfma_f32_16x16x32_bf16 v[104:107], v[216:219], v[200:203], v[104:107]
	v_mfma_f32_16x16x32_bf16 v[100:103], v[216:219], v[204:207], v[100:103]
	v_mfma_f32_16x16x32_bf16 v[96:99], v[216:219], v[208:211], v[96:99]
	s_waitcnt vmcnt(9)
	ds_write_b128 v152, v[120:123] offset:20480
	s_waitcnt lgkmcnt(7)
	v_mfma_f32_16x16x32_bf16 v[92:95], v[222:225], v[196:199], v[92:95]
	v_mfma_f32_16x16x32_bf16 v[88:91], v[222:225], v[200:203], v[88:91]
	v_mfma_f32_16x16x32_bf16 v[84:87], v[222:225], v[204:207], v[84:87]
	v_mfma_f32_16x16x32_bf16 v[80:83], v[222:225], v[208:211], v[80:83]
	s_waitcnt vmcnt(8)
	ds_write_b128 v152, v[124:127] offset:24576
	s_waitcnt lgkmcnt(7)
	v_mfma_f32_16x16x32_bf16 v[76:79], v[226:229], v[196:199], v[76:79]
	v_mfma_f32_16x16x32_bf16 v[72:75], v[226:229], v[200:203], v[72:75]
	v_mfma_f32_16x16x32_bf16 v[68:71], v[226:229], v[204:207], v[68:71]
	v_mfma_f32_16x16x32_bf16 v[64:67], v[226:229], v[208:211], v[64:67]
	s_waitcnt vmcnt(7)
	ds_write_b128 v152, v[132:135] offset:28672
	s_waitcnt lgkmcnt(7)
	v_mfma_f32_16x16x32_bf16 v[60:63], v[230:233], v[196:199], v[60:63]
	v_mfma_f32_16x16x32_bf16 v[56:59], v[230:233], v[200:203], v[56:59]
	v_mfma_f32_16x16x32_bf16 v[52:55], v[230:233], v[204:207], v[52:55]
	v_mfma_f32_16x16x32_bf16 v[48:51], v[230:233], v[208:211], v[48:51]
	s_waitcnt vmcnt(7)
	ds_write_b128 v152, v[116:119] offset:40960
	s_waitcnt lgkmcnt(7)
	v_mfma_f32_16x16x32_bf16 v[44:47], v[234:237], v[196:199], v[44:47]
	v_mfma_f32_16x16x32_bf16 v[40:43], v[234:237], v[200:203], v[40:43]
	v_mfma_f32_16x16x32_bf16 v[36:39], v[234:237], v[204:207], v[36:39]
	v_mfma_f32_16x16x32_bf16 v[32:35], v[234:237], v[208:211], v[32:35]
	s_waitcnt vmcnt(6)
	ds_write_b128 v152, v[136:139] offset:45056
	s_waitcnt lgkmcnt(7)
	v_mfma_f32_16x16x32_bf16 v[28:31], v[238:241], v[196:199], v[28:31]
	v_mfma_f32_16x16x32_bf16 v[24:27], v[238:241], v[200:203], v[24:27]
	v_mfma_f32_16x16x32_bf16 v[20:23], v[238:241], v[204:207], v[20:23]
	v_mfma_f32_16x16x32_bf16 v[16:19], v[238:241], v[208:211], v[16:19]
	s_waitcnt lgkmcnt(6)
	v_mfma_f32_16x16x32_bf16 v[12:15], v[242:245], v[196:199], v[12:15]
	v_mfma_f32_16x16x32_bf16 v[8:11], v[242:245], v[200:203], v[8:11]
	v_mfma_f32_16x16x32_bf16 v[4:7], v[242:245], v[204:207], v[4:7]
	v_mfma_f32_16x16x32_bf16 v[0:3], v[242:245], v[208:211], v[0:3]
	s_min_u32 s10, s10, 0x380
	s_lshl_b32 s16, s10, 1
	s_mov_b32 s27, s17
	s_add_i32 s26, s16, 0xc0
	v_lshl_add_u64 v[112:113], v[154:155], 0, s[16:17]
	v_lshl_add_u64 v[116:117], v[156:157], 0, s[16:17]
	v_lshl_add_u64 v[120:121], v[158:159], 0, s[26:27]
	v_lshl_add_u64 v[124:125], v[160:161], 0, s[26:27]
	v_lshl_add_u64 v[132:133], v[162:163], 0, s[26:27]
	v_lshl_add_u64 v[136:137], v[164:165], 0, s[26:27]
	s_waitcnt lgkmcnt(0)
	s_barrier
	global_load_dwordx4 v[112:115], v[112:113], off offset:192
	ds_read_b128 v[196:199], v168 offset:40960
	global_load_dwordx4 v[116:119], v[116:117], off offset:192
	ds_read_b128 v[200:203], v168 offset:41984
	global_load_dwordx4 v[120:123], v[120:121], off
	ds_read_b128 v[204:207], v168 offset:43008
	global_load_dwordx4 v[124:127], v[124:125], off
	ds_read_b128 v[208:211], v168 offset:44032
	global_load_dwordx4 v[132:135], v[132:133], off
	ds_read_b128 v[212:215], v170
	global_load_dwordx4 v[136:139], v[136:137], off
	ds_read_b128 v[216:219], v170 offset:1024
	ds_read_b128 v[222:225], v170 offset:2048
	ds_read_b128 v[226:229], v170 offset:3072
	ds_read_b128 v[230:233], v170 offset:4096
	ds_read_b128 v[234:237], v170 offset:5120
	ds_read_b128 v[238:241], v170 offset:6144
	ds_read_b128 v[242:245], v170 offset:7168
	s_waitcnt lgkmcnt(7)
	v_mfma_f32_16x16x32_bf16 v[148:151], v[212:215], v[196:199], v[148:151]
	v_mfma_f32_16x16x32_bf16 v[144:147], v[212:215], v[200:203], v[144:147]
	v_mfma_f32_16x16x32_bf16 v[140:143], v[212:215], v[204:207], v[140:143]
	v_mfma_f32_16x16x32_bf16 v[128:131], v[212:215], v[208:211], v[128:131]
	s_waitcnt vmcnt(11)
	ds_write_b128 v152, v[172:175]
	s_waitcnt lgkmcnt(7)
	v_mfma_f32_16x16x32_bf16 v[108:111], v[216:219], v[196:199], v[108:111]
	v_mfma_f32_16x16x32_bf16 v[104:107], v[216:219], v[200:203], v[104:107]
	v_mfma_f32_16x16x32_bf16 v[100:103], v[216:219], v[204:207], v[100:103]
	v_mfma_f32_16x16x32_bf16 v[96:99], v[216:219], v[208:211], v[96:99]
	s_waitcnt vmcnt(10)
	ds_write_b128 v152, v[176:179] offset:4096
	s_waitcnt lgkmcnt(7)
	v_mfma_f32_16x16x32_bf16 v[92:95], v[222:225], v[196:199], v[92:95]
	v_mfma_f32_16x16x32_bf16 v[88:91], v[222:225], v[200:203], v[88:91]
	v_mfma_f32_16x16x32_bf16 v[84:87], v[222:225], v[204:207], v[84:87]
	v_mfma_f32_16x16x32_bf16 v[80:83], v[222:225], v[208:211], v[80:83]
	s_waitcnt vmcnt(9)
	ds_write_b128 v152, v[180:183] offset:8192
	s_waitcnt lgkmcnt(7)
	v_mfma_f32_16x16x32_bf16 v[76:79], v[226:229], v[196:199], v[76:79]
	v_mfma_f32_16x16x32_bf16 v[72:75], v[226:229], v[200:203], v[72:75]
	v_mfma_f32_16x16x32_bf16 v[68:71], v[226:229], v[204:207], v[68:71]
	v_mfma_f32_16x16x32_bf16 v[64:67], v[226:229], v[208:211], v[64:67]
	s_waitcnt vmcnt(8)
	ds_write_b128 v152, v[184:187] offset:12288
	s_waitcnt lgkmcnt(7)
	v_mfma_f32_16x16x32_bf16 v[60:63], v[230:233], v[196:199], v[60:63]
	v_mfma_f32_16x16x32_bf16 v[56:59], v[230:233], v[200:203], v[56:59]
	v_mfma_f32_16x16x32_bf16 v[52:55], v[230:233], v[204:207], v[52:55]
	v_mfma_f32_16x16x32_bf16 v[48:51], v[230:233], v[208:211], v[48:51]
	s_waitcnt vmcnt(7)
	ds_write_b128 v152, v[188:191] offset:32768
	s_waitcnt lgkmcnt(7)
	v_mfma_f32_16x16x32_bf16 v[44:47], v[234:237], v[196:199], v[44:47]
	v_mfma_f32_16x16x32_bf16 v[40:43], v[234:237], v[200:203], v[40:43]
	v_mfma_f32_16x16x32_bf16 v[36:39], v[234:237], v[204:207], v[36:39]
	v_mfma_f32_16x16x32_bf16 v[32:35], v[234:237], v[208:211], v[32:35]
	s_waitcnt vmcnt(6)
	ds_write_b128 v152, v[192:195] offset:36864
	s_waitcnt lgkmcnt(7)
	v_mfma_f32_16x16x32_bf16 v[28:31], v[238:241], v[196:199], v[28:31]
	v_mfma_f32_16x16x32_bf16 v[24:27], v[238:241], v[200:203], v[24:27]
	v_mfma_f32_16x16x32_bf16 v[20:23], v[238:241], v[204:207], v[20:23]
	v_mfma_f32_16x16x32_bf16 v[16:19], v[238:241], v[208:211], v[16:19]
	s_waitcnt lgkmcnt(6)
	v_mfma_f32_16x16x32_bf16 v[12:15], v[242:245], v[196:199], v[12:15]
	v_mfma_f32_16x16x32_bf16 v[8:11], v[242:245], v[200:203], v[8:11]
	v_mfma_f32_16x16x32_bf16 v[4:7], v[242:245], v[204:207], v[4:7]
	v_mfma_f32_16x16x32_bf16 v[0:3], v[242:245], v[208:211], v[0:3]
	s_add_i32 s1, s1, 2
	s_cmp_lt_u32 s1, 30
	s_mov_b32 s10, s11
	s_waitcnt lgkmcnt(0)
	s_barrier
	s_cbranch_scc1 .LBB0_710
	s_waitcnt vmcnt(5)
	v_mov_b32_e32 v114, v220
	v_mov_b32_e32 v115, v153
	v_and_b32_e32 v112, 0xffffff80, v114
	s_waitcnt vmcnt(4)
	v_add_u32_e32 v116, s0, v112
	v_lshrrev_b32_e32 v112, 2, v114
	v_and_b32_e32 v118, 12, v112
	s_waitcnt vmcnt(3)
	v_or_b32_e32 v120, v118, v116
	v_ashrrev_i32_e32 v121, 31, v120
	v_lshl_add_u64 v[112:113], v[120:121], 2, s[14:15]
	global_load_dwordx4 v[132:135], v[112:113], off
	v_ashrrev_i32_e32 v122, 14, v116
	v_ashrrev_i32_e32 v123, 31, v122
	v_lshlrev_b64 v[122:123], 10, v[122:123]
	v_mov_b64_e32 v[112:113], s[34:35]
	s_waitcnt vmcnt(3)
	v_lshrrev_b32_e32 v126, 6, v116
	v_or_b32_e32 v124, 16, v120
	v_lshl_or_b32 v121, s12, 8, v122
	v_ashrrev_i32_e32 v125, 31, v124
	v_and_or_b32 v122, v126, s49, v121
	s_waitcnt vmcnt(1)
	v_lshl_add_u64 v[136:137], v[124:125], 2, s[14:15]
	v_lshlrev_b64 v[124:125], 14, v[122:123]
	v_lshlrev_b32_e32 v114, 7, v114
	v_lshlrev_b32_e32 v152, 1, v118
	v_lshl_add_u64 v[124:125], s[38:39], 0, v[124:125]
	v_and_b32_e32 v114, 0x2780, v114
	v_lshl_add_u64 v[126:127], v[124:125], 0, v[152:153]
	v_mov_b32_e32 v117, v153
	v_mov_b32_e32 v119, v153
	v_or_b32_e32 v116, 0x1000, v114
	v_or_b32_e32 v118, 0x1800, v114
	v_lshl_add_u64 v[124:125], v[126:127], 0, v[114:115]
	v_lshl_add_u64 v[138:139], v[126:127], 0, v[116:117]
	v_lshl_add_u64 v[154:155], v[126:127], 0, v[118:119]
	s_waitcnt vmcnt(0)
	v_pk_fma_f32 v[132:133], v[132:133], s[30:31], v[112:113] op_sel_hi:[1,0,0]
	v_pk_fma_f32 v[134:135], v[134:135], s[30:31], v[112:113] op_sel_hi:[1,0,0]
	v_mul_f32_e32 v122, 0x4b800000, v132
	v_mul_f32_e32 v156, 0x4b800000, v133
	v_mul_f32_e32 v157, 0x4b800000, v134
	v_mul_f32_e32 v158, 0x4b800000, v135
	v_cmp_gt_f32_e32 vcc, s40, v132
	v_cmp_gt_f32_e64 s[0:1], s40, v133
	v_cmp_gt_f32_e64 s[10:11], s40, v134
	v_cmp_gt_f32_e64 s[12:13], s40, v135
	v_cndmask_b32_e32 v122, v132, v122, vcc
	v_cndmask_b32_e64 v132, v133, v156, s[0:1]
	v_cndmask_b32_e64 v133, v134, v157, s[10:11]
	v_cndmask_b32_e64 v134, v135, v158, s[12:13]
	v_rsq_f32_e32 v122, v122
	v_rsq_f32_e32 v132, v132
	v_rsq_f32_e32 v133, v133
	v_rsq_f32_e32 v134, v134
	v_mul_f32_e32 v135, 0x45800000, v122
	v_mul_f32_e32 v156, 0x45800000, v132
	v_mul_f32_e32 v157, 0x45800000, v133
	v_mul_f32_e32 v158, 0x45800000, v134
	v_cndmask_b32_e32 v122, v122, v135, vcc
	v_cndmask_b32_e64 v132, v132, v156, s[0:1]
	v_cndmask_b32_e64 v133, v133, v157, s[10:11]
	v_cndmask_b32_e64 v134, v134, v158, s[12:13]
	v_mul_f32_e32 v135, v148, v122
	v_mul_f32_e32 v148, v149, v132
	v_mul_f32_e32 v149, v150, v133
	v_mul_f32_e32 v150, v151, v134
	v_mul_f32_e32 v144, v144, v122
	v_mul_f32_e32 v140, v140, v122
	v_mul_f32_e32 v122, v128, v122
	v_mul_f32_e32 v151, v129, v132
	v_cvt_pk_bf16_f32 v128, v135, v148
	v_cvt_pk_bf16_f32 v129, v149, v150
	v_mul_f32_e32 v145, v145, v132
	v_mul_f32_e32 v146, v146, v133
	v_mul_f32_e32 v147, v147, v134
	v_mul_f32_e32 v141, v141, v132
	v_mul_f32_e32 v142, v142, v133
	v_mul_f32_e32 v143, v143, v134
	v_mul_f32_e32 v156, v130, v133
	v_mul_f32_e32 v157, v131, v134
	v_cvt_pk_bf16_f32 v130, v144, v145
	v_cvt_pk_bf16_f32 v131, v146, v147
	v_cvt_pk_bf16_f32 v132, v140, v141
	v_cvt_pk_bf16_f32 v133, v142, v143
	v_cvt_pk_bf16_f32 v134, v122, v151
	v_cvt_pk_bf16_f32 v135, v156, v157
	global_store_dwordx2 v[124:125], v[128:129], off
	global_store_dwordx2 v[124:125], v[130:131], off offset:2048
	global_store_dwordx2 v[138:139], v[132:133], off
	global_store_dwordx2 v[154:155], v[134:135], off
	global_load_dwordx4 v[128:131], v[136:137], off
	v_or_b32_e32 v132, 32, v120
	v_ashrrev_i32_e32 v133, 31, v132
	v_lshl_add_u64 v[134:135], v[126:127], 0, 32
	v_lshl_add_u64 v[132:133], v[132:133], 2, s[14:15]
	v_lshl_add_u64 v[136:137], v[134:135], 0, v[116:117]
	v_lshl_add_u64 v[134:135], v[134:135], 0, v[118:119]
	s_waitcnt vmcnt(0)
	v_pk_fma_f32 v[128:129], v[128:129], s[30:31], v[112:113] op_sel_hi:[1,0,0]
	v_pk_fma_f32 v[130:131], v[130:131], s[30:31], v[112:113] op_sel_hi:[1,0,0]
	v_mul_f32_e32 v122, 0x4b800000, v128
	v_mul_f32_e32 v138, 0x4b800000, v129
	v_mul_f32_e32 v139, 0x4b800000, v130
	v_mul_f32_e32 v140, 0x4b800000, v131
	v_cmp_gt_f32_e32 vcc, s40, v128
	v_cmp_gt_f32_e64 s[0:1], s40, v129
	v_cmp_gt_f32_e64 s[10:11], s40, v130
	v_cmp_gt_f32_e64 s[12:13], s40, v131
	v_cndmask_b32_e32 v122, v128, v122, vcc
	v_cndmask_b32_e64 v128, v129, v138, s[0:1]
	v_cndmask_b32_e64 v129, v130, v139, s[10:11]
	v_cndmask_b32_e64 v130, v131, v140, s[12:13]
	v_rsq_f32_e32 v122, v122
	v_rsq_f32_e32 v128, v128
	v_rsq_f32_e32 v129, v129
	v_rsq_f32_e32 v130, v130
	v_mul_f32_e32 v131, 0x45800000, v122
	v_mul_f32_e32 v138, 0x45800000, v128
	v_mul_f32_e32 v139, 0x45800000, v129
	v_mul_f32_e32 v140, 0x45800000, v130
	v_cndmask_b32_e32 v122, v122, v131, vcc
	v_cndmask_b32_e64 v128, v128, v138, s[0:1]
	v_cndmask_b32_e64 v129, v129, v139, s[10:11]
	v_cndmask_b32_e64 v130, v130, v140, s[12:13]
	v_mul_f32_e32 v108, v108, v122
	v_mul_f32_e32 v109, v109, v128
	v_mul_f32_e32 v110, v110, v129
	v_mul_f32_e32 v111, v111, v130
	v_mul_f32_e32 v104, v104, v122
	v_mul_f32_e32 v105, v105, v128
	v_mul_f32_e32 v100, v100, v122
	v_mul_f32_e32 v101, v101, v128
	v_mul_f32_e32 v102, v102, v129
	v_mul_f32_e32 v103, v103, v130
	v_mul_f32_e32 v122, v96, v122
	v_mul_f32_e32 v128, v97, v128
	v_cvt_pk_bf16_f32 v96, v108, v109
	v_cvt_pk_bf16_f32 v97, v110, v111
	v_mul_f32_e32 v106, v106, v129
	v_mul_f32_e32 v107, v107, v130
	v_mul_f32_e32 v129, v98, v129
	v_mul_f32_e32 v130, v99, v130
	v_cvt_pk_bf16_f32 v98, v104, v105
	v_cvt_pk_bf16_f32 v99, v106, v107
	v_cvt_pk_bf16_f32 v100, v100, v101
	v_cvt_pk_bf16_f32 v101, v102, v103
	v_cvt_pk_bf16_f32 v102, v122, v128
	v_cvt_pk_bf16_f32 v103, v129, v130
	global_store_dwordx2 v[124:125], v[96:97], off offset:32
	global_store_dwordx2 v[124:125], v[98:99], off offset:2080
	global_store_dwordx2 v[136:137], v[100:101], off
	global_store_dwordx2 v[134:135], v[102:103], off
	global_load_dwordx4 v[96:99], v[132:133], off
	v_or_b32_e32 v100, 48, v120
	v_ashrrev_i32_e32 v101, 31, v100
	v_lshl_add_u64 v[102:103], v[126:127], 0, 64
	v_lshl_add_u64 v[100:101], v[100:101], 2, s[14:15]
	v_lshl_add_u64 v[104:105], v[102:103], 0, v[116:117]
	v_lshl_add_u64 v[102:103], v[102:103], 0, v[118:119]
	s_waitcnt vmcnt(0)
	v_pk_fma_f32 v[96:97], v[96:97], s[30:31], v[112:113] op_sel_hi:[1,0,0]
	v_pk_fma_f32 v[98:99], v[98:99], s[30:31], v[112:113] op_sel_hi:[1,0,0]
	v_mul_f32_e32 v106, 0x4b800000, v96
	v_mul_f32_e32 v107, 0x4b800000, v97
	v_mul_f32_e32 v108, 0x4b800000, v98
	v_mul_f32_e32 v109, 0x4b800000, v99
	v_cmp_gt_f32_e32 vcc, s40, v96
	v_cmp_gt_f32_e64 s[0:1], s40, v97
	v_cmp_gt_f32_e64 s[10:11], s40, v98
	v_cmp_gt_f32_e64 s[12:13], s40, v99
	v_cndmask_b32_e32 v96, v96, v106, vcc
	v_cndmask_b32_e64 v97, v97, v107, s[0:1]
	v_cndmask_b32_e64 v98, v98, v108, s[10:11]
	v_cndmask_b32_e64 v99, v99, v109, s[12:13]
	v_rsq_f32_e32 v96, v96
	v_rsq_f32_e32 v97, v97
	v_rsq_f32_e32 v98, v98
	v_rsq_f32_e32 v99, v99
	v_mul_f32_e32 v106, 0x45800000, v96
	v_mul_f32_e32 v107, 0x45800000, v97
	v_mul_f32_e32 v108, 0x45800000, v98
	v_mul_f32_e32 v109, 0x45800000, v99
	v_cndmask_b32_e32 v96, v96, v106, vcc
	v_cndmask_b32_e64 v97, v97, v107, s[0:1]
	v_cndmask_b32_e64 v98, v98, v108, s[10:11]
	v_cndmask_b32_e64 v99, v99, v109, s[12:13]
	v_mul_f32_e32 v92, v92, v96
	v_mul_f32_e32 v93, v93, v97
	v_mul_f32_e32 v94, v94, v98
	v_mul_f32_e32 v95, v95, v99
	v_mul_f32_e32 v88, v88, v96
	v_mul_f32_e32 v89, v89, v97
	v_mul_f32_e32 v84, v84, v96
	v_mul_f32_e32 v85, v85, v97
	v_mul_f32_e32 v86, v86, v98
	v_mul_f32_e32 v87, v87, v99
	v_mul_f32_e32 v96, v80, v96
	v_mul_f32_e32 v97, v81, v97
	v_cvt_pk_bf16_f32 v80, v92, v93
	v_cvt_pk_bf16_f32 v81, v94, v95
	v_mul_f32_e32 v90, v90, v98
	v_mul_f32_e32 v91, v91, v99
	v_mul_f32_e32 v98, v82, v98
	v_mul_f32_e32 v99, v83, v99
	v_cvt_pk_bf16_f32 v82, v88, v89
	v_cvt_pk_bf16_f32 v83, v90, v91
	v_cvt_pk_bf16_f32 v84, v84, v85
	v_cvt_pk_bf16_f32 v85, v86, v87
	v_cvt_pk_bf16_f32 v86, v96, v97
	v_cvt_pk_bf16_f32 v87, v98, v99
	global_store_dwordx2 v[124:125], v[80:81], off offset:64
	global_store_dwordx2 v[124:125], v[82:83], off offset:2112
	global_store_dwordx2 v[104:105], v[84:85], off
	global_store_dwordx2 v[102:103], v[86:87], off
	global_load_dwordx4 v[80:83], v[100:101], off
	v_or_b32_e32 v84, 64, v120
	v_ashrrev_i32_e32 v85, 31, v84
	v_lshl_add_u64 v[86:87], v[84:85], 2, s[14:15]
	v_lshl_add_u64 v[88:89], v[126:127], 0, s[36:37]
	v_lshl_add_u64 v[90:91], v[88:89], 0, v[116:117]
	v_lshl_add_u64 v[88:89], v[88:89], 0, v[118:119]
	s_waitcnt vmcnt(0)
	v_pk_fma_f32 v[80:81], v[80:81], s[30:31], v[112:113] op_sel_hi:[1,0,0]
	v_pk_fma_f32 v[82:83], v[82:83], s[30:31], v[112:113] op_sel_hi:[1,0,0]
	v_mul_f32_e32 v85, 0x4b800000, v80
	v_mul_f32_e32 v92, 0x4b800000, v81
	v_mul_f32_e32 v93, 0x4b800000, v82
	v_mul_f32_e32 v94, 0x4b800000, v83
	v_cmp_gt_f32_e32 vcc, s40, v80
	v_cmp_gt_f32_e64 s[0:1], s40, v81
	v_cmp_gt_f32_e64 s[10:11], s40, v82
	v_cmp_gt_f32_e64 s[12:13], s40, v83
	v_cndmask_b32_e32 v80, v80, v85, vcc
	v_cndmask_b32_e64 v81, v81, v92, s[0:1]
	v_cndmask_b32_e64 v82, v82, v93, s[10:11]
	v_cndmask_b32_e64 v83, v83, v94, s[12:13]
	v_rsq_f32_e32 v80, v80
	v_rsq_f32_e32 v81, v81
	v_rsq_f32_e32 v82, v82
	v_rsq_f32_e32 v83, v83
	v_mul_f32_e32 v85, 0x45800000, v80
	v_mul_f32_e32 v92, 0x45800000, v81
	v_mul_f32_e32 v93, 0x45800000, v82
	v_mul_f32_e32 v94, 0x45800000, v83
	v_cndmask_b32_e32 v80, v80, v85, vcc
	v_cndmask_b32_e64 v81, v81, v92, s[0:1]
	v_cndmask_b32_e64 v82, v82, v93, s[10:11]
	v_cndmask_b32_e64 v83, v83, v94, s[12:13]
	v_mul_f32_e32 v76, v76, v80
	v_mul_f32_e32 v77, v77, v81
	v_mul_f32_e32 v78, v78, v82
	v_mul_f32_e32 v79, v79, v83
	v_mul_f32_e32 v72, v72, v80
	v_mul_f32_e32 v73, v73, v81
	v_mul_f32_e32 v68, v68, v80
	v_mul_f32_e32 v69, v69, v81
	v_mul_f32_e32 v70, v70, v82
	v_mul_f32_e32 v71, v71, v83
	v_mul_f32_e32 v80, v64, v80
	v_mul_f32_e32 v81, v65, v81
	v_cvt_pk_bf16_f32 v64, v76, v77
	v_cvt_pk_bf16_f32 v65, v78, v79
	v_mul_f32_e32 v74, v74, v82
	v_mul_f32_e32 v75, v75, v83
	v_mul_f32_e32 v82, v66, v82
	v_mul_f32_e32 v83, v67, v83
	v_cvt_pk_bf16_f32 v66, v72, v73
	v_cvt_pk_bf16_f32 v67, v74, v75
	v_cvt_pk_bf16_f32 v68, v68, v69
	v_cvt_pk_bf16_f32 v69, v70, v71
	v_cvt_pk_bf16_f32 v70, v80, v81
	v_cvt_pk_bf16_f32 v71, v82, v83
	global_store_dwordx2 v[124:125], v[64:65], off offset:96
	global_store_dwordx2 v[124:125], v[66:67], off offset:2144
	global_store_dwordx2 v[90:91], v[68:69], off
	global_store_dwordx2 v[88:89], v[70:71], off
	global_load_dwordx4 v[64:67], v[86:87], off
	v_or_b32_e32 v68, 0x50, v120
	v_ashrrev_i32_e32 v69, 31, v68
	v_lshl_add_u64 v[70:71], v[68:69], 2, s[14:15]
	v_lshrrev_b32_e32 v72, 6, v84
	v_and_or_b32 v122, v72, s50, v121
	v_lshlrev_b64 v[72:73], 14, v[122:123]
	v_lshl_add_u64 v[72:73], s[38:39], 0, v[72:73]
	v_lshl_add_u64 v[72:73], v[72:73], 0, v[152:153]
	v_lshl_add_u64 v[74:75], v[72:73], 0, v[114:115]
	v_lshl_add_u64 v[76:77], v[72:73], 0, v[116:117]
	v_lshl_add_u64 v[72:73], v[72:73], 0, v[118:119]
	s_waitcnt vmcnt(0)
	v_pk_fma_f32 v[64:65], v[64:65], s[30:31], v[112:113] op_sel_hi:[1,0,0]
	v_pk_fma_f32 v[66:67], v[66:67], s[30:31], v[112:113] op_sel_hi:[1,0,0]
	v_mul_f32_e32 v69, 0x4b800000, v64
	v_mul_f32_e32 v78, 0x4b800000, v65
	v_mul_f32_e32 v79, 0x4b800000, v66
	v_mul_f32_e32 v80, 0x4b800000, v67
	v_cmp_gt_f32_e32 vcc, s40, v64
	v_cmp_gt_f32_e64 s[0:1], s40, v65
	v_cmp_gt_f32_e64 s[10:11], s40, v66
	v_cmp_gt_f32_e64 s[12:13], s40, v67
	v_cndmask_b32_e32 v64, v64, v69, vcc
	v_cndmask_b32_e64 v65, v65, v78, s[0:1]
	v_cndmask_b32_e64 v66, v66, v79, s[10:11]
	v_cndmask_b32_e64 v67, v67, v80, s[12:13]
	v_rsq_f32_e32 v64, v64
	v_rsq_f32_e32 v65, v65
	v_rsq_f32_e32 v66, v66
	v_rsq_f32_e32 v67, v67
	v_mul_f32_e32 v69, 0x45800000, v64
	v_mul_f32_e32 v78, 0x45800000, v65
	v_mul_f32_e32 v79, 0x45800000, v66
	v_mul_f32_e32 v80, 0x45800000, v67
	v_cndmask_b32_e32 v64, v64, v69, vcc
	v_cndmask_b32_e64 v65, v65, v78, s[0:1]
	v_cndmask_b32_e64 v66, v66, v79, s[10:11]
	v_cndmask_b32_e64 v67, v67, v80, s[12:13]
	v_mul_f32_e32 v60, v60, v64
	v_mul_f32_e32 v61, v61, v65
	v_mul_f32_e32 v62, v62, v66
	v_mul_f32_e32 v63, v63, v67
	v_mul_f32_e32 v56, v56, v64
	v_mul_f32_e32 v57, v57, v65
	v_mul_f32_e32 v52, v52, v64
	v_mul_f32_e32 v53, v53, v65
	v_mul_f32_e32 v54, v54, v66
	v_mul_f32_e32 v55, v55, v67
	v_mul_f32_e32 v64, v48, v64
	v_mul_f32_e32 v65, v49, v65
	v_cvt_pk_bf16_f32 v48, v60, v61
	v_cvt_pk_bf16_f32 v49, v62, v63
	v_mul_f32_e32 v58, v58, v66
	v_mul_f32_e32 v59, v59, v67
	v_mul_f32_e32 v66, v50, v66
	v_mul_f32_e32 v67, v51, v67
	v_cvt_pk_bf16_f32 v50, v56, v57
	v_cvt_pk_bf16_f32 v51, v58, v59
	v_cvt_pk_bf16_f32 v52, v52, v53
	v_cvt_pk_bf16_f32 v53, v54, v55
	v_cvt_pk_bf16_f32 v54, v64, v65
	v_cvt_pk_bf16_f32 v55, v66, v67
	global_store_dwordx2 v[74:75], v[48:49], off
	global_store_dwordx2 v[74:75], v[50:51], off offset:2048
	global_store_dwordx2 v[76:77], v[52:53], off
	global_store_dwordx2 v[72:73], v[54:55], off
	global_load_dwordx4 v[48:51], v[70:71], off
	v_or_b32_e32 v52, 0x60, v120
	v_ashrrev_i32_e32 v53, 31, v52
	v_lshl_add_u64 v[54:55], v[52:53], 2, s[14:15]
	v_lshrrev_b32_e32 v56, 6, v68
	v_and_or_b32 v122, v56, s50, v121
	v_lshlrev_b64 v[56:57], 14, v[122:123]
	v_lshl_add_u64 v[56:57], s[38:39], 0, v[56:57]
	v_lshl_add_u64 v[56:57], v[56:57], 0, v[152:153]
	v_lshl_add_u64 v[58:59], v[56:57], 0, 32
	v_lshl_add_u64 v[56:57], v[56:57], 0, v[114:115]
	v_lshl_add_u64 v[60:61], v[58:59], 0, v[116:117]
	v_lshl_add_u64 v[58:59], v[58:59], 0, v[118:119]
	s_waitcnt vmcnt(0)
	v_pk_fma_f32 v[48:49], v[48:49], s[30:31], v[112:113] op_sel_hi:[1,0,0]
	v_pk_fma_f32 v[50:51], v[50:51], s[30:31], v[112:113] op_sel_hi:[1,0,0]
	v_mul_f32_e32 v53, 0x4b800000, v48
	v_mul_f32_e32 v62, 0x4b800000, v49
	v_mul_f32_e32 v63, 0x4b800000, v50
	v_mul_f32_e32 v64, 0x4b800000, v51
	v_cmp_gt_f32_e32 vcc, s40, v48
	v_cmp_gt_f32_e64 s[0:1], s40, v49
	v_cmp_gt_f32_e64 s[10:11], s40, v50
	v_cmp_gt_f32_e64 s[12:13], s40, v51
	v_cndmask_b32_e32 v48, v48, v53, vcc
	v_cndmask_b32_e64 v49, v49, v62, s[0:1]
	v_cndmask_b32_e64 v50, v50, v63, s[10:11]
	v_cndmask_b32_e64 v51, v51, v64, s[12:13]
	v_rsq_f32_e32 v48, v48
	v_rsq_f32_e32 v49, v49
	v_rsq_f32_e32 v50, v50
	v_rsq_f32_e32 v51, v51
	v_mul_f32_e32 v53, 0x45800000, v48
	v_mul_f32_e32 v62, 0x45800000, v49
	v_mul_f32_e32 v63, 0x45800000, v50
	v_mul_f32_e32 v64, 0x45800000, v51
	v_cndmask_b32_e32 v48, v48, v53, vcc
	v_cndmask_b32_e64 v49, v49, v62, s[0:1]
	v_cndmask_b32_e64 v50, v50, v63, s[10:11]
	v_cndmask_b32_e64 v51, v51, v64, s[12:13]
	v_mul_f32_e32 v44, v44, v48
	v_mul_f32_e32 v45, v45, v49
	v_mul_f32_e32 v46, v46, v50
	v_mul_f32_e32 v47, v47, v51
	v_mul_f32_e32 v40, v40, v48
	v_mul_f32_e32 v41, v41, v49
	v_mul_f32_e32 v36, v36, v48
	v_mul_f32_e32 v37, v37, v49
	v_mul_f32_e32 v38, v38, v50
	v_mul_f32_e32 v39, v39, v51
	v_mul_f32_e32 v48, v32, v48
	v_mul_f32_e32 v49, v33, v49
	v_cvt_pk_bf16_f32 v32, v44, v45
	v_cvt_pk_bf16_f32 v33, v46, v47
	v_mul_f32_e32 v42, v42, v50
	v_mul_f32_e32 v43, v43, v51
	v_mul_f32_e32 v50, v34, v50
	v_mul_f32_e32 v51, v35, v51
	v_cvt_pk_bf16_f32 v34, v40, v41
	v_cvt_pk_bf16_f32 v35, v42, v43
	v_cvt_pk_bf16_f32 v36, v36, v37
	v_cvt_pk_bf16_f32 v37, v38, v39
	v_cvt_pk_bf16_f32 v38, v48, v49
	v_cvt_pk_bf16_f32 v39, v50, v51
	global_store_dwordx2 v[56:57], v[32:33], off offset:32
	global_store_dwordx2 v[56:57], v[34:35], off offset:2080
	global_store_dwordx2 v[60:61], v[36:37], off
	global_store_dwordx2 v[58:59], v[38:39], off
	global_load_dwordx4 v[32:35], v[54:55], off
	v_or_b32_e32 v36, 0x70, v120
	v_ashrrev_i32_e32 v37, 31, v36
	v_lshl_add_u64 v[38:39], v[36:37], 2, s[14:15]
	v_lshrrev_b32_e32 v40, 6, v52
	v_and_or_b32 v122, v40, s50, v121
	v_lshlrev_b64 v[40:41], 14, v[122:123]
	v_lshl_add_u64 v[40:41], s[38:39], 0, v[40:41]
	v_lshl_add_u64 v[40:41], v[40:41], 0, v[152:153]
	v_lshl_add_u64 v[42:43], v[40:41], 0, 64
	v_lshl_add_u64 v[40:41], v[40:41], 0, v[114:115]
	v_lshl_add_u64 v[44:45], v[42:43], 0, v[116:117]
	v_lshl_add_u64 v[42:43], v[42:43], 0, v[118:119]
	s_waitcnt vmcnt(0)
	v_pk_fma_f32 v[32:33], v[32:33], s[30:31], v[112:113] op_sel_hi:[1,0,0]
	v_pk_fma_f32 v[34:35], v[34:35], s[30:31], v[112:113] op_sel_hi:[1,0,0]
	v_mul_f32_e32 v37, 0x4b800000, v32
	v_mul_f32_e32 v46, 0x4b800000, v33
	v_mul_f32_e32 v47, 0x4b800000, v34
	v_mul_f32_e32 v48, 0x4b800000, v35
	v_cmp_gt_f32_e32 vcc, s40, v32
	v_cmp_gt_f32_e64 s[0:1], s40, v33
	v_cmp_gt_f32_e64 s[10:11], s40, v34
	v_cmp_gt_f32_e64 s[12:13], s40, v35
	v_cndmask_b32_e32 v32, v32, v37, vcc
	v_cndmask_b32_e64 v33, v33, v46, s[0:1]
	v_cndmask_b32_e64 v34, v34, v47, s[10:11]
	v_cndmask_b32_e64 v35, v35, v48, s[12:13]
	v_rsq_f32_e32 v32, v32
	v_rsq_f32_e32 v33, v33
	v_rsq_f32_e32 v34, v34
	v_rsq_f32_e32 v35, v35
	v_mul_f32_e32 v37, 0x45800000, v32
	v_mul_f32_e32 v46, 0x45800000, v33
	v_mul_f32_e32 v47, 0x45800000, v34
	v_mul_f32_e32 v48, 0x45800000, v35
	v_cndmask_b32_e32 v32, v32, v37, vcc
	v_cndmask_b32_e64 v33, v33, v46, s[0:1]
	v_cndmask_b32_e64 v34, v34, v47, s[10:11]
	v_cndmask_b32_e64 v35, v35, v48, s[12:13]
	v_mul_f32_e32 v28, v28, v32
	v_mul_f32_e32 v29, v29, v33
	v_mul_f32_e32 v30, v30, v34
	v_mul_f32_e32 v31, v31, v35
	v_mul_f32_e32 v24, v24, v32
	v_mul_f32_e32 v25, v25, v33
	v_mul_f32_e32 v20, v20, v32
	v_mul_f32_e32 v21, v21, v33
	v_mul_f32_e32 v22, v22, v34
	v_mul_f32_e32 v23, v23, v35
	v_mul_f32_e32 v32, v16, v32
	v_mul_f32_e32 v33, v17, v33
	v_cvt_pk_bf16_f32 v16, v28, v29
	v_cvt_pk_bf16_f32 v17, v30, v31
	v_mul_f32_e32 v26, v26, v34
	v_mul_f32_e32 v27, v27, v35
	v_mul_f32_e32 v34, v18, v34
	v_mul_f32_e32 v35, v19, v35
	v_cvt_pk_bf16_f32 v18, v24, v25
	v_cvt_pk_bf16_f32 v19, v26, v27
	v_cvt_pk_bf16_f32 v20, v20, v21
	v_cvt_pk_bf16_f32 v21, v22, v23
	v_cvt_pk_bf16_f32 v22, v32, v33
	v_cvt_pk_bf16_f32 v23, v34, v35
	global_store_dwordx2 v[40:41], v[16:17], off offset:64
	global_store_dwordx2 v[40:41], v[18:19], off offset:2112
	global_store_dwordx2 v[44:45], v[20:21], off
	global_store_dwordx2 v[42:43], v[22:23], off
	global_load_dwordx4 v[16:19], v[38:39], off
	v_lshrrev_b32_e32 v20, 6, v36
	v_and_or_b32 v122, v20, s50, v121
	v_lshlrev_b64 v[20:21], 14, v[122:123]
	v_lshl_add_u64 v[20:21], s[38:39], 0, v[20:21]
	v_lshl_add_u64 v[20:21], v[20:21], 0, v[152:153]
	v_lshl_add_u64 v[22:23], v[20:21], 0, s[36:37]
	v_lshl_add_u64 v[20:21], v[20:21], 0, v[114:115]
	v_lshl_add_u64 v[24:25], v[22:23], 0, v[116:117]
	v_lshl_add_u64 v[22:23], v[22:23], 0, v[118:119]
	s_waitcnt vmcnt(0)
	v_pk_fma_f32 v[16:17], v[16:17], s[30:31], v[112:113] op_sel_hi:[1,0,0]
	v_pk_fma_f32 v[18:19], v[18:19], s[30:31], v[112:113] op_sel_hi:[1,0,0]
	v_mul_f32_e32 v26, 0x4b800000, v16
	v_mul_f32_e32 v27, 0x4b800000, v17
	v_mul_f32_e32 v28, 0x4b800000, v18
	v_mul_f32_e32 v29, 0x4b800000, v19
	v_cmp_gt_f32_e32 vcc, s40, v16
	v_cmp_gt_f32_e64 s[0:1], s40, v17
	v_cmp_gt_f32_e64 s[10:11], s40, v18
	v_cmp_gt_f32_e64 s[12:13], s40, v19
	v_cndmask_b32_e32 v16, v16, v26, vcc
	v_cndmask_b32_e64 v17, v17, v27, s[0:1]
	v_cndmask_b32_e64 v18, v18, v28, s[10:11]
	v_cndmask_b32_e64 v19, v19, v29, s[12:13]
	v_rsq_f32_e32 v16, v16
	v_rsq_f32_e32 v17, v17
	v_rsq_f32_e32 v18, v18
	v_rsq_f32_e32 v19, v19
	v_mul_f32_e32 v26, 0x45800000, v16
	v_mul_f32_e32 v27, 0x45800000, v17
	v_mul_f32_e32 v28, 0x45800000, v18
	v_mul_f32_e32 v29, 0x45800000, v19
	v_cndmask_b32_e32 v16, v16, v26, vcc
	v_cndmask_b32_e64 v17, v17, v27, s[0:1]
	v_cndmask_b32_e64 v18, v18, v28, s[10:11]
	v_cndmask_b32_e64 v19, v19, v29, s[12:13]
	v_mul_f32_e32 v12, v12, v16
	v_mul_f32_e32 v13, v13, v17
	v_mul_f32_e32 v14, v14, v18
	v_mul_f32_e32 v15, v15, v19
	v_mul_f32_e32 v8, v8, v16
	v_mul_f32_e32 v9, v9, v17
	v_mul_f32_e32 v4, v4, v16
	v_mul_f32_e32 v5, v5, v17
	v_mul_f32_e32 v6, v6, v18
	v_mul_f32_e32 v7, v7, v19
	v_mul_f32_e32 v16, v0, v16
	v_mul_f32_e32 v17, v1, v17
	v_cvt_pk_bf16_f32 v0, v12, v13
	v_cvt_pk_bf16_f32 v1, v14, v15
	v_mul_f32_e32 v10, v10, v18
	v_mul_f32_e32 v11, v11, v19
	v_mul_f32_e32 v18, v2, v18
	v_mul_f32_e32 v19, v3, v19
	v_cvt_pk_bf16_f32 v2, v8, v9
	v_cvt_pk_bf16_f32 v3, v10, v11
	v_cvt_pk_bf16_f32 v4, v4, v5
	v_cvt_pk_bf16_f32 v5, v6, v7
	v_cvt_pk_bf16_f32 v6, v16, v17
	v_cvt_pk_bf16_f32 v7, v18, v19
	global_store_dwordx2 v[20:21], v[0:1], off offset:96
	global_store_dwordx2 v[20:21], v[2:3], off offset:2144
	global_store_dwordx2 v[24:25], v[4:5], off
	global_store_dwordx2 v[22:23], v[6:7], off
	s_branch .LBB0_699

.LBB0_769:
	s_add_i32 s14, s13, 64
	s_min_u32 s15, s14, 0x3e0
	s_lshl_b32 s34, s15, 1
	v_lshl_add_u64 v[172:173], v[154:155], 0, s[34:35]
	v_lshl_add_u64 v[176:177], v[158:159], 0, s[34:35]
	v_lshl_add_u64 v[180:181], v[160:161], 0, s[34:35]
	v_lshl_add_u64 v[184:185], v[162:163], 0, s[34:35]
	v_lshl_add_u64 v[188:189], v[156:157], 0, s[34:35]
	v_lshl_add_u64 v[192:193], v[164:165], 0, s[34:35]
	global_load_dwordx4 v[172:175], v[172:173], off
	ds_read_b128 v[196:199], v171 offset:32768
	global_load_dwordx4 v[176:179], v[176:177], off
	ds_read_b128 v[200:203], v171 offset:33792
	global_load_dwordx4 v[180:183], v[180:181], off
	ds_read_b128 v[204:207], v171 offset:34816
	global_load_dwordx4 v[184:187], v[184:185], off
	ds_read_b128 v[208:211], v171 offset:35840
	global_load_dwordx4 v[188:191], v[188:189], off
	ds_read_b128 v[212:215], v169
	global_load_dwordx4 v[192:195], v[192:193], off
	ds_read_b128 v[216:219], v169 offset:1024
	ds_read_b128 v[222:225], v169 offset:2048
	ds_read_b128 v[226:229], v169 offset:3072
	ds_read_b128 v[230:233], v169 offset:4096
	ds_read_b128 v[234:237], v169 offset:5120
	ds_read_b128 v[238:241], v169 offset:6144
	ds_read_b128 v[242:245], v169 offset:7168
	s_waitcnt lgkmcnt(7)
	v_mfma_f32_16x16x32_bf16 v[148:151], v[196:199], v[212:215], v[148:151]
	v_mfma_f32_16x16x32_bf16 v[144:147], v[200:203], v[212:215], v[144:147]
	v_mfma_f32_16x16x32_bf16 v[116:119], v[204:207], v[212:215], v[116:119]
	v_mfma_f32_16x16x32_bf16 v[112:115], v[208:211], v[212:215], v[112:115]
	s_waitcnt vmcnt(11)
	ds_write_b128 v152, v[120:123] offset:16384
	s_waitcnt lgkmcnt(7)
	v_mfma_f32_16x16x32_bf16 v[108:111], v[196:199], v[216:219], v[108:111]
	v_mfma_f32_16x16x32_bf16 v[104:107], v[200:203], v[216:219], v[104:107]
	v_mfma_f32_16x16x32_bf16 v[100:103], v[204:207], v[216:219], v[100:103]
	v_mfma_f32_16x16x32_bf16 v[96:99], v[208:211], v[216:219], v[96:99]
	s_waitcnt vmcnt(9)
	ds_write_b128 v152, v[128:131] offset:20480
	s_waitcnt lgkmcnt(7)
	v_mfma_f32_16x16x32_bf16 v[92:95], v[196:199], v[222:225], v[92:95]
	v_mfma_f32_16x16x32_bf16 v[88:91], v[200:203], v[222:225], v[88:91]
	v_mfma_f32_16x16x32_bf16 v[84:87], v[204:207], v[222:225], v[84:87]
	v_mfma_f32_16x16x32_bf16 v[80:83], v[208:211], v[222:225], v[80:83]
	s_waitcnt vmcnt(8)
	ds_write_b128 v152, v[132:135] offset:24576
	s_waitcnt lgkmcnt(7)
	v_mfma_f32_16x16x32_bf16 v[76:79], v[196:199], v[226:229], v[76:79]
	v_mfma_f32_16x16x32_bf16 v[72:75], v[200:203], v[226:229], v[72:75]
	v_mfma_f32_16x16x32_bf16 v[68:71], v[204:207], v[226:229], v[68:71]
	v_mfma_f32_16x16x32_bf16 v[64:67], v[208:211], v[226:229], v[64:67]
	s_waitcnt vmcnt(7)
	ds_write_b128 v152, v[136:139] offset:28672
	s_waitcnt lgkmcnt(7)
	v_mfma_f32_16x16x32_bf16 v[60:63], v[196:199], v[230:233], v[60:63]
	v_mfma_f32_16x16x32_bf16 v[56:59], v[200:203], v[230:233], v[56:59]
	v_mfma_f32_16x16x32_bf16 v[52:55], v[204:207], v[230:233], v[52:55]
	v_mfma_f32_16x16x32_bf16 v[48:51], v[208:211], v[230:233], v[48:51]
	s_waitcnt vmcnt(7)
	ds_write_b128 v152, v[124:127] offset:40960
	s_waitcnt lgkmcnt(7)
	v_mfma_f32_16x16x32_bf16 v[44:47], v[196:199], v[234:237], v[44:47]
	v_mfma_f32_16x16x32_bf16 v[40:43], v[200:203], v[234:237], v[40:43]
	v_mfma_f32_16x16x32_bf16 v[36:39], v[204:207], v[234:237], v[36:39]
	v_mfma_f32_16x16x32_bf16 v[32:35], v[208:211], v[234:237], v[32:35]
	s_waitcnt vmcnt(6)
	ds_write_b128 v152, v[140:143] offset:45056
	s_waitcnt lgkmcnt(7)
	v_mfma_f32_16x16x32_bf16 v[28:31], v[196:199], v[238:241], v[28:31]
	v_mfma_f32_16x16x32_bf16 v[24:27], v[200:203], v[238:241], v[24:27]
	v_mfma_f32_16x16x32_bf16 v[20:23], v[204:207], v[238:241], v[20:23]
	v_mfma_f32_16x16x32_bf16 v[16:19], v[208:211], v[238:241], v[16:19]
	s_waitcnt lgkmcnt(6)
	v_mfma_f32_16x16x32_bf16 v[12:15], v[196:199], v[242:245], v[12:15]
	v_mfma_f32_16x16x32_bf16 v[8:11], v[200:203], v[242:245], v[8:11]
	v_mfma_f32_16x16x32_bf16 v[4:7], v[204:207], v[242:245], v[4:7]
	v_mfma_f32_16x16x32_bf16 v[0:3], v[208:211], v[242:245], v[0:3]
	s_min_u32 s13, s13, 0x380
	s_lshl_b32 s34, s13, 1
	s_mov_b32 s17, s35
	s_add_i32 s16, s34, 0xc0
	v_lshl_add_u64 v[120:121], v[154:155], 0, s[34:35]
	v_lshl_add_u64 v[124:125], v[156:157], 0, s[34:35]
	v_lshl_add_u64 v[128:129], v[158:159], 0, s[16:17]
	v_lshl_add_u64 v[132:133], v[160:161], 0, s[16:17]
	v_lshl_add_u64 v[136:137], v[162:163], 0, s[16:17]
	v_lshl_add_u64 v[140:141], v[164:165], 0, s[16:17]
	s_waitcnt lgkmcnt(0)
	s_barrier
	global_load_dwordx4 v[120:123], v[120:121], off offset:192
	ds_read_b128 v[196:199], v168 offset:40960
	global_load_dwordx4 v[124:127], v[124:125], off offset:192
	ds_read_b128 v[200:203], v168 offset:41984
	global_load_dwordx4 v[128:131], v[128:129], off
	ds_read_b128 v[204:207], v168 offset:43008
	global_load_dwordx4 v[132:135], v[132:133], off
	ds_read_b128 v[208:211], v168 offset:44032
	global_load_dwordx4 v[136:139], v[136:137], off
	ds_read_b128 v[212:215], v170
	global_load_dwordx4 v[140:143], v[140:141], off
	ds_read_b128 v[216:219], v170 offset:1024
	ds_read_b128 v[222:225], v170 offset:2048
	ds_read_b128 v[226:229], v170 offset:3072
	ds_read_b128 v[230:233], v170 offset:4096
	ds_read_b128 v[234:237], v170 offset:5120
	ds_read_b128 v[238:241], v170 offset:6144
	ds_read_b128 v[242:245], v170 offset:7168
	s_waitcnt lgkmcnt(7)
	v_mfma_f32_16x16x32_bf16 v[148:151], v[196:199], v[212:215], v[148:151]
	v_mfma_f32_16x16x32_bf16 v[144:147], v[200:203], v[212:215], v[144:147]
	v_mfma_f32_16x16x32_bf16 v[116:119], v[204:207], v[212:215], v[116:119]
	v_mfma_f32_16x16x32_bf16 v[112:115], v[208:211], v[212:215], v[112:115]
	s_waitcnt vmcnt(11)
	ds_write_b128 v152, v[172:175]
	s_waitcnt lgkmcnt(7)
	v_mfma_f32_16x16x32_bf16 v[108:111], v[196:199], v[216:219], v[108:111]
	v_mfma_f32_16x16x32_bf16 v[104:107], v[200:203], v[216:219], v[104:107]
	v_mfma_f32_16x16x32_bf16 v[100:103], v[204:207], v[216:219], v[100:103]
	v_mfma_f32_16x16x32_bf16 v[96:99], v[208:211], v[216:219], v[96:99]
	s_waitcnt vmcnt(10)
	ds_write_b128 v152, v[176:179] offset:4096
	s_waitcnt lgkmcnt(7)
	v_mfma_f32_16x16x32_bf16 v[92:95], v[196:199], v[222:225], v[92:95]
	v_mfma_f32_16x16x32_bf16 v[88:91], v[200:203], v[222:225], v[88:91]
	v_mfma_f32_16x16x32_bf16 v[84:87], v[204:207], v[222:225], v[84:87]
	v_mfma_f32_16x16x32_bf16 v[80:83], v[208:211], v[222:225], v[80:83]
	s_waitcnt vmcnt(9)
	ds_write_b128 v152, v[180:183] offset:8192
	s_waitcnt lgkmcnt(7)
	v_mfma_f32_16x16x32_bf16 v[76:79], v[196:199], v[226:229], v[76:79]
	v_mfma_f32_16x16x32_bf16 v[72:75], v[200:203], v[226:229], v[72:75]
	v_mfma_f32_16x16x32_bf16 v[68:71], v[204:207], v[226:229], v[68:71]
	v_mfma_f32_16x16x32_bf16 v[64:67], v[208:211], v[226:229], v[64:67]
	s_waitcnt vmcnt(8)
	ds_write_b128 v152, v[184:187] offset:12288
	s_waitcnt lgkmcnt(7)
	v_mfma_f32_16x16x32_bf16 v[60:63], v[196:199], v[230:233], v[60:63]
	v_mfma_f32_16x16x32_bf16 v[56:59], v[200:203], v[230:233], v[56:59]
	v_mfma_f32_16x16x32_bf16 v[52:55], v[204:207], v[230:233], v[52:55]
	v_mfma_f32_16x16x32_bf16 v[48:51], v[208:211], v[230:233], v[48:51]
	s_waitcnt vmcnt(7)
	ds_write_b128 v152, v[188:191] offset:32768
	s_waitcnt lgkmcnt(7)
	v_mfma_f32_16x16x32_bf16 v[44:47], v[196:199], v[234:237], v[44:47]
	v_mfma_f32_16x16x32_bf16 v[40:43], v[200:203], v[234:237], v[40:43]
	v_mfma_f32_16x16x32_bf16 v[36:39], v[204:207], v[234:237], v[36:39]
	v_mfma_f32_16x16x32_bf16 v[32:35], v[208:211], v[234:237], v[32:35]
	s_waitcnt vmcnt(6)
	ds_write_b128 v152, v[192:195] offset:36864
	s_waitcnt lgkmcnt(7)
	v_mfma_f32_16x16x32_bf16 v[28:31], v[196:199], v[238:241], v[28:31]
	v_mfma_f32_16x16x32_bf16 v[24:27], v[200:203], v[238:241], v[24:27]
	v_mfma_f32_16x16x32_bf16 v[20:23], v[204:207], v[238:241], v[20:23]
	v_mfma_f32_16x16x32_bf16 v[16:19], v[208:211], v[238:241], v[16:19]
	s_waitcnt lgkmcnt(6)
	v_mfma_f32_16x16x32_bf16 v[12:15], v[196:199], v[242:245], v[12:15]
	v_mfma_f32_16x16x32_bf16 v[8:11], v[200:203], v[242:245], v[8:11]
	v_mfma_f32_16x16x32_bf16 v[4:7], v[204:207], v[242:245], v[4:7]
	v_mfma_f32_16x16x32_bf16 v[0:3], v[208:211], v[242:245], v[0:3]
	s_add_i32 s11, s11, 2
	s_cmp_lt_u32 s11, 30
	s_mov_b32 s13, s14
	s_waitcnt lgkmcnt(0)
	s_barrier
	s_cbranch_scc1 .LBB0_769
	s_waitcnt vmcnt(4)
	v_mov_b32_e32 v126, v220
	v_mov_b64_e32 v[124:125], s[72:73]
	v_and_b32_e32 v120, 0xffffff80, v126
	v_add_u32_e32 v120, s12, v120
	v_and_or_b32 v122, v126, 15, v120
	v_ashrrev_i32_e32 v123, 31, v122
	v_lshl_add_u64 v[120:121], v[122:123], 2, s[0:1]
	global_load_dword v120, v[120:121], off
	v_and_b32_e32 v121, 64, v126
	v_lshrrev_b32_e32 v126, 2, v126
	v_and_b32_e32 v126, 12, v126
	s_waitcnt vmcnt(0)
	v_fmamk_f32 v120, v120, 0x3a800000, v167
	v_mul_f32_e32 v127, 0x4b800000, v120
	v_cmp_gt_f32_e32 vcc, s42, v120
	s_nop 1
	v_cndmask_b32_e32 v120, v120, v127, vcc
	v_rsq_f32_e32 v127, v120
	v_or3_b32 v120, v121, v126, s10
	v_mad_i64_i32 v[124:125], s[10:11], v122, s41, v[124:125]
	v_mul_f32_e32 v121, 0x45800000, v127
	v_cndmask_b32_e32 v129, v127, v121, vcc
	v_mul_f32_e32 v132, v148, v129
	v_mul_f32_e32 v131, v149, v129
	v_mul_f32_e32 v130, v150, v129
	v_mul_f32_e32 v128, v151, v129
	v_cmp_lt_i32_e64 s[10:11], s43, v120
	s_and_saveexec_b64 s[12:13], s[10:11]
	s_xor_b64 s[12:13], exec, s[12:13]
	s_cbranch_execz .LBB0_774
	v_cmp_gt_u32_e32 vcc, s44, v120
	s_and_saveexec_b64 s[14:15], vcc
	s_cbranch_execz .LBB0_773
	v_mul_f32_e32 v121, 0xbfb8aa3b, v132
	v_exp_f32_e32 v121, v121
	v_mul_f32_e32 v126, 0xbfb8aa3b, v131
	v_mul_f32_e32 v127, 0xbfb8aa3b, v128
	v_exp_f32_e32 v126, v126
	v_add_f32_e32 v121, 1.0, v121
	v_rcp_f32_e32 v132, v121
	v_mul_f32_e32 v121, 0xbfb8aa3b, v130
	v_exp_f32_e32 v121, v121
	v_exp_f32_e32 v127, v127
	v_add_f32_e32 v126, 1.0, v126
	v_rcp_f32_e32 v133, v126
	v_add_f32_e32 v121, 1.0, v121
	v_rcp_f32_e32 v134, v121
	v_add_f32_e32 v121, 1.0, v127
	v_rcp_f32_e32 v135, v121
	v_mov_b32_e32 v121, v153
	v_lshl_add_u64 v[126:127], v[120:121], 2, v[124:125]
	v_add_co_u32_e32 v126, vcc, 0x2ffe000, v126
	s_nop 1
	v_addc_co_u32_e32 v127, vcc, 0, v127, vcc
	global_store_dwordx4 v[126:127], v[132:135], off

.LBB0_969:
	s_add_i32 s16, s15, 64
	s_min_u32 s10, s16, 0xfe0
	s_lshl_b32 s10, s10, 1
	v_lshl_add_u64 v[98:99], v[86:87], 0, s[10:11]
	v_lshl_add_u64 v[102:103], v[88:89], 0, s[10:11]
	v_lshl_add_u64 v[106:107], v[82:83], 0, s[10:11]
	v_lshl_add_u64 v[110:111], v[84:85], 0, s[10:11]
	global_load_dwordx4 v[98:101], v[98:99], off
	ds_read_b128 v[114:117], v94
	global_load_dwordx4 v[102:105], v[102:103], off
	ds_read_b128 v[118:121], v94 offset:1024
	global_load_dwordx4 v[106:109], v[106:107], off
	ds_read_b128 v[122:125], v95 offset:16384
	global_load_dwordx4 v[110:113], v[110:111], off
	ds_read_b128 v[126:129], v95 offset:17408
	ds_read_b128 v[130:133], v94 offset:2048
	ds_read_b128 v[134:137], v94 offset:3072
	ds_read_b128 v[138:141], v95 offset:18432
	ds_read_b128 v[142:145], v95 offset:19456
	s_waitcnt lgkmcnt(5)
	v_mfma_f32_16x16x32_bf16 v[60:63], v[114:117], v[122:125], v[60:63]
	s_waitcnt lgkmcnt(4)
	v_mfma_f32_16x16x32_bf16 v[56:59], v[114:117], v[126:129], v[56:59]
	s_waitcnt lgkmcnt(1)
	v_mfma_f32_16x16x32_bf16 v[52:55], v[114:117], v[138:141], v[52:55]
	s_waitcnt lgkmcnt(0)
	v_mfma_f32_16x16x32_bf16 v[48:51], v[114:117], v[142:145], v[48:51]
	v_mfma_f32_16x16x32_bf16 v[44:47], v[118:121], v[122:125], v[44:47]
	v_mfma_f32_16x16x32_bf16 v[40:43], v[118:121], v[126:129], v[40:43]
	v_mfma_f32_16x16x32_bf16 v[36:39], v[118:121], v[138:141], v[36:39]
	v_mfma_f32_16x16x32_bf16 v[32:35], v[118:121], v[142:145], v[32:35]
	v_mfma_f32_16x16x32_bf16 v[28:31], v[130:133], v[122:125], v[28:31]
	v_mfma_f32_16x16x32_bf16 v[24:27], v[130:133], v[126:129], v[24:27]
	v_mfma_f32_16x16x32_bf16 v[20:23], v[130:133], v[138:141], v[20:23]
	v_mfma_f32_16x16x32_bf16 v[16:19], v[130:133], v[142:145], v[16:19]
	v_mfma_f32_16x16x32_bf16 v[12:15], v[134:137], v[122:125], v[12:15]
	v_mfma_f32_16x16x32_bf16 v[8:11], v[134:137], v[126:129], v[8:11]
	v_mfma_f32_16x16x32_bf16 v[4:7], v[134:137], v[138:141], v[4:7]
	v_mfma_f32_16x16x32_bf16 v[0:3], v[134:137], v[142:145], v[0:3]
	s_min_u32 s10, s15, 0xf80
	s_lshl_b32 s10, s10, 1
	s_waitcnt vmcnt(5)
	ds_write_b128 v80, v[64:67] offset:24576
	s_waitcnt vmcnt(4)
	ds_write_b128 v80, v[68:71] offset:28672
	v_lshl_add_u64 v[64:65], v[86:87], 0, s[10:11]
	v_lshl_add_u64 v[66:67], v[88:89], 0, s[10:11]
	v_lshl_add_u64 v[68:69], v[82:83], 0, s[10:11]
	v_lshl_add_u64 v[70:71], v[84:85], 0, s[10:11]
	s_waitcnt vmcnt(5)
	ds_write_b128 v80, v[72:75] offset:8192
	s_waitcnt vmcnt(4)
	ds_write_b128 v80, v[76:79] offset:12288
	s_waitcnt lgkmcnt(0)
	s_barrier
	global_load_dwordx4 v[72:75], v[64:65], off offset:192
	global_load_dwordx4 v[76:79], v[66:67], off offset:192
	ds_read_b128 v[114:117], v96
	global_load_dwordx4 v[64:67], v[68:69], off offset:192
	ds_read_b128 v[118:121], v93 offset:24576
	global_load_dwordx4 v[68:71], v[70:71], off offset:192
	ds_read_b128 v[122:125], v96 offset:1024
	ds_read_b128 v[126:129], v93 offset:25600
	ds_read_b128 v[130:133], v96 offset:2048
	ds_read_b128 v[134:137], v93 offset:26624
	ds_read_b128 v[138:141], v96 offset:3072
	ds_read_b128 v[142:145], v93 offset:27648
	s_waitcnt lgkmcnt(6)
	v_mfma_f32_16x16x32_bf16 v[60:63], v[114:117], v[118:121], v[60:63]
	s_waitcnt lgkmcnt(4)
	v_mfma_f32_16x16x32_bf16 v[56:59], v[114:117], v[126:129], v[56:59]
	s_waitcnt lgkmcnt(2)
	v_mfma_f32_16x16x32_bf16 v[52:55], v[114:117], v[134:137], v[52:55]
	s_waitcnt lgkmcnt(0)
	v_mfma_f32_16x16x32_bf16 v[48:51], v[114:117], v[142:145], v[48:51]
	v_mfma_f32_16x16x32_bf16 v[44:47], v[122:125], v[118:121], v[44:47]
	v_mfma_f32_16x16x32_bf16 v[40:43], v[122:125], v[126:129], v[40:43]
	v_mfma_f32_16x16x32_bf16 v[36:39], v[122:125], v[134:137], v[36:39]
	v_mfma_f32_16x16x32_bf16 v[32:35], v[122:125], v[142:145], v[32:35]
	v_mfma_f32_16x16x32_bf16 v[28:31], v[130:133], v[118:121], v[28:31]
	v_mfma_f32_16x16x32_bf16 v[24:27], v[130:133], v[126:129], v[24:27]
	v_mfma_f32_16x16x32_bf16 v[20:23], v[130:133], v[134:137], v[20:23]
	v_mfma_f32_16x16x32_bf16 v[16:19], v[130:133], v[142:145], v[16:19]
	v_mfma_f32_16x16x32_bf16 v[12:15], v[138:141], v[118:121], v[12:15]
	v_mfma_f32_16x16x32_bf16 v[8:11], v[138:141], v[126:129], v[8:11]
	v_mfma_f32_16x16x32_bf16 v[4:7], v[138:141], v[134:137], v[4:7]
	v_mfma_f32_16x16x32_bf16 v[0:3], v[138:141], v[142:145], v[0:3]
	s_add_i32 s13, s13, 2
	s_cmpk_lt_u32 s13, 0x7e
	s_mov_b32 s15, s16
	s_waitcnt vmcnt(7)
	ds_write_b128 v80, v[98:101]
	s_waitcnt vmcnt(6)
	ds_write_b128 v92, v[102:105]
	s_waitcnt vmcnt(5)
	ds_write_b128 v80, v[106:109] offset:16384
	s_waitcnt vmcnt(4)
	ds_write_b128 v92, v[110:113] offset:16384
	s_waitcnt lgkmcnt(0)
	s_barrier
	s_cbranch_scc1 .LBB0_969
	s_lshl_b32 s12, s12, 13
	v_mov_b32_e32 v200, v220
	s_ashr_i32 s13, s12, 31
	s_lshl_b64 s[12:13], s[12:13], 2
	s_waitcnt vmcnt(1)
	v_and_b32_e32 v64, 0x4f, v200
	v_or_b32_e32 v201, s1, v64
	s_add_u32 s12, s6, s12
	s_addc_u32 s13, s7, s13
	v_lshlrev_b32_e32 v80, 2, v201
	v_lshl_add_u64 v[64:65], s[12:13], 0, v[80:81]
	v_add_co_u32_e32 v66, vcc, s24, v64
	s_ashr_i32 s1, s0, 31
	s_nop 0
	v_addc_co_u32_e32 v67, vcc, 0, v65, vcc
	v_add_co_u32_e32 v104, vcc, s23, v64
	s_lshl_b64 s[0:1], s[0:1], 19
	s_nop 0
	v_addc_co_u32_e32 v105, vcc, 0, v65, vcc
	v_add_co_u32_e32 v112, vcc, s25, v64
	s_nop 1
	v_addc_co_u32_e32 v113, vcc, 0, v65, vcc
	v_add_co_u32_e32 v116, vcc, s26, v64
	s_nop 1
	v_addc_co_u32_e32 v117, vcc, 0, v65, vcc
	v_add_co_u32_e32 v120, vcc, s27, v64
	s_nop 1
	v_addc_co_u32_e32 v121, vcc, 0, v65, vcc
	v_add_co_u32_e32 v134, vcc, s28, v64
	s_nop 1
	v_addc_co_u32_e32 v135, vcc, 0, v65, vcc
	v_add_co_u32_e32 v64, vcc, s29, v64
	s_nop 1
	v_addc_co_u32_e32 v65, vcc, 0, v65, vcc
	global_load_dword v68, v80, s[12:13] offset:1024
	global_load_dword v139, v80, s[12:13] offset:2048
	global_load_dword v136, v80, s[12:13] offset:1088
	global_load_dword v137, v80, s[12:13] offset:2112
	global_load_dword v69, v80, s[12:13] offset:1152
	global_load_dword v70, v80, s[12:13] offset:2176
	global_load_dword v71, v80, s[12:13] offset:1216
	global_load_dword v72, v80, s[12:13] offset:192
	global_load_dword v151, v80, s[12:13] offset:3072
	global_load_dword v152, v[104:105], off offset:-4096
	global_load_dword v149, v[104:105], off
	global_load_dword v141, v80, s[12:13] offset:3136
	global_load_dword v140, v[104:105], off offset:64
	global_load_dword v84, v80, s[12:13] offset:3200
	global_load_dword v73, v80, s[12:13] offset:3264
	global_load_dword v74, v80, s[12:13] offset:2240
	global_load_dword v155, v[66:67], off offset:1024
	global_load_dword v156, v[66:67], off offset:2048
	global_load_dword v142, v[66:67], off offset:64
	global_load_dword v143, v[66:67], off offset:1088
	global_load_dword v87, v[66:67], off offset:128
	global_load_dword v88, v[66:67], off offset:1152
	global_load_dword v75, v[66:67], off offset:1216
	global_load_dword v76, v[66:67], off offset:192
	global_load_dword v159, v[66:67], off offset:3072
	global_load_dword v145, v[66:67], off offset:2112
	global_load_dword v146, v[66:67], off offset:3136
	global_load_dword v144, v[112:113], off offset:64
	global_load_dword v93, v[66:67], off offset:2176
	global_load_dword v94, v[66:67], off offset:3200
	global_load_dword v77, v[66:67], off offset:3264
	global_load_dword v78, v[66:67], off offset:2240
	global_load_dword v162, v[104:105], off offset:1024
	global_load_dword v163, v[104:105], off offset:2048
	global_load_dword v147, v[104:105], off offset:1088
	global_load_dword v148, v[104:105], off offset:2112
	global_load_dword v97, v[104:105], off offset:128
	global_load_dword v98, v[104:105], off offset:1152
	global_load_dword v79, v[104:105], off offset:1216
	global_load_dword v82, v[104:105], off offset:192
	global_load_dword v167, v[104:105], off offset:3072
	global_load_dword v168, v[116:117], off offset:-4096
	global_load_dword v164, v[116:117], off
	global_load_dword v150, v[104:105], off offset:3136
	global_load_dword v101, v[104:105], off offset:2176
	global_load_dword v102, v[104:105], off offset:3200
	global_load_dword v83, v[104:105], off offset:3264
	global_load_dword v85, v[104:105], off offset:2240
	global_load_dword v171, v[112:113], off offset:1024
	global_load_dword v172, v[112:113], off offset:2048
	global_load_dword v153, v[112:113], off offset:1088
	global_load_dword v154, v[112:113], off offset:2112
	s_nop 0
	global_load_dword v105, v[112:113], off offset:128
	global_load_dword v106, v[112:113], off offset:1152
	global_load_dword v86, v[112:113], off offset:1216
	global_load_dword v89, v[112:113], off offset:192
	global_load_dword v175, v[112:113], off offset:3072
	global_load_dword v158, v[112:113], off offset:3136
	global_load_dword v157, v[120:121], off offset:64
	global_load_dword v110, v[112:113], off offset:2176
	global_load_dword v111, v[112:113], off offset:3200
	global_load_dword v108, v[120:121], off offset:128
	global_load_dword v92, v[112:113], off offset:3264
	global_load_dword v95, v[112:113], off offset:2240
	global_load_dword v178, v[116:117], off offset:1024
	global_load_dword v179, v[116:117], off offset:2048
	global_load_dword v160, v[116:117], off offset:64
	global_load_dword v161, v[116:117], off offset:1088
	global_load_dword v114, v[116:117], off offset:128
	global_load_dword v115, v[116:117], off offset:1152
	global_load_dword v96, v[116:117], off offset:1216
	global_load_dword v99, v[116:117], off offset:192
	global_load_dword v182, v[116:117], off offset:3072
	global_load_dword v183, v[134:135], off offset:-4096
	global_load_dword v165, v[116:117], off offset:2112
	global_load_dword v166, v[116:117], off offset:3136
	global_load_dword v118, v[116:117], off offset:2176
	global_load_dword v119, v[116:117], off offset:3200
	global_load_dword v100, v[116:117], off offset:3264
	global_load_dword v103, v[116:117], off offset:2240
	global_load_dword v186, v[120:121], off offset:1024
	global_load_dword v187, v[120:121], off offset:2048
	global_load_dword v169, v[120:121], off offset:1088
	global_load_dword v170, v[120:121], off offset:2112
	global_load_dword v122, v[120:121], off offset:1152
	global_load_dword v123, v[120:121], off offset:2176
	global_load_dword v104, v[120:121], off offset:1216
	global_load_dword v107, v[120:121], off offset:192
	global_load_dword v190, v[120:121], off offset:3072
	global_load_dword v188, v[64:65], off
	global_load_dword v174, v[120:121], off offset:3136
	global_load_dword v173, v[64:65], off offset:64
	global_load_dword v127, v[120:121], off offset:3200
	global_load_dword v125, v[64:65], off offset:128
	global_load_dword v109, v[120:121], off offset:3264
	global_load_dword v112, v[120:121], off offset:2240
	global_load_dword v191, v[134:135], off
	global_load_dword v192, v[134:135], off offset:1024
	global_load_dword v176, v[134:135], off offset:64
	global_load_dword v177, v[134:135], off offset:1088
	global_load_dword v129, v[134:135], off offset:128
	global_load_dword v130, v[134:135], off offset:1152
	global_load_dword v113, v[134:135], off offset:1216
	global_load_dword v116, v[134:135], off offset:192
	global_load_dword v193, v[134:135], off offset:2048
	global_load_dword v194, v[134:135], off offset:3072
	global_load_dword v180, v[134:135], off offset:2112
	global_load_dword v181, v[134:135], off offset:3136
	global_load_dword v131, v[134:135], off offset:2176
	global_load_dword v132, v[134:135], off offset:3200
	global_load_dword v117, v[134:135], off offset:3264
	global_load_dword v120, v[134:135], off offset:2240
	global_load_dword v195, v[64:65], off offset:1024
	global_load_dword v196, v[64:65], off offset:2048
	global_load_dword v184, v[64:65], off offset:1088
	global_load_dword v185, v[64:65], off offset:2112
	global_load_dword v133, v[64:65], off offset:1152
	global_load_dword v134, v[64:65], off offset:2176
	global_load_dword v121, v[64:65], off offset:1216
	global_load_dword v124, v[64:65], off offset:192
	global_load_dword v199, v80, s[12:13]
	global_load_dword v197, v[64:65], off offset:3072
	global_load_dword v198, v80, s[12:13] offset:64
	global_load_dword v189, v[64:65], off offset:3136
	global_load_dword v138, v80, s[12:13] offset:128
	global_load_dword v135, v[64:65], off offset:3200
	global_load_dword v126, v[64:65], off offset:3264
	global_load_dword v128, v[64:65], off offset:2240
	v_ashrrev_i32_e32 v64, 1, v200
	v_and_b32_e32 v64, 0xffffffc0, v64
	v_lshrrev_b32_e32 v65, 2, v200
	v_add_u32_e32 v64, s14, v64
	v_and_or_b32 v64, v65, 12, v64
	s_add_u32 s12, s8, s0
	v_ashrrev_i32_e32 v65, 31, v64
	s_addc_u32 s13, s9, s1
	v_lshlrev_b64 v[66:67], 9, v[64:65]
	v_cmp_lt_i32_e32 vcc, s21, v64
	v_lshl_add_u64 v[66:67], s[12:13], 0, v[66:67]
	v_lshlrev_b32_e32 v80, 1, v201
	s_and_saveexec_b64 s[0:1], vcc
	s_xor_b64 s[0:1], exec, s[0:1]
	s_cbranch_execz .LBB0_972
	v_lshl_add_u64 v[200:201], v[66:67], 0, v[80:81]
	global_store_short v[200:201], v81, off

.LBB0_1408:
	s_ashr_i32 s0, s26, 3
	s_ashr_i32 s1, s0, 31
	s_and_b32 s10, s9, 0x380
	s_lshl_b64 s[16:17], s[0:1], 19
	s_add_u32 s1, s3, s16
	s_addc_u32 s11, s4, s17
	s_lshl_b32 s12, s10, 9
	s_add_u32 s16, s1, s12
	s_addc_u32 s17, s11, 0
	v_mov_b32_e32 v40, v220
	s_cmp_lt_u32 s26, 64
	s_cselect_b32 s1, s21, 0x1a10000
	v_ashrrev_i32_e32 v24, 2, v40
	v_add_u32_e32 v26, 64, v24
	s_add_u32 s28, s72, s1
	v_ashrrev_i32_e32 v27, 31, v26
	v_min_i32_e32 v4, 0x7f, v24
	v_min_i32_e32 v6, 0x7f, v26
	v_lshlrev_b32_e32 v5, 4, v40
	s_addc_u32 s29, s73, 0
	v_ashrrev_i32_e32 v25, 31, v24
	v_lshlrev_b64 v[0:1], 9, v[26:27]
	v_and_b32_e32 v64, 48, v5
	v_ashrrev_i32_e32 v5, 31, v4
	v_ashrrev_i32_e32 v7, 31, v6
	v_lshl_add_u64 v[2:3], s[28:29], 0, v[0:1]
	v_lshlrev_b64 v[0:1], 9, v[24:25]
	v_lshlrev_b64 v[4:5], 9, v[4:5]
	v_lshlrev_b64 v[6:7], 9, v[6:7]
	v_lshl_add_u64 v[0:1], s[28:29], 0, v[0:1]
	v_lshl_add_u64 v[4:5], s[16:17], 0, v[4:5]
	v_lshl_add_u64 v[6:7], s[16:17], 0, v[6:7]
	v_lshl_add_u64 v[0:1], v[0:1], 0, v[64:65]
	v_lshl_add_u64 v[2:3], v[2:3], 0, v[64:65]
	v_lshl_add_u64 v[4:5], v[4:5], 0, v[64:65]
	v_lshl_add_u64 v[6:7], v[6:7], 0, v[64:65]
	global_load_dwordx4 v[8:11], v[4:5], off
	global_load_dwordx4 v[12:15], v[6:7], off
	global_load_dwordx4 v[16:19], v[0:1], off
	global_load_dwordx4 v[20:23], v[2:3], off
	v_lshrrev_b32_e32 v41, 4, v40
	v_sub_u32_e32 v25, 0, v41
	v_xor_b32_e32 v25, v40, v25
	v_lshlrev_b32_e32 v25, 4, v25
	v_and_b32_e32 v25, 48, v25
	v_lshl_or_b32 v64, v24, 6, v25
	v_lshl_or_b32 v79, v26, 6, v25
	global_load_dwordx4 v[24:27], v[4:5], off offset:64
	global_load_dwordx4 v[28:31], v[6:7], off offset:64
	global_load_dwordx4 v[32:35], v[0:1], off offset:64
	global_load_dwordx4 v[36:39], v[2:3], off offset:64
	v_lshrrev_b32_e32 v42, 2, v40
	v_sub_u32_e32 v42, 0, v42
	v_xor_b32_e32 v41, v41, v42
	v_and_b32_e32 v42, 15, v40
	v_lshrrev_b32_e32 v43, 1, v40
	v_lshlrev_b32_e32 v41, 4, v41
	v_and_or_b32 v42, v43, s22, v42
	v_and_b32_e32 v41, 48, v41
	v_lshlrev_b32_e32 v40, 6, v40
	s_waitcnt vmcnt(16)
	v_lshl_or_b32 v144, v42, 6, v41
	v_and_or_b32 v148, v40, s23, v41
	s_lshl_b32 s12, s0, 17
	s_cmp_gt_u32 s26, 63
	s_waitcnt vmcnt(7)
	ds_write_b128 v64, v[8:11]
	s_waitcnt vmcnt(6)
	ds_write_b128 v79, v[12:15]
	s_waitcnt vmcnt(5)
	ds_write_b128 v64, v[16:19] offset:16384
	s_waitcnt vmcnt(4)
	ds_write_b128 v79, v[20:23] offset:16384
	s_waitcnt lgkmcnt(0)
	s_barrier
	global_load_dwordx4 v[8:11], v[4:5], off offset:128
	global_load_dwordx4 v[12:15], v[6:7], off offset:128
	global_load_dwordx4 v[16:19], v[0:1], off offset:128
	global_load_dwordx4 v[20:23], v[2:3], off offset:128
	ds_read_b128 v[40:43], v144
	ds_read_b128 v[44:47], v144 offset:1024
	ds_read_b128 v[48:51], v148 offset:16384
	ds_read_b128 v[52:55], v148 offset:17408
	ds_read_b128 v[56:59], v144 offset:2048
	ds_read_b128 v[60:63], v144 offset:3072
	ds_read_b128 v[66:69], v148 offset:18432
	ds_read_b128 v[70:73], v148 offset:19456
	s_waitcnt lgkmcnt(5)
	v_mfma_f32_16x16x32_bf16 v[74:77], v[40:43], v[48:51], 0
	s_waitcnt lgkmcnt(4)
	v_mfma_f32_16x16x32_bf16 v[80:83], v[40:43], v[52:55], 0
	s_waitcnt lgkmcnt(1)
	v_mfma_f32_16x16x32_bf16 v[84:87], v[40:43], v[66:69], 0
	s_waitcnt lgkmcnt(0)
	v_mfma_f32_16x16x32_bf16 v[40:43], v[40:43], v[70:73], 0
	v_mfma_f32_16x16x32_bf16 v[88:91], v[44:47], v[48:51], 0
	v_mfma_f32_16x16x32_bf16 v[92:95], v[44:47], v[52:55], 0
	v_mfma_f32_16x16x32_bf16 v[96:99], v[44:47], v[66:69], 0
	v_mfma_f32_16x16x32_bf16 v[44:47], v[44:47], v[70:73], 0
	v_mfma_f32_16x16x32_bf16 v[100:103], v[56:59], v[48:51], 0
	v_mfma_f32_16x16x32_bf16 v[104:107], v[56:59], v[52:55], 0
	v_mfma_f32_16x16x32_bf16 v[108:111], v[56:59], v[66:69], 0
	v_mfma_f32_16x16x32_bf16 v[56:59], v[56:59], v[70:73], 0
	v_mfma_f32_16x16x32_bf16 v[48:51], v[60:63], v[48:51], 0
	v_mfma_f32_16x16x32_bf16 v[52:55], v[60:63], v[52:55], 0
	v_mfma_f32_16x16x32_bf16 v[66:69], v[60:63], v[66:69], 0
	v_mfma_f32_16x16x32_bf16 v[60:63], v[60:63], v[70:73], 0
	s_waitcnt vmcnt(7)
	ds_write_b128 v64, v[24:27] offset:8192
	s_waitcnt vmcnt(6)
	ds_write_b128 v64, v[28:31] offset:12288
	s_waitcnt vmcnt(5)
	ds_write_b128 v64, v[32:35] offset:24576
	s_waitcnt vmcnt(4)
	ds_write_b128 v64, v[36:39] offset:28672
	s_waitcnt lgkmcnt(0)
	s_barrier
	global_load_dwordx4 v[24:27], v[4:5], off offset:192
	global_load_dwordx4 v[28:31], v[6:7], off offset:192
	global_load_dwordx4 v[32:35], v[0:1], off offset:192
	global_load_dwordx4 v[36:39], v[2:3], off offset:192
	ds_read_b128 v[70:73], v144 offset:8192
	ds_read_b128 v[112:115], v148 offset:24576
	ds_read_b128 v[116:119], v144 offset:9216
	ds_read_b128 v[120:123], v148 offset:25600
	ds_read_b128 v[124:127], v144 offset:10240
	ds_read_b128 v[128:131], v148 offset:26624
	ds_read_b128 v[132:135], v144 offset:11264
	ds_read_b128 v[136:139], v148 offset:27648
	s_waitcnt lgkmcnt(6)
	v_mfma_f32_16x16x32_bf16 v[74:77], v[70:73], v[112:115], v[74:77]
	s_waitcnt lgkmcnt(4)
	v_mfma_f32_16x16x32_bf16 v[80:83], v[70:73], v[120:123], v[80:83]
	s_waitcnt lgkmcnt(2)
	v_mfma_f32_16x16x32_bf16 v[84:87], v[70:73], v[128:131], v[84:87]
	s_waitcnt lgkmcnt(0)
	v_mfma_f32_16x16x32_bf16 v[40:43], v[70:73], v[136:139], v[40:43]
	v_mfma_f32_16x16x32_bf16 v[70:73], v[116:119], v[112:115], v[88:91]
	v_mfma_f32_16x16x32_bf16 v[44:47], v[116:119], v[136:139], v[44:47]
	v_mfma_f32_16x16x32_bf16 v[56:59], v[124:127], v[136:139], v[56:59]
	v_mfma_f32_16x16x32_bf16 v[48:51], v[132:135], v[112:115], v[48:51]
	v_mfma_f32_16x16x32_bf16 v[52:55], v[132:135], v[120:123], v[52:55]
	v_mfma_f32_16x16x32_bf16 v[66:69], v[132:135], v[128:131], v[66:69]
	v_mfma_f32_16x16x32_bf16 v[60:63], v[132:135], v[136:139], v[60:63]
	v_mfma_f32_16x16x32_bf16 v[88:91], v[116:119], v[120:123], v[92:95]
	v_mfma_f32_16x16x32_bf16 v[92:95], v[116:119], v[128:131], v[96:99]
	v_mfma_f32_16x16x32_bf16 v[96:99], v[124:127], v[112:115], v[100:103]
	v_mfma_f32_16x16x32_bf16 v[100:103], v[124:127], v[120:123], v[104:107]
	v_mfma_f32_16x16x32_bf16 v[104:107], v[124:127], v[128:131], v[108:111]
	s_waitcnt vmcnt(7)
	ds_write_b128 v64, v[8:11]
	s_waitcnt vmcnt(6)
	ds_write_b128 v79, v[12:15]
	s_waitcnt vmcnt(5)
	ds_write_b128 v64, v[16:19] offset:16384
	s_waitcnt vmcnt(4)
	ds_write_b128 v79, v[20:23] offset:16384
	s_waitcnt lgkmcnt(0)
	s_barrier
	global_load_dwordx4 v[8:11], v[4:5], off offset:256
	global_load_dwordx4 v[12:15], v[6:7], off offset:256
	global_load_dwordx4 v[16:19], v[0:1], off offset:256
	global_load_dwordx4 v[20:23], v[2:3], off offset:256
	ds_read_b128 v[108:111], v144
	ds_read_b128 v[112:115], v148 offset:16384
	ds_read_b128 v[116:119], v144 offset:1024
	ds_read_b128 v[120:123], v148 offset:17408
	ds_read_b128 v[124:127], v144 offset:2048
	ds_read_b128 v[128:131], v148 offset:18432
	ds_read_b128 v[132:135], v144 offset:3072
	ds_read_b128 v[136:139], v148 offset:19456
	s_waitcnt lgkmcnt(6)
	v_mfma_f32_16x16x32_bf16 v[74:77], v[108:111], v[112:115], v[74:77]
	s_waitcnt lgkmcnt(0)
	v_mfma_f32_16x16x32_bf16 v[40:43], v[108:111], v[136:139], v[40:43]
	v_mfma_f32_16x16x32_bf16 v[70:73], v[116:119], v[112:115], v[70:73]
	v_mfma_f32_16x16x32_bf16 v[44:47], v[116:119], v[136:139], v[44:47]
	v_mfma_f32_16x16x32_bf16 v[56:59], v[124:127], v[136:139], v[56:59]
	v_mfma_f32_16x16x32_bf16 v[48:51], v[132:135], v[112:115], v[48:51]
	v_mfma_f32_16x16x32_bf16 v[52:55], v[132:135], v[120:123], v[52:55]
	v_mfma_f32_16x16x32_bf16 v[66:69], v[132:135], v[128:131], v[66:69]
	v_mfma_f32_16x16x32_bf16 v[60:63], v[132:135], v[136:139], v[60:63]
	v_mfma_f32_16x16x32_bf16 v[80:83], v[108:111], v[120:123], v[80:83]
	v_mfma_f32_16x16x32_bf16 v[84:87], v[108:111], v[128:131], v[84:87]
	v_mfma_f32_16x16x32_bf16 v[88:91], v[116:119], v[120:123], v[88:91]
	v_mfma_f32_16x16x32_bf16 v[92:95], v[116:119], v[128:131], v[92:95]
	v_mfma_f32_16x16x32_bf16 v[96:99], v[124:127], v[112:115], v[96:99]
	v_mfma_f32_16x16x32_bf16 v[100:103], v[124:127], v[120:123], v[100:103]
	v_mfma_f32_16x16x32_bf16 v[104:107], v[124:127], v[128:131], v[104:107]
	s_waitcnt vmcnt(7)
	ds_write_b128 v64, v[24:27] offset:8192
	s_waitcnt vmcnt(6)
	ds_write_b128 v64, v[28:31] offset:12288
	s_waitcnt vmcnt(5)
	ds_write_b128 v64, v[32:35] offset:24576
	s_waitcnt vmcnt(4)
	ds_write_b128 v64, v[36:39] offset:28672
	s_waitcnt lgkmcnt(0)
	s_barrier
	global_load_dwordx4 v[24:27], v[4:5], off offset:320
	global_load_dwordx4 v[28:31], v[6:7], off offset:320
	global_load_dwordx4 v[32:35], v[0:1], off offset:320
	global_load_dwordx4 v[36:39], v[2:3], off offset:320
	ds_read_b128 v[108:111], v144 offset:8192
	ds_read_b128 v[112:115], v148 offset:24576
	ds_read_b128 v[116:119], v144 offset:9216
	ds_read_b128 v[120:123], v148 offset:25600
	ds_read_b128 v[124:127], v144 offset:10240
	ds_read_b128 v[128:131], v148 offset:26624
	ds_read_b128 v[132:135], v144 offset:11264
	ds_read_b128 v[136:139], v148 offset:27648
	s_waitcnt lgkmcnt(6)
	v_mfma_f32_16x16x32_bf16 v[74:77], v[108:111], v[112:115], v[74:77]
	s_waitcnt lgkmcnt(0)
	v_mfma_f32_16x16x32_bf16 v[40:43], v[108:111], v[136:139], v[40:43]
	v_mfma_f32_16x16x32_bf16 v[70:73], v[116:119], v[112:115], v[70:73]
	v_mfma_f32_16x16x32_bf16 v[44:47], v[116:119], v[136:139], v[44:47]
	v_mfma_f32_16x16x32_bf16 v[56:59], v[124:127], v[136:139], v[56:59]
	v_mfma_f32_16x16x32_bf16 v[48:51], v[132:135], v[112:115], v[48:51]
	v_mfma_f32_16x16x32_bf16 v[52:55], v[132:135], v[120:123], v[52:55]
	v_mfma_f32_16x16x32_bf16 v[66:69], v[132:135], v[128:131], v[66:69]
	v_mfma_f32_16x16x32_bf16 v[60:63], v[132:135], v[136:139], v[60:63]
	v_mfma_f32_16x16x32_bf16 v[80:83], v[108:111], v[120:123], v[80:83]
	v_mfma_f32_16x16x32_bf16 v[84:87], v[108:111], v[128:131], v[84:87]
	v_mfma_f32_16x16x32_bf16 v[88:91], v[116:119], v[120:123], v[88:91]
	v_mfma_f32_16x16x32_bf16 v[92:95], v[116:119], v[128:131], v[92:95]
	v_mfma_f32_16x16x32_bf16 v[96:99], v[124:127], v[112:115], v[96:99]
	v_mfma_f32_16x16x32_bf16 v[100:103], v[124:127], v[120:123], v[100:103]
	v_mfma_f32_16x16x32_bf16 v[104:107], v[124:127], v[128:131], v[104:107]
	s_waitcnt vmcnt(7)
	ds_write_b128 v64, v[8:11]
	s_waitcnt vmcnt(6)
	ds_write_b128 v79, v[12:15]
	s_waitcnt vmcnt(5)
	ds_write_b128 v64, v[16:19] offset:16384
	s_waitcnt vmcnt(4)
	ds_write_b128 v79, v[20:23] offset:16384
	s_waitcnt lgkmcnt(0)
	s_barrier
	global_load_dwordx4 v[8:11], v[4:5], off offset:384
	global_load_dwordx4 v[12:15], v[6:7], off offset:384
	global_load_dwordx4 v[16:19], v[0:1], off offset:384
	global_load_dwordx4 v[20:23], v[2:3], off offset:384
	ds_read_b128 v[108:111], v144
	ds_read_b128 v[112:115], v148 offset:16384
	ds_read_b128 v[116:119], v144 offset:1024
	ds_read_b128 v[120:123], v148 offset:17408
	ds_read_b128 v[124:127], v144 offset:2048
	ds_read_b128 v[128:131], v148 offset:18432
	ds_read_b128 v[132:135], v144 offset:3072
	ds_read_b128 v[136:139], v148 offset:19456
	s_waitcnt lgkmcnt(6)
	v_mfma_f32_16x16x32_bf16 v[74:77], v[108:111], v[112:115], v[74:77]
	s_waitcnt lgkmcnt(0)
	v_mfma_f32_16x16x32_bf16 v[40:43], v[108:111], v[136:139], v[40:43]
	v_mfma_f32_16x16x32_bf16 v[70:73], v[116:119], v[112:115], v[70:73]
	v_mfma_f32_16x16x32_bf16 v[44:47], v[116:119], v[136:139], v[44:47]
	v_mfma_f32_16x16x32_bf16 v[56:59], v[124:127], v[136:139], v[56:59]
	v_mfma_f32_16x16x32_bf16 v[48:51], v[132:135], v[112:115], v[48:51]
	v_mfma_f32_16x16x32_bf16 v[52:55], v[132:135], v[120:123], v[52:55]
	v_mfma_f32_16x16x32_bf16 v[66:69], v[132:135], v[128:131], v[66:69]
	v_mfma_f32_16x16x32_bf16 v[60:63], v[132:135], v[136:139], v[60:63]
	v_mfma_f32_16x16x32_bf16 v[80:83], v[108:111], v[120:123], v[80:83]
	v_mfma_f32_16x16x32_bf16 v[84:87], v[108:111], v[128:131], v[84:87]
	v_mfma_f32_16x16x32_bf16 v[88:91], v[116:119], v[120:123], v[88:91]
	v_mfma_f32_16x16x32_bf16 v[92:95], v[116:119], v[128:131], v[92:95]
	v_mfma_f32_16x16x32_bf16 v[96:99], v[124:127], v[112:115], v[96:99]
	v_mfma_f32_16x16x32_bf16 v[100:103], v[124:127], v[120:123], v[100:103]
	v_mfma_f32_16x16x32_bf16 v[104:107], v[124:127], v[128:131], v[104:107]
	s_waitcnt vmcnt(7)
	ds_write_b128 v64, v[24:27] offset:8192
	s_waitcnt vmcnt(6)
	ds_write_b128 v64, v[28:31] offset:12288
	s_waitcnt vmcnt(5)
	ds_write_b128 v64, v[32:35] offset:24576
	s_waitcnt vmcnt(4)
	ds_write_b128 v64, v[36:39] offset:28672
	s_waitcnt lgkmcnt(0)
	s_barrier
	global_load_dwordx4 v[24:27], v[4:5], off offset:448
	global_load_dwordx4 v[28:31], v[6:7], off offset:448
	global_load_dwordx4 v[32:35], v[0:1], off offset:448
	global_load_dwordx4 v[36:39], v[2:3], off offset:448
	ds_read_b128 v[108:111], v144 offset:8192
	ds_read_b128 v[112:115], v148 offset:24576
	ds_read_b128 v[116:119], v144 offset:9216
	ds_read_b128 v[120:123], v148 offset:25600
	ds_read_b128 v[124:127], v144 offset:10240
	ds_read_b128 v[128:131], v148 offset:26624
	ds_read_b128 v[132:135], v144 offset:11264
	ds_read_b128 v[136:139], v148 offset:27648
	s_waitcnt lgkmcnt(6)
	v_mfma_f32_16x16x32_bf16 v[74:77], v[108:111], v[112:115], v[74:77]
	s_waitcnt lgkmcnt(0)
	v_mfma_f32_16x16x32_bf16 v[40:43], v[108:111], v[136:139], v[40:43]
	v_mfma_f32_16x16x32_bf16 v[70:73], v[116:119], v[112:115], v[70:73]
	v_mfma_f32_16x16x32_bf16 v[44:47], v[116:119], v[136:139], v[44:47]
	v_mfma_f32_16x16x32_bf16 v[56:59], v[124:127], v[136:139], v[56:59]
	v_mfma_f32_16x16x32_bf16 v[48:51], v[132:135], v[112:115], v[48:51]
	v_mfma_f32_16x16x32_bf16 v[52:55], v[132:135], v[120:123], v[52:55]
	v_mfma_f32_16x16x32_bf16 v[66:69], v[132:135], v[128:131], v[66:69]
	v_mfma_f32_16x16x32_bf16 v[60:63], v[132:135], v[136:139], v[60:63]
	v_mfma_f32_16x16x32_bf16 v[80:83], v[108:111], v[120:123], v[80:83]
	v_mfma_f32_16x16x32_bf16 v[84:87], v[108:111], v[128:131], v[84:87]
	v_mfma_f32_16x16x32_bf16 v[88:91], v[116:119], v[120:123], v[88:91]
	v_mfma_f32_16x16x32_bf16 v[92:95], v[116:119], v[128:131], v[92:95]
	v_mfma_f32_16x16x32_bf16 v[96:99], v[124:127], v[112:115], v[96:99]
	v_mfma_f32_16x16x32_bf16 v[100:103], v[124:127], v[120:123], v[100:103]
	v_mfma_f32_16x16x32_bf16 v[104:107], v[124:127], v[128:131], v[104:107]
	s_waitcnt vmcnt(7)
	ds_write_b128 v64, v[8:11]
	s_waitcnt vmcnt(6)
	ds_write_b128 v79, v[12:15]
	s_waitcnt vmcnt(5)
	ds_write_b128 v64, v[16:19] offset:16384
	s_waitcnt vmcnt(4)
	ds_write_b128 v79, v[20:23] offset:16384
	s_waitcnt lgkmcnt(0)
	s_barrier
	global_load_dwordx4 v[108:111], v[4:5], off offset:448
	global_load_dwordx4 v[112:115], v[6:7], off offset:448
	global_load_dwordx4 v[116:119], v[0:1], off offset:448
	global_load_dwordx4 v[120:123], v[2:3], off offset:448
	ds_read_b128 v[0:3], v144
	ds_read_b128 v[4:7], v148 offset:16384
	ds_read_b128 v[8:11], v144 offset:1024
	ds_read_b128 v[12:15], v148 offset:17408
	ds_read_b128 v[16:19], v144 offset:2048
	ds_read_b128 v[20:23], v148 offset:18432
	ds_read_b128 v[124:127], v144 offset:3072
	ds_read_b128 v[128:131], v148 offset:19456
	s_waitcnt lgkmcnt(6)
	v_mfma_f32_16x16x32_bf16 v[74:77], v[0:3], v[4:7], v[74:77]
	s_waitcnt lgkmcnt(4)
	v_mfma_f32_16x16x32_bf16 v[80:83], v[0:3], v[12:15], v[80:83]
	s_waitcnt lgkmcnt(2)
	v_mfma_f32_16x16x32_bf16 v[84:87], v[0:3], v[20:23], v[84:87]
	s_waitcnt lgkmcnt(0)
	v_mfma_f32_16x16x32_bf16 v[0:3], v[0:3], v[128:131], v[40:43]
	v_mfma_f32_16x16x32_bf16 v[40:43], v[8:11], v[4:7], v[70:73]
	v_mfma_f32_16x16x32_bf16 v[70:73], v[8:11], v[12:15], v[88:91]
	v_mfma_f32_16x16x32_bf16 v[88:91], v[8:11], v[20:23], v[92:95]
	v_mfma_f32_16x16x32_bf16 v[8:11], v[8:11], v[128:131], v[44:47]
	v_mfma_f32_16x16x32_bf16 v[92:95], v[16:19], v[4:7], v[96:99]
	v_mfma_f32_16x16x32_bf16 v[96:99], v[16:19], v[12:15], v[100:103]
	v_mfma_f32_16x16x32_bf16 v[100:103], v[16:19], v[20:23], v[104:107]
	v_mfma_f32_16x16x32_bf16 v[16:19], v[16:19], v[128:131], v[56:59]
	v_mfma_f32_16x16x32_bf16 v[4:7], v[124:127], v[4:7], v[48:51]
	v_mfma_f32_16x16x32_bf16 v[66:69], v[124:127], v[20:23], v[66:69]
	v_mfma_f32_16x16x32_bf16 v[104:107], v[124:127], v[12:15], v[52:55]
	v_mfma_f32_16x16x32_bf16 v[124:127], v[124:127], v[128:131], v[60:63]
	s_waitcnt vmcnt(7)
	ds_write_b128 v64, v[24:27] offset:8192
	s_waitcnt vmcnt(6)
	ds_write_b128 v64, v[28:31] offset:12288
	s_waitcnt vmcnt(5)
	ds_write_b128 v64, v[32:35] offset:24576
	s_waitcnt vmcnt(4)
	ds_write_b128 v64, v[36:39] offset:28672
	s_waitcnt lgkmcnt(0)
	s_barrier
	ds_read_b128 v[12:15], v144 offset:8192
	ds_read_b128 v[20:23], v144 offset:9216
	ds_read_b128 v[128:131], v148 offset:24576
	ds_read_b128 v[132:135], v148 offset:25600
	ds_read_b128 v[136:139], v144 offset:10240
	ds_read_b128 v[140:143], v148 offset:26624
	ds_read_b128 v[144:147], v144 offset:11264
	ds_read_b128 v[148:151], v148 offset:27648
	s_waitcnt lgkmcnt(5)
	v_mfma_f32_16x16x32_bf16 v[60:63], v[12:15], v[128:131], v[74:77]
	s_waitcnt lgkmcnt(4)
	v_mfma_f32_16x16x32_bf16 v[56:59], v[12:15], v[132:135], v[80:83]
	s_waitcnt lgkmcnt(2)
	v_mfma_f32_16x16x32_bf16 v[52:55], v[12:15], v[140:143], v[84:87]
	s_waitcnt lgkmcnt(0)
	v_mfma_f32_16x16x32_bf16 v[48:51], v[12:15], v[148:151], v[0:3]
	v_mfma_f32_16x16x32_bf16 v[44:47], v[20:23], v[128:131], v[40:43]
	v_mfma_f32_16x16x32_bf16 v[40:43], v[20:23], v[132:135], v[70:73]
	v_mfma_f32_16x16x32_bf16 v[36:39], v[20:23], v[140:143], v[88:91]
	v_mfma_f32_16x16x32_bf16 v[32:35], v[20:23], v[148:151], v[8:11]
	v_mfma_f32_16x16x32_bf16 v[28:31], v[136:139], v[128:131], v[92:95]
	v_mfma_f32_16x16x32_bf16 v[24:27], v[136:139], v[132:135], v[96:99]
	v_mfma_f32_16x16x32_bf16 v[20:23], v[136:139], v[140:143], v[100:103]
	v_mfma_f32_16x16x32_bf16 v[16:19], v[136:139], v[148:151], v[16:19]
	v_mfma_f32_16x16x32_bf16 v[12:15], v[144:147], v[128:131], v[4:7]
	v_mfma_f32_16x16x32_bf16 v[8:11], v[144:147], v[132:135], v[104:107]
	v_mfma_f32_16x16x32_bf16 v[4:7], v[144:147], v[140:143], v[66:69]
	v_mfma_f32_16x16x32_bf16 v[0:3], v[144:147], v[148:151], v[124:127]
	s_nop 0
	v_mov_b32_e32 v66, v220
	s_waitcnt vmcnt(3)
	ds_write_b128 v64, v[108:111]
	s_waitcnt vmcnt(2)
	ds_write_b128 v79, v[112:115]
	s_waitcnt vmcnt(1)
	ds_write_b128 v64, v[116:119] offset:16384
	s_waitcnt vmcnt(0)
	ds_write_b128 v79, v[120:123] offset:16384
	s_waitcnt lgkmcnt(0)
	s_barrier
	s_mov_b64 s[16:17], -1
	v_ashrrev_i32_e32 v64, 1, v66
	v_and_b32_e32 v64, 0xffffffc0, v64
	v_add_u32_e32 v69, s10, v64
	v_lshrrev_b32_e32 v64, 2, v66
	v_and_b32_e32 v64, 12, v64
	v_or_b32_e32 v68, v69, v64
	v_or_b32_e32 v74, 3, v68
	v_or_b32_e32 v72, 19, v68
	v_or_b32_e32 v70, 35, v68
	v_and_b32_e32 v67, 0x4f, v66
	v_cmp_gt_i32_e64 s[10:11], s24, v74
	v_cmp_gt_i32_e64 s[0:1], s24, v72
	v_cmp_gt_i32_e32 vcc, s24, v70
	v_or_b32_e32 v66, 51, v68
	s_cbranch_scc0 .LBB0_1410
	v_ashrrev_i32_e32 v76, 6, v69
	v_cndmask_b32_e64 v69, 0, v63, s[10:11]
	s_and_b32 s16, s12, 0xe0000
	v_and_b32_sdwa v75, v69, v78 dst_sel:DWORD dst_unused:UNUSED_PAD src0_sel:WORD_1 src1_sel:DWORD
	s_lshl_b32 s16, s16, 1
	v_and_b32_sdwa v71, v62, v78 dst_sel:DWORD dst_unused:UNUSED_PAD src0_sel:WORD_1 src1_sel:DWORD
	v_and_b32_sdwa v79, v61, v78 dst_sel:DWORD dst_unused:UNUSED_PAD src0_sel:WORD_1 src1_sel:DWORD
	v_add3_u32 v69, v69, v75, s25
	s_add_u32 s16, s5, s16
	v_ashrrev_i32_e32 v77, 31, v76
	v_and_b32_sdwa v73, v60, v78 dst_sel:DWORD dst_unused:UNUSED_PAD src0_sel:WORD_1 src1_sel:DWORD
	v_add3_u32 v71, v62, v71, s25
	v_add3_u32 v75, v61, v79, s25
	v_and_b32_e32 v69, 0xffff0000, v69
	s_addc_u32 s17, s6, 0
	v_lshlrev_b64 v[76:77], 14, v[76:77]
	v_add3_u32 v73, v60, v73, s25
	v_and_b32_e32 v75, 0xffff0000, v75
	v_or_b32_sdwa v83, v69, v71 dst_sel:DWORD dst_unused:UNUSED_PAD src0_sel:DWORD src1_sel:WORD_1
	v_cndmask_b32_e64 v69, 0, v59, s[10:11]
	v_lshl_add_u64 v[76:77], s[16:17], 0, v[76:77]
	v_lshlrev_b32_e32 v64, 1, v64
	v_or_b32_sdwa v82, v75, v73 dst_sel:DWORD dst_unused:UNUSED_PAD src0_sel:DWORD src1_sel:WORD_1
	v_and_b32_sdwa v75, v69, v78 dst_sel:DWORD dst_unused:UNUSED_PAD src0_sel:WORD_1 src1_sel:DWORD
	v_lshl_add_u64 v[76:77], v[76:77], 0, v[64:65]
	v_lshlrev_b32_e32 v64, 7, v67
	v_and_b32_sdwa v71, v58, v78 dst_sel:DWORD dst_unused:UNUSED_PAD src0_sel:WORD_1 src1_sel:DWORD
	v_and_b32_sdwa v79, v57, v78 dst_sel:DWORD dst_unused:UNUSED_PAD src0_sel:WORD_1 src1_sel:DWORD
	v_add3_u32 v69, v69, v75, s25
	v_lshl_add_u64 v[80:81], v[76:77], 0, v[64:65]
	v_and_b32_sdwa v73, v56, v78 dst_sel:DWORD dst_unused:UNUSED_PAD src0_sel:WORD_1 src1_sel:DWORD
	v_add3_u32 v71, v58, v71, s25
	v_add3_u32 v75, v57, v79, s25
	v_and_b32_e32 v69, 0xffff0000, v69
	global_store_dwordx2 v[80:81], v[82:83], off
	v_add3_u32 v73, v56, v73, s25
	v_and_b32_e32 v75, 0xffff0000, v75
	v_or_b32_sdwa v83, v69, v71 dst_sel:DWORD dst_unused:UNUSED_PAD src0_sel:DWORD src1_sel:WORD_1
	v_cndmask_b32_e64 v69, 0, v55, s[10:11]
	v_or_b32_sdwa v82, v75, v73 dst_sel:DWORD dst_unused:UNUSED_PAD src0_sel:DWORD src1_sel:WORD_1
	v_and_b32_sdwa v75, v69, v78 dst_sel:DWORD dst_unused:UNUSED_PAD src0_sel:WORD_1 src1_sel:DWORD
	v_and_b32_sdwa v71, v54, v78 dst_sel:DWORD dst_unused:UNUSED_PAD src0_sel:WORD_1 src1_sel:DWORD
	v_and_b32_sdwa v79, v53, v78 dst_sel:DWORD dst_unused:UNUSED_PAD src0_sel:WORD_1 src1_sel:DWORD
	v_add3_u32 v69, v69, v75, s25
	v_and_b32_sdwa v73, v52, v78 dst_sel:DWORD dst_unused:UNUSED_PAD src0_sel:WORD_1 src1_sel:DWORD
	v_add3_u32 v71, v54, v71, s25
	v_add3_u32 v75, v53, v79, s25
	v_and_b32_e32 v69, 0xffff0000, v69
	v_add3_u32 v73, v52, v73, s25
	v_and_b32_e32 v75, 0xffff0000, v75
	v_or_b32_sdwa v87, v69, v71 dst_sel:DWORD dst_unused:UNUSED_PAD src0_sel:DWORD src1_sel:WORD_1
	v_cndmask_b32_e64 v69, 0, v51, s[10:11]
	v_or_b32_sdwa v86, v75, v73 dst_sel:DWORD dst_unused:UNUSED_PAD src0_sel:DWORD src1_sel:WORD_1
	v_and_b32_sdwa v75, v69, v78 dst_sel:DWORD dst_unused:UNUSED_PAD src0_sel:WORD_1 src1_sel:DWORD
	global_store_dwordx2 v[80:81], v[82:83], off offset:2048
	v_or_b32_e32 v82, 0x1000, v64
	v_mov_b32_e32 v83, v65
	v_and_b32_sdwa v71, v50, v78 dst_sel:DWORD dst_unused:UNUSED_PAD src0_sel:WORD_1 src1_sel:DWORD
	v_and_b32_sdwa v79, v49, v78 dst_sel:DWORD dst_unused:UNUSED_PAD src0_sel:WORD_1 src1_sel:DWORD
	v_add3_u32 v69, v69, v75, s25
	v_lshl_add_u64 v[84:85], v[76:77], 0, v[82:83]
	v_and_b32_sdwa v73, v48, v78 dst_sel:DWORD dst_unused:UNUSED_PAD src0_sel:WORD_1 src1_sel:DWORD
	v_add3_u32 v71, v50, v71, s25
	v_add3_u32 v75, v49, v79, s25
	v_and_b32_e32 v69, 0xffff0000, v69
	global_store_dwordx2 v[84:85], v[86:87], off
	v_add3_u32 v73, v48, v73, s25
	v_and_b32_e32 v75, 0xffff0000, v75
	v_or_b32_sdwa v87, v69, v71 dst_sel:DWORD dst_unused:UNUSED_PAD src0_sel:DWORD src1_sel:WORD_1
	v_cndmask_b32_e64 v69, 0, v47, s[0:1]
	v_or_b32_sdwa v86, v75, v73 dst_sel:DWORD dst_unused:UNUSED_PAD src0_sel:DWORD src1_sel:WORD_1
	v_and_b32_sdwa v75, v69, v78 dst_sel:DWORD dst_unused:UNUSED_PAD src0_sel:WORD_1 src1_sel:DWORD
	v_or_b32_e32 v64, 0x1800, v64
	v_and_b32_sdwa v71, v46, v78 dst_sel:DWORD dst_unused:UNUSED_PAD src0_sel:WORD_1 src1_sel:DWORD
	v_and_b32_sdwa v79, v45, v78 dst_sel:DWORD dst_unused:UNUSED_PAD src0_sel:WORD_1 src1_sel:DWORD
	v_add3_u32 v69, v69, v75, s25
	v_lshl_add_u64 v[84:85], v[76:77], 0, v[64:65]
	v_and_b32_sdwa v73, v44, v78 dst_sel:DWORD dst_unused:UNUSED_PAD src0_sel:WORD_1 src1_sel:DWORD
	v_add3_u32 v71, v46, v71, s25
	v_add3_u32 v75, v45, v79, s25
	v_and_b32_e32 v69, 0xffff0000, v69
	global_store_dwordx2 v[84:85], v[86:87], off
	v_add3_u32 v73, v44, v73, s25
	v_and_b32_e32 v75, 0xffff0000, v75
	v_or_b32_sdwa v87, v69, v71 dst_sel:DWORD dst_unused:UNUSED_PAD src0_sel:DWORD src1_sel:WORD_1
	v_cndmask_b32_e64 v69, 0, v43, s[0:1]
	v_or_b32_sdwa v86, v75, v73 dst_sel:DWORD dst_unused:UNUSED_PAD src0_sel:DWORD src1_sel:WORD_1
	v_and_b32_sdwa v75, v69, v78 dst_sel:DWORD dst_unused:UNUSED_PAD src0_sel:WORD_1 src1_sel:DWORD
	v_and_b32_sdwa v71, v42, v78 dst_sel:DWORD dst_unused:UNUSED_PAD src0_sel:WORD_1 src1_sel:DWORD
	v_and_b32_sdwa v79, v41, v78 dst_sel:DWORD dst_unused:UNUSED_PAD src0_sel:WORD_1 src1_sel:DWORD
	v_add3_u32 v69, v69, v75, s25
	v_and_b32_sdwa v73, v40, v78 dst_sel:DWORD dst_unused:UNUSED_PAD src0_sel:WORD_1 src1_sel:DWORD
	v_add3_u32 v71, v42, v71, s25
	v_add3_u32 v75, v41, v79, s25
	v_and_b32_e32 v69, 0xffff0000, v69
	global_store_dwordx2 v[80:81], v[86:87], off offset:32
	v_add3_u32 v73, v40, v73, s25
	v_and_b32_e32 v75, 0xffff0000, v75
	v_or_b32_sdwa v87, v69, v71 dst_sel:DWORD dst_unused:UNUSED_PAD src0_sel:DWORD src1_sel:WORD_1
	v_cndmask_b32_e64 v69, 0, v39, s[0:1]
	v_or_b32_sdwa v86, v75, v73 dst_sel:DWORD dst_unused:UNUSED_PAD src0_sel:DWORD src1_sel:WORD_1
	v_and_b32_sdwa v75, v69, v78 dst_sel:DWORD dst_unused:UNUSED_PAD src0_sel:WORD_1 src1_sel:DWORD
	v_and_b32_sdwa v71, v38, v78 dst_sel:DWORD dst_unused:UNUSED_PAD src0_sel:WORD_1 src1_sel:DWORD
	v_and_b32_sdwa v79, v37, v78 dst_sel:DWORD dst_unused:UNUSED_PAD src0_sel:WORD_1 src1_sel:DWORD
	v_add3_u32 v69, v69, v75, s25
	v_and_b32_sdwa v73, v36, v78 dst_sel:DWORD dst_unused:UNUSED_PAD src0_sel:WORD_1 src1_sel:DWORD
	v_add3_u32 v71, v38, v71, s25
	v_add3_u32 v75, v37, v79, s25
	v_and_b32_e32 v69, 0xffff0000, v69
	v_add3_u32 v73, v36, v73, s25
	v_and_b32_e32 v75, 0xffff0000, v75
	v_or_b32_sdwa v89, v69, v71 dst_sel:DWORD dst_unused:UNUSED_PAD src0_sel:DWORD src1_sel:WORD_1
	v_cndmask_b32_e64 v69, 0, v35, s[0:1]
	v_or_b32_sdwa v88, v75, v73 dst_sel:DWORD dst_unused:UNUSED_PAD src0_sel:DWORD src1_sel:WORD_1
	v_and_b32_sdwa v75, v69, v78 dst_sel:DWORD dst_unused:UNUSED_PAD src0_sel:WORD_1 src1_sel:DWORD
	v_lshl_add_u64 v[84:85], v[76:77], 0, 32
	v_and_b32_sdwa v71, v34, v78 dst_sel:DWORD dst_unused:UNUSED_PAD src0_sel:WORD_1 src1_sel:DWORD
	v_and_b32_sdwa v79, v33, v78 dst_sel:DWORD dst_unused:UNUSED_PAD src0_sel:WORD_1 src1_sel:DWORD
	v_add3_u32 v69, v69, v75, s25
	global_store_dwordx2 v[80:81], v[86:87], off offset:2080
	v_lshl_add_u64 v[86:87], v[84:85], 0, v[82:83]
	v_and_b32_sdwa v73, v32, v78 dst_sel:DWORD dst_unused:UNUSED_PAD src0_sel:WORD_1 src1_sel:DWORD
	v_add3_u32 v71, v34, v71, s25
	v_add3_u32 v75, v33, v79, s25
	v_and_b32_e32 v69, 0xffff0000, v69
	global_store_dwordx2 v[86:87], v[88:89], off
	v_add3_u32 v73, v32, v73, s25
	v_and_b32_e32 v75, 0xffff0000, v75
	v_or_b32_sdwa v87, v69, v71 dst_sel:DWORD dst_unused:UNUSED_PAD src0_sel:DWORD src1_sel:WORD_1
	v_cndmask_b32_e32 v69, 0, v31, vcc
	v_or_b32_sdwa v86, v75, v73 dst_sel:DWORD dst_unused:UNUSED_PAD src0_sel:DWORD src1_sel:WORD_1
	v_and_b32_sdwa v75, v69, v78 dst_sel:DWORD dst_unused:UNUSED_PAD src0_sel:WORD_1 src1_sel:DWORD
	v_and_b32_sdwa v71, v30, v78 dst_sel:DWORD dst_unused:UNUSED_PAD src0_sel:WORD_1 src1_sel:DWORD
	v_and_b32_sdwa v79, v29, v78 dst_sel:DWORD dst_unused:UNUSED_PAD src0_sel:WORD_1 src1_sel:DWORD
	v_add3_u32 v69, v69, v75, s25
	v_lshl_add_u64 v[84:85], v[84:85], 0, v[64:65]
	v_and_b32_sdwa v73, v28, v78 dst_sel:DWORD dst_unused:UNUSED_PAD src0_sel:WORD_1 src1_sel:DWORD
	v_add3_u32 v71, v30, v71, s25
	v_add3_u32 v75, v29, v79, s25
	v_and_b32_e32 v69, 0xffff0000, v69
	global_store_dwordx2 v[84:85], v[86:87], off
	v_add3_u32 v73, v28, v73, s25
	v_and_b32_e32 v75, 0xffff0000, v75
	v_or_b32_sdwa v87, v69, v71 dst_sel:DWORD dst_unused:UNUSED_PAD src0_sel:DWORD src1_sel:WORD_1
	v_cndmask_b32_e32 v69, 0, v27, vcc
	v_or_b32_sdwa v86, v75, v73 dst_sel:DWORD dst_unused:UNUSED_PAD src0_sel:DWORD src1_sel:WORD_1
	v_and_b32_sdwa v75, v69, v78 dst_sel:DWORD dst_unused:UNUSED_PAD src0_sel:WORD_1 src1_sel:DWORD
	v_and_b32_sdwa v71, v26, v78 dst_sel:DWORD dst_unused:UNUSED_PAD src0_sel:WORD_1 src1_sel:DWORD
	v_and_b32_sdwa v79, v25, v78 dst_sel:DWORD dst_unused:UNUSED_PAD src0_sel:WORD_1 src1_sel:DWORD
	v_add3_u32 v69, v69, v75, s25
	v_and_b32_sdwa v73, v24, v78 dst_sel:DWORD dst_unused:UNUSED_PAD src0_sel:WORD_1 src1_sel:DWORD
	v_add3_u32 v71, v26, v71, s25
	v_add3_u32 v75, v25, v79, s25
	v_and_b32_e32 v69, 0xffff0000, v69
	global_store_dwordx2 v[80:81], v[86:87], off offset:64
	v_add3_u32 v73, v24, v73, s25
	v_and_b32_e32 v75, 0xffff0000, v75
	v_or_b32_sdwa v87, v69, v71 dst_sel:DWORD dst_unused:UNUSED_PAD src0_sel:DWORD src1_sel:WORD_1
	v_cndmask_b32_e32 v69, 0, v23, vcc
	v_or_b32_sdwa v86, v75, v73 dst_sel:DWORD dst_unused:UNUSED_PAD src0_sel:DWORD src1_sel:WORD_1
	v_and_b32_sdwa v75, v69, v78 dst_sel:DWORD dst_unused:UNUSED_PAD src0_sel:WORD_1 src1_sel:DWORD
	v_and_b32_sdwa v71, v22, v78 dst_sel:DWORD dst_unused:UNUSED_PAD src0_sel:WORD_1 src1_sel:DWORD
	v_and_b32_sdwa v79, v21, v78 dst_sel:DWORD dst_unused:UNUSED_PAD src0_sel:WORD_1 src1_sel:DWORD
	v_add3_u32 v69, v69, v75, s25
	v_and_b32_sdwa v73, v20, v78 dst_sel:DWORD dst_unused:UNUSED_PAD src0_sel:WORD_1 src1_sel:DWORD
	v_add3_u32 v71, v22, v71, s25
	v_add3_u32 v75, v21, v79, s25
	v_and_b32_e32 v69, 0xffff0000, v69
	v_add3_u32 v73, v20, v73, s25
	v_and_b32_e32 v75, 0xffff0000, v75
	v_or_b32_sdwa v89, v69, v71 dst_sel:DWORD dst_unused:UNUSED_PAD src0_sel:DWORD src1_sel:WORD_1
	v_cndmask_b32_e32 v69, 0, v19, vcc
	v_or_b32_sdwa v88, v75, v73 dst_sel:DWORD dst_unused:UNUSED_PAD src0_sel:DWORD src1_sel:WORD_1
	v_and_b32_sdwa v75, v69, v78 dst_sel:DWORD dst_unused:UNUSED_PAD src0_sel:WORD_1 src1_sel:DWORD
	v_lshl_add_u64 v[84:85], v[76:77], 0, 64
	v_and_b32_sdwa v71, v18, v78 dst_sel:DWORD dst_unused:UNUSED_PAD src0_sel:WORD_1 src1_sel:DWORD
	v_and_b32_sdwa v79, v17, v78 dst_sel:DWORD dst_unused:UNUSED_PAD src0_sel:WORD_1 src1_sel:DWORD
	v_add3_u32 v69, v69, v75, s25
	global_store_dwordx2 v[80:81], v[86:87], off offset:2112
	v_lshl_add_u64 v[86:87], v[84:85], 0, v[82:83]
	v_and_b32_sdwa v73, v16, v78 dst_sel:DWORD dst_unused:UNUSED_PAD src0_sel:WORD_1 src1_sel:DWORD
	v_add3_u32 v71, v18, v71, s25
	v_add3_u32 v75, v17, v79, s25
	v_and_b32_e32 v69, 0xffff0000, v69
	v_cmp_gt_i32_e32 vcc, s24, v66
	global_store_dwordx2 v[86:87], v[88:89], off
	v_add3_u32 v73, v16, v73, s25
	v_and_b32_e32 v75, 0xffff0000, v75
	v_or_b32_sdwa v87, v69, v71 dst_sel:DWORD dst_unused:UNUSED_PAD src0_sel:DWORD src1_sel:WORD_1
	v_cndmask_b32_e32 v69, 0, v15, vcc
	v_or_b32_sdwa v86, v75, v73 dst_sel:DWORD dst_unused:UNUSED_PAD src0_sel:DWORD src1_sel:WORD_1
	v_and_b32_sdwa v75, v69, v78 dst_sel:DWORD dst_unused:UNUSED_PAD src0_sel:WORD_1 src1_sel:DWORD
	v_and_b32_sdwa v71, v14, v78 dst_sel:DWORD dst_unused:UNUSED_PAD src0_sel:WORD_1 src1_sel:DWORD
	v_and_b32_sdwa v79, v13, v78 dst_sel:DWORD dst_unused:UNUSED_PAD src0_sel:WORD_1 src1_sel:DWORD
	v_add3_u32 v69, v69, v75, s25
	v_lshl_add_u64 v[84:85], v[84:85], 0, v[64:65]
	v_and_b32_sdwa v73, v12, v78 dst_sel:DWORD dst_unused:UNUSED_PAD src0_sel:WORD_1 src1_sel:DWORD
	v_add3_u32 v71, v14, v71, s25
	v_add3_u32 v75, v13, v79, s25
	v_and_b32_e32 v69, 0xffff0000, v69
	global_store_dwordx2 v[84:85], v[86:87], off
	v_add3_u32 v73, v12, v73, s25
	v_and_b32_e32 v75, 0xffff0000, v75
	v_or_b32_sdwa v85, v69, v71 dst_sel:DWORD dst_unused:UNUSED_PAD src0_sel:DWORD src1_sel:WORD_1
	v_cndmask_b32_e32 v69, 0, v11, vcc
	v_or_b32_sdwa v84, v75, v73 dst_sel:DWORD dst_unused:UNUSED_PAD src0_sel:DWORD src1_sel:WORD_1
	v_and_b32_sdwa v75, v69, v78 dst_sel:DWORD dst_unused:UNUSED_PAD src0_sel:WORD_1 src1_sel:DWORD
	v_and_b32_sdwa v71, v10, v78 dst_sel:DWORD dst_unused:UNUSED_PAD src0_sel:WORD_1 src1_sel:DWORD
	v_and_b32_sdwa v79, v9, v78 dst_sel:DWORD dst_unused:UNUSED_PAD src0_sel:WORD_1 src1_sel:DWORD
	v_add3_u32 v69, v69, v75, s25
	v_and_b32_sdwa v73, v8, v78 dst_sel:DWORD dst_unused:UNUSED_PAD src0_sel:WORD_1 src1_sel:DWORD
	v_add3_u32 v71, v10, v71, s25
	v_add3_u32 v75, v9, v79, s25
	v_and_b32_e32 v69, 0xffff0000, v69
	global_store_dwordx2 v[80:81], v[84:85], off offset:96
	v_add3_u32 v73, v8, v73, s25
	v_and_b32_e32 v75, 0xffff0000, v75
	v_or_b32_sdwa v85, v69, v71 dst_sel:DWORD dst_unused:UNUSED_PAD src0_sel:DWORD src1_sel:WORD_1
	v_cndmask_b32_e32 v69, 0, v7, vcc
	v_or_b32_sdwa v84, v75, v73 dst_sel:DWORD dst_unused:UNUSED_PAD src0_sel:DWORD src1_sel:WORD_1
	v_and_b32_sdwa v75, v69, v78 dst_sel:DWORD dst_unused:UNUSED_PAD src0_sel:WORD_1 src1_sel:DWORD
	v_and_b32_sdwa v71, v6, v78 dst_sel:DWORD dst_unused:UNUSED_PAD src0_sel:WORD_1 src1_sel:DWORD
	v_and_b32_sdwa v79, v5, v78 dst_sel:DWORD dst_unused:UNUSED_PAD src0_sel:WORD_1 src1_sel:DWORD
	v_add3_u32 v69, v69, v75, s25
	v_lshl_add_u64 v[76:77], v[76:77], 0, s[14:15]
	v_and_b32_sdwa v73, v4, v78 dst_sel:DWORD dst_unused:UNUSED_PAD src0_sel:WORD_1 src1_sel:DWORD
	v_add3_u32 v71, v6, v71, s25
	v_add3_u32 v75, v5, v79, s25
	v_and_b32_e32 v69, 0xffff0000, v69
	global_store_dwordx2 v[80:81], v[84:85], off offset:2144
	v_lshl_add_u64 v[80:81], v[76:77], 0, v[82:83]
	v_add3_u32 v73, v4, v73, s25
	v_and_b32_e32 v75, 0xffff0000, v75
	v_or_b32_sdwa v83, v69, v71 dst_sel:DWORD dst_unused:UNUSED_PAD src0_sel:DWORD src1_sel:WORD_1
	v_cndmask_b32_e32 v69, 0, v3, vcc
	v_or_b32_sdwa v82, v75, v73 dst_sel:DWORD dst_unused:UNUSED_PAD src0_sel:DWORD src1_sel:WORD_1
	v_and_b32_sdwa v73, v69, v78 dst_sel:DWORD dst_unused:UNUSED_PAD src0_sel:WORD_1 src1_sel:DWORD
	v_and_b32_sdwa v75, v1, v78 dst_sel:DWORD dst_unused:UNUSED_PAD src0_sel:WORD_1 src1_sel:DWORD
	v_lshl_add_u64 v[76:77], v[76:77], 0, v[64:65]
	v_and_b32_sdwa v64, v2, v78 dst_sel:DWORD dst_unused:UNUSED_PAD src0_sel:WORD_1 src1_sel:DWORD
	v_and_b32_sdwa v71, v0, v78 dst_sel:DWORD dst_unused:UNUSED_PAD src0_sel:WORD_1 src1_sel:DWORD
	v_add3_u32 v69, v69, v73, s25
	v_add3_u32 v73, v1, v75, s25
	v_add3_u32 v71, v0, v71, s25
	v_add3_u32 v64, v2, v64, s25
	v_and_b32_e32 v69, 0xffff0000, v69
	v_and_b32_e32 v73, 0xffff0000, v73
	global_store_dwordx2 v[80:81], v[82:83], off
	v_or_b32_sdwa v81, v69, v64 dst_sel:DWORD dst_unused:UNUSED_PAD src0_sel:DWORD src1_sel:WORD_1
	v_or_b32_sdwa v80, v73, v71 dst_sel:DWORD dst_unused:UNUSED_PAD src0_sel:DWORD src1_sel:WORD_1
	global_store_dwordx2 v[76:77], v[80:81], off
	s_cbranch_execnz .LBB0_1407
	s_branch .LBB0_1411

.LBB0_1464:
	s_or_b64 exec, exec, s[0:1]
	s_andn2_b64 vcc, exec, s[18:19]
	s_waitcnt lgkmcnt(0)
	s_barrier
	s_cbranch_vccnz .LBB0_1682
	s_cmpk_gt_u32 s2, 0xff
	s_cbranch_scc0 .Lnsa_prio0
.Lnsa_prio0:
	s_add_u32 s100, s72, 0x2f80000
	s_addc_u32 s101, s73, 0
	s_mov_b32 s98, 0x2000
	s_mov_b32 s99, 0
	v_lshrrev_b32_e32 v244, 4, v220
	v_and_b32_e32 v245, 3, v244
	v_lshrrev_b32_e32 v246, 7, v220
	v_lshl_or_b32 v245, v246, 2, v245
	v_and_b32_e32 v246, 15, v220
	v_xor_b32_e32 v245, v245, v246
	v_lshlrev_b32_e32 v245, 4, v245
	v_lshl_or_b32 v249, v244, 8, v245
	v_xor_b32_e32 v250, 0x80, v249
	v_and_b32_e32 v245, 7, v244
	v_and_b32_e32 v246, 7, v220
	v_xor_b32_e32 v245, v245, v246
	v_lshlrev_b32_e32 v245, 4, v245
	v_lshrrev_b32_e32 v246, 3, v220
	v_lshl_or_b32 v251, v246, 7, v245
	v_lshlrev_b32_e32 v252, 4, v220
	v_add_u32_e32 v252, 0x1000, v252
	v_mov_b32_e32 v253, 0
	s_mov_b32 s57, 0
	s_cmpk_lg_i32 s74, 0x200
	s_mov_b32 s3, s57
	s_cselect_b64 s[52:53], -1, 0
	s_lshr_b32 s0, s2, 8
	s_lshl_b64 s[58:59], s[2:3], 8
	s_add_u32 s60, s72, 0x13200000
	s_addc_u32 s61, s73, 0
	s_add_u32 s62, s72, 0x3000000
	s_addc_u32 s63, s73, 0
	s_add_u32 s3, s72, 0x3600000
	s_addc_u32 s87, s73, 0
	s_add_u32 s88, s72, 0x3800000
	s_addc_u32 s89, s73, 0
	s_add_u32 s64, s72, 0x7200000
	s_addc_u32 s65, s73, 0
	s_add_u32 s90, s72, 0xb200000
	s_addc_u32 s91, s73, 0
	v_writelane_b32 v254, s54, 32
	s_add_u32 s92, s72, 0xd200000
	s_addc_u32 s93, s73, 0
	v_writelane_b32 v254, s55, 33
	v_writelane_b32 v254, s0, 24
	s_add_u32 s0, s72, 0x11200000
	v_writelane_b32 v254, s0, 22
	s_addc_u32 s0, s73, 0
	s_add_u32 s96, s72, 0xf200000
	s_addc_u32 s97, s73, 0
	s_movk_i32 s4, 0x1ff
	s_waitcnt vmcnt(15)
	v_mov_b32_e32 v168, 0x10200
	v_mov_b32_e32 v17, 0
	s_mov_b32 s5, 0x8000
	s_movk_i32 s8, 0x400
	s_movk_i32 s9, 0x7fff
	v_mov_b32_e32 v169, 0xf149f2ca
	v_mbcnt_hi_u32_b32 v170, -1, v221
	v_mov_b32_e32 v171, 0xc0
	v_mov_b32_e32 v172, 0x7149f200
	v_mov_b32_e32 v173, 0x7149f2ca
	v_mov_b32_e32 v174, 1
	s_mov_b32 s6, s2
	v_writelane_b32 v254, s0, 26
	s_branch .LBB0_1468

.LBB0_1737:
	s_add_i32 s26, s25, 64
	s_min_u32 s12, s26, 0x3e0
	s_lshl_b32 s12, s12, 1
	v_lshl_add_u64 v[172:173], v[154:155], 0, s[12:13]
	v_lshl_add_u64 v[176:177], v[158:159], 0, s[12:13]
	v_lshl_add_u64 v[180:181], v[160:161], 0, s[12:13]
	v_lshl_add_u64 v[184:185], v[162:163], 0, s[12:13]
	v_lshl_add_u64 v[188:189], v[156:157], 0, s[12:13]
	v_lshl_add_u64 v[192:193], v[164:165], 0, s[12:13]
	global_load_dwordx4 v[172:175], v[172:173], off
	ds_read_b128 v[196:199], v171 offset:32768
	global_load_dwordx4 v[176:179], v[176:177], off
	ds_read_b128 v[200:203], v171 offset:33792
	global_load_dwordx4 v[180:183], v[180:181], off
	ds_read_b128 v[204:207], v171 offset:34816
	global_load_dwordx4 v[184:187], v[184:185], off
	ds_read_b128 v[208:211], v171 offset:35840
	global_load_dwordx4 v[188:191], v[188:189], off
	ds_read_b128 v[212:215], v169
	global_load_dwordx4 v[192:195], v[192:193], off
	ds_read_b128 v[216:219], v169 offset:1024
	ds_read_b128 v[222:225], v169 offset:2048
	ds_read_b128 v[226:229], v169 offset:3072
	ds_read_b128 v[230:233], v169 offset:4096
	ds_read_b128 v[234:237], v169 offset:5120
	ds_read_b128 v[238:241], v169 offset:6144
	ds_read_b128 v[242:245], v169 offset:7168
	s_waitcnt lgkmcnt(7)
	v_mfma_f32_16x16x32_bf16 v[148:151], v[196:199], v[212:215], v[148:151]
	v_mfma_f32_16x16x32_bf16 v[144:147], v[200:203], v[212:215], v[144:147]
	v_mfma_f32_16x16x32_bf16 v[116:119], v[204:207], v[212:215], v[116:119]
	v_mfma_f32_16x16x32_bf16 v[112:115], v[208:211], v[212:215], v[112:115]
	s_waitcnt vmcnt(11)
	ds_write_b128 v152, v[120:123] offset:16384
	s_waitcnt lgkmcnt(7)
	v_mfma_f32_16x16x32_bf16 v[108:111], v[196:199], v[216:219], v[108:111]
	v_mfma_f32_16x16x32_bf16 v[104:107], v[200:203], v[216:219], v[104:107]
	v_mfma_f32_16x16x32_bf16 v[100:103], v[204:207], v[216:219], v[100:103]
	v_mfma_f32_16x16x32_bf16 v[96:99], v[208:211], v[216:219], v[96:99]
	s_waitcnt vmcnt(9)
	ds_write_b128 v152, v[124:127] offset:20480
	s_waitcnt lgkmcnt(7)
	v_mfma_f32_16x16x32_bf16 v[92:95], v[196:199], v[222:225], v[92:95]
	v_mfma_f32_16x16x32_bf16 v[88:91], v[200:203], v[222:225], v[88:91]
	v_mfma_f32_16x16x32_bf16 v[84:87], v[204:207], v[222:225], v[84:87]
	v_mfma_f32_16x16x32_bf16 v[80:83], v[208:211], v[222:225], v[80:83]
	s_waitcnt vmcnt(8)
	ds_write_b128 v152, v[128:131] offset:24576
	s_waitcnt lgkmcnt(7)
	v_mfma_f32_16x16x32_bf16 v[76:79], v[196:199], v[226:229], v[76:79]
	v_mfma_f32_16x16x32_bf16 v[72:75], v[200:203], v[226:229], v[72:75]
	v_mfma_f32_16x16x32_bf16 v[68:71], v[204:207], v[226:229], v[68:71]
	v_mfma_f32_16x16x32_bf16 v[64:67], v[208:211], v[226:229], v[64:67]
	s_waitcnt vmcnt(7)
	ds_write_b128 v152, v[136:139] offset:28672
	s_waitcnt lgkmcnt(7)
	v_mfma_f32_16x16x32_bf16 v[60:63], v[196:199], v[230:233], v[60:63]
	v_mfma_f32_16x16x32_bf16 v[56:59], v[200:203], v[230:233], v[56:59]
	v_mfma_f32_16x16x32_bf16 v[52:55], v[204:207], v[230:233], v[52:55]
	v_mfma_f32_16x16x32_bf16 v[48:51], v[208:211], v[230:233], v[48:51]
	s_waitcnt vmcnt(6)
	ds_write_b128 v152, v[140:143] offset:45056
	s_waitcnt lgkmcnt(7)
	v_mfma_f32_16x16x32_bf16 v[44:47], v[196:199], v[234:237], v[44:47]
	v_mfma_f32_16x16x32_bf16 v[40:43], v[200:203], v[234:237], v[40:43]
	v_mfma_f32_16x16x32_bf16 v[36:39], v[204:207], v[234:237], v[36:39]
	v_mfma_f32_16x16x32_bf16 v[32:35], v[208:211], v[234:237], v[32:35]
	ds_write_b128 v152, v[132:135] offset:40960
	s_waitcnt lgkmcnt(7)
	v_mfma_f32_16x16x32_bf16 v[28:31], v[196:199], v[238:241], v[28:31]
	v_mfma_f32_16x16x32_bf16 v[24:27], v[200:203], v[238:241], v[24:27]
	v_mfma_f32_16x16x32_bf16 v[20:23], v[204:207], v[238:241], v[20:23]
	v_mfma_f32_16x16x32_bf16 v[16:19], v[208:211], v[238:241], v[16:19]
	s_waitcnt lgkmcnt(6)
	v_mfma_f32_16x16x32_bf16 v[12:15], v[196:199], v[242:245], v[12:15]
	v_mfma_f32_16x16x32_bf16 v[8:11], v[200:203], v[242:245], v[8:11]
	v_mfma_f32_16x16x32_bf16 v[4:7], v[204:207], v[242:245], v[4:7]
	v_mfma_f32_16x16x32_bf16 v[0:3], v[208:211], v[242:245], v[0:3]
	s_min_u32 s12, s25, 0x380
	s_lshl_b32 s12, s12, 1
	s_mov_b32 s29, s13
	s_add_i32 s28, s12, 0xc0
	v_lshl_add_u64 v[120:121], v[154:155], 0, s[12:13]
	v_lshl_add_u64 v[124:125], v[156:157], 0, s[12:13]
	v_lshl_add_u64 v[126:127], v[158:159], 0, s[28:29]
	v_lshl_add_u64 v[128:129], v[160:161], 0, s[28:29]
	v_lshl_add_u64 v[136:137], v[162:163], 0, s[28:29]
	v_lshl_add_u64 v[140:141], v[164:165], 0, s[28:29]
	s_waitcnt lgkmcnt(0)
	s_barrier
	global_load_dwordx4 v[120:123], v[120:121], off offset:192
	ds_read_b128 v[196:199], v168 offset:40960
	global_load_dwordx4 v[132:135], v[124:125], off offset:192
	ds_read_b128 v[200:203], v168 offset:41984
	global_load_dwordx4 v[124:127], v[126:127], off
	ds_read_b128 v[204:207], v168 offset:43008
	global_load_dwordx4 v[128:131], v[128:129], off
	ds_read_b128 v[208:211], v168 offset:44032
	global_load_dwordx4 v[136:139], v[136:137], off
	ds_read_b128 v[212:215], v170
	global_load_dwordx4 v[140:143], v[140:141], off
	ds_read_b128 v[216:219], v170 offset:1024
	ds_read_b128 v[222:225], v170 offset:2048
	ds_read_b128 v[226:229], v170 offset:3072
	ds_read_b128 v[230:233], v170 offset:4096
	ds_read_b128 v[234:237], v170 offset:5120
	ds_read_b128 v[238:241], v170 offset:6144
	ds_read_b128 v[242:245], v170 offset:7168
	s_waitcnt lgkmcnt(7)
	v_mfma_f32_16x16x32_bf16 v[148:151], v[196:199], v[212:215], v[148:151]
	v_mfma_f32_16x16x32_bf16 v[144:147], v[200:203], v[212:215], v[144:147]
	v_mfma_f32_16x16x32_bf16 v[116:119], v[204:207], v[212:215], v[116:119]
	v_mfma_f32_16x16x32_bf16 v[112:115], v[208:211], v[212:215], v[112:115]
	s_waitcnt vmcnt(11)
	ds_write_b128 v152, v[172:175]
	s_waitcnt lgkmcnt(7)
	v_mfma_f32_16x16x32_bf16 v[108:111], v[196:199], v[216:219], v[108:111]
	v_mfma_f32_16x16x32_bf16 v[104:107], v[200:203], v[216:219], v[104:107]
	v_mfma_f32_16x16x32_bf16 v[100:103], v[204:207], v[216:219], v[100:103]
	v_mfma_f32_16x16x32_bf16 v[96:99], v[208:211], v[216:219], v[96:99]
	s_waitcnt vmcnt(10)
	ds_write_b128 v152, v[176:179] offset:4096
	s_waitcnt lgkmcnt(7)
	v_mfma_f32_16x16x32_bf16 v[92:95], v[196:199], v[222:225], v[92:95]
	v_mfma_f32_16x16x32_bf16 v[88:91], v[200:203], v[222:225], v[88:91]
	v_mfma_f32_16x16x32_bf16 v[84:87], v[204:207], v[222:225], v[84:87]
	v_mfma_f32_16x16x32_bf16 v[80:83], v[208:211], v[222:225], v[80:83]
	s_waitcnt vmcnt(9)
	ds_write_b128 v152, v[180:183] offset:8192
	s_waitcnt lgkmcnt(7)
	v_mfma_f32_16x16x32_bf16 v[76:79], v[196:199], v[226:229], v[76:79]
	v_mfma_f32_16x16x32_bf16 v[72:75], v[200:203], v[226:229], v[72:75]
	v_mfma_f32_16x16x32_bf16 v[68:71], v[204:207], v[226:229], v[68:71]
	v_mfma_f32_16x16x32_bf16 v[64:67], v[208:211], v[226:229], v[64:67]
	s_waitcnt vmcnt(8)
	ds_write_b128 v152, v[184:187] offset:12288
	s_waitcnt lgkmcnt(7)
	v_mfma_f32_16x16x32_bf16 v[60:63], v[196:199], v[230:233], v[60:63]
	v_mfma_f32_16x16x32_bf16 v[56:59], v[200:203], v[230:233], v[56:59]
	v_mfma_f32_16x16x32_bf16 v[52:55], v[204:207], v[230:233], v[52:55]
	v_mfma_f32_16x16x32_bf16 v[48:51], v[208:211], v[230:233], v[48:51]
	s_waitcnt vmcnt(7)
	ds_write_b128 v152, v[188:191] offset:32768
	s_waitcnt lgkmcnt(7)
	v_mfma_f32_16x16x32_bf16 v[44:47], v[196:199], v[234:237], v[44:47]
	v_mfma_f32_16x16x32_bf16 v[40:43], v[200:203], v[234:237], v[40:43]
	v_mfma_f32_16x16x32_bf16 v[36:39], v[204:207], v[234:237], v[36:39]
	v_mfma_f32_16x16x32_bf16 v[32:35], v[208:211], v[234:237], v[32:35]
	s_waitcnt vmcnt(6)
	ds_write_b128 v152, v[192:195] offset:36864
	s_waitcnt lgkmcnt(7)
	v_mfma_f32_16x16x32_bf16 v[28:31], v[196:199], v[238:241], v[28:31]
	v_mfma_f32_16x16x32_bf16 v[24:27], v[200:203], v[238:241], v[24:27]
	v_mfma_f32_16x16x32_bf16 v[20:23], v[204:207], v[238:241], v[20:23]
	v_mfma_f32_16x16x32_bf16 v[16:19], v[208:211], v[238:241], v[16:19]
	s_waitcnt lgkmcnt(6)
	v_mfma_f32_16x16x32_bf16 v[12:15], v[196:199], v[242:245], v[12:15]
	v_mfma_f32_16x16x32_bf16 v[8:11], v[200:203], v[242:245], v[8:11]
	v_mfma_f32_16x16x32_bf16 v[4:7], v[204:207], v[242:245], v[4:7]
	v_mfma_f32_16x16x32_bf16 v[0:3], v[208:211], v[242:245], v[0:3]
	s_add_i32 s21, s21, 2
	s_cmp_lt_u32 s21, 30
	s_mov_b32 s25, s26
	s_waitcnt lgkmcnt(0)
	s_barrier
	s_cbranch_scc1 .LBB0_1737
	s_waitcnt vmcnt(5)
	v_mov_b32_e32 v120, v220
	s_nop 0
	v_and_b32_e32 v122, 0xffffff80, v120
	v_add_u32_e32 v122, s20, v122
	v_and_b32_e32 v121, 64, v120
	v_and_or_b32 v122, v120, 15, v122
	v_lshrrev_b32_e32 v120, 2, v120
	v_and_b32_e32 v120, 12, v120
	v_or3_b32 v120, v121, v120, s24
	v_ashrrev_i32_e32 v121, 31, v120
	v_ashrrev_i32_e32 v123, 31, v122
	v_lshl_add_u64 v[120:121], v[120:121], 1, s[10:11]
	s_waitcnt vmcnt(3)
	v_lshl_add_u64 v[124:125], v[122:123], 2, s[0:1]
	v_lshlrev_b64 v[126:127], 12, v[122:123]
	v_lshl_add_u64 v[162:163], v[120:121], 0, v[126:127]
	global_load_dword v152, v[124:125], off
	global_load_dwordx2 v[168:169], v[162:163], off
	global_load_dwordx2 v[170:171], v[162:163], off offset:32
	global_load_dwordx2 v[172:173], v[162:163], off offset:64
	v_or_b32_e32 v124, 16, v122
	v_ashrrev_i32_e32 v125, 31, v124
	v_lshl_add_u64 v[126:127], v[124:125], 2, s[0:1]
	v_lshlrev_b64 v[124:125], 12, v[124:125]
	s_waitcnt vmcnt(4)
	v_lshl_add_u64 v[142:143], v[120:121], 0, v[124:125]
	v_or_b32_e32 v124, 32, v122
	v_ashrrev_i32_e32 v125, 31, v124
	global_load_dwordx2 v[174:175], v[162:163], off offset:96
	global_load_dword v176, v[126:127], off
	global_load_dwordx2 v[164:165], v[142:143], off
	global_load_dwordx2 v[160:161], v[142:143], off offset:32
	v_lshl_add_u64 v[126:127], v[124:125], 2, s[0:1]
	v_lshlrev_b64 v[124:125], 12, v[124:125]
	v_lshl_add_u64 v[132:133], v[120:121], 0, v[124:125]
	v_or_b32_e32 v124, 48, v122
	v_ashrrev_i32_e32 v125, 31, v124
	global_load_dwordx2 v[158:159], v[142:143], off offset:64
	global_load_dwordx2 v[156:157], v[142:143], off offset:96
	global_load_dword v177, v[126:127], off
	global_load_dwordx2 v[154:155], v[132:133], off
	v_lshl_add_u64 v[126:127], v[124:125], 2, s[0:1]
	v_lshlrev_b64 v[124:125], 12, v[124:125]
	v_lshl_add_u64 v[124:125], v[120:121], 0, v[124:125]
	global_load_dwordx2 v[140:141], v[132:133], off offset:32
	global_load_dwordx2 v[138:139], v[132:133], off offset:64
	global_load_dwordx2 v[136:137], v[132:133], off offset:96
	global_load_dword v123, v[126:127], off
	global_load_dwordx2 v[134:135], v[124:125], off
	global_load_dwordx2 v[130:131], v[124:125], off offset:32
	global_load_dwordx2 v[128:129], v[124:125], off offset:64
	s_nop 0
	global_load_dwordx2 v[126:127], v[124:125], off offset:96
	s_waitcnt vmcnt(19)
	v_fmamk_f32 v152, v152, 0x3a800000, v167
	v_mul_f32_e32 v178, 0x4b800000, v152
	v_cmp_gt_f32_e32 vcc, s22, v152
	s_nop 1
	v_cndmask_b32_e32 v152, v152, v178, vcc
	v_rsq_f32_e32 v152, v152
	s_waitcnt vmcnt(18)
	v_lshlrev_b32_e32 v178, 16, v168
	v_and_b32_e32 v168, 0xffff0000, v168
	v_mul_f32_e32 v179, 0x45800000, v152
	v_cndmask_b32_e32 v152, v152, v179, vcc
	v_mul_f32_e32 v148, v148, v152
	v_mul_f32_e32 v180, 0xbfb8aa3b, v148
	v_exp_f32_e32 v180, v180
	v_mul_f32_e32 v149, v149, v152
	v_mul_f32_e32 v181, 0xbfb8aa3b, v149
	v_exp_f32_e32 v181, v181
	v_add_f32_e32 v180, 1.0, v180
	v_rcp_f32_e32 v180, v180
	v_mul_f32_e32 v150, v150, v152
	v_mul_f32_e32 v151, v151, v152
	v_lshlrev_b32_e32 v179, 16, v169
	v_mul_f32_e32 v148, v148, v180
	v_mul_f32_e32 v148, v148, v178
	v_add_f32_e32 v178, 1.0, v181
	v_mul_f32_e32 v180, 0xbfb8aa3b, v150
	v_mul_f32_e32 v181, 0xbfb8aa3b, v151
	v_rcp_f32_e32 v178, v178
	v_exp_f32_e32 v180, v180
	v_exp_f32_e32 v181, v181
	v_and_b32_e32 v169, 0xffff0000, v169
	v_mul_f32_e32 v149, v149, v178
	v_add_f32_e32 v178, 1.0, v180
	v_add_f32_e32 v180, 1.0, v181
	v_rcp_f32_e32 v180, v180
	v_rcp_f32_e32 v178, v178
	v_mul_f32_e32 v149, v149, v168
	v_mul_f32_e32 v144, v144, v152
	v_mul_f32_e32 v151, v151, v180
	v_mul_f32_e32 v150, v150, v178
	v_mul_f32_e32 v151, v151, v169
	v_mul_f32_e32 v150, v150, v179
	v_cvt_pk_bf16_f32 v148, v148, v149
	v_cvt_pk_bf16_f32 v149, v150, v151
	v_mul_f32_e32 v151, 0xbfb8aa3b, v144
	v_exp_f32_e32 v151, v151
	v_mul_f32_e32 v145, v145, v152
	v_mul_f32_e32 v169, 0xbfb8aa3b, v145
	v_exp_f32_e32 v169, v169
	v_add_f32_e32 v151, 1.0, v151
	v_rcp_f32_e32 v151, v151
	global_store_dwordx2 v[162:163], v[148:149], off
	s_waitcnt vmcnt(18)
	v_lshlrev_b32_e32 v148, 16, v170
	v_mul_f32_e32 v146, v146, v152
	v_mul_f32_e32 v147, v147, v152
	v_mul_f32_e32 v144, v144, v151
	v_mul_f32_e32 v144, v144, v148
	v_add_f32_e32 v148, 1.0, v169
	v_mul_f32_e32 v151, 0xbfb8aa3b, v146
	v_mul_f32_e32 v169, 0xbfb8aa3b, v147
	v_rcp_f32_e32 v148, v148
	v_exp_f32_e32 v151, v151
	v_exp_f32_e32 v169, v169
	v_and_b32_e32 v149, 0xffff0000, v170
	v_mul_f32_e32 v145, v145, v148
	v_add_f32_e32 v148, 1.0, v151
	v_add_f32_e32 v151, 1.0, v169
	v_rcp_f32_e32 v151, v151
	v_rcp_f32_e32 v148, v148
	v_and_b32_e32 v168, 0xffff0000, v171
	v_lshlrev_b32_e32 v150, 16, v171
	v_mul_f32_e32 v147, v147, v151
	v_mul_f32_e32 v145, v145, v149
	v_mul_f32_e32 v146, v146, v148
	v_mul_f32_e32 v147, v147, v168
	v_mul_f32_e32 v116, v116, v152
	v_mul_f32_e32 v146, v146, v150
	v_cvt_pk_bf16_f32 v144, v144, v145
	v_cvt_pk_bf16_f32 v145, v146, v147
	v_mul_f32_e32 v147, 0xbfb8aa3b, v116
	v_exp_f32_e32 v147, v147
	v_mul_f32_e32 v117, v117, v152
	v_mul_f32_e32 v149, 0xbfb8aa3b, v117
	v_exp_f32_e32 v149, v149
	v_add_f32_e32 v147, 1.0, v147
	v_rcp_f32_e32 v147, v147
	global_store_dwordx2 v[162:163], v[144:145], off offset:32
	s_waitcnt vmcnt(18)
	v_lshlrev_b32_e32 v144, 16, v172
	v_mul_f32_e32 v118, v118, v152
	v_mul_f32_e32 v119, v119, v152
	v_mul_f32_e32 v116, v116, v147
	v_mul_f32_e32 v116, v116, v144
	v_add_f32_e32 v144, 1.0, v149
	v_mul_f32_e32 v147, 0xbfb8aa3b, v118
	v_mul_f32_e32 v149, 0xbfb8aa3b, v119
	v_rcp_f32_e32 v144, v144
	v_exp_f32_e32 v147, v147
	v_exp_f32_e32 v149, v149
	v_and_b32_e32 v145, 0xffff0000, v172
	v_mul_f32_e32 v117, v117, v144
	v_add_f32_e32 v144, 1.0, v147
	v_add_f32_e32 v147, 1.0, v149
	v_rcp_f32_e32 v147, v147
	v_rcp_f32_e32 v144, v144
	v_and_b32_e32 v148, 0xffff0000, v173
	v_lshlrev_b32_e32 v146, 16, v173
	v_mul_f32_e32 v119, v119, v147
	v_mul_f32_e32 v117, v117, v145
	v_mul_f32_e32 v118, v118, v144
	v_mul_f32_e32 v119, v119, v148
	v_mul_f32_e32 v112, v112, v152
	v_mul_f32_e32 v118, v118, v146
	v_cvt_pk_bf16_f32 v116, v116, v117
	v_cvt_pk_bf16_f32 v117, v118, v119
	v_mul_f32_e32 v119, 0xbfb8aa3b, v112
	v_exp_f32_e32 v119, v119
	v_mul_f32_e32 v113, v113, v152
	v_mul_f32_e32 v145, 0xbfb8aa3b, v113
	v_exp_f32_e32 v145, v145
	v_add_f32_e32 v119, 1.0, v119
	v_rcp_f32_e32 v119, v119
	global_store_dwordx2 v[162:163], v[116:117], off offset:64
	s_waitcnt vmcnt(18)
	v_lshlrev_b32_e32 v116, 16, v174
	v_mul_f32_e32 v114, v114, v152
	v_mul_f32_e32 v112, v112, v119
	v_mul_f32_e32 v112, v112, v116
	v_add_f32_e32 v116, 1.0, v145
	v_mul_f32_e32 v119, 0xbfb8aa3b, v114
	v_rcp_f32_e32 v116, v116
	v_exp_f32_e32 v119, v119
	v_mul_f32_e32 v115, v115, v152
	v_mul_f32_e32 v145, 0xbfb8aa3b, v115
	v_mul_f32_e32 v113, v113, v116
	v_add_f32_e32 v116, 1.0, v119
	v_rcp_f32_e32 v116, v116
	v_exp_f32_e32 v145, v145
	v_and_b32_e32 v117, 0xffff0000, v174
	v_mul_f32_e32 v113, v113, v117
	v_mul_f32_e32 v114, v114, v116
	s_waitcnt vmcnt(17)
	v_fmamk_f32 v116, v176, 0x3a800000, v167
	v_add_f32_e32 v119, 1.0, v145
	v_mul_f32_e32 v117, 0x4b800000, v116
	v_cmp_gt_f32_e32 vcc, s22, v116
	v_rcp_f32_e32 v119, v119
	v_lshlrev_b32_e32 v118, 16, v175
	v_cndmask_b32_e32 v116, v116, v117, vcc
	v_rsq_f32_e32 v116, v116
	v_and_b32_e32 v144, 0xffff0000, v175
	v_mul_f32_e32 v115, v115, v119
	v_cvt_pk_bf16_f32 v112, v112, v113
	v_mul_f32_e32 v114, v114, v118
	v_mul_f32_e32 v115, v115, v144
	v_cvt_pk_bf16_f32 v113, v114, v115
	global_store_dwordx2 v[162:163], v[112:113], off offset:96
	v_mul_f32_e32 v112, 0x45800000, v116
	v_cndmask_b32_e32 v112, v116, v112, vcc
	v_mul_f32_e32 v108, v108, v112
	v_mul_f32_e32 v116, 0xbfb8aa3b, v108
	v_exp_f32_e32 v116, v116
	v_mul_f32_e32 v109, v109, v112
	v_mul_f32_e32 v118, 0xbfb8aa3b, v109
	v_exp_f32_e32 v118, v118
	v_add_f32_e32 v116, 1.0, v116
	v_rcp_f32_e32 v116, v116
	s_waitcnt vmcnt(17)
	v_lshlrev_b32_e32 v113, 16, v164
	v_mul_f32_e32 v110, v110, v112
	v_mul_f32_e32 v111, v111, v112
	v_mul_f32_e32 v108, v108, v116
	v_mul_f32_e32 v108, v108, v113
	v_add_f32_e32 v113, 1.0, v118
	v_mul_f32_e32 v116, 0xbfb8aa3b, v110
	v_mul_f32_e32 v118, 0xbfb8aa3b, v111
	v_rcp_f32_e32 v113, v113
	v_exp_f32_e32 v116, v116
	v_exp_f32_e32 v118, v118
	v_and_b32_e32 v114, 0xffff0000, v164
	v_mul_f32_e32 v109, v109, v113
	v_add_f32_e32 v113, 1.0, v116
	v_add_f32_e32 v116, 1.0, v118
	v_rcp_f32_e32 v116, v116
	v_rcp_f32_e32 v113, v113
	v_and_b32_e32 v117, 0xffff0000, v165
	v_lshlrev_b32_e32 v115, 16, v165
	v_mul_f32_e32 v111, v111, v116
	v_mul_f32_e32 v109, v109, v114
	v_mul_f32_e32 v110, v110, v113
	v_mul_f32_e32 v111, v111, v117
	v_mul_f32_e32 v104, v104, v112
	v_mul_f32_e32 v110, v110, v115
	v_cvt_pk_bf16_f32 v108, v108, v109
	v_cvt_pk_bf16_f32 v109, v110, v111
	v_mul_f32_e32 v111, 0xbfb8aa3b, v104
	v_exp_f32_e32 v111, v111
	v_mul_f32_e32 v105, v105, v112
	v_mul_f32_e32 v114, 0xbfb8aa3b, v105
	v_exp_f32_e32 v114, v114
	v_add_f32_e32 v111, 1.0, v111
	v_rcp_f32_e32 v111, v111
	global_store_dwordx2 v[142:143], v[108:109], off
	s_waitcnt vmcnt(17)
	v_lshlrev_b32_e32 v108, 16, v160
	v_mul_f32_e32 v106, v106, v112
	v_mul_f32_e32 v107, v107, v112
	v_mul_f32_e32 v104, v104, v111
	v_mul_f32_e32 v104, v104, v108
	v_add_f32_e32 v108, 1.0, v114
	v_mul_f32_e32 v111, 0xbfb8aa3b, v106
	v_mul_f32_e32 v114, 0xbfb8aa3b, v107
	v_rcp_f32_e32 v108, v108
	v_exp_f32_e32 v111, v111
	v_exp_f32_e32 v114, v114
	v_and_b32_e32 v109, 0xffff0000, v160
	v_mul_f32_e32 v105, v105, v108
	v_add_f32_e32 v108, 1.0, v111
	v_add_f32_e32 v111, 1.0, v114
	v_rcp_f32_e32 v111, v111
	v_rcp_f32_e32 v108, v108
	v_and_b32_e32 v113, 0xffff0000, v161
	v_lshlrev_b32_e32 v110, 16, v161
	v_mul_f32_e32 v107, v107, v111
	v_mul_f32_e32 v105, v105, v109
	v_mul_f32_e32 v106, v106, v108
	v_mul_f32_e32 v107, v107, v113
	v_mul_f32_e32 v100, v100, v112
	v_mul_f32_e32 v106, v106, v110
	v_cvt_pk_bf16_f32 v104, v104, v105
	v_cvt_pk_bf16_f32 v105, v106, v107
	v_mul_f32_e32 v107, 0xbfb8aa3b, v100
	v_exp_f32_e32 v107, v107
	v_mul_f32_e32 v101, v101, v112
	v_mul_f32_e32 v109, 0xbfb8aa3b, v101
	v_exp_f32_e32 v109, v109
	v_add_f32_e32 v107, 1.0, v107
	v_rcp_f32_e32 v107, v107
	global_store_dwordx2 v[142:143], v[104:105], off offset:32
	s_waitcnt vmcnt(17)
	v_lshlrev_b32_e32 v104, 16, v158
	v_mul_f32_e32 v102, v102, v112
	v_mul_f32_e32 v103, v103, v112
	v_mul_f32_e32 v100, v100, v107
	v_mul_f32_e32 v100, v100, v104
	v_add_f32_e32 v104, 1.0, v109
	v_mul_f32_e32 v107, 0xbfb8aa3b, v102
	v_mul_f32_e32 v109, 0xbfb8aa3b, v103
	v_rcp_f32_e32 v104, v104
	v_exp_f32_e32 v107, v107
	v_exp_f32_e32 v109, v109
	v_and_b32_e32 v105, 0xffff0000, v158
	v_mul_f32_e32 v101, v101, v104
	v_add_f32_e32 v104, 1.0, v107
	v_add_f32_e32 v107, 1.0, v109
	v_rcp_f32_e32 v107, v107
	v_rcp_f32_e32 v104, v104
	v_and_b32_e32 v108, 0xffff0000, v159
	v_lshlrev_b32_e32 v106, 16, v159
	v_mul_f32_e32 v103, v103, v107
	v_mul_f32_e32 v101, v101, v105
	v_mul_f32_e32 v102, v102, v104
	v_mul_f32_e32 v103, v103, v108
	v_mul_f32_e32 v96, v96, v112
	v_mul_f32_e32 v102, v102, v106
	v_cvt_pk_bf16_f32 v100, v100, v101
	v_cvt_pk_bf16_f32 v101, v102, v103
	v_mul_f32_e32 v103, 0xbfb8aa3b, v96
	v_exp_f32_e32 v103, v103
	v_mul_f32_e32 v97, v97, v112
	v_mul_f32_e32 v105, 0xbfb8aa3b, v97
	v_exp_f32_e32 v105, v105
	v_add_f32_e32 v103, 1.0, v103
	v_rcp_f32_e32 v103, v103
	global_store_dwordx2 v[142:143], v[100:101], off offset:64
	s_waitcnt vmcnt(17)
	v_lshlrev_b32_e32 v100, 16, v156
	v_mul_f32_e32 v98, v98, v112
	v_mul_f32_e32 v96, v96, v103
	v_mul_f32_e32 v96, v96, v100
	v_add_f32_e32 v100, 1.0, v105
	v_mul_f32_e32 v103, 0xbfb8aa3b, v98
	v_rcp_f32_e32 v100, v100
	v_exp_f32_e32 v103, v103
	v_mul_f32_e32 v99, v99, v112
	v_mul_f32_e32 v105, 0xbfb8aa3b, v99
	v_mul_f32_e32 v97, v97, v100
	v_add_f32_e32 v100, 1.0, v103
	v_rcp_f32_e32 v100, v100
	v_exp_f32_e32 v105, v105
	v_and_b32_e32 v101, 0xffff0000, v156
	v_mul_f32_e32 v97, v97, v101
	v_mul_f32_e32 v98, v98, v100
	s_waitcnt vmcnt(16)
	v_fmamk_f32 v100, v177, 0x3a800000, v167
	v_add_f32_e32 v103, 1.0, v105
	v_mul_f32_e32 v101, 0x4b800000, v100
	v_cmp_gt_f32_e32 vcc, s22, v100
	v_rcp_f32_e32 v103, v103
	v_lshlrev_b32_e32 v102, 16, v157
	v_cndmask_b32_e32 v100, v100, v101, vcc
	v_rsq_f32_e32 v100, v100
	v_and_b32_e32 v104, 0xffff0000, v157
	v_mul_f32_e32 v99, v99, v103
	v_cvt_pk_bf16_f32 v96, v96, v97
	v_mul_f32_e32 v98, v98, v102
	v_mul_f32_e32 v99, v99, v104
	v_cvt_pk_bf16_f32 v97, v98, v99
	global_store_dwordx2 v[142:143], v[96:97], off offset:96
	v_mul_f32_e32 v96, 0x45800000, v100
	v_cndmask_b32_e32 v96, v100, v96, vcc
	v_mul_f32_e32 v92, v92, v96
	v_mul_f32_e32 v100, 0xbfb8aa3b, v92
	v_exp_f32_e32 v100, v100
	v_mul_f32_e32 v93, v93, v96
	v_mul_f32_e32 v102, 0xbfb8aa3b, v93
	v_exp_f32_e32 v102, v102
	v_add_f32_e32 v100, 1.0, v100
	v_rcp_f32_e32 v100, v100
	s_waitcnt vmcnt(16)
	v_lshlrev_b32_e32 v97, 16, v154
	v_mul_f32_e32 v94, v94, v96
	v_mul_f32_e32 v95, v95, v96
	v_mul_f32_e32 v92, v92, v100
	v_mul_f32_e32 v92, v92, v97
	v_add_f32_e32 v97, 1.0, v102
	v_mul_f32_e32 v100, 0xbfb8aa3b, v94
	v_mul_f32_e32 v102, 0xbfb8aa3b, v95
	v_rcp_f32_e32 v97, v97
	v_exp_f32_e32 v100, v100
	v_exp_f32_e32 v102, v102
	v_and_b32_e32 v98, 0xffff0000, v154
	v_mul_f32_e32 v93, v93, v97
	v_add_f32_e32 v97, 1.0, v100
	v_add_f32_e32 v100, 1.0, v102
	v_rcp_f32_e32 v100, v100
	v_rcp_f32_e32 v97, v97
	v_and_b32_e32 v101, 0xffff0000, v155
	v_lshlrev_b32_e32 v99, 16, v155
	v_mul_f32_e32 v95, v95, v100
	v_mul_f32_e32 v93, v93, v98
	v_mul_f32_e32 v94, v94, v97
	v_mul_f32_e32 v95, v95, v101
	v_mul_f32_e32 v88, v88, v96
	v_mul_f32_e32 v94, v94, v99
	v_cvt_pk_bf16_f32 v92, v92, v93
	v_cvt_pk_bf16_f32 v93, v94, v95
	v_mul_f32_e32 v95, 0xbfb8aa3b, v88
	v_exp_f32_e32 v95, v95
	v_mul_f32_e32 v89, v89, v96
	v_mul_f32_e32 v98, 0xbfb8aa3b, v89
	v_exp_f32_e32 v98, v98
	v_add_f32_e32 v95, 1.0, v95
	v_rcp_f32_e32 v95, v95
	global_store_dwordx2 v[132:133], v[92:93], off
	s_waitcnt vmcnt(16)
	v_lshlrev_b32_e32 v92, 16, v140
	v_mul_f32_e32 v90, v90, v96
	v_mul_f32_e32 v91, v91, v96
	v_mul_f32_e32 v88, v88, v95
	v_mul_f32_e32 v88, v88, v92
	v_add_f32_e32 v92, 1.0, v98
	v_mul_f32_e32 v95, 0xbfb8aa3b, v90
	v_mul_f32_e32 v98, 0xbfb8aa3b, v91
	v_rcp_f32_e32 v92, v92
	v_exp_f32_e32 v95, v95
	v_exp_f32_e32 v98, v98
	v_and_b32_e32 v93, 0xffff0000, v140
	v_mul_f32_e32 v89, v89, v92
	v_add_f32_e32 v92, 1.0, v95
	v_add_f32_e32 v95, 1.0, v98
	v_rcp_f32_e32 v95, v95
	v_rcp_f32_e32 v92, v92
	v_and_b32_e32 v97, 0xffff0000, v141
	v_lshlrev_b32_e32 v94, 16, v141
	v_mul_f32_e32 v91, v91, v95
	v_mul_f32_e32 v89, v89, v93
	v_mul_f32_e32 v90, v90, v92
	v_mul_f32_e32 v91, v91, v97
	v_mul_f32_e32 v84, v84, v96
	v_mul_f32_e32 v90, v90, v94
	v_cvt_pk_bf16_f32 v88, v88, v89
	v_cvt_pk_bf16_f32 v89, v90, v91
	v_mul_f32_e32 v91, 0xbfb8aa3b, v84
	v_exp_f32_e32 v91, v91
	v_mul_f32_e32 v85, v85, v96
	v_mul_f32_e32 v93, 0xbfb8aa3b, v85
	v_exp_f32_e32 v93, v93
	v_add_f32_e32 v91, 1.0, v91
	v_rcp_f32_e32 v91, v91
	global_store_dwordx2 v[132:133], v[88:89], off offset:32
	s_waitcnt vmcnt(16)
	v_lshlrev_b32_e32 v88, 16, v138
	v_mul_f32_e32 v86, v86, v96
	v_mul_f32_e32 v87, v87, v96
	v_mul_f32_e32 v84, v84, v91
	v_mul_f32_e32 v84, v84, v88
	v_add_f32_e32 v88, 1.0, v93
	v_mul_f32_e32 v91, 0xbfb8aa3b, v86
	v_mul_f32_e32 v93, 0xbfb8aa3b, v87
	v_rcp_f32_e32 v88, v88
	v_exp_f32_e32 v91, v91
	v_exp_f32_e32 v93, v93
	v_and_b32_e32 v89, 0xffff0000, v138
	v_mul_f32_e32 v85, v85, v88
	v_add_f32_e32 v88, 1.0, v91
	v_add_f32_e32 v91, 1.0, v93
	v_rcp_f32_e32 v91, v91
	v_rcp_f32_e32 v88, v88
	v_and_b32_e32 v92, 0xffff0000, v139
	v_lshlrev_b32_e32 v90, 16, v139
	v_mul_f32_e32 v87, v87, v91
	v_mul_f32_e32 v85, v85, v89
	v_mul_f32_e32 v86, v86, v88
	v_mul_f32_e32 v87, v87, v92
	v_mul_f32_e32 v80, v80, v96
	v_mul_f32_e32 v86, v86, v90
	v_cvt_pk_bf16_f32 v84, v84, v85
	v_cvt_pk_bf16_f32 v85, v86, v87
	v_mul_f32_e32 v87, 0xbfb8aa3b, v80
	v_exp_f32_e32 v87, v87
	v_mul_f32_e32 v81, v81, v96
	v_mul_f32_e32 v89, 0xbfb8aa3b, v81
	v_exp_f32_e32 v89, v89
	v_add_f32_e32 v87, 1.0, v87
	v_rcp_f32_e32 v87, v87
	global_store_dwordx2 v[132:133], v[84:85], off offset:64
	s_waitcnt vmcnt(16)
	v_lshlrev_b32_e32 v84, 16, v136
	v_mul_f32_e32 v82, v82, v96
	v_mul_f32_e32 v80, v80, v87
	v_mul_f32_e32 v80, v80, v84
	v_add_f32_e32 v84, 1.0, v89
	v_mul_f32_e32 v87, 0xbfb8aa3b, v82
	v_rcp_f32_e32 v84, v84
	v_exp_f32_e32 v87, v87
	v_mul_f32_e32 v83, v83, v96
	v_mul_f32_e32 v89, 0xbfb8aa3b, v83
	v_mul_f32_e32 v81, v81, v84
	v_add_f32_e32 v84, 1.0, v87
	v_rcp_f32_e32 v84, v84
	v_exp_f32_e32 v89, v89
	v_and_b32_e32 v85, 0xffff0000, v136
	v_mul_f32_e32 v81, v81, v85
	v_mul_f32_e32 v82, v82, v84
	s_waitcnt vmcnt(15)
	v_fmamk_f32 v84, v123, 0x3a800000, v167
	v_add_f32_e32 v87, 1.0, v89
	v_mul_f32_e32 v85, 0x4b800000, v84
	v_cmp_gt_f32_e32 vcc, s22, v84
	v_rcp_f32_e32 v87, v87
	v_lshlrev_b32_e32 v86, 16, v137
	v_cndmask_b32_e32 v84, v84, v85, vcc
	v_rsq_f32_e32 v84, v84
	v_and_b32_e32 v88, 0xffff0000, v137
	v_mul_f32_e32 v83, v83, v87
	v_cvt_pk_bf16_f32 v80, v80, v81
	v_mul_f32_e32 v82, v82, v86
	v_mul_f32_e32 v83, v83, v88
	v_cvt_pk_bf16_f32 v81, v82, v83
	global_store_dwordx2 v[132:133], v[80:81], off offset:96
	v_mul_f32_e32 v80, 0x45800000, v84
	v_cndmask_b32_e32 v80, v84, v80, vcc
	v_mul_f32_e32 v76, v76, v80
	v_mul_f32_e32 v84, 0xbfb8aa3b, v76
	v_exp_f32_e32 v84, v84
	v_mul_f32_e32 v77, v77, v80
	v_mul_f32_e32 v86, 0xbfb8aa3b, v77
	v_exp_f32_e32 v86, v86
	v_add_f32_e32 v84, 1.0, v84
	v_rcp_f32_e32 v84, v84
	s_waitcnt vmcnt(15)
	v_lshlrev_b32_e32 v81, 16, v134
	v_mul_f32_e32 v78, v78, v80
	v_mul_f32_e32 v79, v79, v80
	v_mul_f32_e32 v76, v76, v84
	v_mul_f32_e32 v76, v76, v81
	v_add_f32_e32 v81, 1.0, v86
	v_mul_f32_e32 v84, 0xbfb8aa3b, v78
	v_mul_f32_e32 v86, 0xbfb8aa3b, v79
	v_rcp_f32_e32 v81, v81
	v_exp_f32_e32 v84, v84
	v_exp_f32_e32 v86, v86
	v_and_b32_e32 v82, 0xffff0000, v134
	v_mul_f32_e32 v77, v77, v81
	v_add_f32_e32 v81, 1.0, v84
	v_add_f32_e32 v84, 1.0, v86
	v_rcp_f32_e32 v84, v84
	v_rcp_f32_e32 v81, v81
	v_and_b32_e32 v85, 0xffff0000, v135
	v_lshlrev_b32_e32 v83, 16, v135
	v_mul_f32_e32 v79, v79, v84
	v_mul_f32_e32 v77, v77, v82
	v_mul_f32_e32 v78, v78, v81
	v_mul_f32_e32 v79, v79, v85
	v_mul_f32_e32 v72, v72, v80
	v_mul_f32_e32 v78, v78, v83
	v_cvt_pk_bf16_f32 v76, v76, v77
	v_cvt_pk_bf16_f32 v77, v78, v79
	v_mul_f32_e32 v79, 0xbfb8aa3b, v72
	v_exp_f32_e32 v79, v79
	v_mul_f32_e32 v73, v73, v80
	v_mul_f32_e32 v82, 0xbfb8aa3b, v73
	v_exp_f32_e32 v82, v82
	v_add_f32_e32 v79, 1.0, v79
	v_rcp_f32_e32 v79, v79
	global_store_dwordx2 v[124:125], v[76:77], off
	s_waitcnt vmcnt(15)
	v_lshlrev_b32_e32 v76, 16, v130
	v_mul_f32_e32 v74, v74, v80
	v_mul_f32_e32 v75, v75, v80
	v_mul_f32_e32 v72, v72, v79
	v_mul_f32_e32 v72, v72, v76
	v_add_f32_e32 v76, 1.0, v82
	v_mul_f32_e32 v79, 0xbfb8aa3b, v74
	v_mul_f32_e32 v82, 0xbfb8aa3b, v75
	v_rcp_f32_e32 v76, v76
	v_exp_f32_e32 v79, v79
	v_exp_f32_e32 v82, v82
	v_and_b32_e32 v77, 0xffff0000, v130
	v_mul_f32_e32 v73, v73, v76
	v_add_f32_e32 v76, 1.0, v79
	v_add_f32_e32 v79, 1.0, v82
	v_rcp_f32_e32 v79, v79
	v_rcp_f32_e32 v76, v76
	v_and_b32_e32 v81, 0xffff0000, v131
	v_lshlrev_b32_e32 v78, 16, v131
	v_mul_f32_e32 v75, v75, v79
	v_mul_f32_e32 v73, v73, v77
	v_mul_f32_e32 v74, v74, v76
	v_mul_f32_e32 v75, v75, v81
	v_mul_f32_e32 v68, v68, v80
	v_mul_f32_e32 v74, v74, v78
	v_cvt_pk_bf16_f32 v72, v72, v73
	v_cvt_pk_bf16_f32 v73, v74, v75
	v_mul_f32_e32 v75, 0xbfb8aa3b, v68
	v_exp_f32_e32 v75, v75
	v_mul_f32_e32 v69, v69, v80
	v_mul_f32_e32 v77, 0xbfb8aa3b, v69
	v_exp_f32_e32 v77, v77
	v_add_f32_e32 v75, 1.0, v75
	v_rcp_f32_e32 v75, v75
	global_store_dwordx2 v[124:125], v[72:73], off offset:32
	s_waitcnt vmcnt(15)
	v_lshlrev_b32_e32 v72, 16, v128
	v_mul_f32_e32 v70, v70, v80
	v_mul_f32_e32 v71, v71, v80
	v_mul_f32_e32 v68, v68, v75
	v_mul_f32_e32 v68, v68, v72
	v_add_f32_e32 v72, 1.0, v77
	v_mul_f32_e32 v75, 0xbfb8aa3b, v70
	v_mul_f32_e32 v77, 0xbfb8aa3b, v71
	v_rcp_f32_e32 v72, v72
	v_exp_f32_e32 v75, v75
	v_exp_f32_e32 v77, v77
	v_and_b32_e32 v73, 0xffff0000, v128
	v_mul_f32_e32 v69, v69, v72
	v_add_f32_e32 v72, 1.0, v75
	v_add_f32_e32 v75, 1.0, v77
	v_rcp_f32_e32 v75, v75
	v_rcp_f32_e32 v72, v72
	v_and_b32_e32 v76, 0xffff0000, v129
	v_lshlrev_b32_e32 v74, 16, v129
	v_mul_f32_e32 v71, v71, v75
	v_mul_f32_e32 v69, v69, v73
	v_mul_f32_e32 v70, v70, v72
	v_mul_f32_e32 v71, v71, v76
	v_mul_f32_e32 v64, v64, v80
	v_mul_f32_e32 v70, v70, v74
	v_cvt_pk_bf16_f32 v68, v68, v69
	v_cvt_pk_bf16_f32 v69, v70, v71
	v_mul_f32_e32 v71, 0xbfb8aa3b, v64
	v_exp_f32_e32 v71, v71
	v_mul_f32_e32 v65, v65, v80
	v_mul_f32_e32 v73, 0xbfb8aa3b, v65
	v_exp_f32_e32 v73, v73
	v_add_f32_e32 v71, 1.0, v71
	v_rcp_f32_e32 v71, v71
	global_store_dwordx2 v[124:125], v[68:69], off offset:64
	s_waitcnt vmcnt(15)
	v_lshlrev_b32_e32 v68, 16, v126
	v_mul_f32_e32 v66, v66, v80
	v_mul_f32_e32 v67, v67, v80
	v_mul_f32_e32 v64, v64, v71
	v_mul_f32_e32 v64, v64, v68
	v_add_f32_e32 v68, 1.0, v73
	v_mul_f32_e32 v71, 0xbfb8aa3b, v66
	v_mul_f32_e32 v73, 0xbfb8aa3b, v67
	v_rcp_f32_e32 v68, v68
	v_exp_f32_e32 v71, v71
	v_exp_f32_e32 v73, v73
	v_and_b32_e32 v69, 0xffff0000, v126
	v_mul_f32_e32 v65, v65, v68
	v_add_f32_e32 v68, 1.0, v71
	v_add_f32_e32 v71, 1.0, v73
	v_rcp_f32_e32 v68, v68
	v_rcp_f32_e32 v71, v71
	v_lshlrev_b32_e32 v70, 16, v127
	v_and_b32_e32 v72, 0xffff0000, v127
	v_mul_f32_e32 v65, v65, v69
	v_mul_f32_e32 v66, v66, v68
	v_mul_f32_e32 v67, v67, v71
	v_mul_f32_e32 v66, v66, v70
	v_mul_f32_e32 v67, v67, v72
	v_cvt_pk_bf16_f32 v64, v64, v65
	v_cvt_pk_bf16_f32 v65, v66, v67
	global_store_dwordx2 v[124:125], v[64:65], off offset:96
	v_or_b32_e32 v64, 64, v122
	v_ashrrev_i32_e32 v65, 31, v64
	v_lshl_add_u64 v[66:67], v[64:65], 2, s[0:1]
	v_lshlrev_b64 v[64:65], 12, v[64:65]
	v_lshl_add_u64 v[92:93], v[120:121], 0, v[64:65]
	v_or_b32_e32 v64, 0x50, v122
	v_ashrrev_i32_e32 v65, 31, v64
	global_load_dword v97, v[66:67], off
	global_load_dwordx2 v[98:99], v[92:93], off
	global_load_dwordx2 v[100:101], v[92:93], off offset:32
	global_load_dwordx2 v[102:103], v[92:93], off offset:64
	v_lshl_add_u64 v[66:67], v[64:65], 2, s[0:1]
	v_lshlrev_b64 v[64:65], 12, v[64:65]
	v_lshl_add_u64 v[82:83], v[120:121], 0, v[64:65]
	v_or_b32_e32 v64, 0x60, v122
	v_ashrrev_i32_e32 v65, 31, v64
	global_load_dwordx2 v[104:105], v[92:93], off offset:96
	global_load_dword v106, v[66:67], off
	global_load_dwordx2 v[94:95], v[82:83], off
	global_load_dwordx2 v[90:91], v[82:83], off offset:32
	v_lshl_add_u64 v[66:67], v[64:65], 2, s[0:1]
	v_lshlrev_b64 v[64:65], 12, v[64:65]
	v_lshl_add_u64 v[72:73], v[120:121], 0, v[64:65]
	v_or_b32_e32 v64, 0x70, v122
	v_ashrrev_i32_e32 v65, 31, v64
	global_load_dwordx2 v[88:89], v[82:83], off offset:64
	global_load_dwordx2 v[86:87], v[82:83], off offset:96
	global_load_dword v107, v[66:67], off
	global_load_dwordx2 v[84:85], v[72:73], off
	v_lshl_add_u64 v[66:67], v[64:65], 2, s[0:1]
	v_lshlrev_b64 v[64:65], 12, v[64:65]
	v_lshl_add_u64 v[64:65], v[120:121], 0, v[64:65]
	global_load_dwordx2 v[80:81], v[72:73], off offset:32
	global_load_dwordx2 v[78:79], v[72:73], off offset:64
	global_load_dwordx2 v[76:77], v[72:73], off offset:96
	global_load_dword v96, v[66:67], off
	global_load_dwordx2 v[74:75], v[64:65], off
	global_load_dwordx2 v[70:71], v[64:65], off offset:32
	global_load_dwordx2 v[68:69], v[64:65], off offset:64
	s_nop 0
	global_load_dwordx2 v[66:67], v[64:65], off offset:96
	s_waitcnt vmcnt(19)
	v_fmamk_f32 v97, v97, 0x3a800000, v167
	v_mul_f32_e32 v108, 0x4b800000, v97
	v_cmp_gt_f32_e32 vcc, s22, v97
	s_nop 1
	v_cndmask_b32_e32 v97, v97, v108, vcc
	v_rsq_f32_e32 v97, v97
	s_waitcnt vmcnt(18)
	v_lshlrev_b32_e32 v108, 16, v98
	v_and_b32_e32 v98, 0xffff0000, v98
	v_mul_f32_e32 v109, 0x45800000, v97
	v_cndmask_b32_e32 v97, v97, v109, vcc
	v_mul_f32_e32 v60, v60, v97
	v_mul_f32_e32 v110, 0xbfb8aa3b, v60
	v_exp_f32_e32 v110, v110
	v_mul_f32_e32 v61, v61, v97
	v_mul_f32_e32 v111, 0xbfb8aa3b, v61
	v_exp_f32_e32 v111, v111
	v_add_f32_e32 v110, 1.0, v110
	v_rcp_f32_e32 v110, v110
	v_mul_f32_e32 v62, v62, v97
	v_mul_f32_e32 v63, v63, v97
	v_lshlrev_b32_e32 v109, 16, v99
	v_mul_f32_e32 v60, v60, v110
	v_mul_f32_e32 v60, v60, v108
	v_add_f32_e32 v108, 1.0, v111
	v_mul_f32_e32 v110, 0xbfb8aa3b, v62
	v_mul_f32_e32 v111, 0xbfb8aa3b, v63
	v_rcp_f32_e32 v108, v108
	v_exp_f32_e32 v110, v110
	v_exp_f32_e32 v111, v111
	v_and_b32_e32 v99, 0xffff0000, v99
	v_mul_f32_e32 v61, v61, v108
	v_add_f32_e32 v108, 1.0, v110
	v_add_f32_e32 v110, 1.0, v111
	v_rcp_f32_e32 v110, v110
	v_rcp_f32_e32 v108, v108
	v_mul_f32_e32 v61, v61, v98
	v_mul_f32_e32 v56, v56, v97
	v_mul_f32_e32 v63, v63, v110
	v_mul_f32_e32 v62, v62, v108
	v_mul_f32_e32 v63, v63, v99
	v_mul_f32_e32 v62, v62, v109
	v_cvt_pk_bf16_f32 v60, v60, v61
	v_cvt_pk_bf16_f32 v61, v62, v63
	v_mul_f32_e32 v63, 0xbfb8aa3b, v56
	v_exp_f32_e32 v63, v63
	v_mul_f32_e32 v57, v57, v97
	v_mul_f32_e32 v99, 0xbfb8aa3b, v57
	v_exp_f32_e32 v99, v99
	v_add_f32_e32 v63, 1.0, v63
	v_rcp_f32_e32 v63, v63
	global_store_dwordx2 v[92:93], v[60:61], off
	s_waitcnt vmcnt(18)
	v_lshlrev_b32_e32 v60, 16, v100
	v_mul_f32_e32 v58, v58, v97
	v_mul_f32_e32 v59, v59, v97
	v_mul_f32_e32 v56, v56, v63
	v_mul_f32_e32 v56, v56, v60
	v_add_f32_e32 v60, 1.0, v99
	v_mul_f32_e32 v63, 0xbfb8aa3b, v58
	v_mul_f32_e32 v99, 0xbfb8aa3b, v59
	v_rcp_f32_e32 v60, v60
	v_exp_f32_e32 v63, v63
	v_exp_f32_e32 v99, v99
	v_and_b32_e32 v61, 0xffff0000, v100
	v_mul_f32_e32 v57, v57, v60
	v_add_f32_e32 v60, 1.0, v63
	v_add_f32_e32 v63, 1.0, v99
	v_rcp_f32_e32 v63, v63
	v_rcp_f32_e32 v60, v60
	v_and_b32_e32 v98, 0xffff0000, v101
	v_lshlrev_b32_e32 v62, 16, v101
	v_mul_f32_e32 v59, v59, v63
	v_mul_f32_e32 v57, v57, v61
	v_mul_f32_e32 v58, v58, v60
	v_mul_f32_e32 v59, v59, v98
	v_mul_f32_e32 v52, v52, v97
	v_mul_f32_e32 v58, v58, v62
	v_cvt_pk_bf16_f32 v56, v56, v57
	v_cvt_pk_bf16_f32 v57, v58, v59
	v_mul_f32_e32 v59, 0xbfb8aa3b, v52
	v_exp_f32_e32 v59, v59
	v_mul_f32_e32 v53, v53, v97
	v_mul_f32_e32 v61, 0xbfb8aa3b, v53
	v_exp_f32_e32 v61, v61
	v_add_f32_e32 v59, 1.0, v59
	v_rcp_f32_e32 v59, v59
	global_store_dwordx2 v[92:93], v[56:57], off offset:32
	s_waitcnt vmcnt(18)
	v_lshlrev_b32_e32 v56, 16, v102
	v_mul_f32_e32 v54, v54, v97
	v_mul_f32_e32 v55, v55, v97
	v_mul_f32_e32 v52, v52, v59
	v_mul_f32_e32 v52, v52, v56
	v_add_f32_e32 v56, 1.0, v61
	v_mul_f32_e32 v59, 0xbfb8aa3b, v54
	v_mul_f32_e32 v61, 0xbfb8aa3b, v55
	v_rcp_f32_e32 v56, v56
	v_exp_f32_e32 v59, v59
	v_exp_f32_e32 v61, v61
	v_and_b32_e32 v57, 0xffff0000, v102
	v_mul_f32_e32 v53, v53, v56
	v_add_f32_e32 v56, 1.0, v59
	v_add_f32_e32 v59, 1.0, v61
	v_rcp_f32_e32 v59, v59
	v_rcp_f32_e32 v56, v56
	v_and_b32_e32 v60, 0xffff0000, v103
	v_lshlrev_b32_e32 v58, 16, v103
	v_mul_f32_e32 v55, v55, v59
	v_mul_f32_e32 v53, v53, v57
	v_mul_f32_e32 v54, v54, v56
	v_mul_f32_e32 v55, v55, v60
	v_mul_f32_e32 v48, v48, v97
	v_mul_f32_e32 v54, v54, v58
	v_cvt_pk_bf16_f32 v52, v52, v53
	v_cvt_pk_bf16_f32 v53, v54, v55
	v_mul_f32_e32 v55, 0xbfb8aa3b, v48
	v_exp_f32_e32 v55, v55
	v_mul_f32_e32 v49, v49, v97
	v_mul_f32_e32 v57, 0xbfb8aa3b, v49
	v_exp_f32_e32 v57, v57
	v_add_f32_e32 v55, 1.0, v55
	v_rcp_f32_e32 v55, v55
	global_store_dwordx2 v[92:93], v[52:53], off offset:64
	s_waitcnt vmcnt(18)
	v_lshlrev_b32_e32 v52, 16, v104
	v_mul_f32_e32 v50, v50, v97
	v_mul_f32_e32 v48, v48, v55
	v_mul_f32_e32 v48, v48, v52
	v_add_f32_e32 v52, 1.0, v57
	v_mul_f32_e32 v55, 0xbfb8aa3b, v50
	v_rcp_f32_e32 v52, v52
	v_exp_f32_e32 v55, v55
	v_mul_f32_e32 v51, v51, v97
	v_mul_f32_e32 v57, 0xbfb8aa3b, v51
	v_mul_f32_e32 v49, v49, v52
	v_add_f32_e32 v52, 1.0, v55
	v_rcp_f32_e32 v52, v52
	v_exp_f32_e32 v57, v57
	v_and_b32_e32 v53, 0xffff0000, v104
	v_mul_f32_e32 v49, v49, v53
	v_mul_f32_e32 v50, v50, v52
	s_waitcnt vmcnt(17)
	v_fmamk_f32 v52, v106, 0x3a800000, v167
	v_add_f32_e32 v55, 1.0, v57
	v_mul_f32_e32 v53, 0x4b800000, v52
	v_cmp_gt_f32_e32 vcc, s22, v52
	v_rcp_f32_e32 v55, v55
	v_lshlrev_b32_e32 v54, 16, v105
	v_cndmask_b32_e32 v52, v52, v53, vcc
	v_rsq_f32_e32 v52, v52
	v_and_b32_e32 v56, 0xffff0000, v105
	v_mul_f32_e32 v51, v51, v55
	v_cvt_pk_bf16_f32 v48, v48, v49
	v_mul_f32_e32 v50, v50, v54
	v_mul_f32_e32 v51, v51, v56
	v_cvt_pk_bf16_f32 v49, v50, v51
	global_store_dwordx2 v[92:93], v[48:49], off offset:96
	v_mul_f32_e32 v48, 0x45800000, v52
	v_cndmask_b32_e32 v48, v52, v48, vcc
	v_mul_f32_e32 v44, v44, v48
	v_mul_f32_e32 v52, 0xbfb8aa3b, v44
	v_exp_f32_e32 v52, v52
	v_mul_f32_e32 v45, v45, v48
	v_mul_f32_e32 v54, 0xbfb8aa3b, v45
	v_exp_f32_e32 v54, v54
	v_add_f32_e32 v52, 1.0, v52
	v_rcp_f32_e32 v52, v52
	s_waitcnt vmcnt(17)
	v_lshlrev_b32_e32 v49, 16, v94
	v_mul_f32_e32 v46, v46, v48
	v_mul_f32_e32 v47, v47, v48
	v_mul_f32_e32 v44, v44, v52
	v_mul_f32_e32 v44, v44, v49
	v_add_f32_e32 v49, 1.0, v54
	v_mul_f32_e32 v52, 0xbfb8aa3b, v46
	v_mul_f32_e32 v54, 0xbfb8aa3b, v47
	v_rcp_f32_e32 v49, v49
	v_exp_f32_e32 v52, v52
	v_exp_f32_e32 v54, v54
	v_and_b32_e32 v50, 0xffff0000, v94
	v_mul_f32_e32 v45, v45, v49
	v_add_f32_e32 v49, 1.0, v52
	v_add_f32_e32 v52, 1.0, v54
	v_rcp_f32_e32 v52, v52
	v_rcp_f32_e32 v49, v49
	v_and_b32_e32 v53, 0xffff0000, v95
	v_lshlrev_b32_e32 v51, 16, v95
	v_mul_f32_e32 v47, v47, v52
	v_mul_f32_e32 v45, v45, v50
	v_mul_f32_e32 v46, v46, v49
	v_mul_f32_e32 v47, v47, v53
	v_mul_f32_e32 v40, v40, v48
	v_mul_f32_e32 v46, v46, v51
	v_cvt_pk_bf16_f32 v44, v44, v45
	v_cvt_pk_bf16_f32 v45, v46, v47
	v_mul_f32_e32 v47, 0xbfb8aa3b, v40
	v_exp_f32_e32 v47, v47
	v_mul_f32_e32 v41, v41, v48
	v_mul_f32_e32 v50, 0xbfb8aa3b, v41
	v_exp_f32_e32 v50, v50
	v_add_f32_e32 v47, 1.0, v47
	v_rcp_f32_e32 v47, v47
	global_store_dwordx2 v[82:83], v[44:45], off
	s_waitcnt vmcnt(17)
	v_lshlrev_b32_e32 v44, 16, v90
	v_mul_f32_e32 v42, v42, v48
	v_mul_f32_e32 v43, v43, v48
	v_mul_f32_e32 v40, v40, v47
	v_mul_f32_e32 v40, v40, v44
	v_add_f32_e32 v44, 1.0, v50
	v_mul_f32_e32 v47, 0xbfb8aa3b, v42
	v_mul_f32_e32 v50, 0xbfb8aa3b, v43
	v_rcp_f32_e32 v44, v44
	v_exp_f32_e32 v47, v47
	v_exp_f32_e32 v50, v50
	v_and_b32_e32 v45, 0xffff0000, v90
	v_mul_f32_e32 v41, v41, v44
	v_add_f32_e32 v44, 1.0, v47
	v_add_f32_e32 v47, 1.0, v50
	v_rcp_f32_e32 v47, v47
	v_rcp_f32_e32 v44, v44
	v_and_b32_e32 v49, 0xffff0000, v91
	v_lshlrev_b32_e32 v46, 16, v91
	v_mul_f32_e32 v43, v43, v47
	v_mul_f32_e32 v41, v41, v45
	v_mul_f32_e32 v42, v42, v44
	v_mul_f32_e32 v43, v43, v49
	v_mul_f32_e32 v36, v36, v48
	v_mul_f32_e32 v42, v42, v46
	v_cvt_pk_bf16_f32 v40, v40, v41
	v_cvt_pk_bf16_f32 v41, v42, v43
	v_mul_f32_e32 v43, 0xbfb8aa3b, v36
	v_exp_f32_e32 v43, v43
	v_mul_f32_e32 v37, v37, v48
	v_mul_f32_e32 v45, 0xbfb8aa3b, v37
	v_exp_f32_e32 v45, v45
	v_add_f32_e32 v43, 1.0, v43
	v_rcp_f32_e32 v43, v43
	global_store_dwordx2 v[82:83], v[40:41], off offset:32
	s_waitcnt vmcnt(17)
	v_lshlrev_b32_e32 v40, 16, v88
	v_mul_f32_e32 v38, v38, v48
	v_mul_f32_e32 v39, v39, v48
	v_mul_f32_e32 v36, v36, v43
	v_mul_f32_e32 v36, v36, v40
	v_add_f32_e32 v40, 1.0, v45
	v_mul_f32_e32 v43, 0xbfb8aa3b, v38
	v_mul_f32_e32 v45, 0xbfb8aa3b, v39
	v_rcp_f32_e32 v40, v40
	v_exp_f32_e32 v43, v43
	v_exp_f32_e32 v45, v45
	v_and_b32_e32 v41, 0xffff0000, v88
	v_mul_f32_e32 v37, v37, v40
	v_add_f32_e32 v40, 1.0, v43
	v_add_f32_e32 v43, 1.0, v45
	v_rcp_f32_e32 v43, v43
	v_rcp_f32_e32 v40, v40
	v_and_b32_e32 v44, 0xffff0000, v89
	v_lshlrev_b32_e32 v42, 16, v89
	v_mul_f32_e32 v39, v39, v43
	v_mul_f32_e32 v37, v37, v41
	v_mul_f32_e32 v38, v38, v40
	v_mul_f32_e32 v39, v39, v44
	v_mul_f32_e32 v32, v32, v48
	v_mul_f32_e32 v38, v38, v42
	v_cvt_pk_bf16_f32 v36, v36, v37
	v_cvt_pk_bf16_f32 v37, v38, v39
	v_mul_f32_e32 v39, 0xbfb8aa3b, v32
	v_exp_f32_e32 v39, v39
	v_mul_f32_e32 v33, v33, v48
	v_mul_f32_e32 v41, 0xbfb8aa3b, v33
	v_exp_f32_e32 v41, v41
	v_add_f32_e32 v39, 1.0, v39
	v_rcp_f32_e32 v39, v39
	global_store_dwordx2 v[82:83], v[36:37], off offset:64
	s_waitcnt vmcnt(17)
	v_lshlrev_b32_e32 v36, 16, v86
	v_mul_f32_e32 v34, v34, v48
	v_mul_f32_e32 v32, v32, v39
	v_mul_f32_e32 v32, v32, v36
	v_add_f32_e32 v36, 1.0, v41
	v_mul_f32_e32 v39, 0xbfb8aa3b, v34
	v_rcp_f32_e32 v36, v36
	v_exp_f32_e32 v39, v39
	v_mul_f32_e32 v35, v35, v48
	v_mul_f32_e32 v41, 0xbfb8aa3b, v35
	v_mul_f32_e32 v33, v33, v36
	v_add_f32_e32 v36, 1.0, v39
	v_rcp_f32_e32 v36, v36
	v_exp_f32_e32 v41, v41
	v_and_b32_e32 v37, 0xffff0000, v86
	v_mul_f32_e32 v33, v33, v37
	v_mul_f32_e32 v34, v34, v36
	s_waitcnt vmcnt(16)
	v_fmamk_f32 v36, v107, 0x3a800000, v167
	v_add_f32_e32 v39, 1.0, v41
	v_mul_f32_e32 v37, 0x4b800000, v36
	v_cmp_gt_f32_e32 vcc, s22, v36
	v_rcp_f32_e32 v39, v39
	v_lshlrev_b32_e32 v38, 16, v87
	v_cndmask_b32_e32 v36, v36, v37, vcc
	v_rsq_f32_e32 v36, v36
	v_and_b32_e32 v40, 0xffff0000, v87
	v_mul_f32_e32 v35, v35, v39
	v_cvt_pk_bf16_f32 v32, v32, v33
	v_mul_f32_e32 v34, v34, v38
	v_mul_f32_e32 v35, v35, v40
	v_cvt_pk_bf16_f32 v33, v34, v35
	global_store_dwordx2 v[82:83], v[32:33], off offset:96
	v_mul_f32_e32 v32, 0x45800000, v36
	v_cndmask_b32_e32 v32, v36, v32, vcc
	v_mul_f32_e32 v28, v28, v32
	v_mul_f32_e32 v36, 0xbfb8aa3b, v28
	v_exp_f32_e32 v36, v36
	v_mul_f32_e32 v29, v29, v32
	v_mul_f32_e32 v38, 0xbfb8aa3b, v29
	v_exp_f32_e32 v38, v38
	v_add_f32_e32 v36, 1.0, v36
	v_rcp_f32_e32 v36, v36
	s_waitcnt vmcnt(16)
	v_lshlrev_b32_e32 v33, 16, v84
	v_mul_f32_e32 v30, v30, v32
	v_mul_f32_e32 v31, v31, v32
	v_mul_f32_e32 v28, v28, v36
	v_mul_f32_e32 v28, v28, v33
	v_add_f32_e32 v33, 1.0, v38
	v_mul_f32_e32 v36, 0xbfb8aa3b, v30
	v_mul_f32_e32 v38, 0xbfb8aa3b, v31
	v_rcp_f32_e32 v33, v33
	v_exp_f32_e32 v36, v36
	v_exp_f32_e32 v38, v38
	v_and_b32_e32 v34, 0xffff0000, v84
	v_mul_f32_e32 v29, v29, v33
	v_add_f32_e32 v33, 1.0, v36
	v_add_f32_e32 v36, 1.0, v38
	v_rcp_f32_e32 v36, v36
	v_rcp_f32_e32 v33, v33
	v_and_b32_e32 v37, 0xffff0000, v85
	v_lshlrev_b32_e32 v35, 16, v85
	v_mul_f32_e32 v31, v31, v36
	v_mul_f32_e32 v29, v29, v34
	v_mul_f32_e32 v30, v30, v33
	v_mul_f32_e32 v31, v31, v37
	v_mul_f32_e32 v24, v24, v32
	v_mul_f32_e32 v30, v30, v35
	v_cvt_pk_bf16_f32 v28, v28, v29
	v_cvt_pk_bf16_f32 v29, v30, v31
	v_mul_f32_e32 v31, 0xbfb8aa3b, v24
	v_exp_f32_e32 v31, v31
	v_mul_f32_e32 v25, v25, v32
	v_mul_f32_e32 v34, 0xbfb8aa3b, v25
	v_exp_f32_e32 v34, v34
	v_add_f32_e32 v31, 1.0, v31
	v_rcp_f32_e32 v31, v31
	global_store_dwordx2 v[72:73], v[28:29], off
	s_waitcnt vmcnt(16)
	v_lshlrev_b32_e32 v28, 16, v80
	v_mul_f32_e32 v26, v26, v32
	v_mul_f32_e32 v27, v27, v32
	v_mul_f32_e32 v24, v24, v31
	v_mul_f32_e32 v24, v24, v28
	v_add_f32_e32 v28, 1.0, v34
	v_mul_f32_e32 v31, 0xbfb8aa3b, v26
	v_mul_f32_e32 v34, 0xbfb8aa3b, v27
	v_rcp_f32_e32 v28, v28
	v_exp_f32_e32 v31, v31
	v_exp_f32_e32 v34, v34
	v_and_b32_e32 v29, 0xffff0000, v80
	v_mul_f32_e32 v25, v25, v28
	v_add_f32_e32 v28, 1.0, v31
	v_add_f32_e32 v31, 1.0, v34
	v_rcp_f32_e32 v31, v31
	v_rcp_f32_e32 v28, v28
	v_and_b32_e32 v33, 0xffff0000, v81
	v_lshlrev_b32_e32 v30, 16, v81
	v_mul_f32_e32 v27, v27, v31
	v_mul_f32_e32 v25, v25, v29
	v_mul_f32_e32 v26, v26, v28
	v_mul_f32_e32 v27, v27, v33
	v_mul_f32_e32 v20, v20, v32
	v_mul_f32_e32 v26, v26, v30
	v_cvt_pk_bf16_f32 v24, v24, v25
	v_cvt_pk_bf16_f32 v25, v26, v27
	v_mul_f32_e32 v27, 0xbfb8aa3b, v20
	v_exp_f32_e32 v27, v27
	v_mul_f32_e32 v21, v21, v32
	v_mul_f32_e32 v29, 0xbfb8aa3b, v21
	v_exp_f32_e32 v29, v29
	v_add_f32_e32 v27, 1.0, v27
	v_rcp_f32_e32 v27, v27
	global_store_dwordx2 v[72:73], v[24:25], off offset:32
	s_waitcnt vmcnt(16)
	v_lshlrev_b32_e32 v24, 16, v78
	v_mul_f32_e32 v22, v22, v32
	v_mul_f32_e32 v23, v23, v32
	v_mul_f32_e32 v20, v20, v27
	v_mul_f32_e32 v20, v20, v24
	v_add_f32_e32 v24, 1.0, v29
	v_mul_f32_e32 v27, 0xbfb8aa3b, v22
	v_mul_f32_e32 v29, 0xbfb8aa3b, v23
	v_rcp_f32_e32 v24, v24
	v_exp_f32_e32 v27, v27
	v_exp_f32_e32 v29, v29
	v_and_b32_e32 v25, 0xffff0000, v78
	v_mul_f32_e32 v21, v21, v24
	v_add_f32_e32 v24, 1.0, v27
	v_add_f32_e32 v27, 1.0, v29
	v_rcp_f32_e32 v27, v27
	v_rcp_f32_e32 v24, v24
	v_and_b32_e32 v28, 0xffff0000, v79
	v_lshlrev_b32_e32 v26, 16, v79
	v_mul_f32_e32 v23, v23, v27
	v_mul_f32_e32 v21, v21, v25
	v_mul_f32_e32 v22, v22, v24
	v_mul_f32_e32 v23, v23, v28
	v_mul_f32_e32 v16, v16, v32
	v_mul_f32_e32 v22, v22, v26
	v_cvt_pk_bf16_f32 v20, v20, v21
	v_cvt_pk_bf16_f32 v21, v22, v23
	v_mul_f32_e32 v23, 0xbfb8aa3b, v16
	v_exp_f32_e32 v23, v23
	v_mul_f32_e32 v17, v17, v32
	v_mul_f32_e32 v25, 0xbfb8aa3b, v17
	v_exp_f32_e32 v25, v25
	v_add_f32_e32 v23, 1.0, v23
	v_rcp_f32_e32 v23, v23
	global_store_dwordx2 v[72:73], v[20:21], off offset:64
	s_waitcnt vmcnt(16)
	v_lshlrev_b32_e32 v20, 16, v76
	v_mul_f32_e32 v18, v18, v32
	v_mul_f32_e32 v16, v16, v23
	v_mul_f32_e32 v16, v16, v20
	v_add_f32_e32 v20, 1.0, v25
	v_mul_f32_e32 v23, 0xbfb8aa3b, v18
	v_rcp_f32_e32 v20, v20
	v_exp_f32_e32 v23, v23
	v_mul_f32_e32 v19, v19, v32
	v_mul_f32_e32 v25, 0xbfb8aa3b, v19
	v_mul_f32_e32 v17, v17, v20
	v_add_f32_e32 v20, 1.0, v23
	v_rcp_f32_e32 v20, v20
	v_exp_f32_e32 v25, v25
	v_and_b32_e32 v21, 0xffff0000, v76
	v_mul_f32_e32 v17, v17, v21
	v_mul_f32_e32 v18, v18, v20
	s_waitcnt vmcnt(15)
	v_fmamk_f32 v20, v96, 0x3a800000, v167
	v_add_f32_e32 v23, 1.0, v25
	v_mul_f32_e32 v21, 0x4b800000, v20
	v_cmp_gt_f32_e32 vcc, s22, v20
	v_rcp_f32_e32 v23, v23
	v_lshlrev_b32_e32 v22, 16, v77
	v_cndmask_b32_e32 v20, v20, v21, vcc
	v_rsq_f32_e32 v20, v20
	v_and_b32_e32 v24, 0xffff0000, v77
	v_mul_f32_e32 v19, v19, v23
	v_cvt_pk_bf16_f32 v16, v16, v17
	v_mul_f32_e32 v18, v18, v22
	v_mul_f32_e32 v19, v19, v24
	v_cvt_pk_bf16_f32 v17, v18, v19
	global_store_dwordx2 v[72:73], v[16:17], off offset:96
	v_mul_f32_e32 v16, 0x45800000, v20
	v_cndmask_b32_e32 v16, v20, v16, vcc
	v_mul_f32_e32 v12, v12, v16
	v_mul_f32_e32 v20, 0xbfb8aa3b, v12
	v_exp_f32_e32 v20, v20
	v_mul_f32_e32 v13, v13, v16
	v_mul_f32_e32 v22, 0xbfb8aa3b, v13
	v_exp_f32_e32 v22, v22
	v_add_f32_e32 v20, 1.0, v20
	v_rcp_f32_e32 v20, v20
	s_waitcnt vmcnt(15)
	v_lshlrev_b32_e32 v17, 16, v74
	v_mul_f32_e32 v14, v14, v16
	v_mul_f32_e32 v15, v15, v16
	v_mul_f32_e32 v12, v12, v20
	v_mul_f32_e32 v12, v12, v17
	v_add_f32_e32 v17, 1.0, v22
	v_mul_f32_e32 v20, 0xbfb8aa3b, v14
	v_mul_f32_e32 v22, 0xbfb8aa3b, v15
	v_rcp_f32_e32 v17, v17
	v_exp_f32_e32 v20, v20
	v_exp_f32_e32 v22, v22
	v_and_b32_e32 v18, 0xffff0000, v74
	v_mul_f32_e32 v13, v13, v17
	v_add_f32_e32 v17, 1.0, v20
	v_add_f32_e32 v20, 1.0, v22
	v_rcp_f32_e32 v20, v20
	v_rcp_f32_e32 v17, v17
	v_and_b32_e32 v21, 0xffff0000, v75
	v_lshlrev_b32_e32 v19, 16, v75
	v_mul_f32_e32 v15, v15, v20
	v_mul_f32_e32 v13, v13, v18
	v_mul_f32_e32 v14, v14, v17
	v_mul_f32_e32 v15, v15, v21
	v_mul_f32_e32 v8, v8, v16
	v_mul_f32_e32 v14, v14, v19
	v_cvt_pk_bf16_f32 v12, v12, v13
	v_cvt_pk_bf16_f32 v13, v14, v15
	v_mul_f32_e32 v15, 0xbfb8aa3b, v8
	v_exp_f32_e32 v15, v15
	v_mul_f32_e32 v9, v9, v16
	v_mul_f32_e32 v18, 0xbfb8aa3b, v9
	v_exp_f32_e32 v18, v18
	v_add_f32_e32 v15, 1.0, v15
	v_rcp_f32_e32 v15, v15
	global_store_dwordx2 v[64:65], v[12:13], off
	s_waitcnt vmcnt(15)
	v_lshlrev_b32_e32 v12, 16, v70
	v_mul_f32_e32 v10, v10, v16
	v_mul_f32_e32 v11, v11, v16
	v_mul_f32_e32 v8, v8, v15
	v_mul_f32_e32 v8, v8, v12
	v_add_f32_e32 v12, 1.0, v18
	v_mul_f32_e32 v15, 0xbfb8aa3b, v10
	v_mul_f32_e32 v18, 0xbfb8aa3b, v11
	v_rcp_f32_e32 v12, v12
	v_exp_f32_e32 v15, v15
	v_exp_f32_e32 v18, v18
	v_and_b32_e32 v13, 0xffff0000, v70
	v_mul_f32_e32 v9, v9, v12
	v_add_f32_e32 v12, 1.0, v15
	v_add_f32_e32 v15, 1.0, v18
	v_rcp_f32_e32 v15, v15
	v_rcp_f32_e32 v12, v12
	v_and_b32_e32 v17, 0xffff0000, v71
	v_lshlrev_b32_e32 v14, 16, v71
	v_mul_f32_e32 v11, v11, v15
	v_mul_f32_e32 v9, v9, v13
	v_mul_f32_e32 v10, v10, v12
	v_mul_f32_e32 v11, v11, v17
	v_mul_f32_e32 v4, v4, v16
	v_mul_f32_e32 v10, v10, v14
	v_cvt_pk_bf16_f32 v8, v8, v9
	v_cvt_pk_bf16_f32 v9, v10, v11
	v_mul_f32_e32 v11, 0xbfb8aa3b, v4
	v_exp_f32_e32 v11, v11
	v_mul_f32_e32 v5, v5, v16
	v_mul_f32_e32 v13, 0xbfb8aa3b, v5
	v_exp_f32_e32 v13, v13
	v_add_f32_e32 v11, 1.0, v11
	v_rcp_f32_e32 v11, v11
	global_store_dwordx2 v[64:65], v[8:9], off offset:32
	s_waitcnt vmcnt(15)
	v_lshlrev_b32_e32 v8, 16, v68
	v_mul_f32_e32 v6, v6, v16
	v_mul_f32_e32 v7, v7, v16
	v_mul_f32_e32 v4, v4, v11
	v_mul_f32_e32 v4, v4, v8
	v_add_f32_e32 v8, 1.0, v13
	v_mul_f32_e32 v11, 0xbfb8aa3b, v6
	v_mul_f32_e32 v13, 0xbfb8aa3b, v7
	v_rcp_f32_e32 v8, v8
	v_exp_f32_e32 v11, v11
	v_exp_f32_e32 v13, v13
	v_and_b32_e32 v9, 0xffff0000, v68
	v_mul_f32_e32 v5, v5, v8
	v_add_f32_e32 v8, 1.0, v11
	v_add_f32_e32 v11, 1.0, v13
	v_rcp_f32_e32 v11, v11
	v_rcp_f32_e32 v8, v8
	v_and_b32_e32 v12, 0xffff0000, v69
	v_lshlrev_b32_e32 v10, 16, v69
	v_mul_f32_e32 v7, v7, v11
	v_mul_f32_e32 v5, v5, v9
	v_mul_f32_e32 v6, v6, v8
	v_mul_f32_e32 v7, v7, v12
	v_mul_f32_e32 v0, v0, v16
	v_mul_f32_e32 v6, v6, v10
	v_cvt_pk_bf16_f32 v4, v4, v5
	v_cvt_pk_bf16_f32 v5, v6, v7
	v_mul_f32_e32 v7, 0xbfb8aa3b, v0
	v_exp_f32_e32 v7, v7
	v_mul_f32_e32 v1, v1, v16
	v_mul_f32_e32 v9, 0xbfb8aa3b, v1
	v_exp_f32_e32 v9, v9
	v_add_f32_e32 v7, 1.0, v7
	v_rcp_f32_e32 v7, v7
	global_store_dwordx2 v[64:65], v[4:5], off offset:64
	s_waitcnt vmcnt(15)
	v_lshlrev_b32_e32 v4, 16, v66
	v_mul_f32_e32 v2, v2, v16
	v_mul_f32_e32 v3, v3, v16
	v_mul_f32_e32 v0, v0, v7
	v_mul_f32_e32 v0, v0, v4
	v_add_f32_e32 v4, 1.0, v9
	v_mul_f32_e32 v7, 0xbfb8aa3b, v2
	v_mul_f32_e32 v9, 0xbfb8aa3b, v3
	v_rcp_f32_e32 v4, v4
	v_exp_f32_e32 v7, v7
	v_exp_f32_e32 v9, v9
	v_and_b32_e32 v5, 0xffff0000, v66
	v_mul_f32_e32 v1, v1, v4
	v_add_f32_e32 v4, 1.0, v7
	v_add_f32_e32 v7, 1.0, v9
	v_rcp_f32_e32 v4, v4
	v_rcp_f32_e32 v7, v7
	v_lshlrev_b32_e32 v6, 16, v67
	v_and_b32_e32 v8, 0xffff0000, v67
	v_mul_f32_e32 v1, v1, v5
	v_mul_f32_e32 v2, v2, v4
	v_mul_f32_e32 v3, v3, v7
	v_mul_f32_e32 v2, v2, v6
	v_mul_f32_e32 v3, v3, v8
	v_cvt_pk_bf16_f32 v0, v0, v1
	v_cvt_pk_bf16_f32 v1, v2, v3
	global_store_dwordx2 v[64:65], v[0:1], off offset:96
	s_add_i32 s23, s23, s74
	s_cmpk_lt_i32 s23, 0x800
	s_cbranch_scc1 .LBB0_1736

.LBB0_1795:
	s_add_i32 s26, s21, 64
	s_min_u32 s18, s26, 0x7e0
	s_lshl_b32 s18, s18, 1
	v_lshl_add_u64 v[174:175], v[156:157], 0, s[18:19]
	global_load_dwordx4 v[178:181], v[174:175], off
	v_lshl_add_u64 v[174:175], v[158:159], 0, s[18:19]
	v_lshl_add_u64 v[170:171], v[152:153], 0, s[18:19]
	v_lshl_add_u64 v[186:187], v[160:161], 0, s[18:19]
	global_load_dwordx4 v[182:185], v[174:175], off
	v_lshl_add_u64 v[174:175], v[154:155], 0, s[18:19]
	v_lshl_add_u64 v[194:195], v[162:163], 0, s[18:19]
	global_load_dwordx4 v[170:173], v[170:171], off
	ds_read_b128 v[200:203], v168 offset:32768
	global_load_dwordx4 v[186:189], v[186:187], off
	ds_read_b128 v[204:207], v168 offset:33792
	global_load_dwordx4 v[190:193], v[174:175], off
	ds_read_b128 v[208:211], v168 offset:34816
	global_load_dwordx4 v[194:197], v[194:195], off
	ds_read_b128 v[212:215], v168 offset:35840
	ds_read_b128 v[216:219], v166
	ds_read_b128 v[222:225], v166 offset:1024
	ds_read_b128 v[226:229], v166 offset:2048
	ds_read_b128 v[230:233], v166 offset:3072
	ds_read_b128 v[234:237], v166 offset:4096
	ds_read_b128 v[238:241], v166 offset:5120
	ds_read_b128 v[242:245], v166 offset:6144
	ds_read_b128 v[246:249], v166 offset:7168
	s_waitcnt lgkmcnt(7)
	v_mfma_f32_16x16x32_bf16 v[148:151], v[200:203], v[216:219], v[148:151]
	v_mfma_f32_16x16x32_bf16 v[144:147], v[204:207], v[216:219], v[144:147]
	v_mfma_f32_16x16x32_bf16 v[140:143], v[208:211], v[216:219], v[140:143]
	v_mfma_f32_16x16x32_bf16 v[116:119], v[212:215], v[216:219], v[116:119]
	s_waitcnt vmcnt(11)
	ds_write_b128 v164, v[112:115] offset:16384
	s_waitcnt lgkmcnt(7)
	v_mfma_f32_16x16x32_bf16 v[108:111], v[200:203], v[222:225], v[108:111]
	v_mfma_f32_16x16x32_bf16 v[104:107], v[204:207], v[222:225], v[104:107]
	v_mfma_f32_16x16x32_bf16 v[100:103], v[208:211], v[222:225], v[100:103]
	v_mfma_f32_16x16x32_bf16 v[96:99], v[212:215], v[222:225], v[96:99]
	s_waitcnt vmcnt(9)
	ds_write_b128 v164, v[120:123] offset:20480
	s_waitcnt lgkmcnt(7)
	v_mfma_f32_16x16x32_bf16 v[92:95], v[200:203], v[226:229], v[92:95]
	v_mfma_f32_16x16x32_bf16 v[88:91], v[204:207], v[226:229], v[88:91]
	v_mfma_f32_16x16x32_bf16 v[84:87], v[208:211], v[226:229], v[84:87]
	v_mfma_f32_16x16x32_bf16 v[80:83], v[212:215], v[226:229], v[80:83]
	s_waitcnt vmcnt(8)
	ds_write_b128 v164, v[124:127] offset:24576
	s_waitcnt lgkmcnt(7)
	v_mfma_f32_16x16x32_bf16 v[76:79], v[200:203], v[230:233], v[76:79]
	v_mfma_f32_16x16x32_bf16 v[72:75], v[204:207], v[230:233], v[72:75]
	v_mfma_f32_16x16x32_bf16 v[68:71], v[208:211], v[230:233], v[68:71]
	v_mfma_f32_16x16x32_bf16 v[64:67], v[212:215], v[230:233], v[64:67]
	s_waitcnt vmcnt(7)
	ds_write_b128 v164, v[132:135] offset:28672
	s_waitcnt lgkmcnt(7)
	v_mfma_f32_16x16x32_bf16 v[60:63], v[200:203], v[234:237], v[60:63]
	v_mfma_f32_16x16x32_bf16 v[56:59], v[204:207], v[234:237], v[56:59]
	v_mfma_f32_16x16x32_bf16 v[52:55], v[208:211], v[234:237], v[52:55]
	v_mfma_f32_16x16x32_bf16 v[48:51], v[212:215], v[234:237], v[48:51]
	s_waitcnt vmcnt(6)
	ds_write_b128 v164, v[136:139] offset:45056
	s_waitcnt lgkmcnt(7)
	v_mfma_f32_16x16x32_bf16 v[44:47], v[200:203], v[238:241], v[44:47]
	v_mfma_f32_16x16x32_bf16 v[40:43], v[204:207], v[238:241], v[40:43]
	v_mfma_f32_16x16x32_bf16 v[36:39], v[208:211], v[238:241], v[36:39]
	v_mfma_f32_16x16x32_bf16 v[32:35], v[212:215], v[238:241], v[32:35]
	ds_write_b128 v164, v[128:131] offset:40960
	s_waitcnt lgkmcnt(7)
	v_mfma_f32_16x16x32_bf16 v[28:31], v[200:203], v[242:245], v[28:31]
	v_mfma_f32_16x16x32_bf16 v[24:27], v[204:207], v[242:245], v[24:27]
	v_mfma_f32_16x16x32_bf16 v[20:23], v[208:211], v[242:245], v[20:23]
	v_mfma_f32_16x16x32_bf16 v[16:19], v[212:215], v[242:245], v[16:19]
	s_waitcnt lgkmcnt(6)
	v_mfma_f32_16x16x32_bf16 v[12:15], v[200:203], v[246:249], v[12:15]
	v_mfma_f32_16x16x32_bf16 v[8:11], v[204:207], v[246:249], v[8:11]
	v_mfma_f32_16x16x32_bf16 v[4:7], v[208:211], v[246:249], v[4:7]
	v_mfma_f32_16x16x32_bf16 v[0:3], v[212:215], v[246:249], v[0:3]
	s_min_u32 s18, s21, 0x780
	s_lshl_b32 s18, s18, 1
	s_mov_b32 s29, s19
	s_add_i32 s28, s18, 0xc0
	v_lshl_add_u64 v[112:113], v[152:153], 0, s[18:19]
	v_lshl_add_u64 v[120:121], v[154:155], 0, s[18:19]
	v_lshl_add_u64 v[122:123], v[156:157], 0, s[28:29]
	v_lshl_add_u64 v[124:125], v[158:159], 0, s[28:29]
	v_lshl_add_u64 v[132:133], v[160:161], 0, s[28:29]
	v_lshl_add_u64 v[136:137], v[162:163], 0, s[28:29]
	s_waitcnt lgkmcnt(0)
	s_barrier
	global_load_dwordx4 v[112:115], v[112:113], off offset:192
	ds_read_b128 v[200:203], v165 offset:40960
	global_load_dwordx4 v[128:131], v[120:121], off offset:192
	ds_read_b128 v[204:207], v165 offset:41984
	global_load_dwordx4 v[120:123], v[122:123], off
	ds_read_b128 v[208:211], v165 offset:43008
	global_load_dwordx4 v[124:127], v[124:125], off
	ds_read_b128 v[212:215], v165 offset:44032
	global_load_dwordx4 v[132:135], v[132:133], off
	ds_read_b128 v[216:219], v167
	global_load_dwordx4 v[136:139], v[136:137], off
	ds_read_b128 v[222:225], v167 offset:1024
	ds_read_b128 v[226:229], v167 offset:2048
	ds_read_b128 v[230:233], v167 offset:3072
	ds_read_b128 v[234:237], v167 offset:4096
	ds_read_b128 v[238:241], v167 offset:5120
	ds_read_b128 v[242:245], v167 offset:6144
	ds_read_b128 v[246:249], v167 offset:7168
	s_waitcnt lgkmcnt(7)
	v_mfma_f32_16x16x32_bf16 v[148:151], v[200:203], v[216:219], v[148:151]
	v_mfma_f32_16x16x32_bf16 v[144:147], v[204:207], v[216:219], v[144:147]
	v_mfma_f32_16x16x32_bf16 v[140:143], v[208:211], v[216:219], v[140:143]
	v_mfma_f32_16x16x32_bf16 v[116:119], v[212:215], v[216:219], v[116:119]
	s_waitcnt vmcnt(9)
	ds_write_b128 v164, v[170:173]
	s_waitcnt lgkmcnt(7)
	v_mfma_f32_16x16x32_bf16 v[108:111], v[200:203], v[222:225], v[108:111]
	v_mfma_f32_16x16x32_bf16 v[104:107], v[204:207], v[222:225], v[104:107]
	v_mfma_f32_16x16x32_bf16 v[100:103], v[208:211], v[222:225], v[100:103]
	v_mfma_f32_16x16x32_bf16 v[96:99], v[212:215], v[222:225], v[96:99]
	ds_write_b128 v164, v[178:181] offset:4096
	s_waitcnt lgkmcnt(7)
	v_mfma_f32_16x16x32_bf16 v[92:95], v[200:203], v[226:229], v[92:95]
	v_mfma_f32_16x16x32_bf16 v[88:91], v[204:207], v[226:229], v[88:91]
	v_mfma_f32_16x16x32_bf16 v[84:87], v[208:211], v[226:229], v[84:87]
	v_mfma_f32_16x16x32_bf16 v[80:83], v[212:215], v[226:229], v[80:83]
	ds_write_b128 v164, v[182:185] offset:8192
	s_waitcnt lgkmcnt(7)
	v_mfma_f32_16x16x32_bf16 v[76:79], v[200:203], v[230:233], v[76:79]
	v_mfma_f32_16x16x32_bf16 v[72:75], v[204:207], v[230:233], v[72:75]
	v_mfma_f32_16x16x32_bf16 v[68:71], v[208:211], v[230:233], v[68:71]
	v_mfma_f32_16x16x32_bf16 v[64:67], v[212:215], v[230:233], v[64:67]
	s_waitcnt vmcnt(8)
	ds_write_b128 v164, v[186:189] offset:12288
	s_waitcnt lgkmcnt(7)
	v_mfma_f32_16x16x32_bf16 v[60:63], v[200:203], v[234:237], v[60:63]
	v_mfma_f32_16x16x32_bf16 v[56:59], v[204:207], v[234:237], v[56:59]
	v_mfma_f32_16x16x32_bf16 v[52:55], v[208:211], v[234:237], v[52:55]
	v_mfma_f32_16x16x32_bf16 v[48:51], v[212:215], v[234:237], v[48:51]
	s_waitcnt vmcnt(7)
	ds_write_b128 v164, v[190:193] offset:32768
	s_waitcnt lgkmcnt(7)
	v_mfma_f32_16x16x32_bf16 v[44:47], v[200:203], v[238:241], v[44:47]
	v_mfma_f32_16x16x32_bf16 v[40:43], v[204:207], v[238:241], v[40:43]
	v_mfma_f32_16x16x32_bf16 v[36:39], v[208:211], v[238:241], v[36:39]
	v_mfma_f32_16x16x32_bf16 v[32:35], v[212:215], v[238:241], v[32:35]
	s_waitcnt vmcnt(6)
	ds_write_b128 v164, v[194:197] offset:36864
	s_waitcnt lgkmcnt(7)
	v_mfma_f32_16x16x32_bf16 v[28:31], v[200:203], v[242:245], v[28:31]
	v_mfma_f32_16x16x32_bf16 v[24:27], v[204:207], v[242:245], v[24:27]
	v_mfma_f32_16x16x32_bf16 v[20:23], v[208:211], v[242:245], v[20:23]
	v_mfma_f32_16x16x32_bf16 v[16:19], v[212:215], v[242:245], v[16:19]
	s_waitcnt lgkmcnt(6)
	v_mfma_f32_16x16x32_bf16 v[12:15], v[200:203], v[246:249], v[12:15]
	v_mfma_f32_16x16x32_bf16 v[8:11], v[204:207], v[246:249], v[8:11]
	v_mfma_f32_16x16x32_bf16 v[4:7], v[208:211], v[246:249], v[4:7]
	v_mfma_f32_16x16x32_bf16 v[0:3], v[212:215], v[246:249], v[0:3]
	s_add_i32 s1, s1, 2
	s_cmp_lt_u32 s1, 62
	s_mov_b32 s21, s26
	s_waitcnt lgkmcnt(0)
	s_barrier
	s_cbranch_scc1 .LBB0_1795
	s_waitcnt vmcnt(5)
	v_mov_b32_e32 v112, v220
	s_nop 0
	v_and_b32_e32 v114, 0xffffff80, v112
	v_bfe_u32 v176, v112, 4, 2
	v_add_u32_e32 v114, s20, v114
	v_and_b32_e32 v113, 64, v112
	v_and_or_b32 v184, v112, 15, v114
	v_lshlrev_b32_e32 v112, 2, v176
	v_or3_b32 v178, v112, v113, s0
	v_ashrrev_i32_e32 v179, 31, v178
	v_lshlrev_b64 v[216:217], 2, v[178:179]
	v_ashrrev_i32_e32 v185, 31, v184
	v_or_b32_e32 v194, 16, v184
	v_lshl_add_u64 v[182:183], s[70:71], 0, v[216:217]
	v_lshlrev_b64 v[218:219], 12, v[184:185]
	v_ashrrev_i32_e32 v195, 31, v194
	v_or_b32_e32 v190, 32, v184
	v_lshl_add_u64 v[112:113], v[182:183], 0, v[218:219]
	v_lshlrev_b64 v[196:197], 12, v[194:195]
	v_ashrrev_i32_e32 v191, 31, v190
	v_or_b32_e32 v186, 48, v184
	global_load_dwordx4 v[200:203], v[112:113], off
	global_load_dwordx4 v[204:207], v[112:113], off offset:64
	global_load_dwordx4 v[208:211], v[112:113], off offset:128
	global_load_dwordx4 v[212:215], v[112:113], off offset:192
	v_lshl_add_u64 v[112:113], v[182:183], 0, v[196:197]
	v_lshlrev_b64 v[192:193], 12, v[190:191]
	v_ashrrev_i32_e32 v187, 31, v186
	global_load_dwordx4 v[172:175], v[112:113], off
	global_load_dwordx4 v[168:171], v[112:113], off offset:64
	global_load_dwordx4 v[164:167], v[112:113], off offset:128
	global_load_dwordx4 v[160:163], v[112:113], off offset:192
	v_lshl_add_u64 v[112:113], v[182:183], 0, v[192:193]
	v_lshlrev_b64 v[188:189], 12, v[186:187]
	global_load_dwordx4 v[156:159], v[112:113], off
	global_load_dwordx4 v[152:155], v[112:113], off offset:64
	global_load_dwordx4 v[136:139], v[112:113], off offset:128
	global_load_dwordx4 v[132:135], v[112:113], off offset:192
	v_lshl_add_u64 v[112:113], v[182:183], 0, v[188:189]
	global_load_dwordx4 v[128:131], v[112:113], off
	global_load_dwordx4 v[124:127], v[112:113], off offset:64
	global_load_dwordx4 v[120:123], v[112:113], off offset:128
	s_nop 0
	global_load_dwordx4 v[112:115], v[112:113], off offset:192
	v_cmp_eq_u32_e32 vcc, 0, v176
	v_lshlrev_b64 v[222:223], 11, v[184:185]
	v_lshlrev_b64 v[180:181], 1, v[178:179]
	v_lshl_add_u64 v[218:219], s[70:71], 0, v[218:219]
	v_lshl_add_u64 v[224:225], s[8:9], 0, v[222:223]
	v_lshl_add_u64 v[216:217], v[218:219], 0, v[216:217]
	v_lshl_add_u64 v[218:219], v[224:225], 0, v[180:181]
	v_lshl_add_u64 v[222:223], s[72:73], 0, v[222:223]
	v_lshl_add_u64 v[222:223], v[222:223], 0, v[180:181]
	s_waitcnt vmcnt(15)
	v_pk_add_f32 v[148:149], v[148:149], v[200:201]
	s_waitcnt vmcnt(14)
	v_pk_add_f32 v[144:145], v[144:145], v[204:205]
	v_pk_add_f32 v[146:147], v[146:147], v[206:207]
	s_waitcnt vmcnt(13)
	v_pk_add_f32 v[140:141], v[140:141], v[208:209]
	v_mul_f32_e32 v176, v149, v149
	v_mul_f32_e32 v206, v145, v145
	v_pk_add_f32 v[150:151], v[150:151], v[202:203]
	s_waitcnt vmcnt(12)
	v_pk_add_f32 v[116:117], v[116:117], v[212:213]
	v_mul_f32_e32 v212, v141, v141
	v_pk_fma_f32 v[226:227], v[148:149], v[148:149], v[176:177] op_sel_hi:[1,1,0]
	v_pk_fma_f32 v[206:207], v[144:145], v[144:145], v[206:207] op_sel_hi:[1,1,0]
	v_pk_add_f32 v[142:143], v[142:143], v[210:211]
	v_mul_f32_e32 v202, v151, v151
	v_mul_f32_e32 v208, v147, v147
	v_pk_fma_f32 v[212:213], v[140:141], v[140:141], v[212:213] op_sel_hi:[1,1,0]
	v_pk_fma_f32 v[226:227], v[150:151], v[150:151], v[226:227]
	v_pk_fma_f32 v[206:207], v[146:147], v[146:147], v[206:207]
	v_mul_f32_e32 v224, v143, v143
	v_pk_fma_f32 v[212:213], v[142:143], v[142:143], v[212:213]
	v_pk_add_f32 v[202:203], v[202:203], v[226:227] op_sel_hi:[0,1]
	v_pk_add_f32 v[206:207], v[208:209], v[206:207] op_sel_hi:[0,1]
	v_pk_add_f32 v[208:209], v[224:225], v[212:213] op_sel_hi:[0,1]
	v_pk_add_f32 v[202:203], v[202:203], v[206:207]
	v_cvt_pk_bf16_f32 v200, v148, v149
	v_cvt_pk_bf16_f32 v201, v150, v151
	v_cvt_pk_bf16_f32 v204, v144, v145
	v_cvt_pk_bf16_f32 v205, v146, v147
	v_cvt_pk_bf16_f32 v210, v140, v141
	v_cvt_pk_bf16_f32 v211, v142, v143
	s_nop 0
	v_pk_add_f32 v[202:203], v[202:203], v[208:209]
	v_pk_add_f32 v[118:119], v[118:119], v[214:215]
	global_store_dwordx4 v[216:217], v[148:151], off
	global_store_dwordx2 v[218:219], v[200:201], off
	global_store_dwordx4 v[216:217], v[144:147], off offset:64
	s_nop 1
	v_add_co_u32_e64 v144, s[0:1], s24, v222
	s_nop 1
	v_addc_co_u32_e64 v145, s[0:1], 0, v223, s[0:1]
	global_store_dwordx2 v[144:145], v[204:205], off offset:32
	global_store_dwordx4 v[216:217], v[140:143], off offset:128
	global_store_dwordx2 v[144:145], v[210:211], off offset:64
	global_store_dwordx4 v[216:217], v[116:119], off offset:192
	v_cvt_pk_bf16_f32 v140, v116, v117
	v_cvt_pk_bf16_f32 v141, v118, v119
	global_store_dwordx2 v[144:145], v[140:141], off offset:96
	v_mul_f32_e32 v140, v117, v117
	v_pk_fma_f32 v[116:117], v[116:117], v[116:117], v[140:141] op_sel_hi:[1,1,0]
	s_nop 0
	v_pk_fma_f32 v[116:117], v[118:119], v[118:119], v[116:117]
	v_mul_f32_e32 v118, v119, v119
	v_pk_add_f32 v[116:117], v[118:119], v[116:117] op_sel_hi:[0,1]
	v_pk_add_f32 v[116:117], v[202:203], v[116:117]
	s_nop 0
	v_mov_b32_e32 v117, v116
	s_nop 1
	v_permlane32_swap_b32_e32 v116, v117
	v_add_f32_e32 v116, v116, v117
	v_mov_b32_e32 v117, v116
	s_nop 1
	v_permlane16_swap_b32_e32 v116, v117
	s_and_saveexec_b64 s[0:1], vcc
	s_cbranch_execz .LBB0_1798
	v_lshl_add_u64 v[118:119], v[184:185], 2, s[10:11]
	v_add_f32_e32 v116, v116, v117
	global_atomic_add_f32 v[118:119], v116, off

.LBB0_1867:
	s_min_u32 s24, s22, 0xe0
	s_lshl_b32 s6, s24, 2
	v_lshl_add_u64 v[94:95], v[70:71], 0, s[6:7]
	v_lshl_add_u64 v[96:97], v[72:73], 0, s[6:7]
	s_lshl_b32 s6, s24, 1
	v_lshl_add_u64 v[102:103], v[66:67], 0, s[6:7]
	v_lshl_add_u64 v[104:105], v[68:69], 0, s[6:7]
	global_load_dwordx4 v[78:81], v[94:95], off offset:16 nt
	global_load_dwordx4 v[82:85], v[94:95], off nt
	global_load_dwordx4 v[86:89], v[96:97], off offset:16 nt
	global_load_dwordx4 v[90:93], v[96:97], off nt
	global_load_dwordx4 v[98:101], v[104:105], off
	s_and_b32 s6, s23, 0x80
	global_load_dwordx4 v[94:97], v[102:103], off
	v_add_u32_e32 v77, s6, v74
	v_or_b32_e32 v102, s6, v76
	v_lshl_or_b32 v77, v77, 6, v75
	v_lshl_or_b32 v130, v102, 6, v75
	ds_read_b128 v[102:105], v77
	ds_read_b128 v[106:109], v77 offset:1024
	ds_read_b128 v[110:113], v130 offset:16384
	ds_read_b128 v[114:117], v130 offset:17408
	ds_read_b128 v[118:121], v77 offset:2048
	ds_read_b128 v[122:125], v77 offset:3072
	ds_read_b128 v[126:129], v130 offset:18432
	ds_read_b128 v[130:133], v130 offset:19456
	s_waitcnt lgkmcnt(5)
	v_mfma_f32_16x16x32_bf16 v[52:55], v[110:113], v[102:105], v[52:55]
	s_waitcnt lgkmcnt(4)
	v_mfma_f32_16x16x32_bf16 v[48:51], v[114:117], v[102:105], v[48:51]
	s_waitcnt lgkmcnt(1)
	v_mfma_f32_16x16x32_bf16 v[40:43], v[126:129], v[102:105], v[40:43]
	s_waitcnt lgkmcnt(0)
	v_mfma_f32_16x16x32_bf16 v[20:23], v[130:133], v[102:105], v[20:23]
	v_mfma_f32_16x16x32_bf16 v[44:47], v[110:113], v[106:109], v[44:47]
	v_mfma_f32_16x16x32_bf16 v[36:39], v[114:117], v[106:109], v[36:39]
	v_mfma_f32_16x16x32_bf16 v[28:31], v[126:129], v[106:109], v[28:31]
	v_mfma_f32_16x16x32_bf16 v[16:19], v[130:133], v[106:109], v[16:19]
	v_mfma_f32_16x16x32_bf16 v[32:35], v[110:113], v[118:121], v[32:35]
	v_mfma_f32_16x16x32_bf16 v[24:27], v[114:117], v[118:121], v[24:27]
	v_mfma_f32_16x16x32_bf16 v[12:15], v[126:129], v[118:121], v[12:15]
	v_mfma_f32_16x16x32_bf16 v[8:11], v[130:133], v[118:121], v[8:11]
	v_mfma_f32_16x16x32_bf16 v[60:63], v[110:113], v[122:125], v[60:63]
	v_mfma_f32_16x16x32_bf16 v[56:59], v[114:117], v[122:125], v[56:59]
	v_mfma_f32_16x16x32_bf16 v[4:7], v[126:129], v[122:125], v[4:7]
	v_mfma_f32_16x16x32_bf16 v[0:3], v[130:133], v[122:125], v[0:3]
	s_waitcnt vmcnt(4)
	v_and_b32_sdwa v102, v84, v155 dst_sel:DWORD dst_unused:UNUSED_PAD src0_sel:WORD_1 src1_sel:DWORD
	v_and_b32_sdwa v103, v82, v155 dst_sel:DWORD dst_unused:UNUSED_PAD src0_sel:WORD_1 src1_sel:DWORD
	v_add3_u32 v84, v84, v102, s17
	v_and_b32_sdwa v102, v85, v155 dst_sel:DWORD dst_unused:UNUSED_PAD src0_sel:WORD_1 src1_sel:DWORD
	v_add3_u32 v82, v82, v103, s17
	v_and_b32_sdwa v103, v83, v155 dst_sel:DWORD dst_unused:UNUSED_PAD src0_sel:WORD_1 src1_sel:DWORD
	v_add3_u32 v85, v85, v102, s17
	v_add3_u32 v83, v83, v103, s17
	v_and_b32_e32 v85, 0xffff0000, v85
	v_and_b32_e32 v102, 0xffff0000, v83
	v_or_b32_sdwa v83, v85, v84 dst_sel:DWORD dst_unused:UNUSED_PAD src0_sel:DWORD src1_sel:WORD_1
	v_and_b32_sdwa v85, v78, v155 dst_sel:DWORD dst_unused:UNUSED_PAD src0_sel:WORD_1 src1_sel:DWORD
	v_and_b32_sdwa v84, v80, v155 dst_sel:DWORD dst_unused:UNUSED_PAD src0_sel:WORD_1 src1_sel:DWORD
	v_add3_u32 v78, v78, v85, s17
	v_and_b32_sdwa v85, v79, v155 dst_sel:DWORD dst_unused:UNUSED_PAD src0_sel:WORD_1 src1_sel:DWORD
	v_add3_u32 v80, v80, v84, s17
	v_and_b32_sdwa v84, v81, v155 dst_sel:DWORD dst_unused:UNUSED_PAD src0_sel:WORD_1 src1_sel:DWORD
	v_add3_u32 v79, v79, v85, s17
	v_add3_u32 v81, v81, v84, s17
	v_and_b32_e32 v79, 0xffff0000, v79
	v_and_b32_e32 v81, 0xffff0000, v81
	v_or_b32_sdwa v84, v79, v78 dst_sel:DWORD dst_unused:UNUSED_PAD src0_sel:DWORD src1_sel:WORD_1
	s_waitcnt vmcnt(2)
	v_and_b32_sdwa v79, v90, v155 dst_sel:DWORD dst_unused:UNUSED_PAD src0_sel:WORD_1 src1_sel:DWORD
	v_or_b32_sdwa v85, v81, v80 dst_sel:DWORD dst_unused:UNUSED_PAD src0_sel:DWORD src1_sel:WORD_1
	v_add3_u32 v80, v90, v79, s17
	v_and_b32_sdwa v79, v93, v155 dst_sel:DWORD dst_unused:UNUSED_PAD src0_sel:WORD_1 src1_sel:DWORD
	v_and_b32_sdwa v81, v91, v155 dst_sel:DWORD dst_unused:UNUSED_PAD src0_sel:WORD_1 src1_sel:DWORD
	s_xor_b32 s6, s6, 0x80
	v_and_b32_sdwa v78, v92, v155 dst_sel:DWORD dst_unused:UNUSED_PAD src0_sel:WORD_1 src1_sel:DWORD
	v_add3_u32 v79, v93, v79, s17
	v_add3_u32 v81, v91, v81, s17
	v_add_u32_e32 v77, s6, v64
	v_add3_u32 v78, v92, v78, s17
	v_and_b32_e32 v79, 0xffff0000, v79
	v_and_b32_e32 v81, 0xffff0000, v81
	v_lshl_or_b32 v77, v77, 6, v65
	v_or_b32_sdwa v82, v102, v82 dst_sel:DWORD dst_unused:UNUSED_PAD src0_sel:DWORD src1_sel:WORD_1
	v_or_b32_sdwa v79, v79, v78 dst_sel:DWORD dst_unused:UNUSED_PAD src0_sel:DWORD src1_sel:WORD_1
	v_or_b32_sdwa v78, v81, v80 dst_sel:DWORD dst_unused:UNUSED_PAD src0_sel:DWORD src1_sel:WORD_1
	v_and_b32_sdwa v81, v86, v155 dst_sel:DWORD dst_unused:UNUSED_PAD src0_sel:WORD_1 src1_sel:DWORD
	ds_write_b128 v77, v[82:85]
	v_add3_u32 v82, v86, v81, s17
	v_and_b32_sdwa v81, v89, v155 dst_sel:DWORD dst_unused:UNUSED_PAD src0_sel:WORD_1 src1_sel:DWORD
	v_and_b32_sdwa v83, v87, v155 dst_sel:DWORD dst_unused:UNUSED_PAD src0_sel:WORD_1 src1_sel:DWORD
	v_and_b32_sdwa v80, v88, v155 dst_sel:DWORD dst_unused:UNUSED_PAD src0_sel:WORD_1 src1_sel:DWORD
	v_add3_u32 v81, v89, v81, s17
	v_add3_u32 v83, v87, v83, s17
	v_add3_u32 v80, v88, v80, s17
	v_and_b32_e32 v81, 0xffff0000, v81
	v_and_b32_e32 v83, 0xffff0000, v83
	s_addk_i32 s23, 0x80
	s_add_i32 s22, s22, 32
	v_or_b32_sdwa v81, v81, v80 dst_sel:DWORD dst_unused:UNUSED_PAD src0_sel:DWORD src1_sel:WORD_1
	v_or_b32_sdwa v80, v83, v82 dst_sel:DWORD dst_unused:UNUSED_PAD src0_sel:DWORD src1_sel:WORD_1
	s_cmpk_lg_i32 s23, 0x400
	ds_write_b128 v77, v[78:81] offset:4096
	s_waitcnt vmcnt(0)
	ds_write_b128 v77, v[94:97] offset:16384
	ds_write_b128 v77, v[98:101] offset:20480
	s_waitcnt lgkmcnt(0)
	s_barrier
	s_cbranch_scc1 .LBB0_1867
	s_lshl_b64 s[22:23], s[10:11], 11
	v_mov_b32_e32 v106, v220
	s_add_u32 s22, s13, s22
	s_addc_u32 s23, s14, s23
	v_ashrrev_i32_e32 v102, 2, v106
	s_lshl_b64 s[24:25], s[8:9], 11
	v_add_u32_e32 v104, 64, v102
	s_add_u32 s24, s15, s24
	v_ashrrev_i32_e32 v105, 31, v104
	s_addc_u32 s25, s16, s25
	v_lshlrev_b64 v[64:65], 11, v[104:105]
	v_min_i32_e32 v66, 0x7f, v102
	v_lshlrev_b32_e32 v67, 4, v106
	v_lshl_add_u64 v[64:65], s[24:25], 0, v[64:65]
	v_and_b32_e32 v144, 48, v67
	v_ashrrev_i32_e32 v67, 31, v66
	v_ashrrev_i32_e32 v103, 31, v102
	v_min_i32_e32 v68, 0x7f, v104
	v_lshl_add_u64 v[148:149], v[64:65], 0, v[144:145]
	v_lshlrev_b64 v[64:65], 11, v[66:67]
	v_lshlrev_b64 v[70:71], 11, v[102:103]
	v_lshl_add_u64 v[64:65], s[22:23], 0, v[64:65]
	v_ashrrev_i32_e32 v69, 31, v68
	v_lshl_add_u64 v[70:71], s[24:25], 0, v[70:71]
	v_lshl_add_u64 v[150:151], v[64:65], 0, v[144:145]
	v_lshlrev_b64 v[64:65], 11, v[68:69]
	v_lshl_add_u64 v[146:147], v[70:71], 0, v[144:145]
	v_lshl_add_u64 v[64:65], s[22:23], 0, v[64:65]
	global_load_dwordx4 v[86:89], v[150:151], off
	global_load_dwordx4 v[90:93], v[146:147], off
	v_lshl_add_u64 v[152:153], v[64:65], 0, v[144:145]
	global_load_dwordx4 v[94:97], v[148:149], off
	global_load_dwordx4 v[98:101], v[152:153], off
	global_load_dwordx4 v[124:127], v[146:147], off offset:64
	global_load_dwordx4 v[128:131], v[150:151], off offset:64
	global_load_dwordx4 v[132:135], v[148:149], off offset:64
	global_load_dwordx4 v[136:139], v[152:153], off offset:64
	v_lshrrev_b32_e32 v103, 4, v106
	v_lshrrev_b32_e32 v105, 2, v106
	v_sub_u32_e32 v110, 0, v103
	v_and_b32_e32 v107, 15, v106
	v_lshrrev_b32_e32 v108, 1, v106
	v_lshlrev_b32_e32 v109, 6, v106
	v_sub_u32_e32 v105, 0, v105
	v_xor_b32_e32 v106, v106, v110
	v_and_or_b32 v107, v108, s19, v107
	v_xor_b32_e32 v103, v103, v105
	v_lshlrev_b32_e32 v105, 4, v106
	v_lshlrev_b32_e32 v156, 6, v107
	v_lshlrev_b32_e32 v103, 4, v103
	v_and_b32_e32 v105, 48, v105
	v_mov_b32_e32 v64, 0
	v_and_b32_e32 v144, 0x13c0, v109
	v_add_u32_e32 v106, 0x2000, v156
	v_and_b32_e32 v157, 48, v103
	v_lshl_or_b32 v158, v102, 6, v105
	s_mov_b32 s11, 0
	s_mov_b32 s9, -2
	v_mov_b32_e32 v65, v64
	v_mov_b32_e32 v66, v64
	v_mov_b32_e32 v67, v64
	v_mov_b32_e32 v68, v64
	v_mov_b32_e32 v69, v64
	v_mov_b32_e32 v70, v64
	v_mov_b32_e32 v71, v64
	v_mov_b32_e32 v72, v64
	v_mov_b32_e32 v73, v64
	v_mov_b32_e32 v74, v64
	v_mov_b32_e32 v75, v64
	v_mov_b32_e32 v76, v64
	v_mov_b32_e32 v77, v64
	v_mov_b32_e32 v78, v64
	v_mov_b32_e32 v79, v64
	v_mov_b32_e32 v80, v64
	v_mov_b32_e32 v81, v64
	v_mov_b32_e32 v82, v64
	v_mov_b32_e32 v83, v64
	v_mov_b32_e32 v84, v64
	v_mov_b32_e32 v85, v64
	v_lshl_or_b32 v159, v104, 6, v105
	v_or_b32_e32 v160, v157, v144
	v_add_u32_e32 v161, v157, v106
	v_mov_b32_e32 v102, v64
	v_mov_b32_e32 v103, v64
	v_mov_b32_e32 v104, v64
	v_mov_b32_e32 v105, v64
	v_mov_b32_e32 v106, v64
	v_mov_b32_e32 v107, v64
	v_mov_b32_e32 v108, v64
	v_mov_b32_e32 v109, v64
	v_mov_b32_e32 v110, v64
	v_mov_b32_e32 v111, v64
	v_mov_b32_e32 v112, v64
	s_waitcnt vmcnt(6)
	ds_write_b128 v158, v[90:93] offset:16384
	ds_write_b128 v158, v[86:89]
	s_waitcnt vmcnt(5)
	ds_write_b128 v159, v[94:97] offset:16384
	s_waitcnt vmcnt(4)
	ds_write_b128 v159, v[98:101]
	v_mov_b32_e32 v86, v64
	v_mov_b32_e32 v87, v64
	v_mov_b32_e32 v88, v64
	v_mov_b32_e32 v89, v64
	v_mov_b32_e32 v90, v64
	v_mov_b32_e32 v91, v64
	v_mov_b32_e32 v92, v64
	v_mov_b32_e32 v93, v64
	v_mov_b32_e32 v94, v64
	v_mov_b32_e32 v95, v64
	v_mov_b32_e32 v96, v64
	v_mov_b32_e32 v97, v64
	v_mov_b32_e32 v98, v64
	v_mov_b32_e32 v99, v64
	v_mov_b32_e32 v100, v64
	v_mov_b32_e32 v101, v64
	v_mov_b32_e32 v113, v64
	v_mov_b32_e32 v114, v64
	v_mov_b32_e32 v115, v64
	v_mov_b32_e32 v116, v64
	v_mov_b32_e32 v117, v64
	v_mov_b32_e32 v118, v64
	v_mov_b32_e32 v119, v64
	v_mov_b32_e32 v120, v64
	v_mov_b32_e32 v121, v64
	v_mov_b32_e32 v122, v64
	v_mov_b32_e32 v123, v64
	v_mov_b32_e32 v140, v64
	v_mov_b32_e32 v141, v64
	v_mov_b32_e32 v142, v64
	v_mov_b32_e32 v143, v64
	s_waitcnt lgkmcnt(0)
	s_barrier
.LBB0_1869:
	s_add_i32 s22, s11, 64
	s_min_u32 s6, s22, 0x3e0
	s_lshl_b32 s6, s6, 1
	v_lshl_add_u64 v[162:163], v[150:151], 0, s[6:7]
	v_lshl_add_u64 v[166:167], v[152:153], 0, s[6:7]
	v_lshl_add_u64 v[170:171], v[146:147], 0, s[6:7]
	v_lshl_add_u64 v[174:175], v[148:149], 0, s[6:7]
	global_load_dwordx4 v[162:165], v[162:163], off
	v_add_u32_e32 v198, v157, v156
	global_load_dwordx4 v[166:169], v[166:167], off
	v_add_u32_e32 v206, v157, v144
	global_load_dwordx4 v[170:173], v[170:171], off
	ds_read_b128 v[178:181], v198
	global_load_dwordx4 v[174:177], v[174:175], off
	ds_read_b128 v[182:185], v198 offset:1024
	ds_read_b128 v[186:189], v206 offset:16384
	ds_read_b128 v[190:193], v206 offset:17408
	ds_read_b128 v[194:197], v198 offset:2048
	ds_read_b128 v[198:201], v198 offset:3072
	ds_read_b128 v[202:205], v206 offset:18432
	ds_read_b128 v[206:209], v206 offset:19456
	s_waitcnt lgkmcnt(5)
	v_mfma_f32_16x16x32_bf16 v[140:143], v[186:189], v[178:181], v[140:143]
	s_waitcnt lgkmcnt(4)
	v_mfma_f32_16x16x32_bf16 v[120:123], v[190:193], v[178:181], v[120:123]
	s_waitcnt lgkmcnt(1)
	v_mfma_f32_16x16x32_bf16 v[116:119], v[202:205], v[178:181], v[116:119]
	s_waitcnt lgkmcnt(0)
	v_mfma_f32_16x16x32_bf16 v[112:115], v[206:209], v[178:181], v[112:115]
	v_mfma_f32_16x16x32_bf16 v[108:111], v[186:189], v[182:185], v[108:111]
	v_mfma_f32_16x16x32_bf16 v[104:107], v[190:193], v[182:185], v[104:107]
	v_mfma_f32_16x16x32_bf16 v[100:103], v[202:205], v[182:185], v[100:103]
	v_mfma_f32_16x16x32_bf16 v[96:99], v[206:209], v[182:185], v[96:99]
	v_mfma_f32_16x16x32_bf16 v[92:95], v[186:189], v[194:197], v[92:95]
	v_mfma_f32_16x16x32_bf16 v[88:91], v[190:193], v[194:197], v[88:91]
	v_mfma_f32_16x16x32_bf16 v[84:87], v[202:205], v[194:197], v[84:87]
	v_mfma_f32_16x16x32_bf16 v[80:83], v[206:209], v[194:197], v[80:83]
	v_mfma_f32_16x16x32_bf16 v[76:79], v[186:189], v[198:201], v[76:79]
	v_mfma_f32_16x16x32_bf16 v[72:75], v[190:193], v[198:201], v[72:75]
	v_mfma_f32_16x16x32_bf16 v[68:71], v[202:205], v[198:201], v[68:71]
	v_mfma_f32_16x16x32_bf16 v[64:67], v[206:209], v[198:201], v[64:67]
	s_min_u32 s6, s11, 0x380
	s_lshl_b32 s6, s6, 1
	s_waitcnt vmcnt(5)
	ds_write_b128 v158, v[124:127] offset:24576
	s_waitcnt vmcnt(4)
	ds_write_b128 v158, v[132:135] offset:28672
	v_lshl_add_u64 v[124:125], v[150:151], 0, s[6:7]
	v_lshl_add_u64 v[126:127], v[152:153], 0, s[6:7]
	v_lshl_add_u64 v[132:133], v[146:147], 0, s[6:7]
	v_lshl_add_u64 v[134:135], v[148:149], 0, s[6:7]
	ds_write_b128 v158, v[128:131] offset:8192
	s_waitcnt vmcnt(4)
	ds_write_b128 v158, v[136:139] offset:12288
	s_waitcnt lgkmcnt(0)
	s_barrier
	global_load_dwordx4 v[128:131], v[124:125], off offset:192
	global_load_dwordx4 v[136:139], v[126:127], off offset:192
	ds_read_b128 v[178:181], v161
	global_load_dwordx4 v[124:127], v[132:133], off offset:192
	ds_read_b128 v[182:185], v160 offset:24576
	global_load_dwordx4 v[132:135], v[134:135], off offset:192
	ds_read_b128 v[186:189], v161 offset:1024
	ds_read_b128 v[190:193], v160 offset:25600
	ds_read_b128 v[194:197], v161 offset:2048
	ds_read_b128 v[198:201], v160 offset:26624
	ds_read_b128 v[202:205], v161 offset:3072
	ds_read_b128 v[206:209], v160 offset:27648
	s_waitcnt lgkmcnt(6)
	v_mfma_f32_16x16x32_bf16 v[140:143], v[182:185], v[178:181], v[140:143]
	s_waitcnt lgkmcnt(4)
	v_mfma_f32_16x16x32_bf16 v[120:123], v[190:193], v[178:181], v[120:123]
	s_waitcnt lgkmcnt(2)
	v_mfma_f32_16x16x32_bf16 v[116:119], v[198:201], v[178:181], v[116:119]
	s_waitcnt lgkmcnt(0)
	v_mfma_f32_16x16x32_bf16 v[112:115], v[206:209], v[178:181], v[112:115]
	v_mfma_f32_16x16x32_bf16 v[108:111], v[182:185], v[186:189], v[108:111]
	v_mfma_f32_16x16x32_bf16 v[104:107], v[190:193], v[186:189], v[104:107]
	v_mfma_f32_16x16x32_bf16 v[100:103], v[198:201], v[186:189], v[100:103]
	v_mfma_f32_16x16x32_bf16 v[96:99], v[206:209], v[186:189], v[96:99]
	v_mfma_f32_16x16x32_bf16 v[92:95], v[182:185], v[194:197], v[92:95]
	v_mfma_f32_16x16x32_bf16 v[88:91], v[190:193], v[194:197], v[88:91]
	v_mfma_f32_16x16x32_bf16 v[84:87], v[198:201], v[194:197], v[84:87]
	v_mfma_f32_16x16x32_bf16 v[80:83], v[206:209], v[194:197], v[80:83]
	v_mfma_f32_16x16x32_bf16 v[76:79], v[182:185], v[202:205], v[76:79]
	v_mfma_f32_16x16x32_bf16 v[72:75], v[190:193], v[202:205], v[72:75]
	v_mfma_f32_16x16x32_bf16 v[68:71], v[198:201], v[202:205], v[68:71]
	v_mfma_f32_16x16x32_bf16 v[64:67], v[206:209], v[202:205], v[64:67]
	s_add_i32 s9, s9, 2
	s_cmp_lt_u32 s9, 30
	s_mov_b32 s11, s22
	s_waitcnt vmcnt(7)
	ds_write_b128 v158, v[162:165]
	s_waitcnt vmcnt(6)
	ds_write_b128 v159, v[166:169]
	s_waitcnt vmcnt(5)
	ds_write_b128 v158, v[170:173] offset:16384
	s_waitcnt vmcnt(4)
	ds_write_b128 v159, v[174:177] offset:16384
	s_waitcnt lgkmcnt(0)
	s_barrier
	s_cbranch_scc1 .LBB0_1869
	s_waitcnt vmcnt(3)
	v_mov_b32_e32 v128, v220
	s_waitcnt vmcnt(1)
	v_ashrrev_i32_e32 v124, 1, v128
	v_and_b32_e32 v124, 0xffffffc0, v124
	v_add_u32_e32 v124, s10, v124
	v_and_or_b32 v124, v128, 15, v124
	v_ashrrev_i32_e32 v125, 31, v124
	v_lshl_add_u64 v[126:127], v[124:125], 2, s[0:1]
	global_load_dword v144, v[126:127], off
	v_and_b32_e32 v126, 64, v128
	v_lshrrev_b32_e32 v127, 2, v128
	v_or_b32_e32 v128, 16, v124
	v_ashrrev_i32_e32 v129, 31, v128
	v_lshl_add_u64 v[136:137], v[128:129], 2, s[0:1]
	global_load_dword v156, v[136:137], off
	v_or_b32_e32 v130, 32, v124
	v_ashrrev_i32_e32 v131, 31, v130
	v_lshlrev_b64 v[152:153], 12, v[128:129]
	v_lshl_add_u64 v[128:129], v[130:131], 2, s[0:1]
	global_load_dword v157, v[128:129], off
	s_waitcnt vmcnt(3)
	v_or_b32_e32 v132, 48, v124
	v_ashrrev_i32_e32 v133, 31, v132
	v_lshlrev_b64 v[150:151], 12, v[130:131]
	v_lshl_add_u64 v[130:131], v[132:133], 2, s[0:1]
	v_and_b32_e32 v127, 12, v127
	v_or3_b32 v126, v126, v127, s8
	v_ashrrev_i32_e32 v127, 31, v126
	v_lshlrev_b64 v[134:135], 2, v[126:127]
	v_lshl_add_u64 v[138:139], s[70:71], 0, v[134:135]
	v_lshlrev_b64 v[124:125], 12, v[124:125]
	v_lshlrev_b64 v[146:147], 12, v[132:133]
	v_lshl_add_u64 v[126:127], v[138:139], 0, v[124:125]
	v_lshl_add_u64 v[132:133], v[138:139], 0, v[152:153]
	v_lshl_add_u64 v[136:137], v[138:139], 0, v[150:151]
	v_lshl_add_u64 v[148:149], v[138:139], 0, v[146:147]
	v_lshl_add_u64 v[124:125], s[70:71], 0, v[124:125]
	v_lshl_add_u64 v[124:125], v[124:125], 0, v[134:135]
	global_load_dwordx4 v[160:163], v[148:149], off offset:128
	global_load_dwordx4 v[164:167], v[136:137], off
	global_load_dwordx4 v[168:171], v[136:137], off offset:64
	global_load_dwordx4 v[172:175], v[136:137], off offset:128
	global_load_dwordx4 v[176:179], v[132:133], off
	global_load_dwordx4 v[180:183], v[132:133], off offset:128
	global_load_dwordx4 v[184:187], v[132:133], off offset:192
	global_load_dwordx4 v[188:191], v[126:127], off
	global_load_dwordx4 v[192:195], v[126:127], off offset:64
	global_load_dwordx4 v[196:199], v[126:127], off offset:128
	global_load_dwordx4 v[200:203], v[126:127], off offset:192
	s_waitcnt vmcnt(13)
	v_fmamk_f32 v128, v144, 0x3a800000, v154
	global_load_dword v144, v[130:131], off
	v_mul_f32_e32 v129, 0x4b800000, v128
	v_cmp_gt_f32_e32 vcc, s20, v128
	s_waitcnt vmcnt(0)
	v_fmamk_f32 v144, v144, 0x3a800000, v154
	v_cndmask_b32_e32 v128, v128, v129, vcc
	v_rsq_f32_e32 v128, v128
	s_nop 0
	v_mul_f32_e32 v129, 0x45800000, v128
	v_cndmask_b32_e32 v138, v128, v129, vcc
	v_mul_f32_e32 v128, v140, v138
	v_mul_f32_e32 v129, v141, v138
	v_mul_f32_e32 v130, v142, v138
	v_mul_f32_e32 v131, v143, v138
	v_mul_f32_e32 v119, v119, v138
	v_mul_f32_e32 v139, v112, v138
	v_mul_f32_e32 v112, 0xbfb8aa3b, v128
	v_mul_f32_e32 v128, 0xbfb8aa3b, v129
	v_mul_f32_e32 v129, 0xbfb8aa3b, v130
	v_mul_f32_e32 v130, 0xbfb8aa3b, v131
	v_mul_f32_e32 v119, 0xbfb8aa3b, v119
	v_exp_f32_e32 v130, v130
	v_exp_f32_e32 v119, v119
	v_mul_f32_e32 v120, v120, v138
	v_mul_f32_e32 v121, v121, v138
	v_mul_f32_e32 v122, v122, v138
	v_mul_f32_e32 v123, v123, v138
	v_mul_f32_e32 v116, v116, v138
	v_mul_f32_e32 v117, v117, v138
	v_mul_f32_e32 v118, v118, v138
	v_add_f32_e32 v130, 1.0, v130
	v_mul_f32_e32 v113, v113, v138
	v_mul_f32_e32 v114, v114, v138
	v_mul_f32_e32 v115, v115, v138
	v_fmamk_f32 v138, v156, 0x3a800000, v154
	v_add_f32_e32 v142, 1.0, v119
	v_rcp_f32_e32 v119, v130
	v_mul_f32_e32 v130, 0xbfb8aa3b, v139
	v_mul_f32_e32 v139, 0x4b800000, v138
	v_cmp_gt_f32_e32 vcc, s20, v138
	v_mul_f32_e32 v117, 0xbfb8aa3b, v117
	v_mul_f32_e32 v118, 0xbfb8aa3b, v118
	v_cndmask_b32_e32 v138, v138, v139, vcc
	v_exp_f32_e32 v129, v129
	v_exp_f32_e32 v117, v117
	v_rsq_f32_e32 v138, v138
	v_exp_f32_e32 v118, v118
	v_mul_f32_e32 v116, 0xbfb8aa3b, v116
	v_exp_f32_e32 v112, v112
	v_exp_f32_e32 v116, v116
	v_add_f32_e32 v129, 1.0, v129
	v_add_f32_e32 v140, 1.0, v117
	v_mul_f32_e32 v139, 0x45800000, v138
	v_add_f32_e32 v141, 1.0, v118
	v_rcp_f32_e32 v118, v129
	v_rcp_f32_e32 v129, v140
	v_cndmask_b32_e32 v140, v138, v139, vcc
	v_mul_f32_e32 v104, v104, v140
	v_add_f32_e32 v112, 1.0, v112
	v_mul_f32_e32 v104, 0xbfb8aa3b, v104
	v_add_f32_e32 v131, 1.0, v116
	v_rcp_f32_e32 v116, v112
	v_rcp_f32_e32 v112, v141
	v_mul_f32_e32 v108, v108, v140
	v_mul_f32_e32 v109, v109, v140
	v_mul_f32_e32 v110, v110, v140
	v_mul_f32_e32 v111, v111, v140
	v_exp_f32_e32 v141, v104
	v_mul_f32_e32 v104, v105, v140
	v_mul_f32_e32 v106, v106, v140
	v_mul_f32_e32 v107, v107, v140
	v_mul_f32_e32 v100, v100, v140
	v_mul_f32_e32 v101, v101, v140
	v_mul_f32_e32 v102, v102, v140
	v_mul_f32_e32 v103, v103, v140
	v_mul_f32_e32 v96, v96, v140
	v_mul_f32_e32 v97, v97, v140
	v_mul_f32_e32 v98, v98, v140
	v_mul_f32_e32 v99, v99, v140
	v_fmamk_f32 v140, v157, 0x3a800000, v154
	global_load_dwordx4 v[156:159], v[148:149], off
	v_exp_f32_e32 v128, v128
	v_mul_f32_e32 v113, 0xbfb8aa3b, v113
	v_lshl_add_u64 v[138:139], s[70:71], 0, v[152:153]
	v_mul_f32_e32 v104, 0xbfb8aa3b, v104
	v_add_f32_e32 v128, 1.0, v128
	v_rcp_f32_e32 v117, v128
	v_rcp_f32_e32 v128, v131
	v_exp_f32_e32 v131, v113
	v_rcp_f32_e32 v113, v142
	v_exp_f32_e32 v142, v104
	v_lshl_add_u64 v[104:105], v[138:139], 0, v[134:135]
	v_add_f32_e32 v138, 1.0, v141
	v_mul_f32_e32 v141, 0x4b800000, v140
	v_cmp_gt_f32_e32 vcc, s20, v140
	v_add_f32_e32 v139, 1.0, v142
	v_mul_f32_e32 v120, 0xbfb8aa3b, v120
	v_cndmask_b32_e32 v140, v140, v141, vcc
	v_rsq_f32_e32 v140, v140
	v_mul_f32_e32 v121, 0xbfb8aa3b, v121
	v_mul_f32_e32 v122, 0xbfb8aa3b, v122
	v_mul_f32_e32 v123, 0xbfb8aa3b, v123
	v_mul_f32_e32 v141, 0x45800000, v140
	v_cndmask_b32_e32 v152, v140, v141, vcc
	v_mul_f32_e32 v84, v84, v152
	v_mul_f32_e32 v88, v88, v152
	v_mul_f32_e32 v84, 0xbfb8aa3b, v84
	v_mul_f32_e32 v85, v85, v152
	v_mul_f32_e32 v88, 0xbfb8aa3b, v88
	v_exp_f32_e32 v84, v84
	v_mul_f32_e32 v85, 0xbfb8aa3b, v85
	v_exp_f32_e32 v142, v88
	v_exp_f32_e32 v85, v85
	v_mul_f32_e32 v88, v89, v152
	v_lshl_add_u64 v[140:141], s[70:71], 0, v[150:151]
	v_mul_f32_e32 v88, 0xbfb8aa3b, v88
	v_add_f32_e32 v84, 1.0, v84
	v_mul_f32_e32 v92, v92, v152
	v_mul_f32_e32 v93, v93, v152
	v_mul_f32_e32 v94, v94, v152
	v_mul_f32_e32 v95, v95, v152
	v_exp_f32_e32 v143, v88
	v_lshl_add_u64 v[88:89], v[140:141], 0, v[134:135]
	v_add_f32_e32 v140, 1.0, v142
	v_mul_f32_e32 v90, v90, v152
	v_mul_f32_e32 v91, v91, v152
	v_rcp_f32_e32 v142, v84
	v_add_f32_e32 v84, 1.0, v85
	v_mul_f32_e32 v85, v86, v152
	v_mul_f32_e32 v86, v87, v152
	v_mul_f32_e32 v80, v80, v152
	v_mul_f32_e32 v81, v81, v152
	v_mul_f32_e32 v82, v82, v152
	v_mul_f32_e32 v83, v83, v152
	v_mul_f32_e32 v152, 0x4b800000, v144
	v_cmp_gt_f32_e32 vcc, s20, v144
	v_mul_f32_e32 v85, 0xbfb8aa3b, v85
	v_exp_f32_e32 v85, v85
	v_cndmask_b32_e32 v144, v144, v152, vcc
	v_rsq_f32_e32 v144, v144
	v_mul_f32_e32 v86, 0xbfb8aa3b, v86
	v_exp_f32_e32 v86, v86
	v_add_f32_e32 v141, 1.0, v143
	v_mul_f32_e32 v152, 0x45800000, v144
	v_cndmask_b32_e32 v144, v144, v152, vcc
	v_mul_f32_e32 v76, v76, v144
	v_mul_f32_e32 v76, 0xbfb8aa3b, v76
	v_mul_f32_e32 v77, v77, v144
	v_exp_f32_e32 v76, v76
	v_mul_f32_e32 v77, 0xbfb8aa3b, v77
	v_exp_f32_e32 v77, v77
	v_rcp_f32_e32 v143, v84
	v_add_f32_e32 v76, 1.0, v76
	v_rcp_f32_e32 v152, v76
	v_add_f32_e32 v76, 1.0, v77
	v_mul_f32_e32 v77, v78, v144
	v_mul_f32_e32 v77, 0xbfb8aa3b, v77
	v_mul_f32_e32 v78, v79, v144
	v_exp_f32_e32 v77, v77
	v_mul_f32_e32 v78, 0xbfb8aa3b, v78
	v_exp_f32_e32 v79, v78
	v_rcp_f32_e32 v153, v76
	v_add_f32_e32 v76, 1.0, v77
	v_rcp_f32_e32 v78, v76
	v_add_f32_e32 v76, 1.0, v79
	v_rcp_f32_e32 v79, v76
	v_add_f32_e32 v84, 1.0, v85
	v_rcp_f32_e32 v150, v84
	v_add_f32_e32 v84, 1.0, v86
	v_lshl_add_u64 v[76:77], s[70:71], 0, v[146:147]
	v_rcp_f32_e32 v151, v84
	global_load_dwordx4 v[84:87], v[148:149], off offset:64
	v_lshl_add_u64 v[76:77], v[76:77], 0, v[134:135]
	global_load_dwordx4 v[146:149], v[148:149], off offset:192
	s_waitcnt vmcnt(2)
	v_pk_fma_f32 v[60:61], v[60:61], v[152:153], v[156:157]
	global_load_dwordx4 v[134:137], v[136:137], off offset:192
	v_pk_fma_f32 v[62:63], v[62:63], v[78:79], v[158:159]
	global_load_dwordx4 v[156:159], v[132:133], off offset:64
	v_mul_f32_e32 v72, v72, v144
	v_mul_f32_e32 v73, v73, v144
	v_mul_f32_e32 v74, v74, v144
	v_mul_f32_e32 v75, v75, v144
	v_mul_f32_e32 v68, v68, v144
	v_mul_f32_e32 v69, v69, v144
	v_mul_f32_e32 v70, v70, v144
	v_mul_f32_e32 v71, v71, v144
	v_mul_f32_e32 v64, v64, v144
	v_mul_f32_e32 v65, v65, v144
	v_mul_f32_e32 v66, v66, v144
	v_mul_f32_e32 v67, v67, v144
	v_mul_f32_e32 v114, 0xbfb8aa3b, v114
	v_mul_f32_e32 v115, 0xbfb8aa3b, v115
	v_mul_f32_e32 v108, 0xbfb8aa3b, v108
	v_mul_f32_e32 v109, 0xbfb8aa3b, v109
	v_mul_f32_e32 v110, 0xbfb8aa3b, v110
	v_mul_f32_e32 v111, 0xbfb8aa3b, v111
	v_mul_f32_e32 v106, 0xbfb8aa3b, v106
	v_mul_f32_e32 v107, 0xbfb8aa3b, v107
	v_mul_f32_e32 v100, 0xbfb8aa3b, v100
	v_mul_f32_e32 v101, 0xbfb8aa3b, v101
	v_mul_f32_e32 v102, 0xbfb8aa3b, v102
	v_mul_f32_e32 v103, 0xbfb8aa3b, v103
	v_mul_f32_e32 v96, 0xbfb8aa3b, v96
	v_mul_f32_e32 v97, 0xbfb8aa3b, v97
	v_mul_f32_e32 v98, 0xbfb8aa3b, v98
	v_mul_f32_e32 v99, 0xbfb8aa3b, v99
	v_mul_f32_e32 v92, 0xbfb8aa3b, v92
	v_mul_f32_e32 v93, 0xbfb8aa3b, v93
	v_mul_f32_e32 v94, 0xbfb8aa3b, v94
	v_mul_f32_e32 v95, 0xbfb8aa3b, v95
	v_mul_f32_e32 v90, 0xbfb8aa3b, v90
	v_mul_f32_e32 v91, 0xbfb8aa3b, v91
	v_mul_f32_e32 v80, 0xbfb8aa3b, v80
	v_mul_f32_e32 v81, 0xbfb8aa3b, v81
	v_mul_f32_e32 v82, 0xbfb8aa3b, v82
	v_mul_f32_e32 v83, 0xbfb8aa3b, v83
	v_mul_f32_e32 v72, 0xbfb8aa3b, v72
	v_mul_f32_e32 v73, 0xbfb8aa3b, v73
	v_mul_f32_e32 v74, 0xbfb8aa3b, v74
	v_mul_f32_e32 v75, 0xbfb8aa3b, v75
	v_mul_f32_e32 v68, 0xbfb8aa3b, v68
	v_mul_f32_e32 v69, 0xbfb8aa3b, v69
	v_mul_f32_e32 v70, 0xbfb8aa3b, v70
	v_mul_f32_e32 v71, 0xbfb8aa3b, v71
	v_mul_f32_e32 v64, 0xbfb8aa3b, v64
	v_mul_f32_e32 v65, 0xbfb8aa3b, v65
	v_mul_f32_e32 v66, 0xbfb8aa3b, v66
	v_mul_f32_e32 v67, 0xbfb8aa3b, v67
	v_exp_f32_e32 v120, v120
	v_exp_f32_e32 v121, v121
	v_exp_f32_e32 v122, v122
	v_exp_f32_e32 v123, v123
	v_exp_f32_e32 v130, v130
	v_exp_f32_e32 v114, v114
	v_exp_f32_e32 v115, v115
	v_exp_f32_e32 v108, v108
	v_exp_f32_e32 v109, v109
	v_exp_f32_e32 v110, v110
	v_exp_f32_e32 v111, v111
	v_exp_f32_e32 v106, v106
	v_exp_f32_e32 v107, v107
	v_exp_f32_e32 v100, v100
	v_exp_f32_e32 v101, v101
	v_exp_f32_e32 v102, v102
	v_exp_f32_e32 v103, v103
	v_exp_f32_e32 v96, v96
	v_exp_f32_e32 v97, v97
	v_exp_f32_e32 v98, v98
	v_exp_f32_e32 v99, v99
	v_exp_f32_e32 v92, v92
	v_exp_f32_e32 v93, v93
	v_exp_f32_e32 v94, v94
	v_exp_f32_e32 v95, v95
	v_exp_f32_e32 v90, v90
	v_exp_f32_e32 v91, v91
	v_exp_f32_e32 v80, v80
	v_exp_f32_e32 v81, v81
	v_exp_f32_e32 v82, v82
	v_exp_f32_e32 v83, v83
	v_exp_f32_e32 v72, v72
	v_exp_f32_e32 v73, v73
	v_exp_f32_e32 v74, v74
	v_exp_f32_e32 v75, v75
	v_exp_f32_e32 v68, v68
	v_exp_f32_e32 v69, v69
	v_exp_f32_e32 v70, v70
	v_exp_f32_e32 v71, v71
	v_exp_f32_e32 v64, v64
	v_exp_f32_e32 v65, v65
	v_exp_f32_e32 v66, v66
	v_exp_f32_e32 v67, v67
	v_add_f32_e32 v120, 1.0, v120
	v_add_f32_e32 v121, 1.0, v121
	v_add_f32_e32 v122, 1.0, v122
	v_add_f32_e32 v123, 1.0, v123
	v_add_f32_e32 v130, 1.0, v130
	v_add_f32_e32 v131, 1.0, v131
	v_add_f32_e32 v114, 1.0, v114
	v_add_f32_e32 v115, 1.0, v115
	v_add_f32_e32 v108, 1.0, v108
	v_add_f32_e32 v109, 1.0, v109
	v_add_f32_e32 v110, 1.0, v110
	v_add_f32_e32 v111, 1.0, v111
	v_add_f32_e32 v106, 1.0, v106
	v_add_f32_e32 v107, 1.0, v107
	v_add_f32_e32 v100, 1.0, v100
	v_add_f32_e32 v101, 1.0, v101
	v_add_f32_e32 v102, 1.0, v102
	v_add_f32_e32 v103, 1.0, v103
	v_add_f32_e32 v96, 1.0, v96
	v_add_f32_e32 v97, 1.0, v97
	v_add_f32_e32 v98, 1.0, v98
	v_add_f32_e32 v99, 1.0, v99
	v_add_f32_e32 v92, 1.0, v92
	v_add_f32_e32 v93, 1.0, v93
	v_add_f32_e32 v94, 1.0, v94
	v_add_f32_e32 v95, 1.0, v95
	v_add_f32_e32 v90, 1.0, v90
	v_add_f32_e32 v91, 1.0, v91
	v_add_f32_e32 v80, 1.0, v80
	v_add_f32_e32 v81, 1.0, v81
	v_add_f32_e32 v82, 1.0, v82
	v_add_f32_e32 v83, 1.0, v83
	v_add_f32_e32 v72, 1.0, v72
	v_add_f32_e32 v73, 1.0, v73
	v_add_f32_e32 v74, 1.0, v74
	v_add_f32_e32 v75, 1.0, v75
	v_add_f32_e32 v68, 1.0, v68
	v_add_f32_e32 v69, 1.0, v69
	v_add_f32_e32 v70, 1.0, v70
	v_add_f32_e32 v71, 1.0, v71
	v_add_f32_e32 v64, 1.0, v64
	v_add_f32_e32 v65, 1.0, v65
	v_add_f32_e32 v66, 1.0, v66
	v_add_f32_e32 v67, 1.0, v67
	v_rcp_f32_e32 v120, v120
	v_rcp_f32_e32 v121, v121
	v_rcp_f32_e32 v122, v122
	v_rcp_f32_e32 v123, v123
	v_rcp_f32_e32 v130, v130
	v_rcp_f32_e32 v131, v131
	v_rcp_f32_e32 v114, v114
	v_rcp_f32_e32 v115, v115
	v_rcp_f32_e32 v108, v108
	v_rcp_f32_e32 v109, v109
	v_rcp_f32_e32 v110, v110
	v_rcp_f32_e32 v111, v111
	v_rcp_f32_e32 v138, v138
	v_rcp_f32_e32 v139, v139
	v_rcp_f32_e32 v106, v106
	v_rcp_f32_e32 v107, v107
	v_rcp_f32_e32 v100, v100
	v_rcp_f32_e32 v101, v101
	v_rcp_f32_e32 v102, v102
	v_rcp_f32_e32 v103, v103
	v_rcp_f32_e32 v96, v96
	v_rcp_f32_e32 v97, v97
	v_rcp_f32_e32 v98, v98
	v_rcp_f32_e32 v99, v99
	v_rcp_f32_e32 v92, v92
	v_rcp_f32_e32 v93, v93
	v_rcp_f32_e32 v94, v94
	v_rcp_f32_e32 v95, v95
	v_rcp_f32_e32 v140, v140
	v_rcp_f32_e32 v141, v141
	v_rcp_f32_e32 v90, v90
	v_rcp_f32_e32 v91, v91
	v_rcp_f32_e32 v80, v80
	v_rcp_f32_e32 v81, v81
	v_rcp_f32_e32 v82, v82
	v_rcp_f32_e32 v83, v83
	v_rcp_f32_e32 v72, v72
	v_rcp_f32_e32 v73, v73
	v_rcp_f32_e32 v74, v74
	v_rcp_f32_e32 v75, v75
	v_rcp_f32_e32 v68, v68
	v_rcp_f32_e32 v69, v69
	v_rcp_f32_e32 v70, v70
	v_rcp_f32_e32 v71, v71
	v_rcp_f32_e32 v64, v64
	v_rcp_f32_e32 v65, v65
	v_rcp_f32_e32 v66, v66
	v_rcp_f32_e32 v67, v67
	s_waitcnt vmcnt(3)
	v_pk_fma_f32 v[56:57], v[56:57], v[72:73], v[84:85]
	v_pk_fma_f32 v[58:59], v[58:59], v[74:75], v[86:87]
	v_pk_fma_f32 v[4:5], v[4:5], v[68:69], v[160:161]
	v_pk_fma_f32 v[6:7], v[6:7], v[70:71], v[162:163]
	s_waitcnt vmcnt(2)
	v_pk_fma_f32 v[0:1], v[0:1], v[64:65], v[146:147]
	v_pk_fma_f32 v[2:3], v[2:3], v[66:67], v[148:149]
	v_pk_fma_f32 v[32:33], v[32:33], v[92:93], v[164:165]
	v_pk_fma_f32 v[34:35], v[34:35], v[94:95], v[166:167]
	v_pk_fma_f32 v[24:25], v[24:25], v[140:141], v[168:169]
	v_pk_fma_f32 v[26:27], v[26:27], v[90:91], v[170:171]
	v_pk_fma_f32 v[12:13], v[12:13], v[142:143], v[172:173]
	v_pk_fma_f32 v[14:15], v[14:15], v[150:151], v[174:175]
	s_waitcnt vmcnt(1)
	v_pk_fma_f32 v[8:9], v[8:9], v[80:81], v[134:135]
	v_pk_fma_f32 v[10:11], v[10:11], v[82:83], v[136:137]
	v_pk_fma_f32 v[44:45], v[44:45], v[108:109], v[176:177]
	v_pk_fma_f32 v[46:47], v[46:47], v[110:111], v[178:179]
	s_waitcnt vmcnt(0)
	v_pk_fma_f32 v[36:37], v[36:37], v[138:139], v[156:157]
	v_pk_fma_f32 v[38:39], v[38:39], v[106:107], v[158:159]
	v_pk_fma_f32 v[28:29], v[28:29], v[100:101], v[180:181]
	v_pk_fma_f32 v[30:31], v[30:31], v[102:103], v[182:183]
	v_pk_fma_f32 v[16:17], v[16:17], v[96:97], v[184:185]
	v_pk_fma_f32 v[18:19], v[18:19], v[98:99], v[186:187]
	v_pk_fma_f32 v[52:53], v[52:53], v[116:117], v[188:189]
	v_pk_fma_f32 v[54:55], v[54:55], v[118:119], v[190:191]
	v_pk_fma_f32 v[48:49], v[48:49], v[120:121], v[192:193]
	v_pk_fma_f32 v[50:51], v[50:51], v[122:123], v[194:195]
	v_pk_fma_f32 v[40:41], v[40:41], v[128:129], v[196:197]
	v_pk_fma_f32 v[42:43], v[42:43], v[112:113], v[198:199]
	v_pk_fma_f32 v[20:21], v[20:21], v[130:131], v[200:201]
	v_pk_fma_f32 v[22:23], v[22:23], v[114:115], v[202:203]
	s_add_i32 s21, s21, s74
	s_cmpk_lt_i32 s21, 0x800
	global_store_dwordx4 v[124:125], v[52:55], off
	global_store_dwordx4 v[124:125], v[48:51], off offset:64
	global_store_dwordx4 v[124:125], v[40:43], off offset:128
	global_store_dwordx4 v[124:125], v[20:23], off offset:192
	global_store_dwordx4 v[104:105], v[44:47], off
	global_store_dwordx4 v[104:105], v[36:39], off offset:64
	global_store_dwordx4 v[104:105], v[28:31], off offset:128
	global_store_dwordx4 v[104:105], v[16:19], off offset:192
	global_store_dwordx4 v[88:89], v[32:35], off
	global_store_dwordx4 v[88:89], v[24:27], off offset:64
	global_store_dwordx4 v[88:89], v[12:15], off offset:128
	global_store_dwordx4 v[88:89], v[8:11], off offset:192
	global_store_dwordx4 v[76:77], v[60:63], off
	global_store_dwordx4 v[76:77], v[56:59], off offset:64
	global_store_dwordx4 v[76:77], v[4:7], off offset:128
	global_store_dwordx4 v[76:77], v[0:3], off offset:192
	s_cbranch_scc1 .LBB0_1866
